# v3: gate_proj/small FFN-out/attn prologue loads pipelined; EVEC commit wait relaxed; s_setprio moved outside the barrier-bounded MFMA segments
# speedup vs baseline: 1.0009x; 1.0009x over previous
.LBB0_491:
	s_ashr_i32 s17, s16, 31
	s_lshl_b64 s[18:19], s[16:17], 19
	s_add_u32 s17, s3, s18
	s_addc_u32 s20, s30, s19
	s_ashr_i32 s15, s14, 31
	s_lshl_b64 s[18:19], s[14:15], 19
	s_add_u32 s15, s31, s18
	s_addc_u32 s23, s34, s19
	s_add_i32 s29, 0, 0x10000
	s_and_b64 s[18:19], s[38:39], exec
	s_cselect_b32 s19, s20, s27
	s_cselect_b32 s18, s17, s26
	s_add_i32 s58, 0, 0x14000
	v_add_u32_e32 v2, s29, v174
	v_add_u32_e32 v85, s58, v174
	ds_read_b128 v[4:7], v2
	ds_read_b128 v[8:11], v2 offset:1024
	ds_read_b128 v[12:15], v2 offset:2048
	ds_read_b128 v[16:19], v2 offset:3072
	ds_read_b128 v[20:23], v85
	ds_read_b128 v[24:27], v85 offset:1024
	ds_read_b128 v[28:31], v85 offset:2048
	ds_read_b128 v[32:35], v85 offset:3072
	s_and_b64 s[20:21], s[38:39], exec
	s_cselect_b32 s21, s23, s25
	s_cselect_b32 s20, s15, s24
	s_add_u32 s54, s26, 0x40080
	s_addc_u32 s55, s27, 0
	s_add_i32 s15, s44, 0xc000
	v_lshl_add_u64 v[68:69], s[54:55], 0, v[0:1]
	s_mov_b32 m0, s15
	s_add_i32 s17, s44, 0xe000
	ds_read_b128 v[36:39], v175
	ds_read_b128 v[40:43], v175 offset:1024
	ds_read_b128 v[44:47], v175 offset:2048
	ds_read_b128 v[48:51], v175 offset:3072
	ds_read_b128 v[52:55], v175 offset:4096
	ds_read_b128 v[56:59], v175 offset:5120
	ds_read_b128 v[60:63], v175 offset:6144
	ds_read_b128 v[64:67], v175 offset:7168
	global_load_lds_dwordx4 v[68:69], off
	v_lshl_add_u64 v[68:69], s[54:55], 0, v[166:167]
	s_mov_b32 m0, s17
	s_nop 0
	global_load_lds_dwordx4 v[68:69], off
	s_waitcnt vmcnt(8)
	s_waitcnt lgkmcnt(0)
	s_setprio 1
	s_barrier
	v_mfma_f32_16x16x32_bf16 v[68:71], v[4:7], v[36:39], 0
	v_mfma_f32_16x16x32_bf16 v[72:75], v[12:15], v[36:39], 0
	v_mfma_f32_16x16x32_bf16 v[80:83], v[12:15], v[44:47], 0
	v_mfma_f32_16x16x32_bf16 v[76:79], v[4:7], v[44:47], 0
	v_mfma_f32_16x16x32_bf16 v[86:89], v[4:7], v[52:55], 0
	v_mfma_f32_16x16x32_bf16 v[68:71], v[8:11], v[40:43], v[68:71]
	v_mfma_f32_16x16x32_bf16 v[72:75], v[16:19], v[40:43], v[72:75]
	v_mfma_f32_16x16x32_bf16 v[140:143], v[8:11], v[48:51], v[76:79]
	v_mfma_f32_16x16x32_bf16 v[80:83], v[16:19], v[48:51], v[80:83]
	v_mfma_f32_16x16x32_bf16 v[144:147], v[8:11], v[56:59], v[86:89]
	v_mfma_f32_16x16x32_bf16 v[92:95], v[12:15], v[52:55], 0
	v_mfma_f32_16x16x32_bf16 v[96:99], v[4:7], v[60:63], 0
	v_mfma_f32_16x16x32_bf16 v[100:103], v[12:15], v[60:63], 0
	v_mfma_f32_16x16x32_bf16 v[92:95], v[16:19], v[56:59], v[92:95]
	v_mfma_f32_16x16x32_bf16 v[96:99], v[8:11], v[64:67], v[96:99]
	v_mfma_f32_16x16x32_bf16 v[100:103], v[16:19], v[64:67], v[100:103]
	v_mfma_f32_16x16x32_bf16 v[104:107], v[20:23], v[36:39], 0
	v_mfma_f32_16x16x32_bf16 v[36:39], v[28:31], v[36:39], 0
	v_mfma_f32_16x16x32_bf16 v[104:107], v[24:27], v[40:43], v[104:107]
	v_mfma_f32_16x16x32_bf16 v[36:39], v[32:35], v[40:43], v[36:39]
	v_mfma_f32_16x16x32_bf16 v[40:43], v[20:23], v[44:47], 0
	v_mfma_f32_16x16x32_bf16 v[44:47], v[28:31], v[44:47], 0
	v_mfma_f32_16x16x32_bf16 v[40:43], v[24:27], v[48:51], v[40:43]
	v_mfma_f32_16x16x32_bf16 v[44:47], v[32:35], v[48:51], v[44:47]
	v_mfma_f32_16x16x32_bf16 v[48:51], v[20:23], v[52:55], 0
	v_mfma_f32_16x16x32_bf16 v[52:55], v[28:31], v[52:55], 0
	v_mfma_f32_16x16x32_bf16 v[48:51], v[24:27], v[56:59], v[48:51]
	v_mfma_f32_16x16x32_bf16 v[52:55], v[32:35], v[56:59], v[52:55]
	v_mfma_f32_16x16x32_bf16 v[56:59], v[20:23], v[60:63], 0
	v_mfma_f32_16x16x32_bf16 v[60:63], v[28:31], v[60:63], 0
	v_mfma_f32_16x16x32_bf16 v[56:59], v[24:27], v[64:67], v[56:59]
	v_mfma_f32_16x16x32_bf16 v[60:63], v[32:35], v[64:67], v[60:63]
	s_barrier
	s_setprio 0
	s_add_i32 s23, s29, s0
	v_lshl_add_u64 v[192:193], s[24:25], 0, v[164:165]
	s_mov_b64 s[60:61], 0x100
	s_add_i32 s53, s23, 0x2000
	v_lshl_add_u64 v[76:77], v[192:193], 0, s[60:61]
	s_mov_b32 m0, s23
	v_lshl_add_u64 v[198:199], s[24:25], 0, v[168:169]
	s_add_u32 s56, s24, 0x40100
	ds_read_b128 v[64:67], v175 offset:16384
	ds_read_b128 v[108:111], v175 offset:17408
	ds_read_b128 v[112:115], v175 offset:18432
	ds_read_b128 v[116:119], v175 offset:19456
	ds_read_b128 v[120:123], v175 offset:20480
	ds_read_b128 v[124:127], v175 offset:21504
	ds_read_b128 v[128:131], v175 offset:22528
	ds_read_b128 v[132:135], v175 offset:23552
	global_load_lds_dwordx4 v[76:77], off
	v_lshl_add_u64 v[76:77], v[198:199], 0, s[60:61]
	s_mov_b32 m0, s53
	s_addc_u32 s57, s25, 0
	s_add_i32 s54, s58, s0
	global_load_lds_dwordx4 v[76:77], off
	v_lshl_add_u64 v[76:77], s[56:57], 0, v[164:165]
	s_mov_b32 m0, s54
	s_add_i32 s55, s54, 0x2000
	global_load_lds_dwordx4 v[76:77], off
	v_lshl_add_u64 v[76:77], s[56:57], 0, v[168:169]
	s_mov_b32 m0, s55
	v_lshl_add_u64 v[228:229], s[26:27], 0, v[0:1]
	global_load_lds_dwordx4 v[76:77], off
	v_lshl_add_u64 v[76:77], v[228:229], 0, s[60:61]
	s_mov_b32 m0, s44
	v_lshl_add_u64 v[234:235], s[26:27], 0, v[166:167]
	global_load_lds_dwordx4 v[76:77], off
	v_lshl_add_u64 v[76:77], v[234:235], 0, s[60:61]
	s_mov_b32 m0, s45
	s_nop 0
	global_load_lds_dwordx4 v[76:77], off
	s_waitcnt vmcnt(8)
	s_waitcnt lgkmcnt(0)
	s_setprio 1
	s_barrier
	v_mfma_f32_16x16x32_bf16 v[136:139], v[4:7], v[64:67], 0
	s_nop 0
	v_mfma_f32_16x16x32_bf16 v[176:179], v[8:11], v[108:111], v[136:139]
	v_mfma_f32_16x16x32_bf16 v[136:139], v[12:15], v[64:67], 0
	s_nop 0
	v_mfma_f32_16x16x32_bf16 v[180:183], v[16:19], v[108:111], v[136:139]
	v_mfma_f32_16x16x32_bf16 v[136:139], v[4:7], v[112:115], 0
	s_nop 0
	v_mfma_f32_16x16x32_bf16 v[184:187], v[8:11], v[116:119], v[136:139]
	v_mfma_f32_16x16x32_bf16 v[136:139], v[12:15], v[112:115], 0
	s_nop 0
	v_mfma_f32_16x16x32_bf16 v[200:203], v[16:19], v[116:119], v[136:139]
	v_mfma_f32_16x16x32_bf16 v[136:139], v[4:7], v[120:123], 0
	v_mfma_f32_16x16x32_bf16 v[4:7], v[4:7], v[128:131], 0
	v_mfma_f32_16x16x32_bf16 v[204:207], v[8:11], v[124:127], v[136:139]
	v_mfma_f32_16x16x32_bf16 v[4:7], v[8:11], v[132:135], v[4:7]
	v_mfma_f32_16x16x32_bf16 v[8:11], v[12:15], v[128:131], 0
	v_mfma_f32_16x16x32_bf16 v[136:139], v[12:15], v[120:123], 0
	v_mfma_f32_16x16x32_bf16 v[12:15], v[16:19], v[132:135], v[8:11]
	v_mfma_f32_16x16x32_bf16 v[208:211], v[16:19], v[124:127], v[136:139]
	v_mfma_f32_16x16x32_bf16 v[8:11], v[20:23], v[64:67], 0
	s_nop 0
	v_mfma_f32_16x16x32_bf16 v[16:19], v[24:27], v[108:111], v[8:11]
	v_mfma_f32_16x16x32_bf16 v[8:11], v[28:31], v[64:67], 0
	s_nop 0
	v_mfma_f32_16x16x32_bf16 v[108:111], v[32:35], v[108:111], v[8:11]
	v_mfma_f32_16x16x32_bf16 v[8:11], v[20:23], v[112:115], 0
	s_nop 0
	v_mfma_f32_16x16x32_bf16 v[212:215], v[24:27], v[116:119], v[8:11]
	v_mfma_f32_16x16x32_bf16 v[8:11], v[28:31], v[112:115], 0
	s_nop 0
	v_mfma_f32_16x16x32_bf16 v[112:115], v[32:35], v[116:119], v[8:11]
	v_mfma_f32_16x16x32_bf16 v[8:11], v[20:23], v[120:123], 0
	s_nop 0
	v_mfma_f32_16x16x32_bf16 v[216:219], v[24:27], v[124:127], v[8:11]
	v_mfma_f32_16x16x32_bf16 v[8:11], v[28:31], v[120:123], 0
	s_nop 0
	v_mfma_f32_16x16x32_bf16 v[220:223], v[32:35], v[124:127], v[8:11]
	v_mfma_f32_16x16x32_bf16 v[8:11], v[20:23], v[128:131], 0
	s_nop 0
	v_mfma_f32_16x16x32_bf16 v[236:239], v[24:27], v[132:135], v[8:11]
	v_mfma_f32_16x16x32_bf16 v[8:11], v[28:31], v[128:131], 0
	s_nop 0
	v_mfma_f32_16x16x32_bf16 v[240:243], v[32:35], v[132:135], v[8:11]
	s_barrier
	s_setprio 0
	s_add_i32 s29, 0, 0x18000
	s_add_i32 s58, 0, 0x1c000
	v_add_u32_e32 v86, s29, v174
	v_add_u32_e32 v87, s58, v174
	ds_read_b128 v[8:11], v86
	ds_read_b128 v[28:31], v86 offset:1024
	ds_read_b128 v[32:35], v86 offset:2048
	ds_read_b128 v[64:67], v86 offset:3072
	ds_read_b128 v[244:247], v87
	ds_read_b128 v[248:251], v87 offset:1024
	ds_read_b128 v[230:233], v87 offset:2048
	ds_read_b128 v[194:197], v87 offset:3072
	s_add_u32 s56, s26, 0x40100
	s_addc_u32 s57, s27, 0
	s_mov_b32 m0, s46
	v_lshl_add_u64 v[116:117], s[56:57], 0, v[0:1]
	ds_read_b128 v[20:23], v175 offset:32768
	ds_read_b128 v[24:27], v175 offset:33792
	ds_read_b128 v[124:127], v175 offset:34816
	ds_read_b128 v[128:131], v175 offset:35840
	ds_read_b128 v[224:227], v175 offset:36864
	ds_read_b128 v[188:191], v175 offset:37888
	ds_read_b128 v[76:79], v175 offset:38912
	ds_read_b128 v[88:91], v175 offset:39936
	global_load_lds_dwordx4 v[116:117], off
	v_lshl_add_u64 v[116:117], s[56:57], 0, v[166:167]
	s_mov_b32 m0, s48
	s_nop 0
	global_load_lds_dwordx4 v[116:117], off
	s_waitcnt vmcnt(8)
	s_waitcnt lgkmcnt(0)
	s_setprio 1
	s_barrier
	v_mfma_f32_16x16x32_bf16 v[68:71], v[8:11], v[20:23], v[68:71]
	v_mfma_f32_16x16x32_bf16 v[152:155], v[28:31], v[24:27], v[68:71]
	v_mfma_f32_16x16x32_bf16 v[68:71], v[32:35], v[20:23], v[72:75]
	v_mfma_f32_16x16x32_bf16 v[148:151], v[64:67], v[24:27], v[68:71]
	v_mfma_f32_16x16x32_bf16 v[68:71], v[8:11], v[124:127], v[140:143]
	v_mfma_f32_16x16x32_bf16 v[136:139], v[28:31], v[128:131], v[68:71]
	v_mfma_f32_16x16x32_bf16 v[68:71], v[32:35], v[124:127], v[80:83]
	v_mfma_f32_16x16x32_bf16 v[132:135], v[64:67], v[128:131], v[68:71]
	v_mfma_f32_16x16x32_bf16 v[68:71], v[8:11], v[224:227], v[144:147]
	v_mfma_f32_16x16x32_bf16 v[120:123], v[28:31], v[188:191], v[68:71]
	v_mfma_f32_16x16x32_bf16 v[68:71], v[32:35], v[224:227], v[92:95]
	v_mfma_f32_16x16x32_bf16 v[116:119], v[64:67], v[188:191], v[68:71]
	v_mfma_f32_16x16x32_bf16 v[68:71], v[8:11], v[76:79], v[96:99]
	v_mfma_f32_16x16x32_bf16 v[72:75], v[28:31], v[88:91], v[68:71]
	v_mfma_f32_16x16x32_bf16 v[68:71], v[32:35], v[76:79], v[100:103]
	v_mfma_f32_16x16x32_bf16 v[68:71], v[64:67], v[88:91], v[68:71]
	v_mfma_f32_16x16x32_bf16 v[80:83], v[244:247], v[20:23], v[104:107]
	v_mfma_f32_16x16x32_bf16 v[20:23], v[230:233], v[20:23], v[36:39]
	v_mfma_f32_16x16x32_bf16 v[156:159], v[194:197], v[24:27], v[20:23]
	v_mfma_f32_16x16x32_bf16 v[20:23], v[244:247], v[124:127], v[40:43]
	v_mfma_f32_16x16x32_bf16 v[144:147], v[248:251], v[128:131], v[20:23]
	v_mfma_f32_16x16x32_bf16 v[20:23], v[230:233], v[124:127], v[44:47]
	v_mfma_f32_16x16x32_bf16 v[140:143], v[194:197], v[128:131], v[20:23]
	v_mfma_f32_16x16x32_bf16 v[20:23], v[244:247], v[224:227], v[48:51]
	v_mfma_f32_16x16x32_bf16 v[128:131], v[248:251], v[188:191], v[20:23]
	v_mfma_f32_16x16x32_bf16 v[20:23], v[230:233], v[224:227], v[52:55]
	v_mfma_f32_16x16x32_bf16 v[124:127], v[194:197], v[188:191], v[20:23]
	v_mfma_f32_16x16x32_bf16 v[20:23], v[244:247], v[76:79], v[56:59]
	v_mfma_f32_16x16x32_bf16 v[160:163], v[248:251], v[24:27], v[80:83]
	v_mfma_f32_16x16x32_bf16 v[80:83], v[248:251], v[88:91], v[20:23]
	v_mfma_f32_16x16x32_bf16 v[20:23], v[230:233], v[76:79], v[60:63]
	v_mfma_f32_16x16x32_bf16 v[76:79], v[194:197], v[88:91], v[20:23]
	s_barrier
	s_setprio 0
	s_add_i32 s56, s29, s0
	s_add_i32 s57, s56, 0x2000
	s_nop 2
	v_lshl_add_u64 v[20:21], v[192:193], 0, s[84:85]
	s_mov_b32 m0, s56
	s_add_u32 s60, s24, 0x40180
	ds_read_b128 v[44:47], v175 offset:49152
	ds_read_b128 v[48:51], v175 offset:50176
	ds_read_b128 v[88:91], v175 offset:51200
	ds_read_b128 v[92:95], v175 offset:52224
	ds_read_b128 v[96:99], v175 offset:53248
	ds_read_b128 v[100:103], v175 offset:54272
	ds_read_b128 v[104:107], v175 offset:55296
	ds_read_b128 v[188:191], v175 offset:56320
	global_load_lds_dwordx4 v[20:21], off
	v_lshl_add_u64 v[20:21], v[198:199], 0, s[84:85]
	s_mov_b32 m0, s57
	s_addc_u32 s61, s25, 0
	s_add_i32 s58, s58, s0
	global_load_lds_dwordx4 v[20:21], off
	v_lshl_add_u64 v[20:21], s[60:61], 0, v[164:165]
	s_mov_b32 m0, s58
	s_add_i32 s59, s58, 0x2000
	global_load_lds_dwordx4 v[20:21], off
	v_lshl_add_u64 v[20:21], s[60:61], 0, v[168:169]
	s_mov_b32 m0, s59
	s_nop 0
	global_load_lds_dwordx4 v[20:21], off
	v_lshl_add_u64 v[20:21], v[228:229], 0, s[84:85]
	s_mov_b32 m0, s49
	s_nop 0
	global_load_lds_dwordx4 v[20:21], off
	v_lshl_add_u64 v[20:21], v[234:235], 0, s[84:85]
	s_mov_b32 m0, s50
	s_nop 0
	global_load_lds_dwordx4 v[20:21], off
	s_waitcnt vmcnt(8)
	s_waitcnt lgkmcnt(0)
	s_setprio 1
	s_barrier
	v_mfma_f32_16x16x32_bf16 v[20:23], v[8:11], v[44:47], v[176:179]
	v_mfma_f32_16x16x32_bf16 v[56:59], v[28:31], v[48:51], v[20:23]
	v_mfma_f32_16x16x32_bf16 v[20:23], v[32:35], v[44:47], v[180:183]
	v_mfma_f32_16x16x32_bf16 v[52:55], v[64:67], v[48:51], v[20:23]
	v_mfma_f32_16x16x32_bf16 v[20:23], v[8:11], v[88:91], v[184:187]
	v_mfma_f32_16x16x32_bf16 v[40:43], v[28:31], v[92:95], v[20:23]
	v_mfma_f32_16x16x32_bf16 v[20:23], v[32:35], v[88:91], v[200:203]
	v_mfma_f32_16x16x32_bf16 v[36:39], v[64:67], v[92:95], v[20:23]
	v_mfma_f32_16x16x32_bf16 v[20:23], v[8:11], v[96:99], v[204:207]
	v_mfma_f32_16x16x32_bf16 v[4:7], v[8:11], v[104:107], v[4:7]
	v_mfma_f32_16x16x32_bf16 v[24:27], v[28:31], v[100:103], v[20:23]
	v_mfma_f32_16x16x32_bf16 v[20:23], v[32:35], v[96:99], v[208:211]
	v_mfma_f32_16x16x32_bf16 v[8:11], v[28:31], v[188:191], v[4:7]
	v_mfma_f32_16x16x32_bf16 v[4:7], v[32:35], v[104:107], v[12:15]
	v_mfma_f32_16x16x32_bf16 v[20:23], v[64:67], v[100:103], v[20:23]
	v_mfma_f32_16x16x32_bf16 v[4:7], v[64:67], v[188:191], v[4:7]
	v_mfma_f32_16x16x32_bf16 v[12:15], v[244:247], v[44:47], v[16:19]
	v_mfma_f32_16x16x32_bf16 v[64:67], v[248:251], v[48:51], v[12:15]
	v_mfma_f32_16x16x32_bf16 v[12:15], v[230:233], v[44:47], v[108:111]
	v_mfma_f32_16x16x32_bf16 v[60:63], v[194:197], v[48:51], v[12:15]
	v_mfma_f32_16x16x32_bf16 v[12:15], v[244:247], v[88:91], v[212:215]
	v_mfma_f32_16x16x32_bf16 v[48:51], v[248:251], v[92:95], v[12:15]
	v_mfma_f32_16x16x32_bf16 v[12:15], v[230:233], v[88:91], v[112:115]
	v_mfma_f32_16x16x32_bf16 v[44:47], v[194:197], v[92:95], v[12:15]
	v_mfma_f32_16x16x32_bf16 v[12:15], v[244:247], v[96:99], v[216:219]
	v_mfma_f32_16x16x32_bf16 v[32:35], v[248:251], v[100:103], v[12:15]
	v_mfma_f32_16x16x32_bf16 v[12:15], v[230:233], v[96:99], v[220:223]
	v_mfma_f32_16x16x32_bf16 v[28:31], v[194:197], v[100:103], v[12:15]
	v_mfma_f32_16x16x32_bf16 v[12:15], v[244:247], v[104:107], v[236:239]
	v_mfma_f32_16x16x32_bf16 v[16:19], v[248:251], v[188:191], v[12:15]
	v_mfma_f32_16x16x32_bf16 v[12:15], v[230:233], v[104:107], v[240:243]
	v_mfma_f32_16x16x32_bf16 v[12:15], v[194:197], v[188:191], v[12:15]
	s_barrier
	s_setprio 0
	s_lshl_b32 s28, s28, 11
	s_and_b32 s28, s28, 0x800
	s_add_i32 s60, s28, 0
	s_add_i32 s60, s60, 0x25a00
	s_lshl_b32 s28, s43, 2
	s_add_i32 s28, s60, s28
	s_add_u32 s26, s26, 0x40180
	s_addc_u32 s27, s27, 0
	v_mbcnt_lo_u32_b32 v88, -1, 0
	v_mbcnt_hi_u32_b32 v88, -1, v88
	s_add_u32 s61, s24, 0x200
	v_lshl_add_u32 v88, v88, 2, s28
	s_addc_u32 s62, s25, 0
	s_mov_b32 s76, 0
	s_waitcnt vmcnt(8)
	ds_write_b32 v88, v84
.LBB0_492:
	ds_read_b128 v[88:91], v2
	ds_read_b128 v[92:95], v2 offset:1024
	ds_read_b128 v[96:99], v2 offset:2048
	ds_read_b128 v[100:103], v2 offset:3072
	ds_read_b128 v[104:107], v85
	ds_read_b128 v[108:111], v85 offset:1024
	ds_read_b128 v[112:115], v85 offset:2048
	ds_read_b128 v[176:179], v85 offset:3072
	s_add_u32 s24, s26, 0xfffc0080
	s_addc_u32 s25, s27, -1
	s_cmp_eq_u32 s76, 12
	s_cselect_b32 s29, s19, s25
	s_cselect_b32 s28, s18, s24
	s_cselect_b32 s25, s21, s62
	s_cselect_b32 s24, s20, s61
	s_mov_b32 m0, s15
	v_lshl_add_u64 v[192:193], s[26:27], 0, v[170:171]
	ds_read_b128 v[180:183], v175
	ds_read_b128 v[184:187], v175 offset:1024
	ds_read_b128 v[188:191], v175 offset:2048
	ds_read_b128 v[194:197], v175 offset:3072
	ds_read_b128 v[200:203], v175 offset:4096
	ds_read_b128 v[204:207], v175 offset:5120
	ds_read_b128 v[208:211], v175 offset:6144
	ds_read_b128 v[212:215], v175 offset:7168
	global_load_lds_dwordx4 v[192:193], off
	v_lshl_add_u64 v[192:193], s[26:27], 0, v[172:173]
	s_mov_b32 m0, s17
	s_nop 0
	global_load_lds_dwordx4 v[192:193], off
	s_waitcnt vmcnt(8)
	s_waitcnt lgkmcnt(0)
	s_setprio 1
	s_barrier
	v_mfma_f32_16x16x32_bf16 v[152:155], v[88:91], v[180:183], v[152:155]
	v_mfma_f32_16x16x32_bf16 v[148:151], v[96:99], v[180:183], v[148:151]
	v_mfma_f32_16x16x32_bf16 v[136:139], v[88:91], v[188:191], v[136:139]
	v_mfma_f32_16x16x32_bf16 v[132:135], v[96:99], v[188:191], v[132:135]
	v_mfma_f32_16x16x32_bf16 v[120:123], v[88:91], v[200:203], v[120:123]
	v_mfma_f32_16x16x32_bf16 v[116:119], v[96:99], v[200:203], v[116:119]
	v_mfma_f32_16x16x32_bf16 v[72:75], v[88:91], v[208:211], v[72:75]
	v_mfma_f32_16x16x32_bf16 v[68:71], v[96:99], v[208:211], v[68:71]
	v_mfma_f32_16x16x32_bf16 v[152:155], v[92:95], v[184:187], v[152:155]
	v_mfma_f32_16x16x32_bf16 v[148:151], v[100:103], v[184:187], v[148:151]
	v_mfma_f32_16x16x32_bf16 v[136:139], v[92:95], v[194:197], v[136:139]
	v_mfma_f32_16x16x32_bf16 v[132:135], v[100:103], v[194:197], v[132:135]
	v_mfma_f32_16x16x32_bf16 v[120:123], v[92:95], v[204:207], v[120:123]
	v_mfma_f32_16x16x32_bf16 v[116:119], v[100:103], v[204:207], v[116:119]
	v_mfma_f32_16x16x32_bf16 v[72:75], v[92:95], v[212:215], v[72:75]
	v_mfma_f32_16x16x32_bf16 v[68:71], v[100:103], v[212:215], v[68:71]
	v_mfma_f32_16x16x32_bf16 v[160:163], v[104:107], v[180:183], v[160:163]
	v_mfma_f32_16x16x32_bf16 v[156:159], v[112:115], v[180:183], v[156:159]
	v_mfma_f32_16x16x32_bf16 v[144:147], v[104:107], v[188:191], v[144:147]
	v_mfma_f32_16x16x32_bf16 v[140:143], v[112:115], v[188:191], v[140:143]
	v_mfma_f32_16x16x32_bf16 v[128:131], v[104:107], v[200:203], v[128:131]
	v_mfma_f32_16x16x32_bf16 v[124:127], v[112:115], v[200:203], v[124:127]
	v_mfma_f32_16x16x32_bf16 v[80:83], v[104:107], v[208:211], v[80:83]
	v_mfma_f32_16x16x32_bf16 v[76:79], v[112:115], v[208:211], v[76:79]
	v_mfma_f32_16x16x32_bf16 v[160:163], v[108:111], v[184:187], v[160:163]
	v_mfma_f32_16x16x32_bf16 v[156:159], v[176:179], v[184:187], v[156:159]
	v_mfma_f32_16x16x32_bf16 v[144:147], v[108:111], v[194:197], v[144:147]
	v_mfma_f32_16x16x32_bf16 v[140:143], v[176:179], v[194:197], v[140:143]
	v_mfma_f32_16x16x32_bf16 v[128:131], v[108:111], v[204:207], v[128:131]
	v_mfma_f32_16x16x32_bf16 v[124:127], v[176:179], v[204:207], v[124:127]
	v_mfma_f32_16x16x32_bf16 v[80:83], v[108:111], v[212:215], v[80:83]
	v_mfma_f32_16x16x32_bf16 v[76:79], v[176:179], v[212:215], v[76:79]
	s_barrier
	s_setprio 0
	s_mov_b32 m0, s23
	v_lshl_add_u64 v[192:193], s[24:25], 0, v[164:165]
	s_add_u32 s90, s24, 0x40000
	ds_read_b128 v[180:183], v175 offset:16384
	ds_read_b128 v[184:187], v175 offset:17408
	ds_read_b128 v[188:191], v175 offset:18432
	ds_read_b128 v[194:197], v175 offset:19456
	ds_read_b128 v[200:203], v175 offset:20480
	ds_read_b128 v[204:207], v175 offset:21504
	ds_read_b128 v[208:211], v175 offset:22528
	ds_read_b128 v[212:215], v175 offset:23552
	global_load_lds_dwordx4 v[192:193], off
	v_lshl_add_u64 v[198:199], s[24:25], 0, v[168:169]
	s_mov_b32 m0, s53
	s_addc_u32 s91, s25, 0
	global_load_lds_dwordx4 v[198:199], off
	v_lshl_add_u64 v[216:217], s[90:91], 0, v[164:165]
	s_mov_b32 m0, s54
	v_lshl_add_u64 v[218:219], s[28:29], 0, v[166:167]
	global_load_lds_dwordx4 v[216:217], off
	v_lshl_add_u64 v[216:217], s[90:91], 0, v[168:169]
	s_mov_b32 m0, s55
	s_nop 0
	global_load_lds_dwordx4 v[216:217], off
	v_lshl_add_u64 v[216:217], s[28:29], 0, v[0:1]
	s_mov_b32 m0, s44
	s_nop 0
	global_load_lds_dwordx4 v[216:217], off
	s_mov_b32 m0, s45
	s_nop 0
	global_load_lds_dwordx4 v[218:219], off
	s_waitcnt vmcnt(8)
	s_waitcnt lgkmcnt(0)
	s_setprio 1
	s_barrier
	v_mfma_f32_16x16x32_bf16 v[56:59], v[88:91], v[180:183], v[56:59]
	v_mfma_f32_16x16x32_bf16 v[52:55], v[96:99], v[180:183], v[52:55]
	v_mfma_f32_16x16x32_bf16 v[40:43], v[88:91], v[188:191], v[40:43]
	v_mfma_f32_16x16x32_bf16 v[36:39], v[96:99], v[188:191], v[36:39]
	v_mfma_f32_16x16x32_bf16 v[24:27], v[88:91], v[200:203], v[24:27]
	v_mfma_f32_16x16x32_bf16 v[20:23], v[96:99], v[200:203], v[20:23]
	v_mfma_f32_16x16x32_bf16 v[8:11], v[88:91], v[208:211], v[8:11]
	v_mfma_f32_16x16x32_bf16 v[4:7], v[96:99], v[208:211], v[4:7]
	v_mfma_f32_16x16x32_bf16 v[56:59], v[92:95], v[184:187], v[56:59]
	v_mfma_f32_16x16x32_bf16 v[52:55], v[100:103], v[184:187], v[52:55]
	v_mfma_f32_16x16x32_bf16 v[40:43], v[92:95], v[194:197], v[40:43]
	v_mfma_f32_16x16x32_bf16 v[36:39], v[100:103], v[194:197], v[36:39]
	v_mfma_f32_16x16x32_bf16 v[24:27], v[92:95], v[204:207], v[24:27]
	v_mfma_f32_16x16x32_bf16 v[20:23], v[100:103], v[204:207], v[20:23]
	v_mfma_f32_16x16x32_bf16 v[8:11], v[92:95], v[212:215], v[8:11]
	v_mfma_f32_16x16x32_bf16 v[4:7], v[100:103], v[212:215], v[4:7]
	v_mfma_f32_16x16x32_bf16 v[64:67], v[104:107], v[180:183], v[64:67]
	v_mfma_f32_16x16x32_bf16 v[60:63], v[112:115], v[180:183], v[60:63]
	v_mfma_f32_16x16x32_bf16 v[48:51], v[104:107], v[188:191], v[48:51]
	v_mfma_f32_16x16x32_bf16 v[44:47], v[112:115], v[188:191], v[44:47]
	v_mfma_f32_16x16x32_bf16 v[32:35], v[104:107], v[200:203], v[32:35]
	v_mfma_f32_16x16x32_bf16 v[28:31], v[112:115], v[200:203], v[28:31]
	v_mfma_f32_16x16x32_bf16 v[16:19], v[104:107], v[208:211], v[16:19]
	v_mfma_f32_16x16x32_bf16 v[12:15], v[112:115], v[208:211], v[12:15]
	v_mfma_f32_16x16x32_bf16 v[64:67], v[108:111], v[184:187], v[64:67]
	v_mfma_f32_16x16x32_bf16 v[60:63], v[176:179], v[184:187], v[60:63]
	v_mfma_f32_16x16x32_bf16 v[48:51], v[108:111], v[194:197], v[48:51]
	v_mfma_f32_16x16x32_bf16 v[44:47], v[176:179], v[194:197], v[44:47]
	v_mfma_f32_16x16x32_bf16 v[32:35], v[108:111], v[204:207], v[32:35]
	v_mfma_f32_16x16x32_bf16 v[28:31], v[176:179], v[204:207], v[28:31]
	v_mfma_f32_16x16x32_bf16 v[16:19], v[108:111], v[212:215], v[16:19]
	v_mfma_f32_16x16x32_bf16 v[12:15], v[176:179], v[212:215], v[12:15]
	s_barrier
	s_setprio 0
	ds_read_b128 v[88:91], v86
	ds_read_b128 v[92:95], v86 offset:1024
	ds_read_b128 v[96:99], v86 offset:2048
	ds_read_b128 v[100:103], v86 offset:3072
	ds_read_b128 v[104:107], v87
	ds_read_b128 v[108:111], v87 offset:1024
	ds_read_b128 v[112:115], v87 offset:2048
	ds_read_b128 v[176:179], v87 offset:3072
	s_add_u32 s28, s28, 0x40000
	s_addc_u32 s29, s29, 0
	s_mov_b32 m0, s46
	v_lshl_add_u64 v[220:221], s[28:29], 0, v[0:1]
	ds_read_b128 v[180:183], v175 offset:32768
	ds_read_b128 v[184:187], v175 offset:33792
	ds_read_b128 v[188:191], v175 offset:34816
	ds_read_b128 v[194:197], v175 offset:35840
	ds_read_b128 v[200:203], v175 offset:36864
	ds_read_b128 v[204:207], v175 offset:37888
	ds_read_b128 v[208:211], v175 offset:38912
	ds_read_b128 v[212:215], v175 offset:39936
	global_load_lds_dwordx4 v[220:221], off
	v_lshl_add_u64 v[220:221], s[28:29], 0, v[166:167]
	s_mov_b32 m0, s48
	s_nop 0
	global_load_lds_dwordx4 v[220:221], off
	s_waitcnt vmcnt(8)
	s_waitcnt lgkmcnt(0)
	s_setprio 1
	s_barrier
	v_mfma_f32_16x16x32_bf16 v[152:155], v[88:91], v[180:183], v[152:155]
	v_mfma_f32_16x16x32_bf16 v[148:151], v[96:99], v[180:183], v[148:151]
	v_mfma_f32_16x16x32_bf16 v[136:139], v[88:91], v[188:191], v[136:139]
	v_mfma_f32_16x16x32_bf16 v[132:135], v[96:99], v[188:191], v[132:135]
	v_mfma_f32_16x16x32_bf16 v[120:123], v[88:91], v[200:203], v[120:123]
	v_mfma_f32_16x16x32_bf16 v[116:119], v[96:99], v[200:203], v[116:119]
	v_mfma_f32_16x16x32_bf16 v[72:75], v[88:91], v[208:211], v[72:75]
	v_mfma_f32_16x16x32_bf16 v[68:71], v[96:99], v[208:211], v[68:71]
	v_mfma_f32_16x16x32_bf16 v[152:155], v[92:95], v[184:187], v[152:155]
	v_mfma_f32_16x16x32_bf16 v[148:151], v[100:103], v[184:187], v[148:151]
	v_mfma_f32_16x16x32_bf16 v[136:139], v[92:95], v[194:197], v[136:139]
	v_mfma_f32_16x16x32_bf16 v[132:135], v[100:103], v[194:197], v[132:135]
	v_mfma_f32_16x16x32_bf16 v[120:123], v[92:95], v[204:207], v[120:123]
	v_mfma_f32_16x16x32_bf16 v[116:119], v[100:103], v[204:207], v[116:119]
	v_mfma_f32_16x16x32_bf16 v[72:75], v[92:95], v[212:215], v[72:75]
	v_mfma_f32_16x16x32_bf16 v[68:71], v[100:103], v[212:215], v[68:71]
	v_mfma_f32_16x16x32_bf16 v[160:163], v[104:107], v[180:183], v[160:163]
	v_mfma_f32_16x16x32_bf16 v[156:159], v[112:115], v[180:183], v[156:159]
	v_mfma_f32_16x16x32_bf16 v[144:147], v[104:107], v[188:191], v[144:147]
	v_mfma_f32_16x16x32_bf16 v[140:143], v[112:115], v[188:191], v[140:143]
	v_mfma_f32_16x16x32_bf16 v[128:131], v[104:107], v[200:203], v[128:131]
	v_mfma_f32_16x16x32_bf16 v[124:127], v[112:115], v[200:203], v[124:127]
	v_mfma_f32_16x16x32_bf16 v[80:83], v[104:107], v[208:211], v[80:83]
	v_mfma_f32_16x16x32_bf16 v[76:79], v[112:115], v[208:211], v[76:79]
	v_mfma_f32_16x16x32_bf16 v[160:163], v[108:111], v[184:187], v[160:163]
	v_mfma_f32_16x16x32_bf16 v[156:159], v[176:179], v[184:187], v[156:159]
	v_mfma_f32_16x16x32_bf16 v[144:147], v[108:111], v[194:197], v[144:147]
	v_mfma_f32_16x16x32_bf16 v[140:143], v[176:179], v[194:197], v[140:143]
	v_mfma_f32_16x16x32_bf16 v[128:131], v[108:111], v[204:207], v[128:131]
	v_mfma_f32_16x16x32_bf16 v[124:127], v[176:179], v[204:207], v[124:127]
	v_mfma_f32_16x16x32_bf16 v[80:83], v[108:111], v[212:215], v[80:83]
	v_mfma_f32_16x16x32_bf16 v[76:79], v[176:179], v[212:215], v[76:79]
	s_barrier
	s_setprio 0
	s_mov_b32 m0, s56
	v_lshl_add_u64 v[192:193], v[192:193], 0, s[74:75]
	s_add_u32 s24, s24, 0x40080
	ds_read_b128 v[180:183], v175 offset:49152
	ds_read_b128 v[184:187], v175 offset:50176
	ds_read_b128 v[188:191], v175 offset:51200
	ds_read_b128 v[194:197], v175 offset:52224
	ds_read_b128 v[200:203], v175 offset:53248
	ds_read_b128 v[204:207], v175 offset:54272
	ds_read_b128 v[208:211], v175 offset:55296
	ds_read_b128 v[212:215], v175 offset:56320
	global_load_lds_dwordx4 v[192:193], off
	v_lshl_add_u64 v[192:193], v[198:199], 0, s[74:75]
	s_mov_b32 m0, s57
	s_addc_u32 s25, s25, 0
	global_load_lds_dwordx4 v[192:193], off
	v_lshl_add_u64 v[192:193], s[24:25], 0, v[164:165]
	s_mov_b32 m0, s58
	s_nop 0
	global_load_lds_dwordx4 v[192:193], off
	v_lshl_add_u64 v[192:193], s[24:25], 0, v[168:169]
	s_mov_b32 m0, s59
	s_nop 0
	global_load_lds_dwordx4 v[192:193], off
	v_lshl_add_u64 v[192:193], v[216:217], 0, s[74:75]
	s_mov_b32 m0, s49
	s_nop 0
	global_load_lds_dwordx4 v[192:193], off
	v_lshl_add_u64 v[192:193], v[218:219], 0, s[74:75]
	s_mov_b32 m0, s50
	s_nop 0
	global_load_lds_dwordx4 v[192:193], off
	s_waitcnt vmcnt(8)
	s_waitcnt lgkmcnt(0)
	s_setprio 1
	s_barrier
	v_mfma_f32_16x16x32_bf16 v[56:59], v[88:91], v[180:183], v[56:59]
	v_mfma_f32_16x16x32_bf16 v[52:55], v[96:99], v[180:183], v[52:55]
	v_mfma_f32_16x16x32_bf16 v[40:43], v[88:91], v[188:191], v[40:43]
	v_mfma_f32_16x16x32_bf16 v[36:39], v[96:99], v[188:191], v[36:39]
	v_mfma_f32_16x16x32_bf16 v[24:27], v[88:91], v[200:203], v[24:27]
	v_mfma_f32_16x16x32_bf16 v[20:23], v[96:99], v[200:203], v[20:23]
	v_mfma_f32_16x16x32_bf16 v[8:11], v[88:91], v[208:211], v[8:11]
	v_mfma_f32_16x16x32_bf16 v[4:7], v[96:99], v[208:211], v[4:7]
	v_mfma_f32_16x16x32_bf16 v[56:59], v[92:95], v[184:187], v[56:59]
	v_mfma_f32_16x16x32_bf16 v[52:55], v[100:103], v[184:187], v[52:55]
	v_mfma_f32_16x16x32_bf16 v[40:43], v[92:95], v[194:197], v[40:43]
	v_mfma_f32_16x16x32_bf16 v[36:39], v[100:103], v[194:197], v[36:39]
	v_mfma_f32_16x16x32_bf16 v[24:27], v[92:95], v[204:207], v[24:27]
	v_mfma_f32_16x16x32_bf16 v[20:23], v[100:103], v[204:207], v[20:23]
	v_mfma_f32_16x16x32_bf16 v[8:11], v[92:95], v[212:215], v[8:11]
	v_mfma_f32_16x16x32_bf16 v[4:7], v[100:103], v[212:215], v[4:7]
	v_mfma_f32_16x16x32_bf16 v[64:67], v[104:107], v[180:183], v[64:67]
	v_mfma_f32_16x16x32_bf16 v[60:63], v[112:115], v[180:183], v[60:63]
	v_mfma_f32_16x16x32_bf16 v[48:51], v[104:107], v[188:191], v[48:51]
	v_mfma_f32_16x16x32_bf16 v[44:47], v[112:115], v[188:191], v[44:47]
	v_mfma_f32_16x16x32_bf16 v[32:35], v[104:107], v[200:203], v[32:35]
	v_mfma_f32_16x16x32_bf16 v[28:31], v[112:115], v[200:203], v[28:31]
	v_mfma_f32_16x16x32_bf16 v[16:19], v[104:107], v[208:211], v[16:19]
	v_mfma_f32_16x16x32_bf16 v[12:15], v[112:115], v[208:211], v[12:15]
	v_mfma_f32_16x16x32_bf16 v[64:67], v[108:111], v[184:187], v[64:67]
	v_mfma_f32_16x16x32_bf16 v[60:63], v[176:179], v[184:187], v[60:63]
	v_mfma_f32_16x16x32_bf16 v[48:51], v[108:111], v[194:197], v[48:51]
	v_mfma_f32_16x16x32_bf16 v[44:47], v[176:179], v[194:197], v[44:47]
	v_mfma_f32_16x16x32_bf16 v[32:35], v[108:111], v[204:207], v[32:35]
	v_mfma_f32_16x16x32_bf16 v[28:31], v[176:179], v[204:207], v[28:31]
	v_mfma_f32_16x16x32_bf16 v[16:19], v[108:111], v[212:215], v[16:19]
	v_mfma_f32_16x16x32_bf16 v[12:15], v[176:179], v[212:215], v[12:15]
	s_barrier
	s_setprio 0
	s_add_i32 s76, s76, 2
	s_add_u32 s26, s26, 0x100
	s_addc_u32 s27, s27, 0
	s_add_u32 s61, s61, 0x100
	s_addc_u32 s62, s62, 0
	s_cmp_gt_u32 s76, 13
	s_cbranch_scc0 .LBB0_492
	s_and_b64 vcc, exec, s[12:13]
	s_cbranch_vccz .LBB0_495
	s_barrier

.LBB0_606:
	s_add_i32 s3, 0, 0x10000
	s_add_i32 s41, 0, 0x14000
	v_add_u32_e32 v2, s3, v204
	v_add_u32_e32 v112, s41, v204
	ds_read_b128 v[4:7], v2
	ds_read_b128 v[8:11], v2 offset:1024
	ds_read_b128 v[12:15], v2 offset:2048
	ds_read_b128 v[16:19], v2 offset:3072
	ds_read_b128 v[20:23], v112
	ds_read_b128 v[24:27], v112 offset:1024
	ds_read_b128 v[28:31], v112 offset:2048
	ds_read_b128 v[32:35], v112 offset:3072
	s_add_u32 s30, s26, 0xb0080
	s_addc_u32 s31, s27, 0
	s_add_i32 s0, s46, 0xc000
	v_lshl_add_u64 v[68:69], s[30:31], 0, v[0:1]
	s_mov_b32 m0, s0
	s_add_i32 s1, s46, 0xe000
	ds_read_b128 v[36:39], v205
	ds_read_b128 v[40:43], v205 offset:1024
	ds_read_b128 v[44:47], v205 offset:2048
	ds_read_b128 v[48:51], v205 offset:3072
	ds_read_b128 v[52:55], v205 offset:4096
	ds_read_b128 v[56:59], v205 offset:5120
	ds_read_b128 v[60:63], v205 offset:6144
	ds_read_b128 v[64:67], v205 offset:7168
	global_load_lds_dwordx4 v[68:69], off
	v_lshl_add_u64 v[68:69], s[30:31], 0, v[162:163]
	s_mov_b32 m0, s1
	s_nop 0
	global_load_lds_dwordx4 v[68:69], off
	s_waitcnt vmcnt(8)
	s_waitcnt lgkmcnt(0)
	s_setprio 1
	s_barrier
	v_mfma_f32_16x16x32_bf16 v[68:71], v[4:7], v[36:39], 0
	v_mfma_f32_16x16x32_bf16 v[72:75], v[12:15], v[36:39], 0
	v_mfma_f32_16x16x32_bf16 v[76:79], v[4:7], v[44:47], 0
	v_mfma_f32_16x16x32_bf16 v[80:83], v[12:15], v[44:47], 0
	v_mfma_f32_16x16x32_bf16 v[84:87], v[4:7], v[52:55], 0
	v_mfma_f32_16x16x32_bf16 v[88:91], v[12:15], v[52:55], 0
	v_mfma_f32_16x16x32_bf16 v[92:95], v[4:7], v[60:63], 0
	v_mfma_f32_16x16x32_bf16 v[96:99], v[12:15], v[60:63], 0
	v_mfma_f32_16x16x32_bf16 v[68:71], v[8:11], v[40:43], v[68:71]
	v_mfma_f32_16x16x32_bf16 v[72:75], v[16:19], v[40:43], v[72:75]
	v_mfma_f32_16x16x32_bf16 v[76:79], v[8:11], v[48:51], v[76:79]
	v_mfma_f32_16x16x32_bf16 v[80:83], v[16:19], v[48:51], v[80:83]
	v_mfma_f32_16x16x32_bf16 v[84:87], v[8:11], v[56:59], v[84:87]
	v_mfma_f32_16x16x32_bf16 v[88:91], v[16:19], v[56:59], v[88:91]
	v_mfma_f32_16x16x32_bf16 v[92:95], v[8:11], v[64:67], v[92:95]
	v_mfma_f32_16x16x32_bf16 v[96:99], v[16:19], v[64:67], v[96:99]
	v_mfma_f32_16x16x32_bf16 v[100:103], v[20:23], v[36:39], 0
	v_mfma_f32_16x16x32_bf16 v[36:39], v[28:31], v[36:39], 0
	v_mfma_f32_16x16x32_bf16 v[104:107], v[24:27], v[40:43], v[100:103]
	v_mfma_f32_16x16x32_bf16 v[36:39], v[32:35], v[40:43], v[36:39]
	v_mfma_f32_16x16x32_bf16 v[40:43], v[20:23], v[44:47], 0
	v_mfma_f32_16x16x32_bf16 v[44:47], v[28:31], v[44:47], 0
	v_mfma_f32_16x16x32_bf16 v[40:43], v[24:27], v[48:51], v[40:43]
	v_mfma_f32_16x16x32_bf16 v[44:47], v[32:35], v[48:51], v[44:47]
	v_mfma_f32_16x16x32_bf16 v[48:51], v[20:23], v[52:55], 0
	v_mfma_f32_16x16x32_bf16 v[52:55], v[28:31], v[52:55], 0
	v_mfma_f32_16x16x32_bf16 v[48:51], v[24:27], v[56:59], v[48:51]
	v_mfma_f32_16x16x32_bf16 v[108:111], v[32:35], v[56:59], v[52:55]
	v_mfma_f32_16x16x32_bf16 v[52:55], v[20:23], v[60:63], 0
	s_nop 0
	v_mfma_f32_16x16x32_bf16 v[120:123], v[24:27], v[64:67], v[52:55]
	v_mfma_f32_16x16x32_bf16 v[52:55], v[28:31], v[60:63], 0
	s_nop 0
	v_mfma_f32_16x16x32_bf16 v[132:135], v[32:35], v[64:67], v[52:55]
	s_barrier
	s_setprio 0
	s_add_i32 s3, s3, s37
	v_lshl_add_u64 v[190:191], s[28:29], 0, v[160:161]
	s_mov_b64 s[76:77], 0x100
	s_add_i32 s40, s3, 0x2000
	v_lshl_add_u64 v[118:119], v[190:191], 0, s[76:77]
	s_mov_b32 m0, s3
	v_lshl_add_u64 v[192:193], s[28:29], 0, v[164:165]
	s_add_u32 s30, s28, 0xb0100
	ds_read_b128 v[52:55], v205 offset:16384
	ds_read_b128 v[56:59], v205 offset:17408
	ds_read_b128 v[60:63], v205 offset:18432
	ds_read_b128 v[64:67], v205 offset:19456
	ds_read_b128 v[100:103], v205 offset:20480
	ds_read_b128 v[114:117], v205 offset:21504
	ds_read_b128 v[124:127], v205 offset:22528
	ds_read_b128 v[128:131], v205 offset:23552
	global_load_lds_dwordx4 v[118:119], off
	v_lshl_add_u64 v[118:119], v[192:193], 0, s[76:77]
	s_mov_b32 m0, s40
	s_addc_u32 s31, s29, 0
	s_add_i32 s41, s41, s37
	global_load_lds_dwordx4 v[118:119], off
	v_lshl_add_u64 v[118:119], s[30:31], 0, v[160:161]
	s_mov_b32 m0, s41
	s_add_i32 s61, s41, 0x2000
	global_load_lds_dwordx4 v[118:119], off
	v_lshl_add_u64 v[118:119], s[30:31], 0, v[164:165]
	s_mov_b32 m0, s61
	v_lshl_add_u64 v[198:199], s[26:27], 0, v[0:1]
	global_load_lds_dwordx4 v[118:119], off
	v_lshl_add_u64 v[118:119], v[198:199], 0, s[76:77]
	s_mov_b32 m0, s46
	v_lshl_add_u64 v[234:235], s[26:27], 0, v[162:163]
	global_load_lds_dwordx4 v[118:119], off
	v_lshl_add_u64 v[118:119], v[234:235], 0, s[76:77]
	s_mov_b32 m0, s48
	s_nop 0
	global_load_lds_dwordx4 v[118:119], off
	s_waitcnt vmcnt(8)
	s_waitcnt lgkmcnt(0)
	s_setprio 1
	s_barrier
	v_mfma_f32_16x16x32_bf16 v[136:139], v[4:7], v[52:55], 0
	s_nop 0
	v_mfma_f32_16x16x32_bf16 v[144:147], v[8:11], v[56:59], v[136:139]
	v_mfma_f32_16x16x32_bf16 v[136:139], v[12:15], v[52:55], 0
	s_nop 0
	v_mfma_f32_16x16x32_bf16 v[148:151], v[16:19], v[56:59], v[136:139]
	v_mfma_f32_16x16x32_bf16 v[136:139], v[4:7], v[60:63], 0
	s_nop 0
	v_mfma_f32_16x16x32_bf16 v[152:155], v[8:11], v[64:67], v[136:139]
	v_mfma_f32_16x16x32_bf16 v[136:139], v[12:15], v[60:63], 0
	s_nop 0
	v_mfma_f32_16x16x32_bf16 v[156:159], v[16:19], v[64:67], v[136:139]
	v_mfma_f32_16x16x32_bf16 v[136:139], v[4:7], v[100:103], 0
	v_mfma_f32_16x16x32_bf16 v[4:7], v[4:7], v[124:127], 0
	v_mfma_f32_16x16x32_bf16 v[170:173], v[8:11], v[114:117], v[136:139]
	v_mfma_f32_16x16x32_bf16 v[4:7], v[8:11], v[128:131], v[4:7]
	v_mfma_f32_16x16x32_bf16 v[8:11], v[12:15], v[124:127], 0
	s_nop 0
	v_mfma_f32_16x16x32_bf16 v[8:11], v[16:19], v[128:131], v[8:11]
	v_mfma_f32_16x16x32_bf16 v[136:139], v[12:15], v[100:103], 0
	s_nop 0
	v_mfma_f32_16x16x32_bf16 v[174:177], v[16:19], v[114:117], v[136:139]
	v_mfma_f32_16x16x32_bf16 v[12:15], v[20:23], v[52:55], 0
	v_mfma_f32_16x16x32_bf16 v[16:19], v[28:31], v[52:55], 0
	v_mfma_f32_16x16x32_bf16 v[52:55], v[20:23], v[60:63], 0
	s_nop 0
	v_mfma_f32_16x16x32_bf16 v[178:181], v[24:27], v[64:67], v[52:55]
	v_mfma_f32_16x16x32_bf16 v[52:55], v[28:31], v[60:63], 0
	v_mfma_f32_16x16x32_bf16 v[12:15], v[24:27], v[56:59], v[12:15]
	v_mfma_f32_16x16x32_bf16 v[16:19], v[32:35], v[56:59], v[16:19]
	v_mfma_f32_16x16x32_bf16 v[182:185], v[32:35], v[64:67], v[52:55]
	v_mfma_f32_16x16x32_bf16 v[52:55], v[20:23], v[100:103], 0
	v_mfma_f32_16x16x32_bf16 v[20:23], v[20:23], v[124:127], 0
	v_mfma_f32_16x16x32_bf16 v[186:189], v[24:27], v[114:117], v[52:55]
	v_mfma_f32_16x16x32_bf16 v[52:55], v[28:31], v[100:103], 0
	v_mfma_f32_16x16x32_bf16 v[200:203], v[24:27], v[128:131], v[20:23]
	v_mfma_f32_16x16x32_bf16 v[20:23], v[28:31], v[124:127], 0
	v_mfma_f32_16x16x32_bf16 v[194:197], v[32:35], v[114:117], v[52:55]
	v_mfma_f32_16x16x32_bf16 v[206:209], v[32:35], v[128:131], v[20:23]
	s_barrier
	s_setprio 0
	s_add_i32 s62, 0, 0x18000
	s_add_i32 s77, 0, 0x1c000
	v_add_u32_e32 v113, s62, v204
	v_add_u32_e32 v114, s77, v204
	ds_read_b128 v[20:23], v113
	ds_read_b128 v[24:27], v113 offset:1024
	ds_read_b128 v[28:31], v113 offset:2048
	ds_read_b128 v[32:35], v113 offset:3072
	ds_read_b128 v[210:213], v114
	ds_read_b128 v[214:217], v114 offset:1024
	ds_read_b128 v[218:221], v114 offset:2048
	ds_read_b128 v[222:225], v114 offset:3072
	s_add_u32 s30, s26, 0xb0100
	s_addc_u32 s31, s27, 0
	s_mov_b32 m0, s49
	v_lshl_add_u64 v[60:61], s[30:31], 0, v[0:1]
	ds_read_b128 v[52:55], v205 offset:32768
	ds_read_b128 v[56:59], v205 offset:33792
	ds_read_b128 v[230:233], v205 offset:34816
	ds_read_b128 v[236:239], v205 offset:35840
	ds_read_b128 v[240:243], v205 offset:36864
	ds_read_b128 v[244:247], v205 offset:37888
	ds_read_b128 v[248:251], v205 offset:38912
	ds_read_b128 v[226:229], v205 offset:39936
	global_load_lds_dwordx4 v[60:61], off
	v_lshl_add_u64 v[60:61], s[30:31], 0, v[162:163]
	s_mov_b32 m0, s50
	s_nop 0
	global_load_lds_dwordx4 v[60:61], off
	s_waitcnt vmcnt(8)
	s_waitcnt lgkmcnt(0)
	s_setprio 1
	s_barrier
	v_mfma_f32_16x16x32_bf16 v[60:63], v[20:23], v[52:55], v[68:71]
	v_mfma_f32_16x16x32_bf16 v[140:143], v[24:27], v[56:59], v[60:63]
	v_mfma_f32_16x16x32_bf16 v[60:63], v[28:31], v[52:55], v[72:75]
	v_mfma_f32_16x16x32_bf16 v[136:139], v[32:35], v[56:59], v[60:63]
	v_mfma_f32_16x16x32_bf16 v[60:63], v[20:23], v[230:233], v[76:79]
	v_mfma_f32_16x16x32_bf16 v[128:131], v[24:27], v[236:239], v[60:63]
	v_mfma_f32_16x16x32_bf16 v[60:63], v[28:31], v[230:233], v[80:83]
	v_mfma_f32_16x16x32_bf16 v[124:127], v[32:35], v[236:239], v[60:63]
	v_mfma_f32_16x16x32_bf16 v[60:63], v[20:23], v[240:243], v[84:87]
	v_mfma_f32_16x16x32_bf16 v[116:119], v[24:27], v[244:247], v[60:63]
	v_mfma_f32_16x16x32_bf16 v[60:63], v[28:31], v[240:243], v[88:91]
	v_mfma_f32_16x16x32_bf16 v[100:103], v[32:35], v[244:247], v[60:63]
	v_mfma_f32_16x16x32_bf16 v[60:63], v[20:23], v[248:251], v[92:95]
	v_mfma_f32_16x16x32_bf16 v[88:91], v[24:27], v[226:229], v[60:63]
	v_mfma_f32_16x16x32_bf16 v[60:63], v[28:31], v[248:251], v[96:99]
	v_mfma_f32_16x16x32_bf16 v[76:79], v[32:35], v[226:229], v[60:63]
	v_mfma_f32_16x16x32_bf16 v[60:63], v[210:213], v[52:55], v[104:107]
	v_mfma_f32_16x16x32_bf16 v[36:39], v[218:221], v[52:55], v[36:39]
	v_mfma_f32_16x16x32_bf16 v[64:67], v[214:217], v[56:59], v[60:63]
	v_mfma_f32_16x16x32_bf16 v[60:63], v[222:225], v[56:59], v[36:39]
	v_mfma_f32_16x16x32_bf16 v[36:39], v[210:213], v[230:233], v[40:43]
	v_mfma_f32_16x16x32_bf16 v[56:59], v[214:217], v[236:239], v[36:39]
	v_mfma_f32_16x16x32_bf16 v[36:39], v[218:221], v[230:233], v[44:47]
	v_mfma_f32_16x16x32_bf16 v[52:55], v[222:225], v[236:239], v[36:39]
	v_mfma_f32_16x16x32_bf16 v[36:39], v[210:213], v[240:243], v[48:51]
	v_mfma_f32_16x16x32_bf16 v[48:51], v[214:217], v[244:247], v[36:39]
	v_mfma_f32_16x16x32_bf16 v[36:39], v[218:221], v[240:243], v[108:111]
	v_mfma_f32_16x16x32_bf16 v[44:47], v[222:225], v[244:247], v[36:39]
	v_mfma_f32_16x16x32_bf16 v[36:39], v[210:213], v[248:251], v[120:123]
	v_mfma_f32_16x16x32_bf16 v[40:43], v[214:217], v[226:229], v[36:39]
	v_mfma_f32_16x16x32_bf16 v[36:39], v[218:221], v[248:251], v[132:135]
	v_mfma_f32_16x16x32_bf16 v[36:39], v[222:225], v[226:229], v[36:39]
	s_barrier
	s_setprio 0
	s_add_i32 s62, s62, s37
	s_add_i32 s76, s62, 0x2000
	v_lshl_add_u64 v[68:69], v[190:191], 0, s[84:85]
	s_mov_b32 m0, s62
	s_add_u32 s30, s28, 0xb0180
	ds_read_b128 v[120:123], v205 offset:49152
	ds_read_b128 v[132:135], v205 offset:50176
	ds_read_b128 v[226:229], v205 offset:51200
	ds_read_b128 v[230:233], v205 offset:52224
	ds_read_b128 v[236:239], v205 offset:53248
	ds_read_b128 v[240:243], v205 offset:54272
	ds_read_b128 v[244:247], v205 offset:55296
	ds_read_b128 v[248:251], v205 offset:56320
	global_load_lds_dwordx4 v[68:69], off
	v_lshl_add_u64 v[68:69], v[192:193], 0, s[84:85]
	s_mov_b32 m0, s76
	s_addc_u32 s31, s29, 0
	s_add_i32 s77, s77, s37
	global_load_lds_dwordx4 v[68:69], off
	v_lshl_add_u64 v[68:69], s[30:31], 0, v[160:161]
	s_mov_b32 m0, s77
	s_add_i32 s79, s77, 0x2000
	global_load_lds_dwordx4 v[68:69], off
	v_lshl_add_u64 v[68:69], s[30:31], 0, v[164:165]
	s_mov_b32 m0, s79
	s_nop 0
	global_load_lds_dwordx4 v[68:69], off
	v_lshl_add_u64 v[68:69], v[198:199], 0, s[84:85]
	s_mov_b32 m0, s52
	s_nop 0
	global_load_lds_dwordx4 v[68:69], off
	v_lshl_add_u64 v[68:69], v[234:235], 0, s[84:85]
	s_mov_b32 m0, s53
	s_nop 0
	global_load_lds_dwordx4 v[68:69], off
	s_waitcnt vmcnt(8)
	s_waitcnt lgkmcnt(0)
	s_setprio 1
	s_barrier
	v_mfma_f32_16x16x32_bf16 v[68:71], v[20:23], v[120:123], v[144:147]
	v_mfma_f32_16x16x32_bf16 v[108:111], v[24:27], v[132:135], v[68:71]
	v_mfma_f32_16x16x32_bf16 v[68:71], v[28:31], v[120:123], v[148:151]
	v_mfma_f32_16x16x32_bf16 v[104:107], v[32:35], v[132:135], v[68:71]
	v_mfma_f32_16x16x32_bf16 v[68:71], v[20:23], v[226:229], v[152:155]
	v_mfma_f32_16x16x32_bf16 v[96:99], v[24:27], v[230:233], v[68:71]
	v_mfma_f32_16x16x32_bf16 v[68:71], v[28:31], v[226:229], v[156:159]
	v_mfma_f32_16x16x32_bf16 v[92:95], v[32:35], v[230:233], v[68:71]
	v_mfma_f32_16x16x32_bf16 v[68:71], v[20:23], v[236:239], v[170:173]
	v_mfma_f32_16x16x32_bf16 v[4:7], v[20:23], v[244:247], v[4:7]
	v_mfma_f32_16x16x32_bf16 v[84:87], v[24:27], v[240:243], v[68:71]
	v_mfma_f32_16x16x32_bf16 v[68:71], v[28:31], v[236:239], v[174:177]
	v_mfma_f32_16x16x32_bf16 v[72:75], v[24:27], v[248:251], v[4:7]
	v_mfma_f32_16x16x32_bf16 v[4:7], v[28:31], v[244:247], v[8:11]
	v_mfma_f32_16x16x32_bf16 v[80:83], v[32:35], v[240:243], v[68:71]
	v_mfma_f32_16x16x32_bf16 v[68:71], v[32:35], v[248:251], v[4:7]
	v_mfma_f32_16x16x32_bf16 v[4:7], v[210:213], v[120:123], v[12:15]
	v_mfma_f32_16x16x32_bf16 v[32:35], v[214:217], v[132:135], v[4:7]
	v_mfma_f32_16x16x32_bf16 v[4:7], v[218:221], v[120:123], v[16:19]
	v_mfma_f32_16x16x32_bf16 v[28:31], v[222:225], v[132:135], v[4:7]
	v_mfma_f32_16x16x32_bf16 v[4:7], v[210:213], v[226:229], v[178:181]
	v_mfma_f32_16x16x32_bf16 v[24:27], v[214:217], v[230:233], v[4:7]
	v_mfma_f32_16x16x32_bf16 v[4:7], v[218:221], v[226:229], v[182:185]
	v_mfma_f32_16x16x32_bf16 v[20:23], v[222:225], v[230:233], v[4:7]
	v_mfma_f32_16x16x32_bf16 v[4:7], v[210:213], v[236:239], v[186:189]
	v_mfma_f32_16x16x32_bf16 v[16:19], v[214:217], v[240:243], v[4:7]
	v_mfma_f32_16x16x32_bf16 v[4:7], v[218:221], v[236:239], v[194:197]
	v_mfma_f32_16x16x32_bf16 v[12:15], v[222:225], v[240:243], v[4:7]
	v_mfma_f32_16x16x32_bf16 v[4:7], v[210:213], v[244:247], v[200:203]
	v_mfma_f32_16x16x32_bf16 v[8:11], v[214:217], v[248:251], v[4:7]
	v_mfma_f32_16x16x32_bf16 v[4:7], v[218:221], v[244:247], v[206:209]
	v_mfma_f32_16x16x32_bf16 v[4:7], v[222:225], v[248:251], v[4:7]
	s_barrier
	s_setprio 0
	s_add_u32 s80, s28, 0x200
	s_addc_u32 s88, s29, 0
	s_mov_b32 s90, 0
.LBB0_607:
	ds_read_b128 v[120:123], v2
	ds_read_b128 v[132:135], v2 offset:1024
	ds_read_b128 v[144:147], v2 offset:2048
	ds_read_b128 v[148:151], v2 offset:3072
	ds_read_b128 v[152:155], v112
	ds_read_b128 v[156:159], v112 offset:1024
	ds_read_b128 v[170:173], v112 offset:2048
	ds_read_b128 v[174:177], v112 offset:3072
	s_add_u32 s28, s26, 0x200
	s_addc_u32 s29, s27, 0
	s_cmp_eq_u32 s90, 40
	s_cselect_b32 s31, s23, s29
	s_cselect_b32 s30, s22, s28
	s_cselect_b32 s29, s25, s88
	s_cselect_b32 s28, s24, s80
	s_mov_b32 m0, s0
	v_lshl_add_u64 v[190:191], s[26:27], 0, v[166:167]
	ds_read_b128 v[178:181], v205
	ds_read_b128 v[182:185], v205 offset:1024
	ds_read_b128 v[186:189], v205 offset:2048
	ds_read_b128 v[194:197], v205 offset:3072
	ds_read_b128 v[200:203], v205 offset:4096
	ds_read_b128 v[206:209], v205 offset:5120
	ds_read_b128 v[210:213], v205 offset:6144
	ds_read_b128 v[214:217], v205 offset:7168
	global_load_lds_dwordx4 v[190:191], off
	v_lshl_add_u64 v[190:191], s[26:27], 0, v[168:169]
	s_mov_b32 m0, s1
	s_nop 0
	global_load_lds_dwordx4 v[190:191], off
	s_waitcnt vmcnt(8)
	s_waitcnt lgkmcnt(0)
	s_setprio 1
	s_barrier
	v_mfma_f32_16x16x32_bf16 v[140:143], v[120:123], v[178:181], v[140:143]
	v_mfma_f32_16x16x32_bf16 v[136:139], v[144:147], v[178:181], v[136:139]
	v_mfma_f32_16x16x32_bf16 v[128:131], v[120:123], v[186:189], v[128:131]
	v_mfma_f32_16x16x32_bf16 v[124:127], v[144:147], v[186:189], v[124:127]
	v_mfma_f32_16x16x32_bf16 v[116:119], v[120:123], v[200:203], v[116:119]
	v_mfma_f32_16x16x32_bf16 v[100:103], v[144:147], v[200:203], v[100:103]
	v_mfma_f32_16x16x32_bf16 v[88:91], v[120:123], v[210:213], v[88:91]
	v_mfma_f32_16x16x32_bf16 v[76:79], v[144:147], v[210:213], v[76:79]
	v_mfma_f32_16x16x32_bf16 v[140:143], v[132:135], v[182:185], v[140:143]
	v_mfma_f32_16x16x32_bf16 v[136:139], v[148:151], v[182:185], v[136:139]
	v_mfma_f32_16x16x32_bf16 v[128:131], v[132:135], v[194:197], v[128:131]
	v_mfma_f32_16x16x32_bf16 v[124:127], v[148:151], v[194:197], v[124:127]
	v_mfma_f32_16x16x32_bf16 v[116:119], v[132:135], v[206:209], v[116:119]
	v_mfma_f32_16x16x32_bf16 v[100:103], v[148:151], v[206:209], v[100:103]
	v_mfma_f32_16x16x32_bf16 v[88:91], v[132:135], v[214:217], v[88:91]
	v_mfma_f32_16x16x32_bf16 v[76:79], v[148:151], v[214:217], v[76:79]
	v_mfma_f32_16x16x32_bf16 v[64:67], v[152:155], v[178:181], v[64:67]
	v_mfma_f32_16x16x32_bf16 v[60:63], v[170:173], v[178:181], v[60:63]
	v_mfma_f32_16x16x32_bf16 v[56:59], v[152:155], v[186:189], v[56:59]
	v_mfma_f32_16x16x32_bf16 v[52:55], v[170:173], v[186:189], v[52:55]
	v_mfma_f32_16x16x32_bf16 v[48:51], v[152:155], v[200:203], v[48:51]
	v_mfma_f32_16x16x32_bf16 v[44:47], v[170:173], v[200:203], v[44:47]
	v_mfma_f32_16x16x32_bf16 v[40:43], v[152:155], v[210:213], v[40:43]
	v_mfma_f32_16x16x32_bf16 v[36:39], v[170:173], v[210:213], v[36:39]
	v_mfma_f32_16x16x32_bf16 v[64:67], v[156:159], v[182:185], v[64:67]
	v_mfma_f32_16x16x32_bf16 v[60:63], v[174:177], v[182:185], v[60:63]
	v_mfma_f32_16x16x32_bf16 v[56:59], v[156:159], v[194:197], v[56:59]
	v_mfma_f32_16x16x32_bf16 v[52:55], v[174:177], v[194:197], v[52:55]
	v_mfma_f32_16x16x32_bf16 v[48:51], v[156:159], v[206:209], v[48:51]
	v_mfma_f32_16x16x32_bf16 v[44:47], v[174:177], v[206:209], v[44:47]
	v_mfma_f32_16x16x32_bf16 v[40:43], v[156:159], v[214:217], v[40:43]
	v_mfma_f32_16x16x32_bf16 v[36:39], v[174:177], v[214:217], v[36:39]
	s_barrier
	s_setprio 0
	s_mov_b32 m0, s3
	v_lshl_add_u64 v[190:191], s[28:29], 0, v[160:161]
	s_add_u32 vcc_lo, s28, 0xb0000
	ds_read_b128 v[178:181], v205 offset:16384
	ds_read_b128 v[182:185], v205 offset:17408
	ds_read_b128 v[186:189], v205 offset:18432
	ds_read_b128 v[194:197], v205 offset:19456
	ds_read_b128 v[200:203], v205 offset:20480
	ds_read_b128 v[206:209], v205 offset:21504
	ds_read_b128 v[210:213], v205 offset:22528
	ds_read_b128 v[214:217], v205 offset:23552
	global_load_lds_dwordx4 v[190:191], off
	v_lshl_add_u64 v[192:193], s[28:29], 0, v[164:165]
	s_mov_b32 m0, s40
	s_addc_u32 vcc_hi, s29, 0
	global_load_lds_dwordx4 v[192:193], off
	v_lshl_add_u64 v[198:199], vcc, 0, v[160:161]
	s_mov_b32 m0, s41
	v_lshl_add_u64 v[218:219], s[30:31], 0, v[162:163]
	global_load_lds_dwordx4 v[198:199], off
	v_lshl_add_u64 v[198:199], vcc, 0, v[164:165]
	s_mov_b32 m0, s61
	s_nop 0
	global_load_lds_dwordx4 v[198:199], off
	v_lshl_add_u64 v[198:199], s[30:31], 0, v[0:1]
	s_mov_b32 m0, s46
	s_nop 0
	global_load_lds_dwordx4 v[198:199], off
	s_mov_b32 m0, s48
	s_nop 0
	global_load_lds_dwordx4 v[218:219], off
	s_waitcnt vmcnt(8)
	s_waitcnt lgkmcnt(0)
	s_setprio 1
	s_barrier
	v_mfma_f32_16x16x32_bf16 v[108:111], v[120:123], v[178:181], v[108:111]
	v_mfma_f32_16x16x32_bf16 v[104:107], v[144:147], v[178:181], v[104:107]
	v_mfma_f32_16x16x32_bf16 v[96:99], v[120:123], v[186:189], v[96:99]
	v_mfma_f32_16x16x32_bf16 v[92:95], v[144:147], v[186:189], v[92:95]
	v_mfma_f32_16x16x32_bf16 v[84:87], v[120:123], v[200:203], v[84:87]
	v_mfma_f32_16x16x32_bf16 v[80:83], v[144:147], v[200:203], v[80:83]
	v_mfma_f32_16x16x32_bf16 v[72:75], v[120:123], v[210:213], v[72:75]
	v_mfma_f32_16x16x32_bf16 v[68:71], v[144:147], v[210:213], v[68:71]
	v_mfma_f32_16x16x32_bf16 v[108:111], v[132:135], v[182:185], v[108:111]
	v_mfma_f32_16x16x32_bf16 v[104:107], v[148:151], v[182:185], v[104:107]
	v_mfma_f32_16x16x32_bf16 v[96:99], v[132:135], v[194:197], v[96:99]
	v_mfma_f32_16x16x32_bf16 v[92:95], v[148:151], v[194:197], v[92:95]
	v_mfma_f32_16x16x32_bf16 v[84:87], v[132:135], v[206:209], v[84:87]
	v_mfma_f32_16x16x32_bf16 v[80:83], v[148:151], v[206:209], v[80:83]
	v_mfma_f32_16x16x32_bf16 v[72:75], v[132:135], v[214:217], v[72:75]
	v_mfma_f32_16x16x32_bf16 v[68:71], v[148:151], v[214:217], v[68:71]
	v_mfma_f32_16x16x32_bf16 v[32:35], v[152:155], v[178:181], v[32:35]
	v_mfma_f32_16x16x32_bf16 v[28:31], v[170:173], v[178:181], v[28:31]
	v_mfma_f32_16x16x32_bf16 v[24:27], v[152:155], v[186:189], v[24:27]
	v_mfma_f32_16x16x32_bf16 v[20:23], v[170:173], v[186:189], v[20:23]
	v_mfma_f32_16x16x32_bf16 v[16:19], v[152:155], v[200:203], v[16:19]
	v_mfma_f32_16x16x32_bf16 v[12:15], v[170:173], v[200:203], v[12:15]
	v_mfma_f32_16x16x32_bf16 v[8:11], v[152:155], v[210:213], v[8:11]
	v_mfma_f32_16x16x32_bf16 v[4:7], v[170:173], v[210:213], v[4:7]
	v_mfma_f32_16x16x32_bf16 v[32:35], v[156:159], v[182:185], v[32:35]
	v_mfma_f32_16x16x32_bf16 v[28:31], v[174:177], v[182:185], v[28:31]
	v_mfma_f32_16x16x32_bf16 v[24:27], v[156:159], v[194:197], v[24:27]
	v_mfma_f32_16x16x32_bf16 v[20:23], v[174:177], v[194:197], v[20:23]
	v_mfma_f32_16x16x32_bf16 v[16:19], v[156:159], v[206:209], v[16:19]
	v_mfma_f32_16x16x32_bf16 v[12:15], v[174:177], v[206:209], v[12:15]
	v_mfma_f32_16x16x32_bf16 v[8:11], v[156:159], v[214:217], v[8:11]
	v_mfma_f32_16x16x32_bf16 v[4:7], v[174:177], v[214:217], v[4:7]
	s_barrier
	s_setprio 0
	ds_read_b128 v[120:123], v113
	ds_read_b128 v[132:135], v113 offset:1024
	ds_read_b128 v[144:147], v113 offset:2048
	ds_read_b128 v[148:151], v113 offset:3072
	ds_read_b128 v[152:155], v114
	ds_read_b128 v[156:159], v114 offset:1024
	ds_read_b128 v[170:173], v114 offset:2048
	ds_read_b128 v[174:177], v114 offset:3072
	s_add_u32 s30, s30, 0xb0000
	s_addc_u32 s31, s31, 0
	s_mov_b32 m0, s49
	v_lshl_add_u64 v[220:221], s[30:31], 0, v[0:1]
	ds_read_b128 v[178:181], v205 offset:32768
	ds_read_b128 v[182:185], v205 offset:33792
	ds_read_b128 v[186:189], v205 offset:34816
	ds_read_b128 v[194:197], v205 offset:35840
	ds_read_b128 v[200:203], v205 offset:36864
	ds_read_b128 v[206:209], v205 offset:37888
	ds_read_b128 v[210:213], v205 offset:38912
	ds_read_b128 v[214:217], v205 offset:39936
	global_load_lds_dwordx4 v[220:221], off
	v_lshl_add_u64 v[220:221], s[30:31], 0, v[162:163]
	s_mov_b32 m0, s50
	s_nop 0
	global_load_lds_dwordx4 v[220:221], off
	s_waitcnt vmcnt(8)
	s_waitcnt lgkmcnt(0)
	s_setprio 1
	s_barrier
	v_mfma_f32_16x16x32_bf16 v[140:143], v[120:123], v[178:181], v[140:143]
	v_mfma_f32_16x16x32_bf16 v[136:139], v[144:147], v[178:181], v[136:139]
	v_mfma_f32_16x16x32_bf16 v[128:131], v[120:123], v[186:189], v[128:131]
	v_mfma_f32_16x16x32_bf16 v[124:127], v[144:147], v[186:189], v[124:127]
	v_mfma_f32_16x16x32_bf16 v[116:119], v[120:123], v[200:203], v[116:119]
	v_mfma_f32_16x16x32_bf16 v[100:103], v[144:147], v[200:203], v[100:103]
	v_mfma_f32_16x16x32_bf16 v[88:91], v[120:123], v[210:213], v[88:91]
	v_mfma_f32_16x16x32_bf16 v[76:79], v[144:147], v[210:213], v[76:79]
	v_mfma_f32_16x16x32_bf16 v[140:143], v[132:135], v[182:185], v[140:143]
	v_mfma_f32_16x16x32_bf16 v[136:139], v[148:151], v[182:185], v[136:139]
	v_mfma_f32_16x16x32_bf16 v[128:131], v[132:135], v[194:197], v[128:131]
	v_mfma_f32_16x16x32_bf16 v[124:127], v[148:151], v[194:197], v[124:127]
	v_mfma_f32_16x16x32_bf16 v[116:119], v[132:135], v[206:209], v[116:119]
	v_mfma_f32_16x16x32_bf16 v[100:103], v[148:151], v[206:209], v[100:103]
	v_mfma_f32_16x16x32_bf16 v[88:91], v[132:135], v[214:217], v[88:91]
	v_mfma_f32_16x16x32_bf16 v[76:79], v[148:151], v[214:217], v[76:79]
	v_mfma_f32_16x16x32_bf16 v[64:67], v[152:155], v[178:181], v[64:67]
	v_mfma_f32_16x16x32_bf16 v[60:63], v[170:173], v[178:181], v[60:63]
	v_mfma_f32_16x16x32_bf16 v[56:59], v[152:155], v[186:189], v[56:59]
	v_mfma_f32_16x16x32_bf16 v[52:55], v[170:173], v[186:189], v[52:55]
	v_mfma_f32_16x16x32_bf16 v[48:51], v[152:155], v[200:203], v[48:51]
	v_mfma_f32_16x16x32_bf16 v[44:47], v[170:173], v[200:203], v[44:47]
	v_mfma_f32_16x16x32_bf16 v[40:43], v[152:155], v[210:213], v[40:43]
	v_mfma_f32_16x16x32_bf16 v[36:39], v[170:173], v[210:213], v[36:39]
	v_mfma_f32_16x16x32_bf16 v[64:67], v[156:159], v[182:185], v[64:67]
	v_mfma_f32_16x16x32_bf16 v[60:63], v[174:177], v[182:185], v[60:63]
	v_mfma_f32_16x16x32_bf16 v[56:59], v[156:159], v[194:197], v[56:59]
	v_mfma_f32_16x16x32_bf16 v[52:55], v[174:177], v[194:197], v[52:55]
	v_mfma_f32_16x16x32_bf16 v[48:51], v[156:159], v[206:209], v[48:51]
	v_mfma_f32_16x16x32_bf16 v[44:47], v[174:177], v[206:209], v[44:47]
	v_mfma_f32_16x16x32_bf16 v[40:43], v[156:159], v[214:217], v[40:43]
	v_mfma_f32_16x16x32_bf16 v[36:39], v[174:177], v[214:217], v[36:39]
	s_barrier
	s_setprio 0
	s_mov_b32 m0, s62
	v_lshl_add_u64 v[190:191], v[190:191], 0, s[74:75]
	s_add_u32 s28, s28, 0xb0080
	ds_read_b128 v[178:181], v205 offset:49152
	ds_read_b128 v[182:185], v205 offset:50176
	ds_read_b128 v[186:189], v205 offset:51200
	ds_read_b128 v[194:197], v205 offset:52224
	ds_read_b128 v[200:203], v205 offset:53248
	ds_read_b128 v[206:209], v205 offset:54272
	ds_read_b128 v[210:213], v205 offset:55296
	ds_read_b128 v[214:217], v205 offset:56320
	global_load_lds_dwordx4 v[190:191], off
	v_lshl_add_u64 v[190:191], v[192:193], 0, s[74:75]
	s_mov_b32 m0, s76
	s_addc_u32 s29, s29, 0
	global_load_lds_dwordx4 v[190:191], off
	v_lshl_add_u64 v[190:191], s[28:29], 0, v[160:161]
	s_mov_b32 m0, s77
	s_nop 0
	global_load_lds_dwordx4 v[190:191], off
	v_lshl_add_u64 v[190:191], s[28:29], 0, v[164:165]
	s_mov_b32 m0, s79
	s_nop 0
	global_load_lds_dwordx4 v[190:191], off
	v_lshl_add_u64 v[190:191], v[198:199], 0, s[74:75]
	s_mov_b32 m0, s52
	s_nop 0
	global_load_lds_dwordx4 v[190:191], off
	v_lshl_add_u64 v[190:191], v[218:219], 0, s[74:75]
	s_mov_b32 m0, s53
	s_nop 0
	global_load_lds_dwordx4 v[190:191], off
	s_waitcnt vmcnt(8)
	s_waitcnt lgkmcnt(0)
	s_setprio 1
	s_barrier
	v_mfma_f32_16x16x32_bf16 v[108:111], v[120:123], v[178:181], v[108:111]
	v_mfma_f32_16x16x32_bf16 v[104:107], v[144:147], v[178:181], v[104:107]
	v_mfma_f32_16x16x32_bf16 v[96:99], v[120:123], v[186:189], v[96:99]
	v_mfma_f32_16x16x32_bf16 v[92:95], v[144:147], v[186:189], v[92:95]
	v_mfma_f32_16x16x32_bf16 v[84:87], v[120:123], v[200:203], v[84:87]
	v_mfma_f32_16x16x32_bf16 v[80:83], v[144:147], v[200:203], v[80:83]
	v_mfma_f32_16x16x32_bf16 v[72:75], v[120:123], v[210:213], v[72:75]
	v_mfma_f32_16x16x32_bf16 v[68:71], v[144:147], v[210:213], v[68:71]
	v_mfma_f32_16x16x32_bf16 v[108:111], v[132:135], v[182:185], v[108:111]
	v_mfma_f32_16x16x32_bf16 v[104:107], v[148:151], v[182:185], v[104:107]
	v_mfma_f32_16x16x32_bf16 v[96:99], v[132:135], v[194:197], v[96:99]
	v_mfma_f32_16x16x32_bf16 v[92:95], v[148:151], v[194:197], v[92:95]
	v_mfma_f32_16x16x32_bf16 v[84:87], v[132:135], v[206:209], v[84:87]
	v_mfma_f32_16x16x32_bf16 v[80:83], v[148:151], v[206:209], v[80:83]
	v_mfma_f32_16x16x32_bf16 v[72:75], v[132:135], v[214:217], v[72:75]
	v_mfma_f32_16x16x32_bf16 v[68:71], v[148:151], v[214:217], v[68:71]
	v_mfma_f32_16x16x32_bf16 v[32:35], v[152:155], v[178:181], v[32:35]
	v_mfma_f32_16x16x32_bf16 v[28:31], v[170:173], v[178:181], v[28:31]
	v_mfma_f32_16x16x32_bf16 v[24:27], v[152:155], v[186:189], v[24:27]
	v_mfma_f32_16x16x32_bf16 v[20:23], v[170:173], v[186:189], v[20:23]
	v_mfma_f32_16x16x32_bf16 v[16:19], v[152:155], v[200:203], v[16:19]
	v_mfma_f32_16x16x32_bf16 v[12:15], v[170:173], v[200:203], v[12:15]
	v_mfma_f32_16x16x32_bf16 v[8:11], v[152:155], v[210:213], v[8:11]
	v_mfma_f32_16x16x32_bf16 v[4:7], v[170:173], v[210:213], v[4:7]
	v_mfma_f32_16x16x32_bf16 v[32:35], v[156:159], v[182:185], v[32:35]
	v_mfma_f32_16x16x32_bf16 v[28:31], v[174:177], v[182:185], v[28:31]
	v_mfma_f32_16x16x32_bf16 v[24:27], v[156:159], v[194:197], v[24:27]
	v_mfma_f32_16x16x32_bf16 v[20:23], v[174:177], v[194:197], v[20:23]
	v_mfma_f32_16x16x32_bf16 v[16:19], v[156:159], v[206:209], v[16:19]
	v_mfma_f32_16x16x32_bf16 v[12:15], v[174:177], v[206:209], v[12:15]
	v_mfma_f32_16x16x32_bf16 v[8:11], v[156:159], v[214:217], v[8:11]
	v_mfma_f32_16x16x32_bf16 v[4:7], v[174:177], v[214:217], v[4:7]
	s_barrier
	s_setprio 0
	s_add_i32 s90, s90, 2
	s_add_u32 s26, s26, 0x100
	s_addc_u32 s27, s27, 0
	s_add_u32 s80, s80, 0x100
	s_addc_u32 s88, s88, 0
	s_cmp_gt_u32 s90, 41
	s_cbranch_scc0 .LBB0_607
	s_and_b64 vcc, exec, s[20:21]
	s_cbranch_vccz .LBB0_610
	s_barrier

.LBB0_661:
	s_and_b32 s15, s2, 0x1e0
	s_bitset1_b32 s15, 15
	v_or_b32_e32 v0, s15, v86
	v_mul_u32_u24_e32 v0, 0xb00, v0
	s_ashr_i32 s16, s1, 4
	v_lshlrev_b32_e32 v2, 1, v0
	s_lshl_b32 s14, s16, 6
	v_lshl_add_u64 v[52:53], v[78:79], 0, v[2:3]
	s_mov_b32 s17, 0x16000
	v_or_b32_e32 v1, s14, v86
	v_add_co_u32_e32 v0, vcc, s17, v52
	v_mad_i64_i32 v[4:5], s[18:19], v1, s60, v[76:77]
	s_nop 0
	v_addc_co_u32_e32 v1, vcc, 0, v53, vcc
	v_add_co_u32_e32 v54, vcc, s17, v4
	s_mov_b32 s17, 0x2c000
	s_nop 0
	v_addc_co_u32_e32 v55, vcc, 0, v5, vcc
	v_add_co_u32_e32 v82, vcc, s17, v4
	s_mov_b32 s17, 0x42000
	s_nop 0
	v_addc_co_u32_e32 v83, vcc, 0, v5, vcc
	v_add_co_u32_e32 v84, vcc, s17, v4
	s_waitcnt lgkmcnt(0)
	s_nop 1
	v_addc_co_u32_e32 v85, vcc, 0, v5, vcc
	v_mov_b64_e32 v[132:133], v[0:1]
	v_mov_b64_e32 v[134:135], v[52:53]
	v_mov_b64_e32 v[136:137], v[54:55]
	v_add_u32_e32 v0, s15, v87
	v_ashrrev_i32_e32 v1, 31, v0
	v_lshlrev_b64 v[24:25], 8, v[0:1]
	v_lshl_add_u64 v[24:25], v[80:81], 0, v[24:25]
	global_load_dwordx4 v[24:27], v[24:25], off
	v_or_b32_e32 v68, s14, v88
	v_lshlrev_b64 v[28:29], 10, v[0:1]
	v_ashrrev_i32_e32 v69, 31, v68
	v_lshl_add_u64 v[28:29], v[28:29], 0, v[68:69]
	v_lshlrev_b64 v[70:71], 1, v[28:29]
	v_lshl_add_u64 v[28:29], s[4:5], 0, v[70:71]
	global_load_dwordx2 v[72:73], v[28:29], off
	v_lshlrev_b64 v[60:61], 2, v[68:69]
	v_lshl_add_u64 v[56:57], s[12:13], 0, v[60:61]
	global_load_dwordx4 v[56:59], v[56:57], off
	v_lshl_add_u64 v[52:53], s[6:7], 0, v[60:61]
	global_load_dwordx4 v[52:55], v[52:53], off
	global_load_dwordx4 v[140:143], v[4:5], off
	global_load_dwordx4 v[144:147], v[136:137], off
	global_load_dwordx4 v[148:151], v[82:83], off
	global_load_dwordx4 v[152:155], v[84:85], off
	global_load_dwordx4 v[156:159], v[134:135], off
	global_load_dwordx4 v[160:163], v[132:133], off
	global_load_dwordx4 v[164:167], v[4:5], off offset:64
	global_load_dwordx4 v[168:171], v[136:137], off offset:64
	global_load_dwordx4 v[172:175], v[82:83], off offset:64
	global_load_dwordx4 v[176:179], v[84:85], off offset:64
	global_load_dwordx4 v[180:183], v[134:135], off offset:64
	global_load_dwordx4 v[184:187], v[132:133], off offset:64
	global_load_dwordx4 v[188:191], v[4:5], off offset:128
	global_load_dwordx4 v[192:195], v[136:137], off offset:128
	global_load_dwordx4 v[196:199], v[82:83], off offset:128
	global_load_dwordx4 v[200:203], v[84:85], off offset:128
	global_load_dwordx4 v[204:207], v[134:135], off offset:128
	global_load_dwordx4 v[208:211], v[132:133], off offset:128
	global_load_dwordx4 v[212:215], v[4:5], off offset:192
	global_load_dwordx4 v[216:219], v[136:137], off offset:192
	global_load_dwordx4 v[220:223], v[82:83], off offset:192
	global_load_dwordx4 v[224:227], v[84:85], off offset:192
	global_load_dwordx4 v[228:231], v[134:135], off offset:192
	global_load_dwordx4 v[232:235], v[132:133], off offset:192
	global_load_dwordx4 v[236:239], v[4:5], off offset:256
	global_load_dwordx4 v[240:243], v[136:137], off offset:256
	global_load_dwordx4 v[6:9], v[82:83], off offset:256
	global_load_dwordx4 v[10:13], v[84:85], off offset:256
	global_load_dwordx4 v[14:17], v[134:135], off offset:256
	global_load_dwordx4 v[18:21], v[132:133], off offset:256
	s_waitcnt vmcnt(24)
	v_mfma_f32_16x16x32_bf16 v[100:103], v[140:143], v[156:159], 0
	v_mfma_f32_16x16x32_bf16 v[104:107], v[144:147], v[156:159], 0
	v_mfma_f32_16x16x32_bf16 v[108:111], v[148:151], v[156:159], 0
	v_mfma_f32_16x16x32_bf16 v[112:115], v[152:155], v[156:159], 0
	v_mfma_f32_16x16x32_bf16 v[116:119], v[140:143], v[160:163], 0
	v_mfma_f32_16x16x32_bf16 v[120:123], v[144:147], v[160:163], 0
	v_mfma_f32_16x16x32_bf16 v[124:127], v[148:151], v[160:163], 0
	v_mfma_f32_16x16x32_bf16 v[128:131], v[152:155], v[160:163], 0
	global_load_dwordx4 v[140:143], v[4:5], off offset:320
	global_load_dwordx4 v[144:147], v[136:137], off offset:320
	global_load_dwordx4 v[148:151], v[82:83], off offset:320
	global_load_dwordx4 v[152:155], v[84:85], off offset:320
	global_load_dwordx4 v[156:159], v[134:135], off offset:320
	global_load_dwordx4 v[160:163], v[132:133], off offset:320
	s_waitcnt vmcnt(24)
	v_mfma_f32_16x16x32_bf16 v[100:103], v[164:167], v[180:183], v[100:103]
	v_mfma_f32_16x16x32_bf16 v[104:107], v[168:171], v[180:183], v[104:107]
	v_mfma_f32_16x16x32_bf16 v[108:111], v[172:175], v[180:183], v[108:111]
	v_mfma_f32_16x16x32_bf16 v[112:115], v[176:179], v[180:183], v[112:115]
	v_mfma_f32_16x16x32_bf16 v[116:119], v[164:167], v[184:187], v[116:119]
	v_mfma_f32_16x16x32_bf16 v[120:123], v[168:171], v[184:187], v[120:123]
	v_mfma_f32_16x16x32_bf16 v[124:127], v[172:175], v[184:187], v[124:127]
	v_mfma_f32_16x16x32_bf16 v[128:131], v[176:179], v[184:187], v[128:131]
	global_load_dwordx4 v[164:167], v[4:5], off offset:384
	global_load_dwordx4 v[168:171], v[136:137], off offset:384
	global_load_dwordx4 v[172:175], v[82:83], off offset:384
	global_load_dwordx4 v[176:179], v[84:85], off offset:384
	global_load_dwordx4 v[180:183], v[134:135], off offset:384
	global_load_dwordx4 v[184:187], v[132:133], off offset:384
	s_waitcnt vmcnt(24)
	v_mfma_f32_16x16x32_bf16 v[100:103], v[188:191], v[204:207], v[100:103]
	v_mfma_f32_16x16x32_bf16 v[104:107], v[192:195], v[204:207], v[104:107]
	v_mfma_f32_16x16x32_bf16 v[108:111], v[196:199], v[204:207], v[108:111]
	v_mfma_f32_16x16x32_bf16 v[112:115], v[200:203], v[204:207], v[112:115]
	v_mfma_f32_16x16x32_bf16 v[116:119], v[188:191], v[208:211], v[116:119]
	v_mfma_f32_16x16x32_bf16 v[120:123], v[192:195], v[208:211], v[120:123]
	v_mfma_f32_16x16x32_bf16 v[124:127], v[196:199], v[208:211], v[124:127]
	v_mfma_f32_16x16x32_bf16 v[128:131], v[200:203], v[208:211], v[128:131]
	global_load_dwordx4 v[188:191], v[4:5], off offset:448
	global_load_dwordx4 v[192:195], v[136:137], off offset:448
	global_load_dwordx4 v[196:199], v[82:83], off offset:448
	global_load_dwordx4 v[200:203], v[84:85], off offset:448
	global_load_dwordx4 v[204:207], v[134:135], off offset:448
	global_load_dwordx4 v[208:211], v[132:133], off offset:448
	s_waitcnt vmcnt(24)
	v_mfma_f32_16x16x32_bf16 v[100:103], v[212:215], v[228:231], v[100:103]
	v_mfma_f32_16x16x32_bf16 v[104:107], v[216:219], v[228:231], v[104:107]
	v_mfma_f32_16x16x32_bf16 v[108:111], v[220:223], v[228:231], v[108:111]
	v_mfma_f32_16x16x32_bf16 v[112:115], v[224:227], v[228:231], v[112:115]
	v_mfma_f32_16x16x32_bf16 v[116:119], v[212:215], v[232:235], v[116:119]
	v_mfma_f32_16x16x32_bf16 v[120:123], v[216:219], v[232:235], v[120:123]
	v_mfma_f32_16x16x32_bf16 v[124:127], v[220:223], v[232:235], v[124:127]
	v_mfma_f32_16x16x32_bf16 v[128:131], v[224:227], v[232:235], v[128:131]
	global_load_dwordx4 v[212:215], v[4:5], off offset:512
	global_load_dwordx4 v[216:219], v[136:137], off offset:512
	global_load_dwordx4 v[220:223], v[82:83], off offset:512
	global_load_dwordx4 v[224:227], v[84:85], off offset:512
	global_load_dwordx4 v[228:231], v[134:135], off offset:512
	global_load_dwordx4 v[232:235], v[132:133], off offset:512
	s_waitcnt vmcnt(24)
	v_mfma_f32_16x16x32_bf16 v[100:103], v[236:239], v[14:17], v[100:103]
	v_mfma_f32_16x16x32_bf16 v[104:107], v[240:243], v[14:17], v[104:107]
	v_mfma_f32_16x16x32_bf16 v[108:111], v[6:9], v[14:17], v[108:111]
	v_mfma_f32_16x16x32_bf16 v[112:115], v[10:13], v[14:17], v[112:115]
	v_mfma_f32_16x16x32_bf16 v[116:119], v[236:239], v[18:21], v[116:119]
	v_mfma_f32_16x16x32_bf16 v[120:123], v[240:243], v[18:21], v[120:123]
	v_mfma_f32_16x16x32_bf16 v[124:127], v[6:9], v[18:21], v[124:127]
	v_mfma_f32_16x16x32_bf16 v[128:131], v[10:13], v[18:21], v[128:131]
	global_load_dwordx4 v[236:239], v[4:5], off offset:576
	global_load_dwordx4 v[240:243], v[136:137], off offset:576
	global_load_dwordx4 v[6:9], v[82:83], off offset:576
	global_load_dwordx4 v[10:13], v[84:85], off offset:576
	global_load_dwordx4 v[14:17], v[134:135], off offset:576
	global_load_dwordx4 v[18:21], v[132:133], off offset:576
	s_waitcnt vmcnt(24)
	v_mfma_f32_16x16x32_bf16 v[100:103], v[140:143], v[156:159], v[100:103]
	v_mfma_f32_16x16x32_bf16 v[104:107], v[144:147], v[156:159], v[104:107]
	v_mfma_f32_16x16x32_bf16 v[108:111], v[148:151], v[156:159], v[108:111]
	v_mfma_f32_16x16x32_bf16 v[112:115], v[152:155], v[156:159], v[112:115]
	v_mfma_f32_16x16x32_bf16 v[116:119], v[140:143], v[160:163], v[116:119]
	v_mfma_f32_16x16x32_bf16 v[120:123], v[144:147], v[160:163], v[120:123]
	v_mfma_f32_16x16x32_bf16 v[124:127], v[148:151], v[160:163], v[124:127]
	v_mfma_f32_16x16x32_bf16 v[128:131], v[152:155], v[160:163], v[128:131]
	global_load_dwordx4 v[140:143], v[4:5], off offset:640
	global_load_dwordx4 v[144:147], v[136:137], off offset:640
	global_load_dwordx4 v[148:151], v[82:83], off offset:640
	global_load_dwordx4 v[152:155], v[84:85], off offset:640
	global_load_dwordx4 v[156:159], v[134:135], off offset:640
	global_load_dwordx4 v[160:163], v[132:133], off offset:640
	s_waitcnt vmcnt(24)
	v_mfma_f32_16x16x32_bf16 v[100:103], v[164:167], v[180:183], v[100:103]
	v_mfma_f32_16x16x32_bf16 v[104:107], v[168:171], v[180:183], v[104:107]
	v_mfma_f32_16x16x32_bf16 v[108:111], v[172:175], v[180:183], v[108:111]
	v_mfma_f32_16x16x32_bf16 v[112:115], v[176:179], v[180:183], v[112:115]
	v_mfma_f32_16x16x32_bf16 v[116:119], v[164:167], v[184:187], v[116:119]
	v_mfma_f32_16x16x32_bf16 v[120:123], v[168:171], v[184:187], v[120:123]
	v_mfma_f32_16x16x32_bf16 v[124:127], v[172:175], v[184:187], v[124:127]
	v_mfma_f32_16x16x32_bf16 v[128:131], v[176:179], v[184:187], v[128:131]
	s_waitcnt vmcnt(18)
	v_mfma_f32_16x16x32_bf16 v[100:103], v[188:191], v[204:207], v[100:103]
	v_mfma_f32_16x16x32_bf16 v[104:107], v[192:195], v[204:207], v[104:107]
	v_mfma_f32_16x16x32_bf16 v[108:111], v[196:199], v[204:207], v[108:111]
	v_mfma_f32_16x16x32_bf16 v[112:115], v[200:203], v[204:207], v[112:115]
	v_mfma_f32_16x16x32_bf16 v[116:119], v[188:191], v[208:211], v[116:119]
	v_mfma_f32_16x16x32_bf16 v[120:123], v[192:195], v[208:211], v[120:123]
	v_mfma_f32_16x16x32_bf16 v[124:127], v[196:199], v[208:211], v[124:127]
	v_mfma_f32_16x16x32_bf16 v[128:131], v[200:203], v[208:211], v[128:131]
	s_waitcnt vmcnt(12)
	v_mfma_f32_16x16x32_bf16 v[100:103], v[212:215], v[228:231], v[100:103]
	v_mfma_f32_16x16x32_bf16 v[104:107], v[216:219], v[228:231], v[104:107]
	v_mfma_f32_16x16x32_bf16 v[108:111], v[220:223], v[228:231], v[108:111]
	v_mfma_f32_16x16x32_bf16 v[112:115], v[224:227], v[228:231], v[112:115]
	v_mfma_f32_16x16x32_bf16 v[116:119], v[212:215], v[232:235], v[116:119]
	v_mfma_f32_16x16x32_bf16 v[120:123], v[216:219], v[232:235], v[120:123]
	v_mfma_f32_16x16x32_bf16 v[124:127], v[220:223], v[232:235], v[124:127]
	v_mfma_f32_16x16x32_bf16 v[128:131], v[224:227], v[232:235], v[128:131]
	s_waitcnt vmcnt(6)
	v_mfma_f32_16x16x32_bf16 v[100:103], v[236:239], v[14:17], v[100:103]
	v_mfma_f32_16x16x32_bf16 v[104:107], v[240:243], v[14:17], v[104:107]
	v_mfma_f32_16x16x32_bf16 v[108:111], v[6:9], v[14:17], v[108:111]
	v_mfma_f32_16x16x32_bf16 v[112:115], v[10:13], v[14:17], v[112:115]
	v_mfma_f32_16x16x32_bf16 v[116:119], v[236:239], v[18:21], v[116:119]
	v_mfma_f32_16x16x32_bf16 v[120:123], v[240:243], v[18:21], v[120:123]
	v_mfma_f32_16x16x32_bf16 v[124:127], v[6:9], v[18:21], v[124:127]
	v_mfma_f32_16x16x32_bf16 v[128:131], v[10:13], v[18:21], v[128:131]
	s_waitcnt vmcnt(0)
	v_mfma_f32_16x16x32_bf16 v[100:103], v[140:143], v[156:159], v[100:103]
	v_mfma_f32_16x16x32_bf16 v[104:107], v[144:147], v[156:159], v[104:107]
	v_mfma_f32_16x16x32_bf16 v[108:111], v[148:151], v[156:159], v[108:111]
	v_mfma_f32_16x16x32_bf16 v[112:115], v[152:155], v[156:159], v[112:115]
	v_mfma_f32_16x16x32_bf16 v[116:119], v[140:143], v[160:163], v[116:119]
	v_mfma_f32_16x16x32_bf16 v[120:123], v[144:147], v[160:163], v[120:123]
	v_mfma_f32_16x16x32_bf16 v[124:127], v[148:151], v[160:163], v[124:127]
	v_mfma_f32_16x16x32_bf16 v[128:131], v[152:155], v[160:163], v[128:131]
	s_nop 7
	s_nop 1
	ds_write_b128 v94, v[100:103]
	ds_write_b128 v95, v[104:107]
	ds_write_b128 v96, v[108:111]
	ds_write_b128 v97, v[112:115]
	ds_write_b128 v94, v[116:119] offset:4096
	ds_write_b128 v95, v[120:123] offset:4096
	ds_write_b128 v96, v[124:127] offset:4096
	ds_write_b128 v97, v[128:131] offset:4096
	s_waitcnt vmcnt(0)
	v_pk_add_f32 v[12:13], v[24:25], v[26:27]
	ds_bpermute_b32 v14, v90, v12
	ds_bpermute_b32 v15, v90, v13
	s_waitcnt lgkmcnt(0)
	v_pk_add_f32 v[12:13], v[12:13], v[14:15]
	ds_bpermute_b32 v14, v91, v12
	ds_bpermute_b32 v15, v91, v13
	s_waitcnt lgkmcnt(0)
	v_pk_add_f32 v[12:13], v[12:13], v[14:15]
	ds_bpermute_b32 v14, v92, v12
	s_waitcnt lgkmcnt(0)
	s_barrier
	ds_read_b128 v[4:7], v89
	ds_read_b128 v[8:11], v89 offset:8192
	ds_bpermute_b32 v15, v92, v13
	s_waitcnt lgkmcnt(2)
	v_pk_add_f32 v[6:7], v[6:7], 0 op_sel_hi:[1,0]
	v_pk_add_f32 v[16:17], v[4:5], 0 op_sel_hi:[1,0]
	s_waitcnt lgkmcnt(1)
	v_pk_add_f32 v[18:19], v[6:7], v[10:11]
	ds_read_b128 v[4:7], v89 offset:16384
	v_pk_add_f32 v[16:17], v[16:17], v[8:9]
	ds_read_b128 v[8:11], v89 offset:24576
	s_waitcnt lgkmcnt(2)
	v_pk_add_f32 v[12:13], v[12:13], v[14:15]
	ds_bpermute_b32 v14, v93, v12
	s_waitcnt lgkmcnt(2)
	v_pk_add_f32 v[6:7], v[18:19], v[6:7]
	v_pk_add_f32 v[4:5], v[16:17], v[4:5]
	s_waitcnt lgkmcnt(1)
	v_pk_add_f32 v[16:17], v[6:7], v[10:11]
	v_pk_add_f32 v[18:19], v[4:5], v[8:9]
	ds_read_b128 v[4:7], v89 offset:32768
	ds_read_b128 v[8:11], v89 offset:40960
	ds_bpermute_b32 v15, v93, v13
	s_waitcnt lgkmcnt(2)
	v_pk_add_f32 v[6:7], v[16:17], v[6:7]
	v_pk_add_f32 v[16:17], v[18:19], v[4:5]
	s_waitcnt lgkmcnt(1)
	v_pk_add_f32 v[18:19], v[6:7], v[10:11]
	s_waitcnt lgkmcnt(0)
	v_pk_add_f32 v[10:11], v[12:13], v[14:15]
	v_pk_add_f32 v[14:15], v[16:17], v[8:9]
	v_pk_mul_f32 v[12:13], v[10:11], s[78:79] op_sel_hi:[1,0]
	ds_read_b128 v[4:7], v89 offset:49152
	v_fma_f32 v2, -v12, v12, v13
	v_max_f32_e32 v2, 0, v2
	v_add_f32_e32 v2, 0x3727c5ac, v2
	v_mul_f32_e32 v10, 0x4f800000, v2
	v_cmp_gt_f32_e32 vcc, s89, v2
	s_nop 1
	v_cndmask_b32_e32 v2, v2, v10, vcc
	v_sqrt_f32_e32 v13, v2
	ds_read_b128 v[8:11], v89 offset:57344
	s_waitcnt lgkmcnt(1)
	v_pk_add_f32 v[4:5], v[14:15], v[4:5]
	v_pk_add_f32 v[6:7], v[18:19], v[6:7]
	v_add_u32_e32 v16, -1, v13
	v_fma_f32 v17, -v16, v13, v2
	v_cmp_ge_f32_e64 s[40:41], 0, v17
	v_add_u32_e32 v17, 1, v13
	s_waitcnt lgkmcnt(0)
	v_pk_add_f32 v[4:5], v[4:5], v[8:9]
	v_cndmask_b32_e64 v16, v13, v16, s[40:41]
	v_fma_f32 v13, -v17, v13, v2
	v_cmp_lt_f32_e64 s[40:41], 0, v13
	v_pk_add_f32 v[6:7], v[6:7], v[10:11]
	s_waitcnt vmcnt(2)
	v_and_b32_e32 v11, 0xffff0000, v73
	v_cndmask_b32_e64 v13, v16, v17, s[40:41]
	v_mul_f32_e32 v16, 0x37800000, v13
	v_cndmask_b32_e32 v13, v13, v16, vcc
	v_cmp_class_f32_e32 vcc, v2, v248
	s_nop 1
	v_cndmask_b32_e32 v2, v13, v2, vcc
	v_div_scale_f32 v13, s[14:15], v2, v2, 1.0
	v_rcp_f32_e32 v16, v13
	s_nop 0
	v_fma_f32 v8, -v13, v16, 1.0
	v_fmac_f32_e32 v16, v8, v16
	v_div_scale_f32 v8, vcc, 1.0, v2, 1.0
	v_mul_f32_e32 v9, v8, v16
	v_fma_f32 v10, -v13, v9, v8
	v_fmac_f32_e32 v9, v10, v16
	v_fma_f32 v8, -v13, v9, v8
	v_div_fmas_f32 v8, v8, v16, v9
	v_div_fixup_f32 v2, v8, v2, 1.0
	v_lshlrev_b32_e32 v8, 16, v72
	v_and_b32_e32 v9, 0xffff0000, v72
	v_mul_f32_e64 v12, v12, -v2
	v_lshlrev_b32_e32 v10, 16, v73
	v_pk_fma_f32 v[8:9], v[2:3], v[8:9], v[12:13] op_sel_hi:[0,1,0]
	v_pk_fma_f32 v[10:11], v[2:3], v[10:11], v[12:13] op_sel_hi:[0,1,0]
	s_waitcnt vmcnt(0)
	v_pk_fma_f32 v[8:9], v[56:57], v[8:9], v[52:53]
	v_pk_fma_f32 v[10:11], v[58:59], v[10:11], v[54:55]
	v_pk_mul_f32 v[8:9], v[8:9], s[94:95] op_sel_hi:[1,0]
	v_pk_mul_f32 v[10:11], v[10:11], s[94:95] op_sel_hi:[1,0]
	v_pk_fma_f32 v[4:5], v[4:5], 0.5, v[8:9] op_sel_hi:[1,0,1]
	v_pk_fma_f32 v[6:7], v[6:7], 0.5, v[10:11] op_sel_hi:[1,0,1]
	v_cvt_pk_f16_f32 v8, v4, v5
	v_cvt_pk_f16_f32 v9, v6, v7
	v_cvt_f32_f16_e32 v4, v8
	v_cvt_f32_f16_sdwa v5, v8 dst_sel:DWORD dst_unused:UNUSED_PAD src0_sel:WORD_1
	v_cvt_f32_f16_e32 v6, v9
	v_cvt_f32_f16_sdwa v7, v9 dst_sel:DWORD dst_unused:UNUSED_PAD src0_sel:WORD_1
	v_mov_b32_e32 v14, v4
	v_pk_mul_f32 v[10:11], v[4:5], v[4:5]
	v_pk_mul_f32 v[12:13], v[6:7], v[6:7]
	v_mov_b32_e32 v15, v10
	v_mov_b32_e32 v10, v5
	v_pk_add_f32 v[4:5], v[14:15], v[10:11]
	v_mov_b32_e32 v10, v6
	v_mov_b32_e32 v11, v12
	v_mov_b32_e32 v12, v7
	v_pk_add_f32 v[6:7], v[10:11], v[12:13]
	v_lshl_add_u64 v[10:11], s[8:9], 0, v[70:71]
	v_pk_add_f32 v[4:5], v[4:5], v[6:7]
	ds_bpermute_b32 v6, v90, v4
	ds_bpermute_b32 v7, v90, v5
	global_store_dwordx2 v[10:11], v[8:9], off
	s_waitcnt lgkmcnt(0)
	v_pk_add_f32 v[4:5], v[4:5], v[6:7]
	ds_bpermute_b32 v6, v91, v4
	ds_bpermute_b32 v7, v91, v5
	s_waitcnt lgkmcnt(0)
	v_pk_add_f32 v[4:5], v[4:5], v[6:7]
	ds_bpermute_b32 v6, v92, v4
	ds_bpermute_b32 v7, v92, v5
	s_waitcnt lgkmcnt(0)
	v_pk_add_f32 v[4:5], v[4:5], v[6:7]
	ds_bpermute_b32 v6, v93, v4
	ds_bpermute_b32 v7, v93, v5
	s_and_saveexec_b64 s[14:15], s[38:39]
	s_cbranch_execz .LBB0_660
	v_lshlrev_b64 v[0:1], 6, v[0:1]
	s_lshl_b32 s16, s16, 2
	v_lshl_add_u64 v[0:1], v[0:1], 2, s[10:11]
	s_ashr_i32 s17, s16, 31
	v_lshl_add_u64 v[8:9], s[16:17], 2, v[0:1]
	s_waitcnt lgkmcnt(0)
	v_pk_add_f32 v[0:1], v[4:5], v[6:7]
	v_mov_b32_e32 v2, v3
	global_store_dwordx4 v[8:9], v[0:3], off
	s_branch .LBB0_660

.LBB0_894:
	s_ashr_i32 s49, s48, 31
	s_lshl_b64 s[0:1], s[48:49], 19
	s_add_u32 s3, s44, s0
	s_addc_u32 s15, s45, s1
	s_ashr_i32 s43, s42, 31
	s_lshl_b64 s[0:1], s[42:43], 9
	s_add_u32 s3, s3, s0
	s_addc_u32 s15, s15, s1
	s_lshl_b64 s[0:1], s[42:43], 17
	s_add_u32 s34, s46, s0
	s_addc_u32 s35, s50, s1
	s_add_i32 s43, 0, 0x10000
	s_and_b64 s[0:1], s[38:39], exec
	s_cselect_b32 s53, s15, s29
	s_cselect_b32 s52, s3, s28
	s_add_i32 s15, 0, 0x14000
	v_add_u32_e32 v2, s43, v210
	v_add_u32_e32 v214, s15, v210
	ds_read_b128 v[4:7], v2
	ds_read_b128 v[8:11], v2 offset:1024
	ds_read_b128 v[12:15], v2 offset:2048
	ds_read_b128 v[16:19], v2 offset:3072
	ds_read_b128 v[20:23], v214
	ds_read_b128 v[24:27], v214 offset:1024
	ds_read_b128 v[28:31], v214 offset:2048
	ds_read_b128 v[32:35], v214 offset:3072
	s_and_b64 s[0:1], s[38:39], exec
	s_cselect_b32 s55, s35, s31
	s_cselect_b32 s54, s34, s30
	s_add_u32 s34, s28, 0x40080
	s_addc_u32 s35, s29, 0
	s_add_i32 s1, s51, 0xc000
	v_lshl_add_u64 v[68:69], s[34:35], 0, v[0:1]
	s_mov_b32 m0, s1
	s_add_i32 s0, s51, 0xe000
	ds_read_b128 v[36:39], v211
	ds_read_b128 v[40:43], v211 offset:1024
	ds_read_b128 v[44:47], v211 offset:2048
	ds_read_b128 v[48:51], v211 offset:3072
	ds_read_b128 v[52:55], v211 offset:4096
	ds_read_b128 v[56:59], v211 offset:5120
	ds_read_b128 v[60:63], v211 offset:6144
	ds_read_b128 v[64:67], v211 offset:7168
	global_load_lds_dwordx4 v[68:69], off
	v_lshl_add_u64 v[68:69], s[34:35], 0, v[170:171]
	s_mov_b32 m0, s0
	s_nop 0
	global_load_lds_dwordx4 v[68:69], off
	s_waitcnt vmcnt(8)
	s_waitcnt lgkmcnt(0)
	s_setprio 1
	s_barrier
	v_mfma_f32_16x16x32_bf16 v[68:71], v[4:7], v[36:39], 0
	v_mfma_f32_16x16x32_bf16 v[72:75], v[12:15], v[36:39], 0
	v_mfma_f32_16x16x32_bf16 v[76:79], v[4:7], v[44:47], 0
	v_mfma_f32_16x16x32_bf16 v[80:83], v[12:15], v[44:47], 0
	v_mfma_f32_16x16x32_bf16 v[84:87], v[4:7], v[52:55], 0
	v_mfma_f32_16x16x32_bf16 v[88:91], v[12:15], v[52:55], 0
	v_mfma_f32_16x16x32_bf16 v[92:95], v[4:7], v[60:63], 0
	v_mfma_f32_16x16x32_bf16 v[68:71], v[8:11], v[40:43], v[68:71]
	v_mfma_f32_16x16x32_bf16 v[72:75], v[16:19], v[40:43], v[72:75]
	v_mfma_f32_16x16x32_bf16 v[76:79], v[8:11], v[48:51], v[76:79]
	v_mfma_f32_16x16x32_bf16 v[80:83], v[16:19], v[48:51], v[80:83]
	v_mfma_f32_16x16x32_bf16 v[84:87], v[8:11], v[56:59], v[84:87]
	v_mfma_f32_16x16x32_bf16 v[88:91], v[16:19], v[56:59], v[88:91]
	v_mfma_f32_16x16x32_bf16 v[92:95], v[8:11], v[64:67], v[92:95]
	v_mfma_f32_16x16x32_bf16 v[96:99], v[12:15], v[60:63], 0
	s_nop 0
	v_mfma_f32_16x16x32_bf16 v[96:99], v[16:19], v[64:67], v[96:99]
	v_mfma_f32_16x16x32_bf16 v[100:103], v[20:23], v[36:39], 0
	v_mfma_f32_16x16x32_bf16 v[36:39], v[28:31], v[36:39], 0
	v_mfma_f32_16x16x32_bf16 v[100:103], v[24:27], v[40:43], v[100:103]
	v_mfma_f32_16x16x32_bf16 v[36:39], v[32:35], v[40:43], v[36:39]
	v_mfma_f32_16x16x32_bf16 v[40:43], v[20:23], v[44:47], 0
	v_mfma_f32_16x16x32_bf16 v[44:47], v[28:31], v[44:47], 0
	v_mfma_f32_16x16x32_bf16 v[40:43], v[24:27], v[48:51], v[40:43]
	v_mfma_f32_16x16x32_bf16 v[44:47], v[32:35], v[48:51], v[44:47]
	v_mfma_f32_16x16x32_bf16 v[48:51], v[20:23], v[52:55], 0
	v_mfma_f32_16x16x32_bf16 v[52:55], v[28:31], v[52:55], 0
	v_mfma_f32_16x16x32_bf16 v[48:51], v[24:27], v[56:59], v[48:51]
	v_mfma_f32_16x16x32_bf16 v[52:55], v[32:35], v[56:59], v[52:55]
	v_mfma_f32_16x16x32_bf16 v[56:59], v[20:23], v[60:63], 0
	v_mfma_f32_16x16x32_bf16 v[60:63], v[28:31], v[60:63], 0
	v_mfma_f32_16x16x32_bf16 v[56:59], v[24:27], v[64:67], v[56:59]
	v_mfma_f32_16x16x32_bf16 v[60:63], v[32:35], v[64:67], v[60:63]
	s_barrier
	s_setprio 0
	s_add_i32 s35, s43, s37
	v_lshl_add_u64 v[198:199], s[30:31], 0, v[168:169]
	s_mov_b64 s[90:91], 0x100
	s_add_i32 s3, s35, 0x2000
	v_lshl_add_u64 v[132:133], v[198:199], 0, s[90:91]
	s_mov_b32 m0, s35
	v_lshl_add_u64 v[204:205], s[30:31], 0, v[172:173]
	s_add_u32 s66, s30, 0x10100
	ds_read_b128 v[64:67], v211 offset:16384
	ds_read_b128 v[104:107], v211 offset:17408
	ds_read_b128 v[108:111], v211 offset:18432
	ds_read_b128 v[112:115], v211 offset:19456
	ds_read_b128 v[116:119], v211 offset:20480
	ds_read_b128 v[120:123], v211 offset:21504
	ds_read_b128 v[124:127], v211 offset:22528
	ds_read_b128 v[128:131], v211 offset:23552
	global_load_lds_dwordx4 v[132:133], off
	v_lshl_add_u64 v[132:133], v[204:205], 0, s[90:91]
	s_mov_b32 m0, s3
	s_addc_u32 s67, s31, 0
	s_add_i32 s15, s15, s37
	global_load_lds_dwordx4 v[132:133], off
	v_lshl_add_u64 v[132:133], s[66:67], 0, v[168:169]
	s_mov_b32 m0, s15
	s_add_i32 s34, s15, 0x2000
	global_load_lds_dwordx4 v[132:133], off
	v_lshl_add_u64 v[132:133], s[66:67], 0, v[172:173]
	s_mov_b32 m0, s34
	v_lshl_add_u64 v[206:207], s[28:29], 0, v[0:1]
	global_load_lds_dwordx4 v[132:133], off
	v_lshl_add_u64 v[132:133], v[206:207], 0, s[90:91]
	s_mov_b32 m0, s51
	v_lshl_add_u64 v[208:209], s[28:29], 0, v[170:171]
	global_load_lds_dwordx4 v[132:133], off
	v_lshl_add_u64 v[132:133], v[208:209], 0, s[90:91]
	s_mov_b32 m0, s56
	s_nop 0
	global_load_lds_dwordx4 v[132:133], off
	s_waitcnt vmcnt(8)
	s_waitcnt lgkmcnt(0)
	s_setprio 1
	s_barrier
	v_mfma_f32_16x16x32_bf16 v[132:135], v[4:7], v[64:67], 0
	v_mfma_f32_16x16x32_bf16 v[140:143], v[4:7], v[108:111], 0
	v_mfma_f32_16x16x32_bf16 v[148:151], v[4:7], v[116:119], 0
	v_mfma_f32_16x16x32_bf16 v[4:7], v[4:7], v[124:127], 0
	v_mfma_f32_16x16x32_bf16 v[132:135], v[8:11], v[104:107], v[132:135]
	v_mfma_f32_16x16x32_bf16 v[140:143], v[8:11], v[112:115], v[140:143]
	v_mfma_f32_16x16x32_bf16 v[144:147], v[12:15], v[108:111], 0
	v_mfma_f32_16x16x32_bf16 v[148:151], v[8:11], v[120:123], v[148:151]
	v_mfma_f32_16x16x32_bf16 v[152:155], v[12:15], v[116:119], 0
	v_mfma_f32_16x16x32_bf16 v[4:7], v[8:11], v[128:131], v[4:7]
	v_mfma_f32_16x16x32_bf16 v[8:11], v[12:15], v[124:127], 0
	v_mfma_f32_16x16x32_bf16 v[144:147], v[16:19], v[112:115], v[144:147]
	v_mfma_f32_16x16x32_bf16 v[152:155], v[16:19], v[120:123], v[152:155]
	v_mfma_f32_16x16x32_bf16 v[8:11], v[16:19], v[128:131], v[8:11]
	v_mfma_f32_16x16x32_bf16 v[136:139], v[12:15], v[64:67], 0
	s_nop 0
	v_mfma_f32_16x16x32_bf16 v[136:139], v[16:19], v[104:107], v[136:139]
	v_mfma_f32_16x16x32_bf16 v[12:15], v[20:23], v[64:67], 0
	v_mfma_f32_16x16x32_bf16 v[16:19], v[28:31], v[64:67], 0
	v_mfma_f32_16x16x32_bf16 v[12:15], v[24:27], v[104:107], v[12:15]
	v_mfma_f32_16x16x32_bf16 v[16:19], v[32:35], v[104:107], v[16:19]
	v_mfma_f32_16x16x32_bf16 v[64:67], v[20:23], v[108:111], 0
	v_mfma_f32_16x16x32_bf16 v[104:107], v[28:31], v[108:111], 0
	v_mfma_f32_16x16x32_bf16 v[108:111], v[20:23], v[116:119], 0
	v_mfma_f32_16x16x32_bf16 v[20:23], v[20:23], v[124:127], 0
	v_mfma_f32_16x16x32_bf16 v[64:67], v[24:27], v[112:115], v[64:67]
	v_mfma_f32_16x16x32_bf16 v[104:107], v[32:35], v[112:115], v[104:107]
	v_mfma_f32_16x16x32_bf16 v[108:111], v[24:27], v[120:123], v[108:111]
	v_mfma_f32_16x16x32_bf16 v[112:115], v[28:31], v[116:119], 0
	v_mfma_f32_16x16x32_bf16 v[20:23], v[24:27], v[128:131], v[20:23]
	v_mfma_f32_16x16x32_bf16 v[24:27], v[28:31], v[124:127], 0
	v_mfma_f32_16x16x32_bf16 v[112:115], v[32:35], v[120:123], v[112:115]
	v_mfma_f32_16x16x32_bf16 v[24:27], v[32:35], v[128:131], v[24:27]
	s_barrier
	s_setprio 0
	s_add_i32 s49, 0, 0x18000
	s_add_i32 s61, 0, 0x1c000
	v_add_u32_e32 v228, s49, v210
	v_add_u32_e32 v229, s61, v210
	ds_read_b128 v[28:31], v228
	ds_read_b128 v[32:35], v228 offset:1024
	ds_read_b128 v[116:119], v228 offset:2048
	ds_read_b128 v[120:123], v228 offset:3072
	ds_read_b128 v[124:127], v229
	ds_read_b128 v[128:131], v229 offset:1024
	ds_read_b128 v[156:159], v229 offset:2048
	ds_read_b128 v[160:163], v229 offset:3072
	s_add_u32 s66, s28, 0x40100
	s_addc_u32 s67, s29, 0
	s_mov_b32 m0, s57
	v_lshl_add_u64 v[212:213], s[66:67], 0, v[0:1]
	ds_read_b128 v[164:167], v211 offset:32768
	ds_read_b128 v[174:177], v211 offset:33792
	ds_read_b128 v[178:181], v211 offset:34816
	ds_read_b128 v[182:185], v211 offset:35840
	ds_read_b128 v[186:189], v211 offset:36864
	ds_read_b128 v[190:193], v211 offset:37888
	ds_read_b128 v[194:197], v211 offset:38912
	ds_read_b128 v[200:203], v211 offset:39936
	global_load_lds_dwordx4 v[212:213], off
	v_lshl_add_u64 v[212:213], s[66:67], 0, v[170:171]
	s_mov_b32 m0, s58
	s_nop 0
	global_load_lds_dwordx4 v[212:213], off
	s_waitcnt vmcnt(8)
	s_waitcnt lgkmcnt(0)
	s_setprio 1
	s_barrier
	v_mfma_f32_16x16x32_bf16 v[68:71], v[28:31], v[164:167], v[68:71]
	v_mfma_f32_16x16x32_bf16 v[72:75], v[116:119], v[164:167], v[72:75]
	v_mfma_f32_16x16x32_bf16 v[76:79], v[28:31], v[178:181], v[76:79]
	v_mfma_f32_16x16x32_bf16 v[80:83], v[116:119], v[178:181], v[80:83]
	v_mfma_f32_16x16x32_bf16 v[84:87], v[28:31], v[186:189], v[84:87]
	v_mfma_f32_16x16x32_bf16 v[88:91], v[116:119], v[186:189], v[88:91]
	v_mfma_f32_16x16x32_bf16 v[92:95], v[28:31], v[194:197], v[92:95]
	v_mfma_f32_16x16x32_bf16 v[68:71], v[32:35], v[174:177], v[68:71]
	v_mfma_f32_16x16x32_bf16 v[72:75], v[120:123], v[174:177], v[72:75]
	v_mfma_f32_16x16x32_bf16 v[76:79], v[32:35], v[182:185], v[76:79]
	v_mfma_f32_16x16x32_bf16 v[80:83], v[120:123], v[182:185], v[80:83]
	v_mfma_f32_16x16x32_bf16 v[84:87], v[32:35], v[190:193], v[84:87]
	v_mfma_f32_16x16x32_bf16 v[88:91], v[120:123], v[190:193], v[88:91]
	v_mfma_f32_16x16x32_bf16 v[92:95], v[32:35], v[200:203], v[92:95]
	v_mfma_f32_16x16x32_bf16 v[96:99], v[116:119], v[194:197], v[96:99]
	v_mfma_f32_16x16x32_bf16 v[96:99], v[120:123], v[200:203], v[96:99]
	v_mfma_f32_16x16x32_bf16 v[36:39], v[156:159], v[164:167], v[36:39]
	v_mfma_f32_16x16x32_bf16 v[40:43], v[124:127], v[178:181], v[40:43]
	v_mfma_f32_16x16x32_bf16 v[44:47], v[156:159], v[178:181], v[44:47]
	v_mfma_f32_16x16x32_bf16 v[48:51], v[124:127], v[186:189], v[48:51]
	v_mfma_f32_16x16x32_bf16 v[52:55], v[156:159], v[186:189], v[52:55]
	v_mfma_f32_16x16x32_bf16 v[56:59], v[124:127], v[194:197], v[56:59]
	v_mfma_f32_16x16x32_bf16 v[60:63], v[156:159], v[194:197], v[60:63]
	v_mfma_f32_16x16x32_bf16 v[100:103], v[124:127], v[164:167], v[100:103]
	v_mfma_f32_16x16x32_bf16 v[36:39], v[160:163], v[174:177], v[36:39]
	v_mfma_f32_16x16x32_bf16 v[40:43], v[128:131], v[182:185], v[40:43]
	v_mfma_f32_16x16x32_bf16 v[44:47], v[160:163], v[182:185], v[44:47]
	v_mfma_f32_16x16x32_bf16 v[48:51], v[128:131], v[190:193], v[48:51]
	v_mfma_f32_16x16x32_bf16 v[52:55], v[160:163], v[190:193], v[52:55]
	v_mfma_f32_16x16x32_bf16 v[56:59], v[128:131], v[200:203], v[56:59]
	v_mfma_f32_16x16x32_bf16 v[60:63], v[160:163], v[200:203], v[60:63]
	v_mfma_f32_16x16x32_bf16 v[100:103], v[128:131], v[174:177], v[100:103]
	s_barrier
	s_setprio 0
	s_add_i32 s49, s49, s37
	s_add_i32 s43, s49, 0x2000
	v_lshl_add_u64 v[198:199], v[198:199], 0, s[84:85]
	s_mov_b32 m0, s49
	s_add_u32 s66, s30, 0x10180
	ds_read_b128 v[164:167], v211 offset:49152
	ds_read_b128 v[174:177], v211 offset:50176
	ds_read_b128 v[178:181], v211 offset:51200
	ds_read_b128 v[182:185], v211 offset:52224
	ds_read_b128 v[186:189], v211 offset:53248
	ds_read_b128 v[190:193], v211 offset:54272
	ds_read_b128 v[194:197], v211 offset:55296
	ds_read_b128 v[200:203], v211 offset:56320
	global_load_lds_dwordx4 v[198:199], off
	v_lshl_add_u64 v[198:199], v[204:205], 0, s[84:85]
	s_mov_b32 m0, s43
	s_addc_u32 s67, s31, 0
	s_add_i32 s30, s61, s37
	global_load_lds_dwordx4 v[198:199], off
	v_lshl_add_u64 v[198:199], s[66:67], 0, v[168:169]
	s_mov_b32 m0, s30
	s_add_i32 s31, s30, 0x2000
	global_load_lds_dwordx4 v[198:199], off
	v_lshl_add_u64 v[198:199], s[66:67], 0, v[172:173]
	s_mov_b32 m0, s31
	s_nop 0
	global_load_lds_dwordx4 v[198:199], off
	v_lshl_add_u64 v[198:199], v[206:207], 0, s[84:85]
	s_mov_b32 m0, s62
	s_nop 0
	global_load_lds_dwordx4 v[198:199], off
	v_lshl_add_u64 v[198:199], v[208:209], 0, s[84:85]
	s_mov_b32 m0, s76
	s_nop 0
	global_load_lds_dwordx4 v[198:199], off
	s_waitcnt vmcnt(8)
	s_waitcnt lgkmcnt(0)
	s_setprio 1
	s_barrier
	v_mfma_f32_16x16x32_bf16 v[140:143], v[28:31], v[178:181], v[140:143]
	v_mfma_f32_16x16x32_bf16 v[144:147], v[116:119], v[178:181], v[144:147]
	v_mfma_f32_16x16x32_bf16 v[152:155], v[116:119], v[186:189], v[152:155]
	v_mfma_f32_16x16x32_bf16 v[4:7], v[28:31], v[194:197], v[4:7]
	v_mfma_f32_16x16x32_bf16 v[8:11], v[116:119], v[194:197], v[8:11]
	v_mfma_f32_16x16x32_bf16 v[132:135], v[28:31], v[164:167], v[132:135]
	v_mfma_f32_16x16x32_bf16 v[136:139], v[116:119], v[164:167], v[136:139]
	v_mfma_f32_16x16x32_bf16 v[140:143], v[32:35], v[182:185], v[140:143]
	v_mfma_f32_16x16x32_bf16 v[144:147], v[120:123], v[182:185], v[144:147]
	v_mfma_f32_16x16x32_bf16 v[148:151], v[28:31], v[186:189], v[148:151]
	v_mfma_f32_16x16x32_bf16 v[152:155], v[120:123], v[190:193], v[152:155]
	v_mfma_f32_16x16x32_bf16 v[4:7], v[32:35], v[200:203], v[4:7]
	v_mfma_f32_16x16x32_bf16 v[8:11], v[120:123], v[200:203], v[8:11]
	v_mfma_f32_16x16x32_bf16 v[132:135], v[32:35], v[174:177], v[132:135]
	v_mfma_f32_16x16x32_bf16 v[136:139], v[120:123], v[174:177], v[136:139]
	v_mfma_f32_16x16x32_bf16 v[148:151], v[32:35], v[190:193], v[148:151]
	v_mfma_f32_16x16x32_bf16 v[12:15], v[124:127], v[164:167], v[12:15]
	v_mfma_f32_16x16x32_bf16 v[16:19], v[156:159], v[164:167], v[16:19]
	v_mfma_f32_16x16x32_bf16 v[28:31], v[124:127], v[178:181], v[64:67]
	v_mfma_f32_16x16x32_bf16 v[32:35], v[156:159], v[178:181], v[104:107]
	v_mfma_f32_16x16x32_bf16 v[64:67], v[124:127], v[186:189], v[108:111]
	v_mfma_f32_16x16x32_bf16 v[20:23], v[124:127], v[194:197], v[20:23]
	v_mfma_f32_16x16x32_bf16 v[24:27], v[156:159], v[194:197], v[24:27]
	v_mfma_f32_16x16x32_bf16 v[12:15], v[128:131], v[174:177], v[12:15]
	v_mfma_f32_16x16x32_bf16 v[16:19], v[160:163], v[174:177], v[16:19]
	v_mfma_f32_16x16x32_bf16 v[28:31], v[128:131], v[182:185], v[28:31]
	v_mfma_f32_16x16x32_bf16 v[32:35], v[160:163], v[182:185], v[32:35]
	v_mfma_f32_16x16x32_bf16 v[64:67], v[128:131], v[190:193], v[64:67]
	v_mfma_f32_16x16x32_bf16 v[104:107], v[156:159], v[186:189], v[112:115]
	v_mfma_f32_16x16x32_bf16 v[20:23], v[128:131], v[200:203], v[20:23]
	v_mfma_f32_16x16x32_bf16 v[24:27], v[160:163], v[200:203], v[24:27]
	v_mfma_f32_16x16x32_bf16 v[104:107], v[160:163], v[190:193], v[104:107]
	s_barrier
	s_setprio 0
	ds_read_b128 v[108:111], v2
	ds_read_b128 v[112:115], v2 offset:1024
	ds_read_b128 v[116:119], v2 offset:2048
	ds_read_b128 v[120:123], v2 offset:3072
	ds_read_b128 v[124:127], v214
	ds_read_b128 v[128:131], v214 offset:1024
	ds_read_b128 v[156:159], v214 offset:2048
	ds_read_b128 v[160:163], v214 offset:3072
	s_add_u32 s28, s28, 0x40180
	s_addc_u32 s29, s29, 0
	s_mov_b32 m0, s1
	v_lshl_add_u64 v[198:199], s[28:29], 0, v[0:1]
	ds_read_b128 v[164:167], v211
	ds_read_b128 v[174:177], v211 offset:1024
	ds_read_b128 v[178:181], v211 offset:2048
	ds_read_b128 v[182:185], v211 offset:3072
	ds_read_b128 v[186:189], v211 offset:4096
	ds_read_b128 v[190:193], v211 offset:5120
	ds_read_b128 v[194:197], v211 offset:6144
	ds_read_b128 v[200:203], v211 offset:7168
	global_load_lds_dwordx4 v[198:199], off
	v_lshl_add_u64 v[198:199], s[28:29], 0, v[170:171]
	s_mov_b32 m0, s0
	s_nop 0
	global_load_lds_dwordx4 v[198:199], off
	s_waitcnt vmcnt(8)
	s_waitcnt lgkmcnt(0)
	s_setprio 1
	s_barrier
	v_mfma_f32_16x16x32_bf16 v[68:71], v[108:111], v[164:167], v[68:71]
	v_mfma_f32_16x16x32_bf16 v[72:75], v[116:119], v[164:167], v[72:75]
	v_mfma_f32_16x16x32_bf16 v[76:79], v[108:111], v[178:181], v[76:79]
	v_mfma_f32_16x16x32_bf16 v[80:83], v[116:119], v[178:181], v[80:83]
	v_mfma_f32_16x16x32_bf16 v[84:87], v[108:111], v[186:189], v[84:87]
	v_mfma_f32_16x16x32_bf16 v[88:91], v[116:119], v[186:189], v[88:91]
	v_mfma_f32_16x16x32_bf16 v[92:95], v[108:111], v[194:197], v[92:95]
	v_mfma_f32_16x16x32_bf16 v[68:71], v[112:115], v[174:177], v[68:71]
	v_mfma_f32_16x16x32_bf16 v[72:75], v[120:123], v[174:177], v[72:75]
	v_mfma_f32_16x16x32_bf16 v[76:79], v[112:115], v[182:185], v[76:79]
	v_mfma_f32_16x16x32_bf16 v[80:83], v[120:123], v[182:185], v[80:83]
	v_mfma_f32_16x16x32_bf16 v[84:87], v[112:115], v[190:193], v[84:87]
	v_mfma_f32_16x16x32_bf16 v[88:91], v[120:123], v[190:193], v[88:91]
	v_mfma_f32_16x16x32_bf16 v[204:207], v[112:115], v[200:203], v[92:95]
	v_mfma_f32_16x16x32_bf16 v[92:95], v[116:119], v[194:197], v[96:99]
	v_mfma_f32_16x16x32_bf16 v[96:99], v[120:123], v[200:203], v[92:95]
	v_mfma_f32_16x16x32_bf16 v[52:55], v[156:159], v[186:189], v[52:55]
	v_mfma_f32_16x16x32_bf16 v[92:95], v[124:127], v[164:167], v[100:103]
	v_mfma_f32_16x16x32_bf16 v[36:39], v[156:159], v[164:167], v[36:39]
	v_mfma_f32_16x16x32_bf16 v[40:43], v[124:127], v[178:181], v[40:43]
	v_mfma_f32_16x16x32_bf16 v[44:47], v[156:159], v[178:181], v[44:47]
	v_mfma_f32_16x16x32_bf16 v[48:51], v[124:127], v[186:189], v[48:51]
	v_mfma_f32_16x16x32_bf16 v[164:167], v[160:163], v[190:193], v[52:55]
	v_mfma_f32_16x16x32_bf16 v[52:55], v[124:127], v[194:197], v[56:59]
	v_mfma_f32_16x16x32_bf16 v[100:103], v[128:131], v[174:177], v[92:95]
	v_mfma_f32_16x16x32_bf16 v[36:39], v[160:163], v[174:177], v[36:39]
	v_mfma_f32_16x16x32_bf16 v[40:43], v[128:131], v[182:185], v[40:43]
	v_mfma_f32_16x16x32_bf16 v[44:47], v[160:163], v[182:185], v[44:47]
	v_mfma_f32_16x16x32_bf16 v[48:51], v[128:131], v[190:193], v[48:51]
	v_mfma_f32_16x16x32_bf16 v[174:177], v[128:131], v[200:203], v[52:55]
	v_mfma_f32_16x16x32_bf16 v[52:55], v[156:159], v[194:197], v[60:63]
	v_mfma_f32_16x16x32_bf16 v[178:181], v[160:163], v[200:203], v[52:55]
	s_barrier
	s_setprio 0
	s_mov_b32 m0, s35
	v_lshl_add_u64 v[198:199], s[54:55], 0, v[168:169]
	s_add_u32 s0, s54, 0x10000
	s_nop 1
	ds_read_b128 v[52:55], v211 offset:16384
	ds_read_b128 v[56:59], v211 offset:17408
	ds_read_b128 v[60:63], v211 offset:18432
	ds_read_b128 v[92:95], v211 offset:19456
	ds_read_b128 v[182:185], v211 offset:20480
	ds_read_b128 v[186:189], v211 offset:21504
	ds_read_b128 v[190:193], v211 offset:22528
	ds_read_b128 v[194:197], v211 offset:23552
	global_load_lds_dwordx4 v[198:199], off
	v_lshl_add_u64 v[208:209], s[54:55], 0, v[172:173]
	s_mov_b32 m0, s3
	s_addc_u32 s1, s55, 0
	global_load_lds_dwordx4 v[208:209], off
	v_lshl_add_u64 v[200:201], s[0:1], 0, v[168:169]
	s_mov_b32 m0, s15
	v_lshl_add_u64 v[240:241], s[52:53], 0, v[0:1]
	global_load_lds_dwordx4 v[200:201], off
	v_lshl_add_u64 v[200:201], s[0:1], 0, v[172:173]
	s_mov_b32 m0, s34
	v_lshl_add_u64 v[242:243], s[52:53], 0, v[170:171]
	global_load_lds_dwordx4 v[200:201], off
	s_mov_b32 m0, s51
	s_nop 0
	global_load_lds_dwordx4 v[240:241], off
	s_mov_b32 m0, s56
	s_nop 0
	global_load_lds_dwordx4 v[242:243], off
	s_waitcnt vmcnt(8)
	s_waitcnt lgkmcnt(0)
	s_setprio 1
	s_barrier
	v_mfma_f32_16x16x32_bf16 v[140:143], v[108:111], v[60:63], v[140:143]
	v_mfma_f32_16x16x32_bf16 v[200:203], v[112:115], v[92:95], v[140:143]
	v_mfma_f32_16x16x32_bf16 v[140:143], v[116:119], v[60:63], v[144:147]
	v_mfma_f32_16x16x32_bf16 v[212:215], v[120:123], v[92:95], v[140:143]
	v_mfma_f32_16x16x32_bf16 v[140:143], v[108:111], v[182:185], v[148:151]
	v_mfma_f32_16x16x32_bf16 v[4:7], v[108:111], v[190:193], v[4:7]
	v_mfma_f32_16x16x32_bf16 v[8:11], v[116:119], v[190:193], v[8:11]
	v_mfma_f32_16x16x32_bf16 v[132:135], v[108:111], v[52:55], v[132:135]
	v_mfma_f32_16x16x32_bf16 v[136:139], v[116:119], v[52:55], v[136:139]
	v_mfma_f32_16x16x32_bf16 v[148:151], v[112:115], v[186:189], v[140:143]
	v_mfma_f32_16x16x32_bf16 v[140:143], v[116:119], v[182:185], v[152:155]
	v_mfma_f32_16x16x32_bf16 v[4:7], v[112:115], v[194:197], v[4:7]
	v_mfma_f32_16x16x32_bf16 v[8:11], v[120:123], v[194:197], v[8:11]
	v_mfma_f32_16x16x32_bf16 v[132:135], v[112:115], v[56:59], v[132:135]
	v_mfma_f32_16x16x32_bf16 v[136:139], v[120:123], v[56:59], v[136:139]
	v_mfma_f32_16x16x32_bf16 v[216:219], v[120:123], v[186:189], v[140:143]
	v_mfma_f32_16x16x32_bf16 v[28:31], v[124:127], v[60:63], v[28:31]
	v_mfma_f32_16x16x32_bf16 v[116:119], v[128:131], v[92:95], v[28:31]
	v_mfma_f32_16x16x32_bf16 v[28:31], v[156:159], v[60:63], v[32:35]
	v_mfma_f32_16x16x32_bf16 v[12:15], v[124:127], v[52:55], v[12:15]
	v_mfma_f32_16x16x32_bf16 v[16:19], v[156:159], v[52:55], v[16:19]
	v_mfma_f32_16x16x32_bf16 v[220:223], v[160:163], v[92:95], v[28:31]
	v_mfma_f32_16x16x32_bf16 v[28:31], v[124:127], v[182:185], v[64:67]
	v_mfma_f32_16x16x32_bf16 v[20:23], v[124:127], v[190:193], v[20:23]
	v_mfma_f32_16x16x32_bf16 v[12:15], v[128:131], v[56:59], v[12:15]
	v_mfma_f32_16x16x32_bf16 v[16:19], v[160:163], v[56:59], v[16:19]
	v_mfma_f32_16x16x32_bf16 v[224:227], v[128:131], v[186:189], v[28:31]
	v_mfma_f32_16x16x32_bf16 v[28:31], v[156:159], v[182:185], v[104:107]
	v_mfma_f32_16x16x32_bf16 v[182:185], v[128:131], v[194:197], v[20:23]
	v_mfma_f32_16x16x32_bf16 v[20:23], v[156:159], v[190:193], v[24:27]
	v_mfma_f32_16x16x32_bf16 v[104:107], v[160:163], v[186:189], v[28:31]
	v_mfma_f32_16x16x32_bf16 v[160:163], v[160:163], v[194:197], v[20:23]
	s_barrier
	s_setprio 0
	s_nop 3
	ds_read_b128 v[20:23], v228
	ds_read_b128 v[24:27], v228 offset:1024
	ds_read_b128 v[28:31], v228 offset:2048
	ds_read_b128 v[32:35], v228 offset:3072
	ds_read_b128 v[186:189], v229
	ds_read_b128 v[190:193], v229 offset:1024
	ds_read_b128 v[194:197], v229 offset:2048
	ds_read_b128 v[228:231], v229 offset:3072
	s_add_u32 s0, s52, 0x40000
	s_addc_u32 s1, s53, 0
	s_mov_b32 m0, s57
	v_lshl_add_u64 v[60:61], s[0:1], 0, v[0:1]
	ds_read_b128 v[52:55], v211 offset:32768
	ds_read_b128 v[56:59], v211 offset:33792
	ds_read_b128 v[108:111], v211 offset:34816
	ds_read_b128 v[112:115], v211 offset:35840
	ds_read_b128 v[124:127], v211 offset:36864
	ds_read_b128 v[128:131], v211 offset:37888
	ds_read_b128 v[232:235], v211 offset:38912
	ds_read_b128 v[236:239], v211 offset:39936
	global_load_lds_dwordx4 v[60:61], off
	v_lshl_add_u64 v[60:61], s[0:1], 0, v[170:171]
	s_mov_b32 m0, s58
	s_nop 0
	global_load_lds_dwordx4 v[60:61], off
	s_waitcnt vmcnt(8)
	s_waitcnt lgkmcnt(0)
	s_setprio 1
	s_barrier
	v_mfma_f32_16x16x32_bf16 v[60:63], v[20:23], v[52:55], v[68:71]
	v_mfma_f32_16x16x32_bf16 v[156:159], v[24:27], v[56:59], v[60:63]
	v_mfma_f32_16x16x32_bf16 v[60:63], v[28:31], v[52:55], v[72:75]
	v_mfma_f32_16x16x32_bf16 v[152:155], v[32:35], v[56:59], v[60:63]
	v_mfma_f32_16x16x32_bf16 v[60:63], v[20:23], v[108:111], v[76:79]
	v_mfma_f32_16x16x32_bf16 v[144:147], v[24:27], v[112:115], v[60:63]
	v_mfma_f32_16x16x32_bf16 v[60:63], v[28:31], v[108:111], v[80:83]
	v_mfma_f32_16x16x32_bf16 v[140:143], v[32:35], v[112:115], v[60:63]
	v_mfma_f32_16x16x32_bf16 v[60:63], v[20:23], v[124:127], v[84:87]
	v_mfma_f32_16x16x32_bf16 v[120:123], v[24:27], v[128:131], v[60:63]
	v_mfma_f32_16x16x32_bf16 v[60:63], v[28:31], v[124:127], v[88:91]
	v_mfma_f32_16x16x32_bf16 v[92:95], v[32:35], v[128:131], v[60:63]
	v_mfma_f32_16x16x32_bf16 v[60:63], v[20:23], v[232:235], v[204:207]
	v_mfma_f32_16x16x32_bf16 v[80:83], v[24:27], v[236:239], v[60:63]
	v_mfma_f32_16x16x32_bf16 v[60:63], v[28:31], v[232:235], v[96:99]
	v_mfma_f32_16x16x32_bf16 v[68:71], v[32:35], v[236:239], v[60:63]
	v_mfma_f32_16x16x32_bf16 v[36:39], v[194:197], v[52:55], v[36:39]
	v_mfma_f32_16x16x32_bf16 v[60:63], v[186:189], v[52:55], v[100:103]
	v_mfma_f32_16x16x32_bf16 v[64:67], v[228:231], v[56:59], v[36:39]
	v_mfma_f32_16x16x32_bf16 v[36:39], v[186:189], v[108:111], v[40:43]
	v_mfma_f32_16x16x32_bf16 v[60:63], v[190:193], v[56:59], v[60:63]
	v_mfma_f32_16x16x32_bf16 v[56:59], v[190:193], v[112:115], v[36:39]
	v_mfma_f32_16x16x32_bf16 v[36:39], v[194:197], v[108:111], v[44:47]
	v_mfma_f32_16x16x32_bf16 v[52:55], v[228:231], v[112:115], v[36:39]
	v_mfma_f32_16x16x32_bf16 v[36:39], v[186:189], v[124:127], v[48:51]
	v_mfma_f32_16x16x32_bf16 v[48:51], v[190:193], v[128:131], v[36:39]
	v_mfma_f32_16x16x32_bf16 v[36:39], v[194:197], v[124:127], v[164:167]
	v_mfma_f32_16x16x32_bf16 v[44:47], v[228:231], v[128:131], v[36:39]
	v_mfma_f32_16x16x32_bf16 v[36:39], v[186:189], v[232:235], v[174:177]
	v_mfma_f32_16x16x32_bf16 v[40:43], v[190:193], v[236:239], v[36:39]
	v_mfma_f32_16x16x32_bf16 v[36:39], v[194:197], v[232:235], v[178:181]
	v_mfma_f32_16x16x32_bf16 v[36:39], v[228:231], v[236:239], v[36:39]
	s_barrier
	s_setprio 0
	s_mov_b32 m0, s49
	v_lshl_add_u64 v[72:73], v[198:199], 0, s[74:75]
	s_add_u32 s0, s54, 0x10080
	ds_read_b128 v[96:99], v211 offset:49152
	ds_read_b128 v[100:103], v211 offset:50176
	ds_read_b128 v[164:167], v211 offset:51200
	ds_read_b128 v[174:177], v211 offset:52224
	ds_read_b128 v[178:181], v211 offset:53248
	ds_read_b128 v[204:207], v211 offset:54272
	ds_read_b128 v[232:235], v211 offset:55296
	ds_read_b128 v[236:239], v211 offset:56320
	global_load_lds_dwordx4 v[72:73], off
	v_lshl_add_u64 v[72:73], v[208:209], 0, s[74:75]
	s_mov_b32 m0, s43
	s_addc_u32 s1, s55, 0
	global_load_lds_dwordx4 v[72:73], off
	v_lshl_add_u64 v[72:73], s[0:1], 0, v[168:169]
	s_mov_b32 m0, s30
	s_nop 0
	global_load_lds_dwordx4 v[72:73], off
	v_lshl_add_u64 v[72:73], s[0:1], 0, v[172:173]
	s_mov_b32 m0, s31
	s_nop 0
	global_load_lds_dwordx4 v[72:73], off
	v_lshl_add_u64 v[72:73], v[240:241], 0, s[74:75]
	s_mov_b32 m0, s62
	s_nop 0
	global_load_lds_dwordx4 v[72:73], off
	v_lshl_add_u64 v[72:73], v[242:243], 0, s[74:75]
	s_mov_b32 m0, s76
	s_nop 0
	global_load_lds_dwordx4 v[72:73], off
	s_waitcnt vmcnt(8)
	s_waitcnt lgkmcnt(0)
	s_setprio 1
	s_barrier
	v_mfma_f32_16x16x32_bf16 v[72:75], v[20:23], v[96:99], v[132:135]
	v_mfma_f32_16x16x32_bf16 v[128:131], v[24:27], v[100:103], v[72:75]
	v_mfma_f32_16x16x32_bf16 v[72:75], v[28:31], v[96:99], v[136:139]
	v_mfma_f32_16x16x32_bf16 v[124:127], v[32:35], v[100:103], v[72:75]
	v_mfma_f32_16x16x32_bf16 v[72:75], v[20:23], v[164:167], v[200:203]
	v_mfma_f32_16x16x32_bf16 v[112:115], v[24:27], v[174:177], v[72:75]
	v_mfma_f32_16x16x32_bf16 v[72:75], v[28:31], v[164:167], v[212:215]
	v_mfma_f32_16x16x32_bf16 v[108:111], v[32:35], v[174:177], v[72:75]
	v_mfma_f32_16x16x32_bf16 v[72:75], v[20:23], v[178:181], v[148:151]
	v_mfma_f32_16x16x32_bf16 v[4:7], v[20:23], v[232:235], v[4:7]
	v_mfma_f32_16x16x32_bf16 v[88:91], v[24:27], v[204:207], v[72:75]
	v_mfma_f32_16x16x32_bf16 v[72:75], v[28:31], v[178:181], v[216:219]
	v_mfma_f32_16x16x32_bf16 v[76:79], v[24:27], v[236:239], v[4:7]
	v_mfma_f32_16x16x32_bf16 v[4:7], v[28:31], v[232:235], v[8:11]
	v_mfma_f32_16x16x32_bf16 v[84:87], v[32:35], v[204:207], v[72:75]
	v_mfma_f32_16x16x32_bf16 v[72:75], v[32:35], v[236:239], v[4:7]
	v_mfma_f32_16x16x32_bf16 v[4:7], v[186:189], v[96:99], v[12:15]
	v_mfma_f32_16x16x32_bf16 v[32:35], v[190:193], v[100:103], v[4:7]
	v_mfma_f32_16x16x32_bf16 v[4:7], v[194:197], v[96:99], v[16:19]
	v_mfma_f32_16x16x32_bf16 v[28:31], v[228:231], v[100:103], v[4:7]
	v_mfma_f32_16x16x32_bf16 v[4:7], v[186:189], v[164:167], v[116:119]
	v_mfma_f32_16x16x32_bf16 v[24:27], v[190:193], v[174:177], v[4:7]
	v_mfma_f32_16x16x32_bf16 v[4:7], v[194:197], v[164:167], v[220:223]
	v_mfma_f32_16x16x32_bf16 v[20:23], v[228:231], v[174:177], v[4:7]
	v_mfma_f32_16x16x32_bf16 v[4:7], v[186:189], v[178:181], v[224:227]
	v_mfma_f32_16x16x32_bf16 v[16:19], v[190:193], v[204:207], v[4:7]
	v_mfma_f32_16x16x32_bf16 v[4:7], v[194:197], v[178:181], v[104:107]
	v_mfma_f32_16x16x32_bf16 v[12:15], v[228:231], v[204:207], v[4:7]
	v_mfma_f32_16x16x32_bf16 v[4:7], v[186:189], v[232:235], v[182:185]
	v_mfma_f32_16x16x32_bf16 v[8:11], v[190:193], v[236:239], v[4:7]
	v_mfma_f32_16x16x32_bf16 v[4:7], v[194:197], v[232:235], v[160:163]
	v_mfma_f32_16x16x32_bf16 v[4:7], v[228:231], v[236:239], v[4:7]
	s_barrier
	s_setprio 0
	s_andn2_b64 vcc, exec, s[40:41]
	s_cbranch_vccnz .LBB0_896
	s_barrier

.LBB0_950:
	s_ashr_i32 s25, s24, 31
	s_lshl_b64 s[26:27], s[24:25], 19
	s_add_u32 s0, s49, s26
	s_addc_u32 s4, s50, s27
	s_ashr_i32 s23, s22, 31
	s_lshl_b64 s[26:27], s[22:23], 19
	s_add_u32 s5, s51, s26
	s_addc_u32 s23, s56, s27
	s_add_i32 s25, 0, 0x10000
	s_and_b64 s[26:27], s[38:39], exec
	s_cselect_b32 s27, s4, s37
	s_cselect_b32 s26, s0, s36
	s_add_i32 s42, 0, 0x14000
	v_add_u32_e32 v2, s25, v184
	v_add_u32_e32 v52, s42, v184
	ds_read_b128 v[4:7], v2
	ds_read_b128 v[8:11], v2 offset:1024
	ds_read_b128 v[12:15], v2 offset:2048
	ds_read_b128 v[16:19], v2 offset:3072
	ds_read_b128 v[20:23], v52
	ds_read_b128 v[24:27], v52 offset:1024
	ds_read_b128 v[28:31], v52 offset:2048
	ds_read_b128 v[32:35], v52 offset:3072
	s_and_b64 s[28:29], s[38:39], exec
	s_cselect_b32 s29, s23, s35
	s_cselect_b32 s28, s5, s34
	s_add_u32 s40, s36, 0x40080
	s_addc_u32 s41, s37, 0
	s_add_i32 s0, s58, 0xc000
	v_lshl_add_u64 v[70:71], s[40:41], 0, v[0:1]
	s_mov_b32 m0, s0
	s_add_i32 s23, s58, 0xe000
	ds_read_b128 v[36:39], v185
	ds_read_b128 v[40:43], v185 offset:1024
	ds_read_b128 v[44:47], v185 offset:2048
	ds_read_b128 v[48:51], v185 offset:3072
	ds_read_b128 v[54:57], v185 offset:4096
	ds_read_b128 v[58:61], v185 offset:5120
	ds_read_b128 v[62:65], v185 offset:6144
	ds_read_b128 v[66:69], v185 offset:7168
	global_load_lds_dwordx4 v[70:71], off
	v_lshl_add_u64 v[70:71], s[40:41], 0, v[166:167]
	s_mov_b32 m0, s23
	s_nop 0
	global_load_lds_dwordx4 v[70:71], off
	s_waitcnt vmcnt(8)
	s_waitcnt lgkmcnt(0)
	s_setprio 1
	s_barrier
	v_mfma_f32_16x16x32_f16 v[94:97], v[4:7], v[62:65], 0
	v_mfma_f32_16x16x32_f16 v[98:101], v[12:15], v[62:65], 0
	v_mfma_f32_16x16x32_f16 v[70:73], v[4:7], v[36:39], 0
	v_mfma_f32_16x16x32_f16 v[74:77], v[12:15], v[36:39], 0
	v_mfma_f32_16x16x32_f16 v[78:81], v[4:7], v[44:47], 0
	v_mfma_f32_16x16x32_f16 v[82:85], v[12:15], v[44:47], 0
	v_mfma_f32_16x16x32_f16 v[90:93], v[12:15], v[54:57], 0
	v_mfma_f32_16x16x32_f16 v[156:159], v[8:11], v[40:43], v[70:73]
	v_mfma_f32_16x16x32_f16 v[142:145], v[16:19], v[40:43], v[74:77]
	v_mfma_f32_16x16x32_f16 v[152:155], v[8:11], v[48:51], v[78:81]
	v_mfma_f32_16x16x32_f16 v[138:141], v[16:19], v[48:51], v[82:85]
	v_mfma_f32_16x16x32_f16 v[148:151], v[16:19], v[58:61], v[90:93]
	v_mfma_f32_16x16x32_f16 v[94:97], v[8:11], v[66:69], v[94:97]
	v_mfma_f32_16x16x32_f16 v[98:101], v[16:19], v[66:69], v[98:101]
	v_mfma_f32_16x16x32_f16 v[86:89], v[4:7], v[54:57], 0
	s_nop 0
	v_mfma_f32_16x16x32_f16 v[84:87], v[8:11], v[58:61], v[86:89]
	v_mfma_f32_16x16x32_f16 v[102:105], v[20:23], v[36:39], 0
	v_mfma_f32_16x16x32_f16 v[36:39], v[28:31], v[36:39], 0
	v_mfma_f32_16x16x32_f16 v[102:105], v[24:27], v[40:43], v[102:105]
	v_mfma_f32_16x16x32_f16 v[88:91], v[32:35], v[40:43], v[36:39]
	v_mfma_f32_16x16x32_f16 v[40:43], v[20:23], v[44:47], 0
	v_mfma_f32_16x16x32_f16 v[44:47], v[28:31], v[44:47], 0
	v_mfma_f32_16x16x32_f16 v[40:43], v[24:27], v[48:51], v[40:43]
	v_mfma_f32_16x16x32_f16 v[36:39], v[32:35], v[48:51], v[44:47]
	v_mfma_f32_16x16x32_f16 v[48:51], v[20:23], v[54:57], 0
	s_nop 0
	v_mfma_f32_16x16x32_f16 v[48:51], v[24:27], v[58:61], v[48:51]
	v_mfma_f32_16x16x32_f16 v[54:57], v[28:31], v[54:57], 0
	s_nop 0
	v_mfma_f32_16x16x32_f16 v[56:59], v[32:35], v[58:61], v[54:57]
	v_mfma_f32_16x16x32_f16 v[106:109], v[20:23], v[62:65], 0
	v_mfma_f32_16x16x32_f16 v[60:63], v[28:31], v[62:65], 0
	v_mfma_f32_16x16x32_f16 v[174:177], v[24:27], v[66:69], v[106:109]
	v_mfma_f32_16x16x32_f16 v[60:63], v[32:35], v[66:69], v[60:63]
	s_barrier
	s_setprio 0
	s_add_i32 s25, s25, s57
	v_lshl_add_u64 v[182:183], s[34:35], 0, v[164:165]
	s_mov_b64 s[4:5], 0x100
	s_add_i32 s31, s25, 0x2000
	v_lshl_add_u64 v[54:55], v[182:183], 0, s[4:5]
	s_mov_b32 m0, s25
	v_lshl_add_u64 v[198:199], s[34:35], 0, v[168:169]
	s_add_u32 s40, s34, 0x40100
	ds_read_b128 v[64:67], v185 offset:16384
	ds_read_b128 v[106:109], v185 offset:17408
	ds_read_b128 v[110:113], v185 offset:18432
	ds_read_b128 v[114:117], v185 offset:19456
	ds_read_b128 v[118:121], v185 offset:20480
	ds_read_b128 v[122:125], v185 offset:21504
	ds_read_b128 v[126:129], v185 offset:22528
	ds_read_b128 v[130:133], v185 offset:23552
	global_load_lds_dwordx4 v[54:55], off
	v_lshl_add_u64 v[54:55], v[198:199], 0, s[4:5]
	s_mov_b32 m0, s31
	s_addc_u32 s41, s35, 0
	s_add_i32 s42, s42, s57
	global_load_lds_dwordx4 v[54:55], off
	v_lshl_add_u64 v[54:55], s[40:41], 0, v[164:165]
	s_mov_b32 m0, s42
	s_add_i32 s43, s42, 0x2000
	global_load_lds_dwordx4 v[54:55], off
	v_lshl_add_u64 v[54:55], s[40:41], 0, v[168:169]
	s_mov_b32 m0, s43
	v_lshl_add_u64 v[252:253], s[36:37], 0, v[0:1]
	global_load_lds_dwordx4 v[54:55], off
	v_lshl_add_u64 v[54:55], v[252:253], 0, s[4:5]
	s_mov_b32 m0, s58
	v_lshl_add_u64 v[44:45], s[36:37], 0, v[166:167]
	global_load_lds_dwordx4 v[54:55], off
	v_lshl_add_u64 v[46:47], v[44:45], 0, s[4:5]
	s_mov_b32 m0, s59
	s_nop 0
	global_load_lds_dwordx4 v[46:47], off
	s_waitcnt vmcnt(8)
	s_waitcnt lgkmcnt(0)
	s_setprio 1
	s_barrier
	v_mfma_f32_16x16x32_f16 v[134:137], v[4:7], v[64:67], 0
	s_nop 0
	v_mfma_f32_16x16x32_f16 v[178:181], v[8:11], v[106:109], v[134:137]
	v_mfma_f32_16x16x32_f16 v[134:137], v[12:15], v[64:67], 0
	s_nop 0
	v_mfma_f32_16x16x32_f16 v[186:189], v[16:19], v[106:109], v[134:137]
	v_mfma_f32_16x16x32_f16 v[134:137], v[4:7], v[110:113], 0
	s_nop 0
	v_mfma_f32_16x16x32_f16 v[194:197], v[8:11], v[114:117], v[134:137]
	v_mfma_f32_16x16x32_f16 v[134:137], v[12:15], v[110:113], 0
	s_nop 0
	v_mfma_f32_16x16x32_f16 v[200:203], v[16:19], v[114:117], v[134:137]
	v_mfma_f32_16x16x32_f16 v[134:137], v[4:7], v[118:121], 0
	v_mfma_f32_16x16x32_f16 v[4:7], v[4:7], v[126:129], 0
	v_mfma_f32_16x16x32_f16 v[204:207], v[8:11], v[122:125], v[134:137]
	v_mfma_f32_16x16x32_f16 v[4:7], v[8:11], v[130:133], v[4:7]
	v_mfma_f32_16x16x32_f16 v[8:11], v[12:15], v[126:129], 0
	s_nop 0
	v_mfma_f32_16x16x32_f16 v[8:11], v[16:19], v[130:133], v[8:11]
	v_mfma_f32_16x16x32_f16 v[134:137], v[12:15], v[118:121], 0
	s_nop 0
	v_mfma_f32_16x16x32_f16 v[208:211], v[16:19], v[122:125], v[134:137]
	v_mfma_f32_16x16x32_f16 v[12:15], v[20:23], v[64:67], 0
	s_nop 0
	v_mfma_f32_16x16x32_f16 v[212:215], v[24:27], v[106:109], v[12:15]
	v_mfma_f32_16x16x32_f16 v[12:15], v[28:31], v[64:67], 0
	s_nop 0
	v_mfma_f32_16x16x32_f16 v[64:67], v[32:35], v[106:109], v[12:15]
	v_mfma_f32_16x16x32_f16 v[12:15], v[20:23], v[110:113], 0
	s_nop 0
	v_mfma_f32_16x16x32_f16 v[216:219], v[24:27], v[114:117], v[12:15]
	v_mfma_f32_16x16x32_f16 v[12:15], v[28:31], v[110:113], 0
	s_nop 0
	v_mfma_f32_16x16x32_f16 v[220:223], v[32:35], v[114:117], v[12:15]
	v_mfma_f32_16x16x32_f16 v[12:15], v[20:23], v[118:121], 0
	s_nop 0
	v_mfma_f32_16x16x32_f16 v[224:227], v[24:27], v[122:125], v[12:15]
	v_mfma_f32_16x16x32_f16 v[12:15], v[28:31], v[118:121], 0
	s_nop 0
	v_mfma_f32_16x16x32_f16 v[228:231], v[32:35], v[122:125], v[12:15]
	v_mfma_f32_16x16x32_f16 v[12:15], v[20:23], v[126:129], 0
	s_nop 0
	v_mfma_f32_16x16x32_f16 v[236:239], v[24:27], v[130:133], v[12:15]
	v_mfma_f32_16x16x32_f16 v[12:15], v[28:31], v[126:129], 0
	s_nop 0
	v_mfma_f32_16x16x32_f16 v[240:243], v[32:35], v[130:133], v[12:15]
	s_barrier
	s_setprio 0
	s_add_i32 s44, 0, 0x18000
	s_add_i32 s90, 0, 0x1c000
	v_add_u32_e32 v53, s44, v184
	v_add_u32_e32 v54, s90, v184
	ds_read_b128 v[12:15], v53
	ds_read_b128 v[16:19], v53 offset:1024
	ds_read_b128 v[20:23], v53 offset:2048
	ds_read_b128 v[24:27], v53 offset:3072
	ds_read_b128 v[244:247], v54
	ds_read_b128 v[248:251], v54 offset:1024
	ds_read_b128 v[190:193], v54 offset:2048
	ds_read_b128 v[232:235], v54 offset:3072
	s_add_u32 s40, s36, 0x40100
	s_addc_u32 s41, s37, 0
	s_mov_b32 m0, s60
	v_lshl_add_u64 v[46:47], s[40:41], 0, v[0:1]
	ds_read_b128 v[28:31], v185 offset:32768
	ds_read_b128 v[32:35], v185 offset:33792
	ds_read_b128 v[116:119], v185 offset:34816
	ds_read_b128 v[120:123], v185 offset:35840
	ds_read_b128 v[68:71], v185 offset:36864
	ds_read_b128 v[72:75], v185 offset:37888
	ds_read_b128 v[76:79], v185 offset:38912
	ds_read_b128 v[80:83], v185 offset:39936
	global_load_lds_dwordx4 v[46:47], off
	v_lshl_add_u64 v[46:47], s[40:41], 0, v[166:167]
	s_mov_b32 m0, s62
	s_nop 0
	global_load_lds_dwordx4 v[46:47], off
	s_waitcnt vmcnt(8)
	s_waitcnt lgkmcnt(0)
	s_setprio 1
	s_barrier
	v_mfma_f32_16x16x32_f16 v[106:109], v[12:15], v[28:31], v[156:159]
	v_mfma_f32_16x16x32_f16 v[84:87], v[12:15], v[68:71], v[84:87]
	v_mfma_f32_16x16x32_f16 v[160:163], v[16:19], v[32:35], v[106:109]
	v_mfma_f32_16x16x32_f16 v[106:109], v[20:23], v[28:31], v[142:145]
	v_mfma_f32_16x16x32_f16 v[128:131], v[16:19], v[72:75], v[84:87]
	v_mfma_f32_16x16x32_f16 v[84:87], v[20:23], v[68:71], v[148:151]
	v_mfma_f32_16x16x32_f16 v[156:159], v[24:27], v[32:35], v[106:109]
	v_mfma_f32_16x16x32_f16 v[106:109], v[12:15], v[116:119], v[152:155]
	v_mfma_f32_16x16x32_f16 v[124:127], v[24:27], v[72:75], v[84:87]
	v_mfma_f32_16x16x32_f16 v[84:87], v[12:15], v[76:79], v[94:97]
	v_mfma_f32_16x16x32_f16 v[144:147], v[16:19], v[120:123], v[106:109]
	v_mfma_f32_16x16x32_f16 v[106:109], v[20:23], v[116:119], v[138:141]
	v_mfma_f32_16x16x32_f16 v[112:115], v[16:19], v[80:83], v[84:87]
	v_mfma_f32_16x16x32_f16 v[84:87], v[20:23], v[76:79], v[98:101]
	v_mfma_f32_16x16x32_f16 v[140:143], v[24:27], v[120:123], v[106:109]
	v_mfma_f32_16x16x32_f16 v[108:111], v[24:27], v[80:83], v[84:87]
	v_mfma_f32_16x16x32_f16 v[84:87], v[244:247], v[28:31], v[102:105]
	v_mfma_f32_16x16x32_f16 v[28:31], v[190:193], v[28:31], v[88:91]
	v_mfma_f32_16x16x32_f16 v[148:151], v[232:235], v[32:35], v[28:31]
	v_mfma_f32_16x16x32_f16 v[28:31], v[244:247], v[116:119], v[40:43]
	v_mfma_f32_16x16x32_f16 v[136:139], v[248:251], v[120:123], v[28:31]
	v_mfma_f32_16x16x32_f16 v[28:31], v[190:193], v[116:119], v[36:39]
	v_mfma_f32_16x16x32_f16 v[132:135], v[232:235], v[120:123], v[28:31]
	v_mfma_f32_16x16x32_f16 v[28:31], v[244:247], v[68:71], v[48:51]
	v_mfma_f32_16x16x32_f16 v[120:123], v[248:251], v[72:75], v[28:31]
	v_mfma_f32_16x16x32_f16 v[28:31], v[190:193], v[68:71], v[56:59]
	v_mfma_f32_16x16x32_f16 v[116:119], v[232:235], v[72:75], v[28:31]
	v_mfma_f32_16x16x32_f16 v[28:31], v[244:247], v[76:79], v[174:177]
	v_mfma_f32_16x16x32_f16 v[104:107], v[248:251], v[80:83], v[28:31]
	v_mfma_f32_16x16x32_f16 v[28:31], v[190:193], v[76:79], v[60:63]
	v_mfma_f32_16x16x32_f16 v[152:155], v[248:251], v[32:35], v[84:87]
	v_mfma_f32_16x16x32_f16 v[100:103], v[232:235], v[80:83], v[28:31]
	s_barrier
	s_setprio 0
	s_add_i32 s44, s44, s57
	s_add_i32 s45, s44, 0x2000
	s_nop 1
	v_lshl_add_u64 v[28:29], v[182:183], 0, s[84:85]
	s_mov_b32 m0, s44
	s_add_u32 s40, s34, 0x40180
	ds_read_b128 v[36:39], v185 offset:49152
	ds_read_b128 v[40:43], v185 offset:50176
	ds_read_b128 v[56:59], v185 offset:51200
	ds_read_b128 v[60:63], v185 offset:52224
	ds_read_b128 v[68:71], v185 offset:53248
	ds_read_b128 v[76:79], v185 offset:54272
	ds_read_b128 v[84:87], v185 offset:55296
	ds_read_b128 v[88:91], v185 offset:56320
	global_load_lds_dwordx4 v[28:29], off
	v_lshl_add_u64 v[28:29], v[198:199], 0, s[84:85]
	s_mov_b32 m0, s45
	s_addc_u32 s41, s35, 0
	s_add_i32 s90, s90, s57
	global_load_lds_dwordx4 v[28:29], off
	v_lshl_add_u64 v[28:29], s[40:41], 0, v[164:165]
	s_mov_b32 m0, s90
	s_add_i32 s91, s90, 0x2000
	global_load_lds_dwordx4 v[28:29], off
	v_lshl_add_u64 v[28:29], s[40:41], 0, v[168:169]
	s_mov_b32 m0, s91
	s_nop 0
	global_load_lds_dwordx4 v[28:29], off
	v_lshl_add_u64 v[28:29], v[252:253], 0, s[84:85]
	s_mov_b32 m0, s76
	s_nop 0
	global_load_lds_dwordx4 v[28:29], off
	v_lshl_add_u64 v[28:29], v[44:45], 0, s[84:85]
	s_mov_b32 m0, s77
	s_nop 0
	global_load_lds_dwordx4 v[28:29], off
	s_waitcnt vmcnt(8)
	s_waitcnt lgkmcnt(0)
	s_setprio 1
	s_barrier
	v_mfma_f32_16x16x32_f16 v[28:31], v[12:15], v[36:39], v[178:181]
	v_mfma_f32_16x16x32_f16 v[96:99], v[16:19], v[40:43], v[28:31]
	v_mfma_f32_16x16x32_f16 v[28:31], v[20:23], v[36:39], v[186:189]
	v_mfma_f32_16x16x32_f16 v[92:95], v[24:27], v[40:43], v[28:31]
	v_mfma_f32_16x16x32_f16 v[28:31], v[12:15], v[56:59], v[194:197]
	v_mfma_f32_16x16x32_f16 v[48:51], v[16:19], v[60:63], v[28:31]
	v_mfma_f32_16x16x32_f16 v[28:31], v[20:23], v[56:59], v[200:203]
	v_mfma_f32_16x16x32_f16 v[44:47], v[24:27], v[60:63], v[28:31]
	v_mfma_f32_16x16x32_f16 v[28:31], v[12:15], v[68:71], v[204:207]
	v_mfma_f32_16x16x32_f16 v[4:7], v[12:15], v[84:87], v[4:7]
	v_mfma_f32_16x16x32_f16 v[32:35], v[16:19], v[76:79], v[28:31]
	v_mfma_f32_16x16x32_f16 v[28:31], v[20:23], v[68:71], v[208:211]
	v_mfma_f32_16x16x32_f16 v[16:19], v[16:19], v[88:91], v[4:7]
	v_mfma_f32_16x16x32_f16 v[4:7], v[20:23], v[84:87], v[8:11]
	v_mfma_f32_16x16x32_f16 v[28:31], v[24:27], v[76:79], v[28:31]
	v_mfma_f32_16x16x32_f16 v[12:15], v[24:27], v[88:91], v[4:7]
	v_mfma_f32_16x16x32_f16 v[4:7], v[244:247], v[36:39], v[212:215]
	v_mfma_f32_16x16x32_f16 v[80:83], v[248:251], v[40:43], v[4:7]
	v_mfma_f32_16x16x32_f16 v[4:7], v[190:193], v[36:39], v[64:67]
	v_mfma_f32_16x16x32_f16 v[72:75], v[232:235], v[40:43], v[4:7]
	v_mfma_f32_16x16x32_f16 v[4:7], v[244:247], v[56:59], v[216:219]
	v_mfma_f32_16x16x32_f16 v[40:43], v[248:251], v[60:63], v[4:7]
	v_mfma_f32_16x16x32_f16 v[4:7], v[190:193], v[56:59], v[220:223]
	v_mfma_f32_16x16x32_f16 v[36:39], v[232:235], v[60:63], v[4:7]
	v_mfma_f32_16x16x32_f16 v[4:7], v[244:247], v[68:71], v[224:227]
	v_mfma_f32_16x16x32_f16 v[24:27], v[248:251], v[76:79], v[4:7]
	v_mfma_f32_16x16x32_f16 v[4:7], v[190:193], v[68:71], v[228:231]
	v_mfma_f32_16x16x32_f16 v[20:23], v[232:235], v[76:79], v[4:7]
	v_mfma_f32_16x16x32_f16 v[4:7], v[244:247], v[84:87], v[236:239]
	v_mfma_f32_16x16x32_f16 v[8:11], v[248:251], v[88:91], v[4:7]
	v_mfma_f32_16x16x32_f16 v[4:7], v[190:193], v[84:87], v[240:243]
	v_mfma_f32_16x16x32_f16 v[4:7], v[232:235], v[88:91], v[4:7]
	s_barrier
	s_setprio 0
	s_add_u32 s36, s36, 0x40180
	s_addc_u32 s37, s37, 0
	s_add_u32 s95, s34, 0x200
	s_addc_u32 vcc_lo, s35, 0
	s_mov_b32 vcc_hi, 0
.LBB0_951:
	ds_read_b128 v[56:59], v2
	ds_read_b128 v[60:63], v2 offset:1024
	ds_read_b128 v[64:67], v2 offset:2048
	ds_read_b128 v[68:71], v2 offset:3072
	ds_read_b128 v[76:79], v52
	ds_read_b128 v[84:87], v52 offset:1024
	ds_read_b128 v[88:91], v52 offset:2048
	ds_read_b128 v[174:177], v52 offset:3072
	s_add_u32 s4, s36, 0xfffc0080
	s_addc_u32 s5, s37, -1
	s_cmp_eq_u32 vcc_hi, 12
	s_cselect_b32 s41, s27, s5
	s_cselect_b32 s40, s26, s4
	s_cselect_b32 s35, s29, vcc_lo
	s_cselect_b32 s34, s28, s95
	s_mov_b32 m0, s0
	v_lshl_add_u64 v[182:183], s[36:37], 0, v[170:171]
	ds_read_b128 v[178:181], v185
	ds_read_b128 v[186:189], v185 offset:1024
	ds_read_b128 v[190:193], v185 offset:2048
	ds_read_b128 v[194:197], v185 offset:3072
	ds_read_b128 v[200:203], v185 offset:4096
	ds_read_b128 v[204:207], v185 offset:5120
	ds_read_b128 v[208:211], v185 offset:6144
	ds_read_b128 v[212:215], v185 offset:7168
	global_load_lds_dwordx4 v[182:183], off
	v_lshl_add_u64 v[182:183], s[36:37], 0, v[172:173]
	s_mov_b32 m0, s23
	s_nop 0
	global_load_lds_dwordx4 v[182:183], off
	s_waitcnt vmcnt(8)
	s_waitcnt lgkmcnt(0)
	s_setprio 1
	s_barrier
	v_mfma_f32_16x16x32_f16 v[160:163], v[56:59], v[178:181], v[160:163]
	v_mfma_f32_16x16x32_f16 v[156:159], v[64:67], v[178:181], v[156:159]
	v_mfma_f32_16x16x32_f16 v[144:147], v[56:59], v[190:193], v[144:147]
	v_mfma_f32_16x16x32_f16 v[140:143], v[64:67], v[190:193], v[140:143]
	v_mfma_f32_16x16x32_f16 v[128:131], v[56:59], v[200:203], v[128:131]
	v_mfma_f32_16x16x32_f16 v[124:127], v[64:67], v[200:203], v[124:127]
	v_mfma_f32_16x16x32_f16 v[112:115], v[56:59], v[208:211], v[112:115]
	v_mfma_f32_16x16x32_f16 v[108:111], v[64:67], v[208:211], v[108:111]
	v_mfma_f32_16x16x32_f16 v[160:163], v[60:63], v[186:189], v[160:163]
	v_mfma_f32_16x16x32_f16 v[156:159], v[68:71], v[186:189], v[156:159]
	v_mfma_f32_16x16x32_f16 v[144:147], v[60:63], v[194:197], v[144:147]
	v_mfma_f32_16x16x32_f16 v[140:143], v[68:71], v[194:197], v[140:143]
	v_mfma_f32_16x16x32_f16 v[128:131], v[60:63], v[204:207], v[128:131]
	v_mfma_f32_16x16x32_f16 v[124:127], v[68:71], v[204:207], v[124:127]
	v_mfma_f32_16x16x32_f16 v[112:115], v[60:63], v[212:215], v[112:115]
	v_mfma_f32_16x16x32_f16 v[108:111], v[68:71], v[212:215], v[108:111]
	v_mfma_f32_16x16x32_f16 v[152:155], v[76:79], v[178:181], v[152:155]
	v_mfma_f32_16x16x32_f16 v[148:151], v[88:91], v[178:181], v[148:151]
	v_mfma_f32_16x16x32_f16 v[136:139], v[76:79], v[190:193], v[136:139]
	v_mfma_f32_16x16x32_f16 v[132:135], v[88:91], v[190:193], v[132:135]
	v_mfma_f32_16x16x32_f16 v[120:123], v[76:79], v[200:203], v[120:123]
	v_mfma_f32_16x16x32_f16 v[116:119], v[88:91], v[200:203], v[116:119]
	v_mfma_f32_16x16x32_f16 v[104:107], v[76:79], v[208:211], v[104:107]
	v_mfma_f32_16x16x32_f16 v[100:103], v[88:91], v[208:211], v[100:103]
	v_mfma_f32_16x16x32_f16 v[152:155], v[84:87], v[186:189], v[152:155]
	v_mfma_f32_16x16x32_f16 v[148:151], v[174:177], v[186:189], v[148:151]
	v_mfma_f32_16x16x32_f16 v[136:139], v[84:87], v[194:197], v[136:139]
	v_mfma_f32_16x16x32_f16 v[132:135], v[174:177], v[194:197], v[132:135]
	v_mfma_f32_16x16x32_f16 v[120:123], v[84:87], v[204:207], v[120:123]
	v_mfma_f32_16x16x32_f16 v[116:119], v[174:177], v[204:207], v[116:119]
	v_mfma_f32_16x16x32_f16 v[104:107], v[84:87], v[212:215], v[104:107]
	v_mfma_f32_16x16x32_f16 v[100:103], v[174:177], v[212:215], v[100:103]
	s_barrier
	s_setprio 0
	s_mov_b32 m0, s25
	v_lshl_add_u64 v[182:183], s[34:35], 0, v[164:165]
	s_add_u32 s4, s34, 0x40000
	ds_read_b128 v[178:181], v185 offset:16384
	ds_read_b128 v[186:189], v185 offset:17408
	ds_read_b128 v[190:193], v185 offset:18432
	ds_read_b128 v[194:197], v185 offset:19456
	ds_read_b128 v[200:203], v185 offset:20480
	ds_read_b128 v[204:207], v185 offset:21504
	ds_read_b128 v[208:211], v185 offset:22528
	ds_read_b128 v[212:215], v185 offset:23552
	global_load_lds_dwordx4 v[182:183], off
	v_lshl_add_u64 v[198:199], s[34:35], 0, v[168:169]
	s_mov_b32 m0, s31
	s_addc_u32 s5, s35, 0
	global_load_lds_dwordx4 v[198:199], off
	v_lshl_add_u64 v[216:217], s[4:5], 0, v[164:165]
	s_mov_b32 m0, s42
	v_lshl_add_u64 v[220:221], s[40:41], 0, v[0:1]
	global_load_lds_dwordx4 v[216:217], off
	v_lshl_add_u64 v[216:217], s[4:5], 0, v[168:169]
	s_mov_b32 m0, s43
	v_lshl_add_u64 v[222:223], s[40:41], 0, v[166:167]
	global_load_lds_dwordx4 v[216:217], off
	s_mov_b32 m0, s58
	s_nop 0
	global_load_lds_dwordx4 v[220:221], off
	s_mov_b32 m0, s59
	s_nop 0
	global_load_lds_dwordx4 v[222:223], off
	s_waitcnt vmcnt(8)
	s_waitcnt lgkmcnt(0)
	s_setprio 1
	s_barrier
	v_mfma_f32_16x16x32_f16 v[96:99], v[56:59], v[178:181], v[96:99]
	v_mfma_f32_16x16x32_f16 v[92:95], v[64:67], v[178:181], v[92:95]
	v_mfma_f32_16x16x32_f16 v[48:51], v[56:59], v[190:193], v[48:51]
	v_mfma_f32_16x16x32_f16 v[44:47], v[64:67], v[190:193], v[44:47]
	v_mfma_f32_16x16x32_f16 v[32:35], v[56:59], v[200:203], v[32:35]
	v_mfma_f32_16x16x32_f16 v[28:31], v[64:67], v[200:203], v[28:31]
	v_mfma_f32_16x16x32_f16 v[16:19], v[56:59], v[208:211], v[16:19]
	v_mfma_f32_16x16x32_f16 v[12:15], v[64:67], v[208:211], v[12:15]
	v_mfma_f32_16x16x32_f16 v[96:99], v[60:63], v[186:189], v[96:99]
	v_mfma_f32_16x16x32_f16 v[92:95], v[68:71], v[186:189], v[92:95]
	v_mfma_f32_16x16x32_f16 v[48:51], v[60:63], v[194:197], v[48:51]
	v_mfma_f32_16x16x32_f16 v[44:47], v[68:71], v[194:197], v[44:47]
	v_mfma_f32_16x16x32_f16 v[32:35], v[60:63], v[204:207], v[32:35]
	v_mfma_f32_16x16x32_f16 v[28:31], v[68:71], v[204:207], v[28:31]
	v_mfma_f32_16x16x32_f16 v[16:19], v[60:63], v[212:215], v[16:19]
	v_mfma_f32_16x16x32_f16 v[12:15], v[68:71], v[212:215], v[12:15]
	v_mfma_f32_16x16x32_f16 v[40:43], v[76:79], v[190:193], v[40:43]
	v_mfma_f32_16x16x32_f16 v[36:39], v[88:91], v[190:193], v[36:39]
	v_mfma_f32_16x16x32_f16 v[24:27], v[76:79], v[200:203], v[24:27]
	v_mfma_f32_16x16x32_f16 v[20:23], v[88:91], v[200:203], v[20:23]
	v_mfma_f32_16x16x32_f16 v[8:11], v[76:79], v[208:211], v[8:11]
	v_mfma_f32_16x16x32_f16 v[4:7], v[88:91], v[208:211], v[4:7]
	v_mfma_f32_16x16x32_f16 v[56:59], v[76:79], v[178:181], v[80:83]
	v_mfma_f32_16x16x32_f16 v[60:63], v[88:91], v[178:181], v[72:75]
	v_mfma_f32_16x16x32_f16 v[40:43], v[84:87], v[194:197], v[40:43]
	v_mfma_f32_16x16x32_f16 v[36:39], v[174:177], v[194:197], v[36:39]
	v_mfma_f32_16x16x32_f16 v[24:27], v[84:87], v[204:207], v[24:27]
	v_mfma_f32_16x16x32_f16 v[20:23], v[174:177], v[204:207], v[20:23]
	v_mfma_f32_16x16x32_f16 v[8:11], v[84:87], v[212:215], v[8:11]
	v_mfma_f32_16x16x32_f16 v[4:7], v[174:177], v[212:215], v[4:7]
	v_mfma_f32_16x16x32_f16 v[56:59], v[84:87], v[186:189], v[56:59]
	v_mfma_f32_16x16x32_f16 v[60:63], v[174:177], v[186:189], v[60:63]
	s_barrier
	s_setprio 0
	ds_read_b128 v[64:67], v53
	ds_read_b128 v[68:71], v53 offset:1024
	ds_read_b128 v[72:75], v53 offset:2048
	ds_read_b128 v[76:79], v53 offset:3072
	ds_read_b128 v[84:87], v54
	ds_read_b128 v[88:91], v54 offset:1024
	ds_read_b128 v[174:177], v54 offset:2048
	ds_read_b128 v[178:181], v54 offset:3072
	s_add_u32 s4, s40, 0x40000
	s_addc_u32 s5, s41, 0
	s_mov_b32 m0, s60
	v_lshl_add_u64 v[216:217], s[4:5], 0, v[0:1]
	ds_read_b128 v[80:83], v185 offset:32768
	ds_read_b128 v[186:189], v185 offset:33792
	ds_read_b128 v[190:193], v185 offset:34816
	ds_read_b128 v[194:197], v185 offset:35840
	ds_read_b128 v[200:203], v185 offset:36864
	ds_read_b128 v[204:207], v185 offset:37888
	ds_read_b128 v[208:211], v185 offset:38912
	ds_read_b128 v[212:215], v185 offset:39936
	global_load_lds_dwordx4 v[216:217], off
	v_lshl_add_u64 v[216:217], s[4:5], 0, v[166:167]
	s_mov_b32 m0, s62
	s_nop 0
	global_load_lds_dwordx4 v[216:217], off
	s_waitcnt vmcnt(8)
	s_waitcnt lgkmcnt(0)
	s_setprio 1
	s_barrier
	v_mfma_f32_16x16x32_f16 v[160:163], v[64:67], v[80:83], v[160:163]
	v_mfma_f32_16x16x32_f16 v[156:159], v[72:75], v[80:83], v[156:159]
	v_mfma_f32_16x16x32_f16 v[144:147], v[64:67], v[190:193], v[144:147]
	v_mfma_f32_16x16x32_f16 v[140:143], v[72:75], v[190:193], v[140:143]
	v_mfma_f32_16x16x32_f16 v[128:131], v[64:67], v[200:203], v[128:131]
	v_mfma_f32_16x16x32_f16 v[124:127], v[72:75], v[200:203], v[124:127]
	v_mfma_f32_16x16x32_f16 v[112:115], v[64:67], v[208:211], v[112:115]
	v_mfma_f32_16x16x32_f16 v[108:111], v[72:75], v[208:211], v[108:111]
	v_mfma_f32_16x16x32_f16 v[160:163], v[68:71], v[186:189], v[160:163]
	v_mfma_f32_16x16x32_f16 v[156:159], v[76:79], v[186:189], v[156:159]
	v_mfma_f32_16x16x32_f16 v[144:147], v[68:71], v[194:197], v[144:147]
	v_mfma_f32_16x16x32_f16 v[140:143], v[76:79], v[194:197], v[140:143]
	v_mfma_f32_16x16x32_f16 v[128:131], v[68:71], v[204:207], v[128:131]
	v_mfma_f32_16x16x32_f16 v[124:127], v[76:79], v[204:207], v[124:127]
	v_mfma_f32_16x16x32_f16 v[112:115], v[68:71], v[212:215], v[112:115]
	v_mfma_f32_16x16x32_f16 v[108:111], v[76:79], v[212:215], v[108:111]
	v_mfma_f32_16x16x32_f16 v[152:155], v[84:87], v[80:83], v[152:155]
	v_mfma_f32_16x16x32_f16 v[80:83], v[174:177], v[80:83], v[148:151]
	v_mfma_f32_16x16x32_f16 v[148:151], v[178:181], v[186:189], v[80:83]
	v_mfma_f32_16x16x32_f16 v[80:83], v[84:87], v[190:193], v[136:139]
	v_mfma_f32_16x16x32_f16 v[136:139], v[88:91], v[194:197], v[80:83]
	v_mfma_f32_16x16x32_f16 v[80:83], v[174:177], v[190:193], v[132:135]
	v_mfma_f32_16x16x32_f16 v[132:135], v[178:181], v[194:197], v[80:83]
	v_mfma_f32_16x16x32_f16 v[80:83], v[84:87], v[200:203], v[120:123]
	v_mfma_f32_16x16x32_f16 v[120:123], v[88:91], v[204:207], v[80:83]
	v_mfma_f32_16x16x32_f16 v[80:83], v[174:177], v[200:203], v[116:119]
	v_mfma_f32_16x16x32_f16 v[116:119], v[178:181], v[204:207], v[80:83]
	v_mfma_f32_16x16x32_f16 v[80:83], v[84:87], v[208:211], v[104:107]
	v_mfma_f32_16x16x32_f16 v[104:107], v[88:91], v[212:215], v[80:83]
	v_mfma_f32_16x16x32_f16 v[80:83], v[174:177], v[208:211], v[100:103]
	v_mfma_f32_16x16x32_f16 v[152:155], v[88:91], v[186:189], v[152:155]
	v_mfma_f32_16x16x32_f16 v[100:103], v[178:181], v[212:215], v[80:83]
	s_barrier
	s_setprio 0
	s_mov_b32 m0, s44
	s_nop 2
	v_lshl_add_u64 v[80:81], v[182:183], 0, s[74:75]
	s_add_u32 s4, s34, 0x40080
	ds_read_b128 v[186:189], v185 offset:49152
	ds_read_b128 v[190:193], v185 offset:50176
	ds_read_b128 v[194:197], v185 offset:51200
	ds_read_b128 v[200:203], v185 offset:52224
	ds_read_b128 v[204:207], v185 offset:53248
	ds_read_b128 v[208:211], v185 offset:54272
	ds_read_b128 v[212:215], v185 offset:55296
	ds_read_b128 v[216:219], v185 offset:56320
	global_load_lds_dwordx4 v[80:81], off
	v_lshl_add_u64 v[80:81], v[198:199], 0, s[74:75]
	s_mov_b32 m0, s45
	s_addc_u32 s5, s35, 0
	global_load_lds_dwordx4 v[80:81], off
	v_lshl_add_u64 v[80:81], s[4:5], 0, v[164:165]
	s_mov_b32 m0, s90
	s_nop 0
	global_load_lds_dwordx4 v[80:81], off
	v_lshl_add_u64 v[80:81], s[4:5], 0, v[168:169]
	s_mov_b32 m0, s91
	s_nop 0
	global_load_lds_dwordx4 v[80:81], off
	v_lshl_add_u64 v[80:81], v[220:221], 0, s[74:75]
	s_mov_b32 m0, s76
	s_nop 0
	global_load_lds_dwordx4 v[80:81], off
	v_lshl_add_u64 v[80:81], v[222:223], 0, s[74:75]
	s_mov_b32 m0, s77
	s_nop 0
	global_load_lds_dwordx4 v[80:81], off
	s_waitcnt vmcnt(8)
	s_waitcnt lgkmcnt(0)
	s_setprio 1
	s_barrier
	v_mfma_f32_16x16x32_f16 v[80:83], v[64:67], v[186:189], v[96:99]
	v_mfma_f32_16x16x32_f16 v[96:99], v[68:71], v[190:193], v[80:83]
	v_mfma_f32_16x16x32_f16 v[80:83], v[72:75], v[186:189], v[92:95]
	v_mfma_f32_16x16x32_f16 v[48:51], v[64:67], v[194:197], v[48:51]
	v_mfma_f32_16x16x32_f16 v[44:47], v[72:75], v[194:197], v[44:47]
	v_mfma_f32_16x16x32_f16 v[32:35], v[64:67], v[204:207], v[32:35]
	v_mfma_f32_16x16x32_f16 v[28:31], v[72:75], v[204:207], v[28:31]
	v_mfma_f32_16x16x32_f16 v[16:19], v[64:67], v[212:215], v[16:19]
	v_mfma_f32_16x16x32_f16 v[12:15], v[72:75], v[212:215], v[12:15]
	v_mfma_f32_16x16x32_f16 v[92:95], v[76:79], v[190:193], v[80:83]
	v_mfma_f32_16x16x32_f16 v[48:51], v[68:71], v[200:203], v[48:51]
	v_mfma_f32_16x16x32_f16 v[44:47], v[76:79], v[200:203], v[44:47]
	v_mfma_f32_16x16x32_f16 v[32:35], v[68:71], v[208:211], v[32:35]
	v_mfma_f32_16x16x32_f16 v[28:31], v[76:79], v[208:211], v[28:31]
	v_mfma_f32_16x16x32_f16 v[16:19], v[68:71], v[216:219], v[16:19]
	v_mfma_f32_16x16x32_f16 v[12:15], v[76:79], v[216:219], v[12:15]
	v_mfma_f32_16x16x32_f16 v[56:59], v[84:87], v[186:189], v[56:59]
	v_mfma_f32_16x16x32_f16 v[80:83], v[88:91], v[190:193], v[56:59]
	v_mfma_f32_16x16x32_f16 v[56:59], v[174:177], v[186:189], v[60:63]
	v_mfma_f32_16x16x32_f16 v[40:43], v[84:87], v[194:197], v[40:43]
	v_mfma_f32_16x16x32_f16 v[36:39], v[174:177], v[194:197], v[36:39]
	v_mfma_f32_16x16x32_f16 v[24:27], v[84:87], v[204:207], v[24:27]
	v_mfma_f32_16x16x32_f16 v[20:23], v[174:177], v[204:207], v[20:23]
	v_mfma_f32_16x16x32_f16 v[8:11], v[84:87], v[212:215], v[8:11]
	v_mfma_f32_16x16x32_f16 v[4:7], v[174:177], v[212:215], v[4:7]
	v_mfma_f32_16x16x32_f16 v[72:75], v[178:181], v[190:193], v[56:59]
	v_mfma_f32_16x16x32_f16 v[40:43], v[88:91], v[200:203], v[40:43]
	v_mfma_f32_16x16x32_f16 v[36:39], v[178:181], v[200:203], v[36:39]
	v_mfma_f32_16x16x32_f16 v[24:27], v[88:91], v[208:211], v[24:27]
	v_mfma_f32_16x16x32_f16 v[20:23], v[178:181], v[208:211], v[20:23]
	v_mfma_f32_16x16x32_f16 v[8:11], v[88:91], v[216:219], v[8:11]
	v_mfma_f32_16x16x32_f16 v[4:7], v[178:181], v[216:219], v[4:7]
	s_barrier
	s_setprio 0
	s_add_i32 vcc_hi, vcc_hi, 2
	s_add_u32 s36, s36, 0x100
	s_addc_u32 s37, s37, 0
	s_add_u32 s95, s95, 0x100
	s_addc_u32 vcc_lo, vcc_lo, 0
	s_cmp_gt_u32 vcc_hi, 13
	s_cbranch_scc0 .LBB0_951
	s_and_b64 vcc, exec, s[20:21]
	s_cbranch_vccz .LBB0_954
	s_barrier

.LBB0_1032:
	v_lshl_add_u64 v[8:9], v[26:27], 0, s[6:7]
	v_add_co_u32_e32 v8, vcc, 0x16500000, v8
	v_lshl_add_u64 v[10:11], v[18:19], 0, s[6:7]
	s_nop 0
	v_addc_co_u32_e32 v9, vcc, 0, v9, vcc
	global_load_dwordx4 v[100:103], v[8:9], off
	global_load_dwordx4 v[104:107], v[10:11], off offset:-512
	global_load_dwordx4 v[108:111], v[8:9], off offset:64
	global_load_dwordx4 v[112:115], v[10:11], off offset:-448
	global_load_dwordx4 v[116:119], v[8:9], off offset:128
	global_load_dwordx4 v[120:123], v[10:11], off offset:-384
	global_load_dwordx4 v[124:127], v[8:9], off offset:192
	global_load_dwordx4 v[128:131], v[10:11], off offset:-320
	global_load_dwordx4 v[132:135], v[8:9], off offset:256
	global_load_dwordx4 v[136:139], v[10:11], off offset:-256
	global_load_dwordx4 v[140:143], v[8:9], off offset:320
	global_load_dwordx4 v[144:147], v[10:11], off offset:-192
	global_load_dwordx4 v[148:151], v[8:9], off offset:384
	global_load_dwordx4 v[152:155], v[10:11], off offset:-128
	global_load_dwordx4 v[156:159], v[8:9], off offset:448
	global_load_dwordx4 v[160:163], v[10:11], off offset:-64
	global_load_dwordx4 v[164:167], v[8:9], off offset:512
	global_load_dwordx4 v[168:171], v[10:11], off
	global_load_dwordx4 v[172:175], v[8:9], off offset:576
	global_load_dwordx4 v[176:179], v[10:11], off offset:64
	global_load_dwordx4 v[180:183], v[8:9], off offset:640
	global_load_dwordx4 v[184:187], v[10:11], off offset:128
	global_load_dwordx4 v[188:191], v[8:9], off offset:704
	global_load_dwordx4 v[192:195], v[10:11], off offset:192
	global_load_dwordx4 v[196:199], v[8:9], off offset:768
	global_load_dwordx4 v[200:203], v[10:11], off offset:256
	global_load_dwordx4 v[204:207], v[8:9], off offset:832
	global_load_dwordx4 v[208:211], v[10:11], off offset:320
	global_load_dwordx4 v[212:215], v[8:9], off offset:896
	global_load_dwordx4 v[216:219], v[10:11], off offset:384
	global_load_dwordx4 v[220:223], v[8:9], off offset:960
	global_load_dwordx4 v[224:227], v[10:11], off offset:448
	s_waitcnt vmcnt(30)
	v_mfma_f32_16x16x32_f16 v[4:7], v[100:103], v[104:107], v[4:7]
	global_load_dwordx4 v[100:103], v[8:9], off offset:1024
	global_load_dwordx4 v[104:107], v[10:11], off offset:512
	s_waitcnt vmcnt(30)
	v_mfma_f32_16x16x32_f16 v[4:7], v[108:111], v[112:115], v[4:7]
	global_load_dwordx4 v[108:111], v[8:9], off offset:1088
	global_load_dwordx4 v[112:115], v[10:11], off offset:576
	s_waitcnt vmcnt(30)
	v_mfma_f32_16x16x32_f16 v[4:7], v[116:119], v[120:123], v[4:7]
	global_load_dwordx4 v[116:119], v[8:9], off offset:1152
	global_load_dwordx4 v[120:123], v[10:11], off offset:640
	s_waitcnt vmcnt(30)
	v_mfma_f32_16x16x32_f16 v[4:7], v[124:127], v[128:131], v[4:7]
	global_load_dwordx4 v[124:127], v[8:9], off offset:1216
	global_load_dwordx4 v[128:131], v[10:11], off offset:704
	s_waitcnt vmcnt(30)
	v_mfma_f32_16x16x32_f16 v[4:7], v[132:135], v[136:139], v[4:7]
	global_load_dwordx4 v[132:135], v[8:9], off offset:1280
	global_load_dwordx4 v[136:139], v[10:11], off offset:768
	s_waitcnt vmcnt(30)
	v_mfma_f32_16x16x32_f16 v[4:7], v[140:143], v[144:147], v[4:7]
	global_load_dwordx4 v[140:143], v[8:9], off offset:1344
	global_load_dwordx4 v[144:147], v[10:11], off offset:832
	s_waitcnt vmcnt(30)
	v_mfma_f32_16x16x32_f16 v[4:7], v[148:151], v[152:155], v[4:7]
	global_load_dwordx4 v[148:151], v[8:9], off offset:1408
	global_load_dwordx4 v[152:155], v[10:11], off offset:896
	s_waitcnt vmcnt(30)
	v_mfma_f32_16x16x32_f16 v[4:7], v[156:159], v[160:163], v[4:7]
	global_load_dwordx4 v[156:159], v[8:9], off offset:1472
	global_load_dwordx4 v[160:163], v[10:11], off offset:960
	s_waitcnt vmcnt(30)
	v_mfma_f32_16x16x32_f16 v[4:7], v[164:167], v[168:171], v[4:7]
	global_load_dwordx4 v[164:167], v[8:9], off offset:1536
	global_load_dwordx4 v[168:171], v[10:11], off offset:1024
	s_waitcnt vmcnt(30)
	v_mfma_f32_16x16x32_f16 v[4:7], v[172:175], v[176:179], v[4:7]
	global_load_dwordx4 v[172:175], v[8:9], off offset:1600
	global_load_dwordx4 v[176:179], v[10:11], off offset:1088
	s_waitcnt vmcnt(30)
	v_mfma_f32_16x16x32_f16 v[4:7], v[180:183], v[184:187], v[4:7]
	global_load_dwordx4 v[180:183], v[8:9], off offset:1664
	global_load_dwordx4 v[184:187], v[10:11], off offset:1152
	s_waitcnt vmcnt(30)
	v_mfma_f32_16x16x32_f16 v[4:7], v[188:191], v[192:195], v[4:7]
	global_load_dwordx4 v[188:191], v[8:9], off offset:1728
	global_load_dwordx4 v[192:195], v[10:11], off offset:1216
	s_waitcnt vmcnt(30)
	v_mfma_f32_16x16x32_f16 v[4:7], v[196:199], v[200:203], v[4:7]
	global_load_dwordx4 v[196:199], v[8:9], off offset:1792
	global_load_dwordx4 v[200:203], v[10:11], off offset:1280
	s_waitcnt vmcnt(30)
	v_mfma_f32_16x16x32_f16 v[4:7], v[204:207], v[208:211], v[4:7]
	global_load_dwordx4 v[204:207], v[8:9], off offset:1856
	global_load_dwordx4 v[208:211], v[10:11], off offset:1344
	s_waitcnt vmcnt(30)
	v_mfma_f32_16x16x32_f16 v[4:7], v[212:215], v[216:219], v[4:7]
	global_load_dwordx4 v[212:215], v[8:9], off offset:1920
	global_load_dwordx4 v[216:219], v[10:11], off offset:1408
	s_waitcnt vmcnt(30)
	v_mfma_f32_16x16x32_f16 v[4:7], v[220:223], v[224:227], v[4:7]
	global_load_dwordx4 v[220:223], v[8:9], off offset:1984
	global_load_dwordx4 v[224:227], v[10:11], off offset:1472
	s_waitcnt vmcnt(30)
	v_mfma_f32_16x16x32_f16 v[4:7], v[100:103], v[104:107], v[4:7]
	s_waitcnt vmcnt(28)
	v_mfma_f32_16x16x32_f16 v[4:7], v[108:111], v[112:115], v[4:7]
	s_waitcnt vmcnt(26)
	v_mfma_f32_16x16x32_f16 v[4:7], v[116:119], v[120:123], v[4:7]
	s_waitcnt vmcnt(24)
	v_mfma_f32_16x16x32_f16 v[4:7], v[124:127], v[128:131], v[4:7]
	s_waitcnt vmcnt(22)
	v_mfma_f32_16x16x32_f16 v[4:7], v[132:135], v[136:139], v[4:7]
	s_waitcnt vmcnt(20)
	v_mfma_f32_16x16x32_f16 v[4:7], v[140:143], v[144:147], v[4:7]
	s_waitcnt vmcnt(18)
	v_mfma_f32_16x16x32_f16 v[4:7], v[148:151], v[152:155], v[4:7]
	s_waitcnt vmcnt(16)
	v_mfma_f32_16x16x32_f16 v[4:7], v[156:159], v[160:163], v[4:7]
	s_waitcnt vmcnt(14)
	v_mfma_f32_16x16x32_f16 v[4:7], v[164:167], v[168:171], v[4:7]
	s_waitcnt vmcnt(12)
	v_mfma_f32_16x16x32_f16 v[4:7], v[172:175], v[176:179], v[4:7]
	s_waitcnt vmcnt(10)
	v_mfma_f32_16x16x32_f16 v[4:7], v[180:183], v[184:187], v[4:7]
	s_waitcnt vmcnt(8)
	v_mfma_f32_16x16x32_f16 v[4:7], v[188:191], v[192:195], v[4:7]
	s_waitcnt vmcnt(6)
	v_mfma_f32_16x16x32_f16 v[4:7], v[196:199], v[200:203], v[4:7]
	s_waitcnt vmcnt(4)
	v_mfma_f32_16x16x32_f16 v[4:7], v[204:207], v[208:211], v[4:7]
	s_waitcnt vmcnt(2)
	v_mfma_f32_16x16x32_f16 v[4:7], v[212:215], v[216:219], v[4:7]
	s_waitcnt vmcnt(0)
	v_mfma_f32_16x16x32_f16 v[4:7], v[220:223], v[224:227], v[4:7]
	s_nop 7
	s_mov_b64 s[6:7], 0

.LBB0_1036:
	v_lshl_add_u64 v[30:31], v[26:27], 0, s[6:7]
	v_add_co_u32_e32 v38, vcc, 0x16500000, v30
	v_lshl_add_u64 v[34:35], v[28:29], 0, s[6:7]
	s_nop 0
	v_addc_co_u32_e32 v39, vcc, 0, v31, vcc
	v_add_co_u32_e32 v54, vcc, 0x16500000, v34
	v_lshl_add_u64 v[56:57], v[20:21], 0, s[6:7]
	s_nop 1
	v_addc_co_u32_e32 v55, vcc, 0, v35, vcc
	global_load_dwordx4 v[100:103], v[38:39], off
	global_load_dwordx4 v[104:107], v[54:55], off
	global_load_dwordx4 v[108:111], v[56:57], off offset:-256
	global_load_dwordx4 v[112:115], v[38:39], off offset:64
	global_load_dwordx4 v[116:119], v[54:55], off offset:64
	global_load_dwordx4 v[120:123], v[56:57], off offset:-192
	global_load_dwordx4 v[124:127], v[38:39], off offset:128
	global_load_dwordx4 v[128:131], v[54:55], off offset:128
	global_load_dwordx4 v[132:135], v[56:57], off offset:-128
	global_load_dwordx4 v[136:139], v[38:39], off offset:192
	global_load_dwordx4 v[140:143], v[54:55], off offset:192
	global_load_dwordx4 v[144:147], v[56:57], off offset:-64
	global_load_dwordx4 v[148:151], v[38:39], off offset:256
	global_load_dwordx4 v[152:155], v[54:55], off offset:256
	global_load_dwordx4 v[156:159], v[56:57], off
	global_load_dwordx4 v[160:163], v[38:39], off offset:320
	global_load_dwordx4 v[164:167], v[54:55], off offset:320
	global_load_dwordx4 v[168:171], v[56:57], off offset:64
	global_load_dwordx4 v[172:175], v[38:39], off offset:384
	global_load_dwordx4 v[176:179], v[54:55], off offset:384
	global_load_dwordx4 v[180:183], v[56:57], off offset:128
	global_load_dwordx4 v[184:187], v[38:39], off offset:448
	global_load_dwordx4 v[188:191], v[54:55], off offset:448
	global_load_dwordx4 v[192:195], v[56:57], off offset:192
	global_load_dwordx4 v[196:199], v[38:39], off offset:512
	global_load_dwordx4 v[200:203], v[54:55], off offset:512
	global_load_dwordx4 v[204:207], v[56:57], off offset:256
	global_load_dwordx4 v[208:211], v[38:39], off offset:576
	global_load_dwordx4 v[212:215], v[54:55], off offset:576
	global_load_dwordx4 v[216:219], v[56:57], off offset:320
	s_waitcnt vmcnt(27)
	v_mfma_f32_16x16x32_f16 v[4:7], v[100:103], v[108:111], v[4:7]
	v_mfma_f32_16x16x32_f16 v[8:11], v[104:107], v[108:111], v[8:11]
	global_load_dwordx4 v[100:103], v[38:39], off offset:640
	global_load_dwordx4 v[104:107], v[54:55], off offset:640
	global_load_dwordx4 v[108:111], v[56:57], off offset:384
	s_waitcnt vmcnt(27)
	v_mfma_f32_16x16x32_f16 v[4:7], v[112:115], v[120:123], v[4:7]
	v_mfma_f32_16x16x32_f16 v[8:11], v[116:119], v[120:123], v[8:11]
	global_load_dwordx4 v[112:115], v[38:39], off offset:704
	global_load_dwordx4 v[116:119], v[54:55], off offset:704
	global_load_dwordx4 v[120:123], v[56:57], off offset:448
	s_waitcnt vmcnt(27)
	v_mfma_f32_16x16x32_f16 v[4:7], v[124:127], v[132:135], v[4:7]
	v_mfma_f32_16x16x32_f16 v[8:11], v[128:131], v[132:135], v[8:11]
	global_load_dwordx4 v[124:127], v[38:39], off offset:768
	global_load_dwordx4 v[128:131], v[54:55], off offset:768
	global_load_dwordx4 v[132:135], v[56:57], off offset:512
	s_waitcnt vmcnt(27)
	v_mfma_f32_16x16x32_f16 v[4:7], v[136:139], v[144:147], v[4:7]
	v_mfma_f32_16x16x32_f16 v[8:11], v[140:143], v[144:147], v[8:11]
	global_load_dwordx4 v[136:139], v[38:39], off offset:832
	global_load_dwordx4 v[140:143], v[54:55], off offset:832
	global_load_dwordx4 v[144:147], v[56:57], off offset:576
	s_waitcnt vmcnt(27)
	v_mfma_f32_16x16x32_f16 v[4:7], v[148:151], v[156:159], v[4:7]
	v_mfma_f32_16x16x32_f16 v[8:11], v[152:155], v[156:159], v[8:11]
	global_load_dwordx4 v[148:151], v[38:39], off offset:896
	global_load_dwordx4 v[152:155], v[54:55], off offset:896
	global_load_dwordx4 v[156:159], v[56:57], off offset:640
	s_waitcnt vmcnt(27)
	v_mfma_f32_16x16x32_f16 v[4:7], v[160:163], v[168:171], v[4:7]
	v_mfma_f32_16x16x32_f16 v[8:11], v[164:167], v[168:171], v[8:11]
	global_load_dwordx4 v[160:163], v[38:39], off offset:960
	global_load_dwordx4 v[164:167], v[54:55], off offset:960
	global_load_dwordx4 v[168:171], v[56:57], off offset:704
	s_waitcnt vmcnt(27)
	v_mfma_f32_16x16x32_f16 v[4:7], v[172:175], v[180:183], v[4:7]
	v_mfma_f32_16x16x32_f16 v[8:11], v[176:179], v[180:183], v[8:11]
	global_load_dwordx4 v[172:175], v[38:39], off offset:1024
	global_load_dwordx4 v[176:179], v[54:55], off offset:1024
	global_load_dwordx4 v[180:183], v[56:57], off offset:768
	s_waitcnt vmcnt(27)
	v_mfma_f32_16x16x32_f16 v[4:7], v[184:187], v[192:195], v[4:7]
	v_mfma_f32_16x16x32_f16 v[8:11], v[188:191], v[192:195], v[8:11]
	global_load_dwordx4 v[184:187], v[38:39], off offset:1088
	global_load_dwordx4 v[188:191], v[54:55], off offset:1088
	global_load_dwordx4 v[192:195], v[56:57], off offset:832
	s_waitcnt vmcnt(27)
	v_mfma_f32_16x16x32_f16 v[4:7], v[196:199], v[204:207], v[4:7]
	v_mfma_f32_16x16x32_f16 v[8:11], v[200:203], v[204:207], v[8:11]
	global_load_dwordx4 v[196:199], v[38:39], off offset:1152
	global_load_dwordx4 v[200:203], v[54:55], off offset:1152
	global_load_dwordx4 v[204:207], v[56:57], off offset:896
	s_waitcnt vmcnt(27)
	v_mfma_f32_16x16x32_f16 v[4:7], v[208:211], v[216:219], v[4:7]
	v_mfma_f32_16x16x32_f16 v[8:11], v[212:215], v[216:219], v[8:11]
	global_load_dwordx4 v[208:211], v[38:39], off offset:1216
	global_load_dwordx4 v[212:215], v[54:55], off offset:1216
	global_load_dwordx4 v[216:219], v[56:57], off offset:960
	s_waitcnt vmcnt(27)
	v_mfma_f32_16x16x32_f16 v[4:7], v[100:103], v[108:111], v[4:7]
	v_mfma_f32_16x16x32_f16 v[8:11], v[104:107], v[108:111], v[8:11]
	global_load_dwordx4 v[100:103], v[38:39], off offset:1280
	global_load_dwordx4 v[104:107], v[54:55], off offset:1280
	global_load_dwordx4 v[108:111], v[56:57], off offset:1024
	s_waitcnt vmcnt(27)
	v_mfma_f32_16x16x32_f16 v[4:7], v[112:115], v[120:123], v[4:7]
	v_mfma_f32_16x16x32_f16 v[8:11], v[116:119], v[120:123], v[8:11]
	global_load_dwordx4 v[112:115], v[38:39], off offset:1344
	global_load_dwordx4 v[116:119], v[54:55], off offset:1344
	global_load_dwordx4 v[120:123], v[56:57], off offset:1088
	s_waitcnt vmcnt(27)
	v_mfma_f32_16x16x32_f16 v[4:7], v[124:127], v[132:135], v[4:7]
	v_mfma_f32_16x16x32_f16 v[8:11], v[128:131], v[132:135], v[8:11]
	global_load_dwordx4 v[124:127], v[38:39], off offset:1408
	global_load_dwordx4 v[128:131], v[54:55], off offset:1408
	global_load_dwordx4 v[132:135], v[56:57], off offset:1152
	s_waitcnt vmcnt(27)
	v_mfma_f32_16x16x32_f16 v[4:7], v[136:139], v[144:147], v[4:7]
	v_mfma_f32_16x16x32_f16 v[8:11], v[140:143], v[144:147], v[8:11]
	global_load_dwordx4 v[136:139], v[38:39], off offset:1472
	global_load_dwordx4 v[140:143], v[54:55], off offset:1472
	global_load_dwordx4 v[144:147], v[56:57], off offset:1216
	s_waitcnt vmcnt(27)
	v_mfma_f32_16x16x32_f16 v[4:7], v[148:151], v[156:159], v[4:7]
	v_mfma_f32_16x16x32_f16 v[8:11], v[152:155], v[156:159], v[8:11]
	global_load_dwordx4 v[148:151], v[38:39], off offset:1536
	global_load_dwordx4 v[152:155], v[54:55], off offset:1536
	global_load_dwordx4 v[156:159], v[56:57], off offset:1280
	s_waitcnt vmcnt(27)
	v_mfma_f32_16x16x32_f16 v[4:7], v[160:163], v[168:171], v[4:7]
	v_mfma_f32_16x16x32_f16 v[8:11], v[164:167], v[168:171], v[8:11]
	global_load_dwordx4 v[160:163], v[38:39], off offset:1600
	global_load_dwordx4 v[164:167], v[54:55], off offset:1600
	global_load_dwordx4 v[168:171], v[56:57], off offset:1344
	s_waitcnt vmcnt(27)
	v_mfma_f32_16x16x32_f16 v[4:7], v[172:175], v[180:183], v[4:7]
	v_mfma_f32_16x16x32_f16 v[8:11], v[176:179], v[180:183], v[8:11]
	global_load_dwordx4 v[172:175], v[38:39], off offset:1664
	global_load_dwordx4 v[176:179], v[54:55], off offset:1664
	global_load_dwordx4 v[180:183], v[56:57], off offset:1408
	s_waitcnt vmcnt(27)
	v_mfma_f32_16x16x32_f16 v[4:7], v[184:187], v[192:195], v[4:7]
	v_mfma_f32_16x16x32_f16 v[8:11], v[188:191], v[192:195], v[8:11]
	global_load_dwordx4 v[184:187], v[38:39], off offset:1728
	global_load_dwordx4 v[188:191], v[54:55], off offset:1728
	global_load_dwordx4 v[192:195], v[56:57], off offset:1472
	s_waitcnt vmcnt(27)
	v_mfma_f32_16x16x32_f16 v[4:7], v[196:199], v[204:207], v[4:7]
	v_mfma_f32_16x16x32_f16 v[8:11], v[200:203], v[204:207], v[8:11]
	global_load_dwordx4 v[196:199], v[38:39], off offset:1792
	global_load_dwordx4 v[200:203], v[54:55], off offset:1792
	global_load_dwordx4 v[204:207], v[56:57], off offset:1536
	s_waitcnt vmcnt(27)
	v_mfma_f32_16x16x32_f16 v[4:7], v[208:211], v[216:219], v[4:7]
	v_mfma_f32_16x16x32_f16 v[8:11], v[212:215], v[216:219], v[8:11]
	global_load_dwordx4 v[208:211], v[38:39], off offset:1856
	global_load_dwordx4 v[212:215], v[54:55], off offset:1856
	global_load_dwordx4 v[216:219], v[56:57], off offset:1600
	s_waitcnt vmcnt(27)
	v_mfma_f32_16x16x32_f16 v[4:7], v[100:103], v[108:111], v[4:7]
	v_mfma_f32_16x16x32_f16 v[8:11], v[104:107], v[108:111], v[8:11]
	global_load_dwordx4 v[100:103], v[38:39], off offset:1920
	global_load_dwordx4 v[104:107], v[54:55], off offset:1920
	global_load_dwordx4 v[108:111], v[56:57], off offset:1664
	s_waitcnt vmcnt(27)
	v_mfma_f32_16x16x32_f16 v[4:7], v[112:115], v[120:123], v[4:7]
	v_mfma_f32_16x16x32_f16 v[8:11], v[116:119], v[120:123], v[8:11]
	global_load_dwordx4 v[112:115], v[38:39], off offset:1984
	global_load_dwordx4 v[116:119], v[54:55], off offset:1984
	global_load_dwordx4 v[120:123], v[56:57], off offset:1728
	s_waitcnt vmcnt(27)
	v_mfma_f32_16x16x32_f16 v[4:7], v[124:127], v[132:135], v[4:7]
	v_mfma_f32_16x16x32_f16 v[8:11], v[128:131], v[132:135], v[8:11]
	s_waitcnt vmcnt(24)
	v_mfma_f32_16x16x32_f16 v[4:7], v[136:139], v[144:147], v[4:7]
	v_mfma_f32_16x16x32_f16 v[8:11], v[140:143], v[144:147], v[8:11]
	s_waitcnt vmcnt(21)
	v_mfma_f32_16x16x32_f16 v[4:7], v[148:151], v[156:159], v[4:7]
	v_mfma_f32_16x16x32_f16 v[8:11], v[152:155], v[156:159], v[8:11]
	s_waitcnt vmcnt(18)
	v_mfma_f32_16x16x32_f16 v[4:7], v[160:163], v[168:171], v[4:7]
	v_mfma_f32_16x16x32_f16 v[8:11], v[164:167], v[168:171], v[8:11]
	s_waitcnt vmcnt(15)
	v_mfma_f32_16x16x32_f16 v[4:7], v[172:175], v[180:183], v[4:7]
	v_mfma_f32_16x16x32_f16 v[8:11], v[176:179], v[180:183], v[8:11]
	s_waitcnt vmcnt(12)
	v_mfma_f32_16x16x32_f16 v[4:7], v[184:187], v[192:195], v[4:7]
	v_mfma_f32_16x16x32_f16 v[8:11], v[188:191], v[192:195], v[8:11]
	s_waitcnt vmcnt(9)
	v_mfma_f32_16x16x32_f16 v[4:7], v[196:199], v[204:207], v[4:7]
	v_mfma_f32_16x16x32_f16 v[8:11], v[200:203], v[204:207], v[8:11]
	s_waitcnt vmcnt(6)
	v_mfma_f32_16x16x32_f16 v[4:7], v[208:211], v[216:219], v[4:7]
	v_mfma_f32_16x16x32_f16 v[8:11], v[212:215], v[216:219], v[8:11]
	s_waitcnt vmcnt(3)
	v_mfma_f32_16x16x32_f16 v[4:7], v[100:103], v[108:111], v[4:7]
	v_mfma_f32_16x16x32_f16 v[8:11], v[104:107], v[108:111], v[8:11]
	s_waitcnt vmcnt(0)
	v_mfma_f32_16x16x32_f16 v[4:7], v[112:115], v[120:123], v[4:7]
	v_mfma_f32_16x16x32_f16 v[8:11], v[116:119], v[120:123], v[8:11]
	s_nop 7
	s_mov_b32 s0, 2
	s_branch .LBB0_1039

.LBB0_1330:
	s_or_b64 exec, exec, s[14:15]
	s_add_u32 s18, s54, 0x2bc00000
	s_addc_u32 s25, s55, 0
	s_ashr_i32 s11, s10, 31
	s_lshl_b64 s[8:9], s[64:65], 15
	s_ashr_i32 s19, s20, 6
	s_lshl_b32 s30, s3, 8
	s_lshl_b64 s[4:5], s[10:11], 16
	s_lshl_b32 s0, s23, 23
	s_add_u32 s4, s4, s0
	s_addc_u32 s5, s5, 0
	s_lshl_b64 s[4:5], s[4:5], 1
	s_lshl_b32 s0, s24, 7
	s_add_u32 s4, s54, s4
	s_addc_u32 s5, s55, s5
	s_add_u32 s4, s4, s0
	s_addc_u32 s5, s5, 0
	v_lshlrev_b32_e32 v2, 11, v204
	v_lshl_add_u64 v[0:1], s[4:5], 0, v[2:3]
	s_lshl_b32 s0, s19, 4
	v_lshrrev_b32_e32 v2, 2, v204
	v_and_or_b32 v2, s0, 48, v2
	v_lshlrev_b32_e32 v2, 11, v2
	s_ashr_i32 s0, s20, 3
	v_lshl_add_u64 v[4:5], s[4:5], 0, v[2:3]
	s_and_b32 s4, s0, 0xffffffe0
	v_lshlrev_b32_e32 v205, 3, v47
	s_lshl_b32 s14, s19, 3
	s_ashr_i32 s5, s4, 31
	v_and_b32_e32 v208, 24, v205
	s_ashr_i32 s15, s14, 31
	v_lshl_add_u64 v[4:5], s[4:5], 1, v[4:5]
	v_lshlrev_b32_e32 v2, 1, v208
	s_lshl_b32 s0, s19, 10
	v_lshl_add_u64 v[4:5], v[4:5], 0, v[2:3]
	s_mov_b64 s[4:5], 0x23a00000
	s_cmp_lg_u32 0, -1
	v_lshl_add_u64 v[0:1], s[14:15], 1, v[0:1]
	s_mov_b64 s[14:15], 0x1f900000
	v_lshl_add_u64 v[202:203], v[4:5], 0, s[4:5]
	s_cselect_b32 s4, 0, 0
	v_lshl_add_u64 v[200:201], v[0:1], 0, s[14:15]
	s_add_i32 s21, s0, s4
	s_mov_b32 s4, m0
	s_mov_b32 m0, s21
	s_nop 0
	global_load_lds_dwordx4 v[200:201], off
	s_mov_b32 m0, s4
	s_add_i32 s22, s21, 0x6000
	s_mov_b32 s4, m0
	s_mov_b32 m0, s22
	s_nop 0
	global_load_lds_dwordx4 v[202:203], off
	s_mov_b32 m0, s4
	s_mov_b64 s[4:5], 0x1f920000
	v_lshl_add_u64 v[0:1], v[0:1], 0, s[4:5]
	s_add_i32 s4, s21, 0x2000
	s_mov_b32 s5, m0
	s_mov_b32 m0, s4
	s_nop 0
	global_load_lds_dwordx4 v[0:1], off
	s_mov_b32 m0, s5
	s_add_i32 s31, s30, 0x100
	v_lshlrev_b32_e32 v0, 2, v47
	v_lshlrev_b32_e32 v2, 4, v46
	v_readlane_b32 s4, v255, 9
	v_ashrrev_i32_e32 v1, 31, v0
	s_mov_b64 s[16:17], 0x2000
	v_add_u32_e32 v7, s4, v2
	s_add_u32 s4, s18, s8
	s_addc_u32 s5, s25, s9
	v_lshl_add_u64 v[4:5], v[0:1], 2, s[4:5]
	global_load_dwordx4 v[8:11], v[4:5], off
	v_lshl_add_u64 v[4:5], v[4:5], 0, s[16:17]
	global_load_dwordx4 v[12:15], v[4:5], off
	v_lshl_add_u64 v[4:5], v[4:5], 0, s[16:17]
	global_load_dwordx4 v[16:19], v[4:5], off
	v_lshl_add_u64 v[4:5], v[4:5], 0, s[16:17]
	global_load_dwordx4 v[20:23], v[4:5], off
	s_lshl_b32 s14, s24, 6
	s_add_u32 s4, s18, s8
	s_addc_u32 s5, s25, s9
	s_lshl_b32 s8, s23, 13
	s_lshl_b32 s11, s19, 5
	s_xor_b32 s18, s27, 1
	s_or_b32 s8, s30, s8
	s_ashr_i32 s9, s11, 31
	s_add_u32 s8, s11, s8
	s_addc_u32 s9, s9, 0
	s_lshl_b64 s[8:9], s[8:9], 11
	s_add_u32 s8, s28, s8
	s_addc_u32 s9, s29, s9
	s_lshl_b32 s14, s14, 1
	s_add_u32 s44, s8, s14
	v_and_b32_e32 v206, 31, v46
	s_addc_u32 s45, s9, 0
	s_add_i32 s8, s11, s30
	v_or_b32_e32 v0, s8, v206
	v_ashrrev_i32_e32 v1, 31, v0
	v_lshrrev_b32_e32 v207, 5, v204
	v_lshl_add_u64 v[0:1], v[0:1], 2, s[4:5]
	v_lshlrev_b32_e32 v4, 11, v206
	v_lshl_or_b32 v4, v207, 4, v4
	global_load_dword v214, v[0:1], off
	global_load_dwordx4 v[124:127], v4, s[44:45]
	global_load_dwordx4 v[120:123], v4, s[44:45] offset:32
	global_load_dwordx4 v[116:119], v4, s[44:45] offset:64
	global_load_dwordx4 v[112:115], v4, s[44:45] offset:96
	s_waitcnt vmcnt(0)
	ds_write_b128 v7, v[8:11]
	ds_write_b128 v7, v[12:15] offset:8192
	ds_write_b128 v7, v[16:19] offset:16384
	ds_write_b128 v7, v[20:23] offset:24576
	s_waitcnt vmcnt(0) lgkmcnt(0)
	s_and_saveexec_b64 s[8:9], s[12:13]
	s_lshl_b32 s4, s18, 2
	s_add_i32 s4, s4, 0
	s_add_i32 s4, s4, 0x20180
	v_mov_b32_e32 v0, s4
	ds_write_b32 v0, v6
	s_or_b64 exec, exec, s[8:9]
	v_or_b32_e32 v212, s11, v206
	s_lshl_b32 s11, s10, 8
	s_add_i32 s8, s11, 0
	s_lshr_b32 s4, s31, 6
	s_add_i32 s23, s8, 0x14800
	s_sub_i32 s24, s4, s10
	s_cmp_lg_u32 0, -1
	v_lshlrev_b32_e32 v0, 10, v207
	v_lshlrev_b32_e32 v1, 4, v206
	s_cselect_b32 s4, 0, 0
	v_add3_u32 v215, 0, v0, v1
	s_waitcnt lgkmcnt(0)
	s_barrier
	v_lshl_add_u64 v[0:1], v[200:201], 0, s[82:83]
	s_add_i32 s4, s4, s0
	v_lshlrev_b32_e32 v209, 4, v207
	s_addk_i32 s4, 0x4000
	s_mov_b32 s5, m0
	s_mov_b32 m0, s4
	s_nop 0
	global_load_lds_dwordx4 v[0:1], off
	s_mov_b32 m0, s5
	v_add_u32_e32 v0, s23, v209
	ds_read_b128 v[20:23], v0 offset:128
	ds_read_b128 v[4:7], v0
	ds_read_b128 v[8:11], v0 offset:32
	ds_read_b128 v[24:27], v0 offset:160
	ds_read_b128 v[12:15], v0 offset:64
	ds_read_b128 v[28:31], v0 offset:192
	ds_read_b128 v[16:19], v0 offset:96
	ds_read_b128 v[32:35], v0 offset:224
	ds_read_b128 v[36:39], v215
	ds_read_b128 v[40:43], v215 offset:512
	s_waitcnt vmcnt(0) lgkmcnt(0)
	v_sub_f32_e32 v15, v214, v15
	v_sub_f32_e32 v14, v214, v14
	v_sub_f32_e32 v19, v214, v19
	v_sub_f32_e32 v18, v214, v18
	v_sub_f32_e32 v17, v214, v17
	v_sub_f32_e32 v16, v214, v16
	v_sub_f32_e32 v13, v214, v13
	v_sub_f32_e32 v12, v214, v12
	v_sub_f32_e32 v11, v214, v11
	v_sub_f32_e32 v10, v214, v10
	v_sub_f32_e32 v9, v214, v9
	v_sub_f32_e32 v8, v214, v8
	v_sub_f32_e32 v7, v214, v7
	v_sub_f32_e32 v6, v214, v6
	v_sub_f32_e32 v5, v214, v5
	v_sub_f32_e32 v4, v214, v4
	v_sub_f32_e32 v35, v214, v35
	v_sub_f32_e32 v34, v214, v34
	v_sub_f32_e32 v33, v214, v33
	v_sub_f32_e32 v32, v214, v32
	v_sub_f32_e32 v31, v214, v31
	v_sub_f32_e32 v30, v214, v30
	v_sub_f32_e32 v29, v214, v29
	v_sub_f32_e32 v28, v214, v28
	v_sub_f32_e32 v27, v214, v27
	v_sub_f32_e32 v26, v214, v26
	v_sub_f32_e32 v25, v214, v25
	v_sub_f32_e32 v24, v214, v24
	v_sub_f32_e32 v23, v214, v23
	v_sub_f32_e32 v22, v214, v22
	v_sub_f32_e32 v21, v214, v21
	v_sub_f32_e32 v20, v214, v20
	v_mfma_f32_32x32x16_bf16 v[4:19], v[36:39], v[124:127], v[4:19]
	s_cmp_gt_i32 s24, 4
	v_mfma_f32_32x32x16_bf16 v[20:35], v[40:43], v[124:127], v[20:35]
	ds_read_b128 v[36:39], v215 offset:2048
	ds_read_b128 v[40:43], v215 offset:2560
	s_waitcnt lgkmcnt(1)
	v_mfma_f32_32x32x16_bf16 v[4:19], v[36:39], v[120:123], v[4:19]
	s_waitcnt lgkmcnt(0)
	v_mfma_f32_32x32x16_bf16 v[20:35], v[40:43], v[120:123], v[20:35]
	ds_read_b128 v[36:39], v215 offset:4096
	ds_read_b128 v[40:43], v215 offset:4608
	s_waitcnt lgkmcnt(1)
	v_mfma_f32_32x32x16_bf16 v[4:19], v[36:39], v[116:119], v[4:19]
	s_waitcnt lgkmcnt(0)
	v_mfma_f32_32x32x16_bf16 v[20:35], v[40:43], v[116:119], v[20:35]
	ds_read_b128 v[36:39], v215 offset:6144
	ds_read_b128 v[40:43], v215 offset:6656
	s_waitcnt lgkmcnt(1)
	v_mfma_f32_32x32x16_bf16 v[4:19], v[36:39], v[112:115], v[4:19]
	s_waitcnt lgkmcnt(0)
	v_mfma_f32_32x32x16_bf16 v[20:35], v[40:43], v[112:115], v[20:35]
	s_nop 15
	s_nop 7
	s_cbranch_scc1 .LBB0_1338
	s_sub_i32 s9, 4, s24
	s_lshl_b32 s4, s9, 1
	s_add_i32 s4, s4, 2
	v_mov_b32_e32 v253, 1
	s_cmp_ge_i32 s19, s4
	s_cbranch_scc1 .LBB0_1339
	v_lshlrev_b32_e32 v0, 2, v207
	v_lshl_or_b32 v0, s9, 6, v0
	v_or_b32_e32 v1, 32, v0
	v_cmp_le_i32_e32 vcc, v1, v212
	v_or_b32_e32 v1, 33, v0
	s_nop 0
	v_cndmask_b32_e32 v20, v252, v20, vcc
	v_cmp_lt_i32_e32 vcc, v0, v212
	s_nop 1
	v_cndmask_b32_e32 v5, v252, v5, vcc
	v_cmp_le_i32_e32 vcc, v0, v212
	s_nop 1
	v_cndmask_b32_e32 v4, v252, v4, vcc
	v_cmp_le_i32_e32 vcc, v1, v212
	v_or_b32_e32 v1, 2, v0
	s_nop 0
	v_cndmask_b32_e32 v21, v252, v21, vcc
	v_cmp_le_i32_e32 vcc, v1, v212
	v_or_b32_e32 v1, 34, v0
	s_nop 0
	v_cndmask_b32_e32 v6, v252, v6, vcc
	v_cmp_le_i32_e32 vcc, v1, v212
	v_or_b32_e32 v1, 3, v0
	s_nop 0
	v_cndmask_b32_e32 v22, v252, v22, vcc
	v_cmp_le_i32_e32 vcc, v1, v212
	v_or_b32_e32 v1, 35, v0
	s_nop 0
	v_cndmask_b32_e32 v7, v252, v7, vcc
	v_cmp_le_i32_e32 vcc, v1, v212
	v_or_b32_e32 v1, 8, v0
	s_nop 0
	v_cndmask_b32_e32 v23, v252, v23, vcc
	v_cmp_le_i32_e32 vcc, v1, v212
	v_or_b32_e32 v1, 40, v0
	s_nop 0
	v_cndmask_b32_e32 v8, v252, v8, vcc
	v_cmp_le_i32_e32 vcc, v1, v212
	v_or_b32_e32 v1, 9, v0
	s_nop 0
	v_cndmask_b32_e32 v24, v252, v24, vcc
	v_cmp_le_i32_e32 vcc, v1, v212
	v_or_b32_e32 v1, 41, v0
	s_nop 0
	v_cndmask_b32_e32 v9, v252, v9, vcc
	v_cmp_le_i32_e32 vcc, v1, v212
	v_or_b32_e32 v1, 10, v0
	s_nop 0
	v_cndmask_b32_e32 v25, v252, v25, vcc
	v_cmp_le_i32_e32 vcc, v1, v212
	v_or_b32_e32 v1, 42, v0
	s_nop 0
	v_cndmask_b32_e32 v10, v252, v10, vcc
	v_cmp_le_i32_e32 vcc, v1, v212
	v_or_b32_e32 v1, 11, v0
	s_nop 0
	v_cndmask_b32_e32 v26, v252, v26, vcc
	v_cmp_le_i32_e32 vcc, v1, v212
	v_or_b32_e32 v1, 43, v0
	s_nop 0
	v_cndmask_b32_e32 v11, v252, v11, vcc
	v_cmp_le_i32_e32 vcc, v1, v212
	v_or_b32_e32 v1, 16, v0
	s_nop 0
	v_cndmask_b32_e32 v27, v252, v27, vcc
	v_cmp_le_i32_e32 vcc, v1, v212
	v_or_b32_e32 v1, 48, v0
	s_nop 0
	v_cndmask_b32_e32 v12, v252, v12, vcc
	v_cmp_le_i32_e32 vcc, v1, v212
	v_or_b32_e32 v1, 17, v0
	s_nop 0
	v_cndmask_b32_e32 v28, v252, v28, vcc
	v_cmp_le_i32_e32 vcc, v1, v212
	v_or_b32_e32 v1, 49, v0
	s_nop 0
	v_cndmask_b32_e32 v13, v252, v13, vcc
	v_cmp_le_i32_e32 vcc, v1, v212
	v_or_b32_e32 v1, 18, v0
	s_nop 0
	v_cndmask_b32_e32 v29, v252, v29, vcc
	v_cmp_le_i32_e32 vcc, v1, v212
	v_or_b32_e32 v1, 50, v0
	s_nop 0
	v_cndmask_b32_e32 v14, v252, v14, vcc
	v_cmp_le_i32_e32 vcc, v1, v212
	v_or_b32_e32 v1, 19, v0
	s_nop 0
	v_cndmask_b32_e32 v30, v252, v30, vcc
	v_cmp_le_i32_e32 vcc, v1, v212
	v_or_b32_e32 v1, 51, v0
	s_nop 0
	v_cndmask_b32_e32 v15, v252, v15, vcc
	v_cmp_le_i32_e32 vcc, v1, v212
	v_or_b32_e32 v1, 24, v0
	s_nop 0
	v_cndmask_b32_e32 v31, v252, v31, vcc
	v_cmp_le_i32_e32 vcc, v1, v212
	v_or_b32_e32 v1, 56, v0
	s_nop 0
	v_cndmask_b32_e32 v16, v252, v16, vcc
	v_cmp_le_i32_e32 vcc, v1, v212
	v_or_b32_e32 v1, 25, v0
	s_nop 0
	v_cndmask_b32_e32 v32, v252, v32, vcc
	v_cmp_le_i32_e32 vcc, v1, v212
	v_or_b32_e32 v1, 57, v0
	s_nop 0
	v_cndmask_b32_e32 v17, v252, v17, vcc
	v_cmp_le_i32_e32 vcc, v1, v212
	v_or_b32_e32 v1, 26, v0
	s_nop 0
	v_cndmask_b32_e32 v33, v252, v33, vcc
	v_cmp_le_i32_e32 vcc, v1, v212
	v_or_b32_e32 v1, 58, v0
	s_nop 0
	v_cndmask_b32_e32 v18, v252, v18, vcc
	v_cmp_le_i32_e32 vcc, v1, v212
	v_or_b32_e32 v1, 27, v0
	v_or_b32_e32 v0, 59, v0
	v_cndmask_b32_e32 v34, v252, v34, vcc
	v_cmp_le_i32_e32 vcc, v1, v212
	s_nop 1
	v_cndmask_b32_e32 v19, v252, v19, vcc
	v_cmp_le_i32_e32 vcc, v0, v212
	s_nop 1
	v_cndmask_b32_e32 v35, v252, v35, vcc
	s_branch .LBB0_1339

.LBB0_1513:
	s_ashr_i32 s27, s26, 31
	s_lshl_b64 s[0:1], s[26:27], 19
	s_add_u32 s3, s46, s0
	s_addc_u32 s13, s48, s1
	s_ashr_i32 s25, s24, 31
	s_lshl_b64 s[0:1], s[24:25], 19
	s_add_u32 s25, s49, s0
	s_addc_u32 s27, s50, s1
	s_add_i32 s55, 0, 0x10000
	s_and_b64 s[0:1], s[38:39], exec
	s_cselect_b32 s41, s13, s31
	s_cselect_b32 s40, s3, s30
	s_add_i32 s61, 0, 0x14000
	v_add_u32_e32 v2, s55, v204
	v_add_u32_e32 v112, s61, v204
	ds_read_b128 v[4:7], v2
	ds_read_b128 v[8:11], v2 offset:1024
	ds_read_b128 v[12:15], v2 offset:2048
	ds_read_b128 v[16:19], v2 offset:3072
	ds_read_b128 v[20:23], v112
	ds_read_b128 v[24:27], v112 offset:1024
	ds_read_b128 v[28:31], v112 offset:2048
	ds_read_b128 v[32:35], v112 offset:3072
	s_and_b64 s[0:1], s[38:39], exec
	v_mov_b32_e32 v253, 0x3eaaaaab
	v_mov_b32_e32 v252, 0x260
	s_cselect_b32 s43, s27, s29
	s_cselect_b32 s42, s25, s28
	s_add_u32 s34, s30, 0x40080
	s_addc_u32 s35, s31, 0
	s_add_i32 s0, s51, 0xc000
	v_lshl_add_u64 v[68:69], s[34:35], 0, v[0:1]
	s_mov_b32 m0, s0
	s_add_i32 s1, s51, 0xe000
	ds_read_b128 v[36:39], v205
	ds_read_b128 v[40:43], v205 offset:1024
	ds_read_b128 v[44:47], v205 offset:2048
	ds_read_b128 v[48:51], v205 offset:3072
	ds_read_b128 v[52:55], v205 offset:4096
	ds_read_b128 v[56:59], v205 offset:5120
	ds_read_b128 v[60:63], v205 offset:6144
	ds_read_b128 v[64:67], v205 offset:7168
	global_load_lds_dwordx4 v[68:69], off
	v_lshl_add_u64 v[68:69], s[34:35], 0, v[162:163]
	s_mov_b32 m0, s1
	s_nop 0
	global_load_lds_dwordx4 v[68:69], off
	s_waitcnt vmcnt(8)
	s_waitcnt lgkmcnt(0)
	s_setprio 1
	s_barrier
	v_mfma_f32_16x16x32_bf16 v[68:71], v[4:7], v[36:39], 0
	v_mfma_f32_16x16x32_bf16 v[72:75], v[12:15], v[36:39], 0
	v_mfma_f32_16x16x32_bf16 v[76:79], v[4:7], v[44:47], 0
	v_mfma_f32_16x16x32_bf16 v[80:83], v[12:15], v[44:47], 0
	v_mfma_f32_16x16x32_bf16 v[84:87], v[4:7], v[52:55], 0
	v_mfma_f32_16x16x32_bf16 v[88:91], v[12:15], v[52:55], 0
	v_mfma_f32_16x16x32_bf16 v[92:95], v[4:7], v[60:63], 0
	v_mfma_f32_16x16x32_bf16 v[96:99], v[12:15], v[60:63], 0
	v_mfma_f32_16x16x32_bf16 v[68:71], v[8:11], v[40:43], v[68:71]
	v_mfma_f32_16x16x32_bf16 v[72:75], v[16:19], v[40:43], v[72:75]
	v_mfma_f32_16x16x32_bf16 v[76:79], v[8:11], v[48:51], v[76:79]
	v_mfma_f32_16x16x32_bf16 v[80:83], v[16:19], v[48:51], v[80:83]
	v_mfma_f32_16x16x32_bf16 v[84:87], v[8:11], v[56:59], v[84:87]
	v_mfma_f32_16x16x32_bf16 v[88:91], v[16:19], v[56:59], v[88:91]
	v_mfma_f32_16x16x32_bf16 v[92:95], v[8:11], v[64:67], v[92:95]
	v_mfma_f32_16x16x32_bf16 v[96:99], v[16:19], v[64:67], v[96:99]
	v_mfma_f32_16x16x32_bf16 v[100:103], v[20:23], v[36:39], 0
	v_mfma_f32_16x16x32_bf16 v[36:39], v[28:31], v[36:39], 0
	v_mfma_f32_16x16x32_bf16 v[104:107], v[24:27], v[40:43], v[100:103]
	v_mfma_f32_16x16x32_bf16 v[36:39], v[32:35], v[40:43], v[36:39]
	v_mfma_f32_16x16x32_bf16 v[40:43], v[20:23], v[44:47], 0
	v_mfma_f32_16x16x32_bf16 v[44:47], v[28:31], v[44:47], 0
	v_mfma_f32_16x16x32_bf16 v[40:43], v[24:27], v[48:51], v[40:43]
	v_mfma_f32_16x16x32_bf16 v[44:47], v[32:35], v[48:51], v[44:47]
	v_mfma_f32_16x16x32_bf16 v[48:51], v[20:23], v[52:55], 0
	v_mfma_f32_16x16x32_bf16 v[52:55], v[28:31], v[52:55], 0
	v_mfma_f32_16x16x32_bf16 v[48:51], v[24:27], v[56:59], v[48:51]
	v_mfma_f32_16x16x32_bf16 v[108:111], v[32:35], v[56:59], v[52:55]
	v_mfma_f32_16x16x32_bf16 v[52:55], v[20:23], v[60:63], 0
	s_nop 0
	v_mfma_f32_16x16x32_bf16 v[120:123], v[24:27], v[64:67], v[52:55]
	v_mfma_f32_16x16x32_bf16 v[52:55], v[28:31], v[60:63], 0
	s_nop 0
	v_mfma_f32_16x16x32_bf16 v[132:135], v[32:35], v[64:67], v[52:55]
	s_barrier
	s_setprio 0
	s_add_i32 s3, s55, s45
	v_lshl_add_u64 v[198:199], s[28:29], 0, v[160:161]
	s_mov_b64 s[76:77], 0x100
	s_add_i32 s13, s3, 0x2000
	v_lshl_add_u64 v[118:119], v[198:199], 0, s[76:77]
	s_mov_b32 m0, s3
	v_lshl_add_u64 v[246:247], s[28:29], 0, v[164:165]
	s_add_u32 s34, s28, 0x40100
	ds_read_b128 v[52:55], v205 offset:16384
	ds_read_b128 v[56:59], v205 offset:17408
	ds_read_b128 v[60:63], v205 offset:18432
	ds_read_b128 v[64:67], v205 offset:19456
	ds_read_b128 v[100:103], v205 offset:20480
	ds_read_b128 v[114:117], v205 offset:21504
	ds_read_b128 v[124:127], v205 offset:22528
	ds_read_b128 v[128:131], v205 offset:23552
	global_load_lds_dwordx4 v[118:119], off
	v_lshl_add_u64 v[118:119], v[246:247], 0, s[76:77]
	s_mov_b32 m0, s13
	s_addc_u32 s35, s29, 0
	s_add_i32 s25, s61, s45
	global_load_lds_dwordx4 v[118:119], off
	v_lshl_add_u64 v[118:119], s[34:35], 0, v[160:161]
	s_mov_b32 m0, s25
	s_add_i32 s27, s25, 0x2000
	global_load_lds_dwordx4 v[118:119], off
	v_lshl_add_u64 v[118:119], s[34:35], 0, v[164:165]
	s_mov_b32 m0, s27
	v_lshl_add_u64 v[248:249], s[30:31], 0, v[0:1]
	global_load_lds_dwordx4 v[118:119], off
	v_lshl_add_u64 v[118:119], v[248:249], 0, s[76:77]
	s_mov_b32 m0, s51
	v_lshl_add_u64 v[250:251], s[30:31], 0, v[162:163]
	global_load_lds_dwordx4 v[118:119], off
	v_lshl_add_u64 v[118:119], v[250:251], 0, s[76:77]
	s_mov_b32 m0, s56
	s_nop 0
	global_load_lds_dwordx4 v[118:119], off
	s_waitcnt vmcnt(8)
	s_waitcnt lgkmcnt(0)
	s_setprio 1
	s_barrier
	v_mfma_f32_16x16x32_bf16 v[136:139], v[4:7], v[52:55], 0
	s_nop 0
	v_mfma_f32_16x16x32_bf16 v[144:147], v[8:11], v[56:59], v[136:139]
	v_mfma_f32_16x16x32_bf16 v[136:139], v[12:15], v[52:55], 0
	s_nop 0
	v_mfma_f32_16x16x32_bf16 v[148:151], v[16:19], v[56:59], v[136:139]
	v_mfma_f32_16x16x32_bf16 v[136:139], v[4:7], v[60:63], 0
	s_nop 0
	v_mfma_f32_16x16x32_bf16 v[152:155], v[8:11], v[64:67], v[136:139]
	v_mfma_f32_16x16x32_bf16 v[136:139], v[12:15], v[60:63], 0
	s_nop 0
	v_mfma_f32_16x16x32_bf16 v[156:159], v[16:19], v[64:67], v[136:139]
	v_mfma_f32_16x16x32_bf16 v[136:139], v[4:7], v[100:103], 0
	v_mfma_f32_16x16x32_bf16 v[4:7], v[4:7], v[124:127], 0
	v_mfma_f32_16x16x32_bf16 v[170:173], v[8:11], v[114:117], v[136:139]
	v_mfma_f32_16x16x32_bf16 v[4:7], v[8:11], v[128:131], v[4:7]
	v_mfma_f32_16x16x32_bf16 v[8:11], v[12:15], v[124:127], 0
	s_nop 0
	v_mfma_f32_16x16x32_bf16 v[8:11], v[16:19], v[128:131], v[8:11]
	v_mfma_f32_16x16x32_bf16 v[136:139], v[12:15], v[100:103], 0
	s_nop 0
	v_mfma_f32_16x16x32_bf16 v[174:177], v[16:19], v[114:117], v[136:139]
	v_mfma_f32_16x16x32_bf16 v[12:15], v[20:23], v[52:55], 0
	v_mfma_f32_16x16x32_bf16 v[16:19], v[28:31], v[52:55], 0
	v_mfma_f32_16x16x32_bf16 v[52:55], v[20:23], v[60:63], 0
	s_nop 0
	v_mfma_f32_16x16x32_bf16 v[178:181], v[24:27], v[64:67], v[52:55]
	v_mfma_f32_16x16x32_bf16 v[52:55], v[28:31], v[60:63], 0
	v_mfma_f32_16x16x32_bf16 v[12:15], v[24:27], v[56:59], v[12:15]
	v_mfma_f32_16x16x32_bf16 v[16:19], v[32:35], v[56:59], v[16:19]
	v_mfma_f32_16x16x32_bf16 v[182:185], v[32:35], v[64:67], v[52:55]
	v_mfma_f32_16x16x32_bf16 v[52:55], v[20:23], v[100:103], 0
	v_mfma_f32_16x16x32_bf16 v[20:23], v[20:23], v[124:127], 0
	v_mfma_f32_16x16x32_bf16 v[186:189], v[24:27], v[114:117], v[52:55]
	v_mfma_f32_16x16x32_bf16 v[52:55], v[28:31], v[100:103], 0
	v_mfma_f32_16x16x32_bf16 v[194:197], v[24:27], v[128:131], v[20:23]
	v_mfma_f32_16x16x32_bf16 v[20:23], v[28:31], v[124:127], 0
	v_mfma_f32_16x16x32_bf16 v[190:193], v[32:35], v[114:117], v[52:55]
	v_mfma_f32_16x16x32_bf16 v[200:203], v[32:35], v[128:131], v[20:23]
	s_barrier
	s_setprio 0
	s_add_i32 s55, 0, 0x18000
	s_add_i32 s62, 0, 0x1c000
	v_add_u32_e32 v113, s55, v204
	v_add_u32_e32 v114, s62, v204
	ds_read_b128 v[20:23], v113
	ds_read_b128 v[24:27], v113 offset:1024
	ds_read_b128 v[28:31], v113 offset:2048
	ds_read_b128 v[32:35], v113 offset:3072
	ds_read_b128 v[206:209], v114
	ds_read_b128 v[210:213], v114 offset:1024
	ds_read_b128 v[214:217], v114 offset:2048
	ds_read_b128 v[218:221], v114 offset:3072
	s_add_u32 s34, s30, 0x40100
	s_addc_u32 s35, s31, 0
	s_mov_b32 m0, s57
	v_lshl_add_u64 v[60:61], s[34:35], 0, v[0:1]
	ds_read_b128 v[52:55], v205 offset:32768
	ds_read_b128 v[56:59], v205 offset:33792
	ds_read_b128 v[222:225], v205 offset:34816
	ds_read_b128 v[226:229], v205 offset:35840
	ds_read_b128 v[230:233], v205 offset:36864
	ds_read_b128 v[234:237], v205 offset:37888
	ds_read_b128 v[238:241], v205 offset:38912
	ds_read_b128 v[242:245], v205 offset:39936
	global_load_lds_dwordx4 v[60:61], off
	v_lshl_add_u64 v[60:61], s[34:35], 0, v[162:163]
	s_mov_b32 m0, s58
	s_nop 0
	global_load_lds_dwordx4 v[60:61], off
	s_waitcnt vmcnt(8)
	s_waitcnt lgkmcnt(0)
	s_setprio 1
	s_barrier
	v_mfma_f32_16x16x32_bf16 v[60:63], v[20:23], v[52:55], v[68:71]
	v_mfma_f32_16x16x32_bf16 v[140:143], v[24:27], v[56:59], v[60:63]
	v_mfma_f32_16x16x32_bf16 v[60:63], v[28:31], v[52:55], v[72:75]
	v_mfma_f32_16x16x32_bf16 v[136:139], v[32:35], v[56:59], v[60:63]
	v_mfma_f32_16x16x32_bf16 v[60:63], v[20:23], v[222:225], v[76:79]
	v_mfma_f32_16x16x32_bf16 v[128:131], v[24:27], v[226:229], v[60:63]
	v_mfma_f32_16x16x32_bf16 v[60:63], v[28:31], v[222:225], v[80:83]
	v_mfma_f32_16x16x32_bf16 v[124:127], v[32:35], v[226:229], v[60:63]
	v_mfma_f32_16x16x32_bf16 v[60:63], v[20:23], v[230:233], v[84:87]
	v_mfma_f32_16x16x32_bf16 v[116:119], v[24:27], v[234:237], v[60:63]
	v_mfma_f32_16x16x32_bf16 v[60:63], v[28:31], v[230:233], v[88:91]
	v_mfma_f32_16x16x32_bf16 v[100:103], v[32:35], v[234:237], v[60:63]
	v_mfma_f32_16x16x32_bf16 v[60:63], v[20:23], v[238:241], v[92:95]
	v_mfma_f32_16x16x32_bf16 v[88:91], v[24:27], v[242:245], v[60:63]
	v_mfma_f32_16x16x32_bf16 v[60:63], v[28:31], v[238:241], v[96:99]
	v_mfma_f32_16x16x32_bf16 v[76:79], v[32:35], v[242:245], v[60:63]
	v_mfma_f32_16x16x32_bf16 v[60:63], v[206:209], v[52:55], v[104:107]
	v_mfma_f32_16x16x32_bf16 v[36:39], v[214:217], v[52:55], v[36:39]
	v_mfma_f32_16x16x32_bf16 v[64:67], v[210:213], v[56:59], v[60:63]
	v_mfma_f32_16x16x32_bf16 v[60:63], v[218:221], v[56:59], v[36:39]
	v_mfma_f32_16x16x32_bf16 v[36:39], v[206:209], v[222:225], v[40:43]
	v_mfma_f32_16x16x32_bf16 v[56:59], v[210:213], v[226:229], v[36:39]
	v_mfma_f32_16x16x32_bf16 v[36:39], v[214:217], v[222:225], v[44:47]
	v_mfma_f32_16x16x32_bf16 v[52:55], v[218:221], v[226:229], v[36:39]
	v_mfma_f32_16x16x32_bf16 v[36:39], v[206:209], v[230:233], v[48:51]
	v_mfma_f32_16x16x32_bf16 v[48:51], v[210:213], v[234:237], v[36:39]
	v_mfma_f32_16x16x32_bf16 v[36:39], v[214:217], v[230:233], v[108:111]
	v_mfma_f32_16x16x32_bf16 v[44:47], v[218:221], v[234:237], v[36:39]
	v_mfma_f32_16x16x32_bf16 v[36:39], v[206:209], v[238:241], v[120:123]
	v_mfma_f32_16x16x32_bf16 v[40:43], v[210:213], v[242:245], v[36:39]
	v_mfma_f32_16x16x32_bf16 v[36:39], v[214:217], v[238:241], v[132:135]
	v_mfma_f32_16x16x32_bf16 v[36:39], v[218:221], v[242:245], v[36:39]
	s_barrier
	s_setprio 0
	s_add_i32 s55, s55, s45
	s_add_i32 s61, s55, 0x2000
	v_lshl_add_u64 v[68:69], v[198:199], 0, s[84:85]
	s_mov_b32 m0, s55
	s_add_u32 s34, s28, 0x40180
	ds_read_b128 v[120:123], v205 offset:49152
	ds_read_b128 v[132:135], v205 offset:50176
	ds_read_b128 v[222:225], v205 offset:51200
	ds_read_b128 v[226:229], v205 offset:52224
	ds_read_b128 v[230:233], v205 offset:53248
	ds_read_b128 v[234:237], v205 offset:54272
	ds_read_b128 v[238:241], v205 offset:55296
	ds_read_b128 v[242:245], v205 offset:56320
	global_load_lds_dwordx4 v[68:69], off
	v_lshl_add_u64 v[68:69], v[246:247], 0, s[84:85]
	s_mov_b32 m0, s61
	s_addc_u32 s35, s29, 0
	s_add_i32 s62, s62, s45
	global_load_lds_dwordx4 v[68:69], off
	v_lshl_add_u64 v[68:69], s[34:35], 0, v[160:161]
	s_mov_b32 m0, s62
	s_add_i32 s76, s62, 0x2000
	global_load_lds_dwordx4 v[68:69], off
	v_lshl_add_u64 v[68:69], s[34:35], 0, v[164:165]
	s_mov_b32 m0, s76
	s_nop 0
	global_load_lds_dwordx4 v[68:69], off
	v_lshl_add_u64 v[68:69], v[248:249], 0, s[84:85]
	s_mov_b32 m0, s52
	s_nop 0
	global_load_lds_dwordx4 v[68:69], off
	v_lshl_add_u64 v[68:69], v[250:251], 0, s[84:85]
	s_mov_b32 m0, s53
	s_nop 0
	global_load_lds_dwordx4 v[68:69], off
	s_waitcnt vmcnt(8)
	s_waitcnt lgkmcnt(0)
	s_setprio 1
	s_barrier
	v_mfma_f32_16x16x32_bf16 v[68:71], v[20:23], v[120:123], v[144:147]
	v_mfma_f32_16x16x32_bf16 v[108:111], v[24:27], v[132:135], v[68:71]
	v_mfma_f32_16x16x32_bf16 v[68:71], v[28:31], v[120:123], v[148:151]
	v_mfma_f32_16x16x32_bf16 v[104:107], v[32:35], v[132:135], v[68:71]
	v_mfma_f32_16x16x32_bf16 v[68:71], v[20:23], v[222:225], v[152:155]
	v_mfma_f32_16x16x32_bf16 v[96:99], v[24:27], v[226:229], v[68:71]
	v_mfma_f32_16x16x32_bf16 v[68:71], v[28:31], v[222:225], v[156:159]
	v_mfma_f32_16x16x32_bf16 v[92:95], v[32:35], v[226:229], v[68:71]
	v_mfma_f32_16x16x32_bf16 v[68:71], v[20:23], v[230:233], v[170:173]
	v_mfma_f32_16x16x32_bf16 v[4:7], v[20:23], v[238:241], v[4:7]
	v_mfma_f32_16x16x32_bf16 v[84:87], v[24:27], v[234:237], v[68:71]
	v_mfma_f32_16x16x32_bf16 v[68:71], v[28:31], v[230:233], v[174:177]
	v_mfma_f32_16x16x32_bf16 v[72:75], v[24:27], v[242:245], v[4:7]
	v_mfma_f32_16x16x32_bf16 v[4:7], v[28:31], v[238:241], v[8:11]
	v_mfma_f32_16x16x32_bf16 v[80:83], v[32:35], v[234:237], v[68:71]
	v_mfma_f32_16x16x32_bf16 v[68:71], v[32:35], v[242:245], v[4:7]
	v_mfma_f32_16x16x32_bf16 v[4:7], v[206:209], v[120:123], v[12:15]
	v_mfma_f32_16x16x32_bf16 v[32:35], v[210:213], v[132:135], v[4:7]
	v_mfma_f32_16x16x32_bf16 v[4:7], v[214:217], v[120:123], v[16:19]
	v_mfma_f32_16x16x32_bf16 v[28:31], v[218:221], v[132:135], v[4:7]
	v_mfma_f32_16x16x32_bf16 v[4:7], v[206:209], v[222:225], v[178:181]
	v_mfma_f32_16x16x32_bf16 v[24:27], v[210:213], v[226:229], v[4:7]
	v_mfma_f32_16x16x32_bf16 v[4:7], v[214:217], v[222:225], v[182:185]
	v_mfma_f32_16x16x32_bf16 v[20:23], v[218:221], v[226:229], v[4:7]
	v_mfma_f32_16x16x32_bf16 v[4:7], v[206:209], v[230:233], v[186:189]
	v_mfma_f32_16x16x32_bf16 v[16:19], v[210:213], v[234:237], v[4:7]
	v_mfma_f32_16x16x32_bf16 v[4:7], v[214:217], v[230:233], v[190:193]
	v_mfma_f32_16x16x32_bf16 v[12:15], v[218:221], v[234:237], v[4:7]
	v_mfma_f32_16x16x32_bf16 v[4:7], v[206:209], v[238:241], v[194:197]
	v_mfma_f32_16x16x32_bf16 v[8:11], v[210:213], v[242:245], v[4:7]
	v_mfma_f32_16x16x32_bf16 v[4:7], v[214:217], v[238:241], v[200:203]
	v_mfma_f32_16x16x32_bf16 v[4:7], v[218:221], v[242:245], v[4:7]
	s_barrier
	s_setprio 0
	s_add_u32 s30, s30, 0x40180
	s_addc_u32 s31, s31, 0
	s_add_u32 s77, s28, 0x200
	s_addc_u32 s79, s29, 0
	s_mov_b32 s80, 0
.LBB0_1514:
	ds_read_b128 v[120:123], v2
	ds_read_b128 v[132:135], v2 offset:1024
	ds_read_b128 v[144:147], v2 offset:2048
	ds_read_b128 v[148:151], v2 offset:3072
	ds_read_b128 v[152:155], v112
	ds_read_b128 v[156:159], v112 offset:1024
	ds_read_b128 v[170:173], v112 offset:2048
	ds_read_b128 v[174:177], v112 offset:3072
	s_add_u32 s28, s30, 0xfffc0080
	s_addc_u32 s29, s31, -1
	s_cmp_eq_u32 s80, 12
	s_cselect_b32 s35, s41, s29
	s_cselect_b32 s34, s40, s28
	s_cselect_b32 s29, s43, s79
	s_cselect_b32 s28, s42, s77
	s_mov_b32 m0, s0
	v_lshl_add_u64 v[198:199], s[30:31], 0, v[166:167]
	ds_read_b128 v[178:181], v205
	ds_read_b128 v[182:185], v205 offset:1024
	ds_read_b128 v[186:189], v205 offset:2048
	ds_read_b128 v[190:193], v205 offset:3072
	ds_read_b128 v[194:197], v205 offset:4096
	ds_read_b128 v[200:203], v205 offset:5120
	ds_read_b128 v[206:209], v205 offset:6144
	ds_read_b128 v[210:213], v205 offset:7168
	global_load_lds_dwordx4 v[198:199], off
	v_lshl_add_u64 v[198:199], s[30:31], 0, v[168:169]
	s_mov_b32 m0, s1
	s_nop 0
	global_load_lds_dwordx4 v[198:199], off
	s_waitcnt vmcnt(8)
	s_waitcnt lgkmcnt(0)
	s_setprio 1
	s_barrier
	v_mfma_f32_16x16x32_bf16 v[140:143], v[120:123], v[178:181], v[140:143]
	v_mfma_f32_16x16x32_bf16 v[136:139], v[144:147], v[178:181], v[136:139]
	v_mfma_f32_16x16x32_bf16 v[128:131], v[120:123], v[186:189], v[128:131]
	v_mfma_f32_16x16x32_bf16 v[124:127], v[144:147], v[186:189], v[124:127]
	v_mfma_f32_16x16x32_bf16 v[116:119], v[120:123], v[194:197], v[116:119]
	v_mfma_f32_16x16x32_bf16 v[100:103], v[144:147], v[194:197], v[100:103]
	v_mfma_f32_16x16x32_bf16 v[88:91], v[120:123], v[206:209], v[88:91]
	v_mfma_f32_16x16x32_bf16 v[76:79], v[144:147], v[206:209], v[76:79]
	v_mfma_f32_16x16x32_bf16 v[140:143], v[132:135], v[182:185], v[140:143]
	v_mfma_f32_16x16x32_bf16 v[136:139], v[148:151], v[182:185], v[136:139]
	v_mfma_f32_16x16x32_bf16 v[128:131], v[132:135], v[190:193], v[128:131]
	v_mfma_f32_16x16x32_bf16 v[124:127], v[148:151], v[190:193], v[124:127]
	v_mfma_f32_16x16x32_bf16 v[116:119], v[132:135], v[200:203], v[116:119]
	v_mfma_f32_16x16x32_bf16 v[100:103], v[148:151], v[200:203], v[100:103]
	v_mfma_f32_16x16x32_bf16 v[88:91], v[132:135], v[210:213], v[88:91]
	v_mfma_f32_16x16x32_bf16 v[76:79], v[148:151], v[210:213], v[76:79]
	v_mfma_f32_16x16x32_bf16 v[64:67], v[152:155], v[178:181], v[64:67]
	v_mfma_f32_16x16x32_bf16 v[60:63], v[170:173], v[178:181], v[60:63]
	v_mfma_f32_16x16x32_bf16 v[56:59], v[152:155], v[186:189], v[56:59]
	v_mfma_f32_16x16x32_bf16 v[52:55], v[170:173], v[186:189], v[52:55]
	v_mfma_f32_16x16x32_bf16 v[48:51], v[152:155], v[194:197], v[48:51]
	v_mfma_f32_16x16x32_bf16 v[44:47], v[170:173], v[194:197], v[44:47]
	v_mfma_f32_16x16x32_bf16 v[40:43], v[152:155], v[206:209], v[40:43]
	v_mfma_f32_16x16x32_bf16 v[36:39], v[170:173], v[206:209], v[36:39]
	v_mfma_f32_16x16x32_bf16 v[64:67], v[156:159], v[182:185], v[64:67]
	v_mfma_f32_16x16x32_bf16 v[60:63], v[174:177], v[182:185], v[60:63]
	v_mfma_f32_16x16x32_bf16 v[56:59], v[156:159], v[190:193], v[56:59]
	v_mfma_f32_16x16x32_bf16 v[52:55], v[174:177], v[190:193], v[52:55]
	v_mfma_f32_16x16x32_bf16 v[48:51], v[156:159], v[200:203], v[48:51]
	v_mfma_f32_16x16x32_bf16 v[44:47], v[174:177], v[200:203], v[44:47]
	v_mfma_f32_16x16x32_bf16 v[40:43], v[156:159], v[210:213], v[40:43]
	v_mfma_f32_16x16x32_bf16 v[36:39], v[174:177], v[210:213], v[36:39]
	s_barrier
	s_setprio 0
	s_mov_b32 m0, s3
	v_lshl_add_u64 v[198:199], s[28:29], 0, v[160:161]
	s_add_u32 s90, s28, 0x40000
	ds_read_b128 v[178:181], v205 offset:16384
	ds_read_b128 v[182:185], v205 offset:17408
	ds_read_b128 v[186:189], v205 offset:18432
	ds_read_b128 v[190:193], v205 offset:19456
	ds_read_b128 v[194:197], v205 offset:20480
	ds_read_b128 v[200:203], v205 offset:21504
	ds_read_b128 v[206:209], v205 offset:22528
	ds_read_b128 v[210:213], v205 offset:23552
	global_load_lds_dwordx4 v[198:199], off
	v_lshl_add_u64 v[214:215], s[28:29], 0, v[164:165]
	s_mov_b32 m0, s13
	s_addc_u32 s91, s29, 0
	global_load_lds_dwordx4 v[214:215], off
	v_lshl_add_u64 v[216:217], s[90:91], 0, v[160:161]
	s_mov_b32 m0, s25
	v_lshl_add_u64 v[218:219], s[34:35], 0, v[162:163]
	global_load_lds_dwordx4 v[216:217], off
	v_lshl_add_u64 v[216:217], s[90:91], 0, v[164:165]
	s_mov_b32 m0, s27
	s_nop 0
	global_load_lds_dwordx4 v[216:217], off
	v_lshl_add_u64 v[216:217], s[34:35], 0, v[0:1]
	s_mov_b32 m0, s51
	s_nop 0
	global_load_lds_dwordx4 v[216:217], off
	s_mov_b32 m0, s56
	s_nop 0
	global_load_lds_dwordx4 v[218:219], off
	s_waitcnt vmcnt(8)
	s_waitcnt lgkmcnt(0)
	s_setprio 1
	s_barrier
	v_mfma_f32_16x16x32_bf16 v[108:111], v[120:123], v[178:181], v[108:111]
	v_mfma_f32_16x16x32_bf16 v[104:107], v[144:147], v[178:181], v[104:107]
	v_mfma_f32_16x16x32_bf16 v[96:99], v[120:123], v[186:189], v[96:99]
	v_mfma_f32_16x16x32_bf16 v[92:95], v[144:147], v[186:189], v[92:95]
	v_mfma_f32_16x16x32_bf16 v[84:87], v[120:123], v[194:197], v[84:87]
	v_mfma_f32_16x16x32_bf16 v[80:83], v[144:147], v[194:197], v[80:83]
	v_mfma_f32_16x16x32_bf16 v[72:75], v[120:123], v[206:209], v[72:75]
	v_mfma_f32_16x16x32_bf16 v[68:71], v[144:147], v[206:209], v[68:71]
	v_mfma_f32_16x16x32_bf16 v[108:111], v[132:135], v[182:185], v[108:111]
	v_mfma_f32_16x16x32_bf16 v[104:107], v[148:151], v[182:185], v[104:107]
	v_mfma_f32_16x16x32_bf16 v[96:99], v[132:135], v[190:193], v[96:99]
	v_mfma_f32_16x16x32_bf16 v[92:95], v[148:151], v[190:193], v[92:95]
	v_mfma_f32_16x16x32_bf16 v[84:87], v[132:135], v[200:203], v[84:87]
	v_mfma_f32_16x16x32_bf16 v[80:83], v[148:151], v[200:203], v[80:83]
	v_mfma_f32_16x16x32_bf16 v[72:75], v[132:135], v[210:213], v[72:75]
	v_mfma_f32_16x16x32_bf16 v[68:71], v[148:151], v[210:213], v[68:71]
	v_mfma_f32_16x16x32_bf16 v[32:35], v[152:155], v[178:181], v[32:35]
	v_mfma_f32_16x16x32_bf16 v[28:31], v[170:173], v[178:181], v[28:31]
	v_mfma_f32_16x16x32_bf16 v[24:27], v[152:155], v[186:189], v[24:27]
	v_mfma_f32_16x16x32_bf16 v[20:23], v[170:173], v[186:189], v[20:23]
	v_mfma_f32_16x16x32_bf16 v[16:19], v[152:155], v[194:197], v[16:19]
	v_mfma_f32_16x16x32_bf16 v[12:15], v[170:173], v[194:197], v[12:15]
	v_mfma_f32_16x16x32_bf16 v[8:11], v[152:155], v[206:209], v[8:11]
	v_mfma_f32_16x16x32_bf16 v[4:7], v[170:173], v[206:209], v[4:7]
	v_mfma_f32_16x16x32_bf16 v[32:35], v[156:159], v[182:185], v[32:35]
	v_mfma_f32_16x16x32_bf16 v[28:31], v[174:177], v[182:185], v[28:31]
	v_mfma_f32_16x16x32_bf16 v[24:27], v[156:159], v[190:193], v[24:27]
	v_mfma_f32_16x16x32_bf16 v[20:23], v[174:177], v[190:193], v[20:23]
	v_mfma_f32_16x16x32_bf16 v[16:19], v[156:159], v[200:203], v[16:19]
	v_mfma_f32_16x16x32_bf16 v[12:15], v[174:177], v[200:203], v[12:15]
	v_mfma_f32_16x16x32_bf16 v[8:11], v[156:159], v[210:213], v[8:11]
	v_mfma_f32_16x16x32_bf16 v[4:7], v[174:177], v[210:213], v[4:7]
	s_barrier
	s_setprio 0
	ds_read_b128 v[120:123], v113
	ds_read_b128 v[132:135], v113 offset:1024
	ds_read_b128 v[144:147], v113 offset:2048
	ds_read_b128 v[148:151], v113 offset:3072
	ds_read_b128 v[152:155], v114
	ds_read_b128 v[156:159], v114 offset:1024
	ds_read_b128 v[170:173], v114 offset:2048
	ds_read_b128 v[174:177], v114 offset:3072
	s_add_u32 s34, s34, 0x40000
	s_addc_u32 s35, s35, 0
	s_mov_b32 m0, s57
	v_lshl_add_u64 v[220:221], s[34:35], 0, v[0:1]
	ds_read_b128 v[178:181], v205 offset:32768
	ds_read_b128 v[182:185], v205 offset:33792
	ds_read_b128 v[186:189], v205 offset:34816
	ds_read_b128 v[190:193], v205 offset:35840
	ds_read_b128 v[194:197], v205 offset:36864
	ds_read_b128 v[200:203], v205 offset:37888
	ds_read_b128 v[206:209], v205 offset:38912
	ds_read_b128 v[210:213], v205 offset:39936
	global_load_lds_dwordx4 v[220:221], off
	v_lshl_add_u64 v[220:221], s[34:35], 0, v[162:163]
	s_mov_b32 m0, s58
	s_nop 0
	global_load_lds_dwordx4 v[220:221], off
	s_waitcnt vmcnt(8)
	s_waitcnt lgkmcnt(0)
	s_setprio 1
	s_barrier
	v_mfma_f32_16x16x32_bf16 v[140:143], v[120:123], v[178:181], v[140:143]
	v_mfma_f32_16x16x32_bf16 v[136:139], v[144:147], v[178:181], v[136:139]
	v_mfma_f32_16x16x32_bf16 v[128:131], v[120:123], v[186:189], v[128:131]
	v_mfma_f32_16x16x32_bf16 v[124:127], v[144:147], v[186:189], v[124:127]
	v_mfma_f32_16x16x32_bf16 v[116:119], v[120:123], v[194:197], v[116:119]
	v_mfma_f32_16x16x32_bf16 v[100:103], v[144:147], v[194:197], v[100:103]
	v_mfma_f32_16x16x32_bf16 v[88:91], v[120:123], v[206:209], v[88:91]
	v_mfma_f32_16x16x32_bf16 v[76:79], v[144:147], v[206:209], v[76:79]
	v_mfma_f32_16x16x32_bf16 v[140:143], v[132:135], v[182:185], v[140:143]
	v_mfma_f32_16x16x32_bf16 v[136:139], v[148:151], v[182:185], v[136:139]
	v_mfma_f32_16x16x32_bf16 v[128:131], v[132:135], v[190:193], v[128:131]
	v_mfma_f32_16x16x32_bf16 v[124:127], v[148:151], v[190:193], v[124:127]
	v_mfma_f32_16x16x32_bf16 v[116:119], v[132:135], v[200:203], v[116:119]
	v_mfma_f32_16x16x32_bf16 v[100:103], v[148:151], v[200:203], v[100:103]
	v_mfma_f32_16x16x32_bf16 v[88:91], v[132:135], v[210:213], v[88:91]
	v_mfma_f32_16x16x32_bf16 v[76:79], v[148:151], v[210:213], v[76:79]
	v_mfma_f32_16x16x32_bf16 v[64:67], v[152:155], v[178:181], v[64:67]
	v_mfma_f32_16x16x32_bf16 v[60:63], v[170:173], v[178:181], v[60:63]
	v_mfma_f32_16x16x32_bf16 v[56:59], v[152:155], v[186:189], v[56:59]
	v_mfma_f32_16x16x32_bf16 v[52:55], v[170:173], v[186:189], v[52:55]
	v_mfma_f32_16x16x32_bf16 v[48:51], v[152:155], v[194:197], v[48:51]
	v_mfma_f32_16x16x32_bf16 v[44:47], v[170:173], v[194:197], v[44:47]
	v_mfma_f32_16x16x32_bf16 v[40:43], v[152:155], v[206:209], v[40:43]
	v_mfma_f32_16x16x32_bf16 v[36:39], v[170:173], v[206:209], v[36:39]
	v_mfma_f32_16x16x32_bf16 v[64:67], v[156:159], v[182:185], v[64:67]
	v_mfma_f32_16x16x32_bf16 v[60:63], v[174:177], v[182:185], v[60:63]
	v_mfma_f32_16x16x32_bf16 v[56:59], v[156:159], v[190:193], v[56:59]
	v_mfma_f32_16x16x32_bf16 v[52:55], v[174:177], v[190:193], v[52:55]
	v_mfma_f32_16x16x32_bf16 v[48:51], v[156:159], v[200:203], v[48:51]
	v_mfma_f32_16x16x32_bf16 v[44:47], v[174:177], v[200:203], v[44:47]
	v_mfma_f32_16x16x32_bf16 v[40:43], v[156:159], v[210:213], v[40:43]
	v_mfma_f32_16x16x32_bf16 v[36:39], v[174:177], v[210:213], v[36:39]
	s_barrier
	s_setprio 0
	s_mov_b32 m0, s55
	v_lshl_add_u64 v[198:199], v[198:199], 0, s[74:75]
	s_add_u32 s28, s28, 0x40080
	ds_read_b128 v[178:181], v205 offset:49152
	ds_read_b128 v[182:185], v205 offset:50176
	ds_read_b128 v[186:189], v205 offset:51200
	ds_read_b128 v[190:193], v205 offset:52224
	ds_read_b128 v[194:197], v205 offset:53248
	ds_read_b128 v[200:203], v205 offset:54272
	ds_read_b128 v[206:209], v205 offset:55296
	ds_read_b128 v[210:213], v205 offset:56320
	global_load_lds_dwordx4 v[198:199], off
	v_lshl_add_u64 v[198:199], v[214:215], 0, s[74:75]
	s_mov_b32 m0, s61
	s_addc_u32 s29, s29, 0
	global_load_lds_dwordx4 v[198:199], off
	v_lshl_add_u64 v[198:199], s[28:29], 0, v[160:161]
	s_mov_b32 m0, s62
	s_nop 0
	global_load_lds_dwordx4 v[198:199], off
	v_lshl_add_u64 v[198:199], s[28:29], 0, v[164:165]
	s_mov_b32 m0, s76
	s_nop 0
	global_load_lds_dwordx4 v[198:199], off
	v_lshl_add_u64 v[198:199], v[216:217], 0, s[74:75]
	s_mov_b32 m0, s52
	s_nop 0
	global_load_lds_dwordx4 v[198:199], off
	v_lshl_add_u64 v[198:199], v[218:219], 0, s[74:75]
	s_mov_b32 m0, s53
	s_nop 0
	global_load_lds_dwordx4 v[198:199], off
	s_waitcnt vmcnt(8)
	s_waitcnt lgkmcnt(0)
	s_setprio 1
	s_barrier
	v_mfma_f32_16x16x32_bf16 v[108:111], v[120:123], v[178:181], v[108:111]
	v_mfma_f32_16x16x32_bf16 v[104:107], v[144:147], v[178:181], v[104:107]
	v_mfma_f32_16x16x32_bf16 v[96:99], v[120:123], v[186:189], v[96:99]
	v_mfma_f32_16x16x32_bf16 v[92:95], v[144:147], v[186:189], v[92:95]
	v_mfma_f32_16x16x32_bf16 v[84:87], v[120:123], v[194:197], v[84:87]
	v_mfma_f32_16x16x32_bf16 v[80:83], v[144:147], v[194:197], v[80:83]
	v_mfma_f32_16x16x32_bf16 v[72:75], v[120:123], v[206:209], v[72:75]
	v_mfma_f32_16x16x32_bf16 v[68:71], v[144:147], v[206:209], v[68:71]
	v_mfma_f32_16x16x32_bf16 v[108:111], v[132:135], v[182:185], v[108:111]
	v_mfma_f32_16x16x32_bf16 v[104:107], v[148:151], v[182:185], v[104:107]
	v_mfma_f32_16x16x32_bf16 v[96:99], v[132:135], v[190:193], v[96:99]
	v_mfma_f32_16x16x32_bf16 v[92:95], v[148:151], v[190:193], v[92:95]
	v_mfma_f32_16x16x32_bf16 v[84:87], v[132:135], v[200:203], v[84:87]
	v_mfma_f32_16x16x32_bf16 v[80:83], v[148:151], v[200:203], v[80:83]
	v_mfma_f32_16x16x32_bf16 v[72:75], v[132:135], v[210:213], v[72:75]
	v_mfma_f32_16x16x32_bf16 v[68:71], v[148:151], v[210:213], v[68:71]
	v_mfma_f32_16x16x32_bf16 v[32:35], v[152:155], v[178:181], v[32:35]
	v_mfma_f32_16x16x32_bf16 v[28:31], v[170:173], v[178:181], v[28:31]
	v_mfma_f32_16x16x32_bf16 v[24:27], v[152:155], v[186:189], v[24:27]
	v_mfma_f32_16x16x32_bf16 v[20:23], v[170:173], v[186:189], v[20:23]
	v_mfma_f32_16x16x32_bf16 v[16:19], v[152:155], v[194:197], v[16:19]
	v_mfma_f32_16x16x32_bf16 v[12:15], v[170:173], v[194:197], v[12:15]
	v_mfma_f32_16x16x32_bf16 v[8:11], v[152:155], v[206:209], v[8:11]
	v_mfma_f32_16x16x32_bf16 v[4:7], v[170:173], v[206:209], v[4:7]
	v_mfma_f32_16x16x32_bf16 v[32:35], v[156:159], v[182:185], v[32:35]
	v_mfma_f32_16x16x32_bf16 v[28:31], v[174:177], v[182:185], v[28:31]
	v_mfma_f32_16x16x32_bf16 v[24:27], v[156:159], v[190:193], v[24:27]
	v_mfma_f32_16x16x32_bf16 v[20:23], v[174:177], v[190:193], v[20:23]
	v_mfma_f32_16x16x32_bf16 v[16:19], v[156:159], v[200:203], v[16:19]
	v_mfma_f32_16x16x32_bf16 v[12:15], v[174:177], v[200:203], v[12:15]
	v_mfma_f32_16x16x32_bf16 v[8:11], v[156:159], v[210:213], v[8:11]
	v_mfma_f32_16x16x32_bf16 v[4:7], v[174:177], v[210:213], v[4:7]
	s_barrier
	s_setprio 0
	s_add_i32 s80, s80, 2
	s_add_u32 s30, s30, 0x100
	s_addc_u32 s31, s31, 0
	s_add_u32 s77, s77, 0x100
	s_addc_u32 s79, s79, 0
	s_cmp_gt_u32 s80, 13
	s_cbranch_scc0 .LBB0_1514
	s_and_b64 vcc, exec, s[22:23]
	s_cbranch_vccz .LBB0_1517
	s_barrier

.LBB0_1647:
	s_ashr_i32 s17, s16, 31
	s_lshl_b64 s[18:19], s[16:17], 19
	s_add_u32 s17, s3, s18
	s_addc_u32 s20, s30, s19
	s_ashr_i32 s15, s14, 31
	s_lshl_b64 s[18:19], s[14:15], 19
	s_add_u32 s15, s31, s18
	s_addc_u32 s23, s34, s19
	s_add_i32 s29, 0, 0x10000
	s_and_b64 s[18:19], s[38:39], exec
	s_cselect_b32 s19, s20, s27
	s_cselect_b32 s18, s17, s26
	s_add_i32 s58, 0, 0x14000
	v_add_u32_e32 v2, s29, v174
	v_add_u32_e32 v85, s58, v174
	ds_read_b128 v[4:7], v2
	ds_read_b128 v[8:11], v2 offset:1024
	ds_read_b128 v[12:15], v2 offset:2048
	ds_read_b128 v[16:19], v2 offset:3072
	ds_read_b128 v[20:23], v85
	ds_read_b128 v[24:27], v85 offset:1024
	ds_read_b128 v[28:31], v85 offset:2048
	ds_read_b128 v[32:35], v85 offset:3072
	s_and_b64 s[20:21], s[38:39], exec
	s_cselect_b32 s21, s23, s25
	s_cselect_b32 s20, s15, s24
	s_add_u32 s54, s26, 0x40080
	s_addc_u32 s55, s27, 0
	s_add_i32 s15, s44, 0xc000
	v_lshl_add_u64 v[68:69], s[54:55], 0, v[0:1]
	s_mov_b32 m0, s15
	s_add_i32 s17, s44, 0xe000
	ds_read_b128 v[36:39], v175
	ds_read_b128 v[40:43], v175 offset:1024
	ds_read_b128 v[44:47], v175 offset:2048
	ds_read_b128 v[48:51], v175 offset:3072
	ds_read_b128 v[52:55], v175 offset:4096
	ds_read_b128 v[56:59], v175 offset:5120
	ds_read_b128 v[60:63], v175 offset:6144
	ds_read_b128 v[64:67], v175 offset:7168
	global_load_lds_dwordx4 v[68:69], off
	v_lshl_add_u64 v[68:69], s[54:55], 0, v[166:167]
	s_mov_b32 m0, s17
	s_nop 0
	global_load_lds_dwordx4 v[68:69], off
	s_waitcnt vmcnt(8)
	s_waitcnt lgkmcnt(0)
	s_setprio 1
	s_barrier
	v_mfma_f32_16x16x32_bf16 v[68:71], v[4:7], v[36:39], 0
	v_mfma_f32_16x16x32_bf16 v[72:75], v[12:15], v[36:39], 0
	v_mfma_f32_16x16x32_bf16 v[76:79], v[4:7], v[44:47], 0
	v_mfma_f32_16x16x32_bf16 v[80:83], v[12:15], v[44:47], 0
	v_mfma_f32_16x16x32_bf16 v[68:71], v[8:11], v[40:43], v[68:71]
	v_mfma_f32_16x16x32_bf16 v[72:75], v[16:19], v[40:43], v[72:75]
	v_mfma_f32_16x16x32_bf16 v[76:79], v[8:11], v[48:51], v[76:79]
	v_mfma_f32_16x16x32_bf16 v[80:83], v[16:19], v[48:51], v[80:83]
	v_mfma_f32_16x16x32_bf16 v[86:89], v[4:7], v[52:55], 0
	v_mfma_f32_16x16x32_bf16 v[92:95], v[12:15], v[52:55], 0
	v_mfma_f32_16x16x32_bf16 v[96:99], v[4:7], v[60:63], 0
	v_mfma_f32_16x16x32_bf16 v[100:103], v[12:15], v[60:63], 0
	v_mfma_f32_16x16x32_bf16 v[88:91], v[8:11], v[56:59], v[86:89]
	v_mfma_f32_16x16x32_bf16 v[92:95], v[16:19], v[56:59], v[92:95]
	v_mfma_f32_16x16x32_bf16 v[96:99], v[8:11], v[64:67], v[96:99]
	v_mfma_f32_16x16x32_bf16 v[100:103], v[16:19], v[64:67], v[100:103]
	v_mfma_f32_16x16x32_bf16 v[104:107], v[20:23], v[36:39], 0
	v_mfma_f32_16x16x32_bf16 v[36:39], v[28:31], v[36:39], 0
	v_mfma_f32_16x16x32_bf16 v[104:107], v[24:27], v[40:43], v[104:107]
	v_mfma_f32_16x16x32_bf16 v[140:143], v[32:35], v[40:43], v[36:39]
	v_mfma_f32_16x16x32_bf16 v[40:43], v[20:23], v[44:47], 0
	v_mfma_f32_16x16x32_bf16 v[44:47], v[28:31], v[44:47], 0
	v_mfma_f32_16x16x32_bf16 v[144:147], v[24:27], v[48:51], v[40:43]
	v_mfma_f32_16x16x32_bf16 v[44:47], v[32:35], v[48:51], v[44:47]
	v_mfma_f32_16x16x32_bf16 v[48:51], v[20:23], v[52:55], 0
	v_mfma_f32_16x16x32_bf16 v[52:55], v[28:31], v[52:55], 0
	v_mfma_f32_16x16x32_bf16 v[48:51], v[24:27], v[56:59], v[48:51]
	v_mfma_f32_16x16x32_bf16 v[52:55], v[32:35], v[56:59], v[52:55]
	v_mfma_f32_16x16x32_bf16 v[56:59], v[20:23], v[60:63], 0
	v_mfma_f32_16x16x32_bf16 v[60:63], v[28:31], v[60:63], 0
	v_mfma_f32_16x16x32_bf16 v[56:59], v[24:27], v[64:67], v[56:59]
	v_mfma_f32_16x16x32_bf16 v[60:63], v[32:35], v[64:67], v[60:63]
	s_barrier
	s_setprio 0
	s_add_i32 s23, s29, s0
	v_lshl_add_u64 v[252:253], s[24:25], 0, v[164:165]
	s_mov_b64 s[60:61], 0x100
	s_add_i32 s53, s23, 0x2000
	v_lshl_add_u64 v[86:87], v[252:253], 0, s[60:61]
	s_mov_b32 m0, s23
	v_lshl_add_u64 v[36:37], s[24:25], 0, v[168:169]
	s_add_u32 s56, s24, 0x40100
	ds_read_b128 v[64:67], v175 offset:16384
	ds_read_b128 v[108:111], v175 offset:17408
	ds_read_b128 v[112:115], v175 offset:18432
	ds_read_b128 v[116:119], v175 offset:19456
	ds_read_b128 v[120:123], v175 offset:20480
	ds_read_b128 v[124:127], v175 offset:21504
	ds_read_b128 v[128:131], v175 offset:22528
	ds_read_b128 v[132:135], v175 offset:23552
	global_load_lds_dwordx4 v[86:87], off
	v_lshl_add_u64 v[38:39], v[36:37], 0, s[60:61]
	s_mov_b32 m0, s53
	s_addc_u32 s57, s25, 0
	s_add_i32 s54, s58, s0
	global_load_lds_dwordx4 v[38:39], off
	v_lshl_add_u64 v[38:39], s[56:57], 0, v[164:165]
	s_mov_b32 m0, s54
	s_add_i32 s55, s54, 0x2000
	global_load_lds_dwordx4 v[38:39], off
	v_lshl_add_u64 v[38:39], s[56:57], 0, v[168:169]
	s_mov_b32 m0, s55
	v_lshl_add_u64 v[40:41], s[26:27], 0, v[166:167]
	global_load_lds_dwordx4 v[38:39], off
	v_lshl_add_u64 v[38:39], s[26:27], 0, v[0:1]
	v_lshl_add_u64 v[86:87], v[38:39], 0, s[60:61]
	s_mov_b32 m0, s44
	v_lshl_add_u64 v[42:43], v[40:41], 0, s[60:61]
	global_load_lds_dwordx4 v[86:87], off
	s_mov_b32 m0, s45
	s_nop 0
	global_load_lds_dwordx4 v[42:43], off
	s_waitcnt vmcnt(8)
	s_waitcnt lgkmcnt(0)
	s_setprio 1
	s_barrier
	v_mfma_f32_16x16x32_bf16 v[136:139], v[4:7], v[64:67], 0
	s_nop 0
	v_mfma_f32_16x16x32_bf16 v[176:179], v[8:11], v[108:111], v[136:139]
	v_mfma_f32_16x16x32_bf16 v[136:139], v[12:15], v[64:67], 0
	s_nop 0
	v_mfma_f32_16x16x32_bf16 v[180:183], v[16:19], v[108:111], v[136:139]
	v_mfma_f32_16x16x32_bf16 v[136:139], v[4:7], v[112:115], 0
	s_nop 0
	v_mfma_f32_16x16x32_bf16 v[184:187], v[8:11], v[116:119], v[136:139]
	v_mfma_f32_16x16x32_bf16 v[136:139], v[12:15], v[112:115], 0
	s_nop 0
	v_mfma_f32_16x16x32_bf16 v[188:191], v[16:19], v[116:119], v[136:139]
	v_mfma_f32_16x16x32_bf16 v[136:139], v[4:7], v[120:123], 0
	v_mfma_f32_16x16x32_bf16 v[4:7], v[4:7], v[128:131], 0
	v_mfma_f32_16x16x32_bf16 v[192:195], v[8:11], v[124:127], v[136:139]
	v_mfma_f32_16x16x32_bf16 v[4:7], v[8:11], v[132:135], v[4:7]
	v_mfma_f32_16x16x32_bf16 v[8:11], v[12:15], v[128:131], 0
	v_mfma_f32_16x16x32_bf16 v[136:139], v[12:15], v[120:123], 0
	v_mfma_f32_16x16x32_bf16 v[12:15], v[16:19], v[132:135], v[8:11]
	v_mfma_f32_16x16x32_bf16 v[200:203], v[16:19], v[124:127], v[136:139]
	v_mfma_f32_16x16x32_bf16 v[8:11], v[20:23], v[64:67], 0
	s_nop 0
	v_mfma_f32_16x16x32_bf16 v[16:19], v[24:27], v[108:111], v[8:11]
	v_mfma_f32_16x16x32_bf16 v[8:11], v[28:31], v[64:67], 0
	s_nop 0
	v_mfma_f32_16x16x32_bf16 v[108:111], v[32:35], v[108:111], v[8:11]
	v_mfma_f32_16x16x32_bf16 v[8:11], v[20:23], v[112:115], 0
	s_nop 0
	v_mfma_f32_16x16x32_bf16 v[204:207], v[24:27], v[116:119], v[8:11]
	v_mfma_f32_16x16x32_bf16 v[8:11], v[28:31], v[112:115], 0
	s_nop 0
	v_mfma_f32_16x16x32_bf16 v[112:115], v[32:35], v[116:119], v[8:11]
	v_mfma_f32_16x16x32_bf16 v[8:11], v[20:23], v[120:123], 0
	s_nop 0
	v_mfma_f32_16x16x32_bf16 v[208:211], v[24:27], v[124:127], v[8:11]
	v_mfma_f32_16x16x32_bf16 v[8:11], v[28:31], v[120:123], 0
	s_nop 0
	v_mfma_f32_16x16x32_bf16 v[212:215], v[32:35], v[124:127], v[8:11]
	v_mfma_f32_16x16x32_bf16 v[8:11], v[20:23], v[128:131], 0
	s_nop 0
	v_mfma_f32_16x16x32_bf16 v[216:219], v[24:27], v[132:135], v[8:11]
	v_mfma_f32_16x16x32_bf16 v[8:11], v[28:31], v[128:131], 0
	s_nop 0
	v_mfma_f32_16x16x32_bf16 v[220:223], v[32:35], v[132:135], v[8:11]
	s_barrier
	s_setprio 0
	s_add_i32 s29, 0, 0x18000
	s_add_i32 s58, 0, 0x1c000
	v_add_u32_e32 v86, s29, v174
	v_add_u32_e32 v87, s58, v174
	ds_read_b128 v[8:11], v86
	ds_read_b128 v[28:31], v86 offset:1024
	ds_read_b128 v[32:35], v86 offset:2048
	ds_read_b128 v[64:67], v86 offset:3072
	ds_read_b128 v[224:227], v87
	ds_read_b128 v[228:231], v87 offset:1024
	ds_read_b128 v[232:235], v87 offset:2048
	ds_read_b128 v[236:239], v87 offset:3072
	s_add_u32 s56, s26, 0x40100
	s_addc_u32 s57, s27, 0
	s_mov_b32 m0, s46
	v_lshl_add_u64 v[42:43], s[56:57], 0, v[0:1]
	ds_read_b128 v[20:23], v175 offset:32768
	ds_read_b128 v[24:27], v175 offset:33792
	ds_read_b128 v[124:127], v175 offset:34816
	ds_read_b128 v[128:131], v175 offset:35840
	ds_read_b128 v[240:243], v175 offset:36864
	ds_read_b128 v[244:247], v175 offset:37888
	ds_read_b128 v[248:251], v175 offset:38912
	ds_read_b128 v[196:199], v175 offset:39936
	global_load_lds_dwordx4 v[42:43], off
	v_lshl_add_u64 v[42:43], s[56:57], 0, v[166:167]
	s_mov_b32 m0, s48
	s_nop 0
	global_load_lds_dwordx4 v[42:43], off
	s_waitcnt vmcnt(8)
	s_waitcnt lgkmcnt(0)
	s_setprio 1
	s_barrier
	v_mfma_f32_16x16x32_bf16 v[68:71], v[8:11], v[20:23], v[68:71]
	v_mfma_f32_16x16x32_bf16 v[152:155], v[28:31], v[24:27], v[68:71]
	v_mfma_f32_16x16x32_bf16 v[68:71], v[32:35], v[20:23], v[72:75]
	v_mfma_f32_16x16x32_bf16 v[148:151], v[64:67], v[24:27], v[68:71]
	v_mfma_f32_16x16x32_bf16 v[68:71], v[8:11], v[124:127], v[76:79]
	v_mfma_f32_16x16x32_bf16 v[136:139], v[28:31], v[128:131], v[68:71]
	v_mfma_f32_16x16x32_bf16 v[68:71], v[32:35], v[124:127], v[80:83]
	v_mfma_f32_16x16x32_bf16 v[132:135], v[64:67], v[128:131], v[68:71]
	v_mfma_f32_16x16x32_bf16 v[68:71], v[8:11], v[240:243], v[88:91]
	v_mfma_f32_16x16x32_bf16 v[120:123], v[28:31], v[244:247], v[68:71]
	v_mfma_f32_16x16x32_bf16 v[68:71], v[32:35], v[240:243], v[92:95]
	v_mfma_f32_16x16x32_bf16 v[116:119], v[64:67], v[244:247], v[68:71]
	v_mfma_f32_16x16x32_bf16 v[68:71], v[8:11], v[248:251], v[96:99]
	v_mfma_f32_16x16x32_bf16 v[72:75], v[28:31], v[196:199], v[68:71]
	v_mfma_f32_16x16x32_bf16 v[68:71], v[32:35], v[248:251], v[100:103]
	v_mfma_f32_16x16x32_bf16 v[68:71], v[64:67], v[196:199], v[68:71]
	v_mfma_f32_16x16x32_bf16 v[76:79], v[224:227], v[20:23], v[104:107]
	v_mfma_f32_16x16x32_bf16 v[20:23], v[232:235], v[20:23], v[140:143]
	v_mfma_f32_16x16x32_bf16 v[156:159], v[236:239], v[24:27], v[20:23]
	v_mfma_f32_16x16x32_bf16 v[20:23], v[224:227], v[124:127], v[144:147]
	v_mfma_f32_16x16x32_bf16 v[144:147], v[228:231], v[128:131], v[20:23]
	v_mfma_f32_16x16x32_bf16 v[20:23], v[232:235], v[124:127], v[44:47]
	v_mfma_f32_16x16x32_bf16 v[140:143], v[236:239], v[128:131], v[20:23]
	v_mfma_f32_16x16x32_bf16 v[20:23], v[224:227], v[240:243], v[48:51]
	v_mfma_f32_16x16x32_bf16 v[128:131], v[228:231], v[244:247], v[20:23]
	v_mfma_f32_16x16x32_bf16 v[20:23], v[232:235], v[240:243], v[52:55]
	v_mfma_f32_16x16x32_bf16 v[124:127], v[236:239], v[244:247], v[20:23]
	v_mfma_f32_16x16x32_bf16 v[20:23], v[224:227], v[248:251], v[56:59]
	v_mfma_f32_16x16x32_bf16 v[80:83], v[228:231], v[196:199], v[20:23]
	v_mfma_f32_16x16x32_bf16 v[20:23], v[232:235], v[248:251], v[60:63]
	v_mfma_f32_16x16x32_bf16 v[160:163], v[228:231], v[24:27], v[76:79]
	v_mfma_f32_16x16x32_bf16 v[76:79], v[236:239], v[196:199], v[20:23]
	s_barrier
	s_setprio 0
	s_add_i32 s56, s29, s0
	s_add_i32 s57, s56, 0x2000
	s_nop 1
	v_lshl_add_u64 v[20:21], v[252:253], 0, s[84:85]
	s_mov_b32 m0, s56
	s_add_u32 s60, s24, 0x40180
	ds_read_b128 v[44:47], v175 offset:49152
	ds_read_b128 v[48:51], v175 offset:50176
	ds_read_b128 v[88:91], v175 offset:51200
	ds_read_b128 v[92:95], v175 offset:52224
	ds_read_b128 v[96:99], v175 offset:53248
	ds_read_b128 v[100:103], v175 offset:54272
	ds_read_b128 v[104:107], v175 offset:55296
	ds_read_b128 v[196:199], v175 offset:56320
	global_load_lds_dwordx4 v[20:21], off
	v_lshl_add_u64 v[20:21], v[36:37], 0, s[84:85]
	s_mov_b32 m0, s57
	s_addc_u32 s61, s25, 0
	s_add_i32 s58, s58, s0
	global_load_lds_dwordx4 v[20:21], off
	v_lshl_add_u64 v[20:21], s[60:61], 0, v[164:165]
	s_mov_b32 m0, s58
	s_add_i32 s59, s58, 0x2000
	global_load_lds_dwordx4 v[20:21], off
	v_lshl_add_u64 v[20:21], s[60:61], 0, v[168:169]
	s_mov_b32 m0, s59
	s_nop 0
	global_load_lds_dwordx4 v[20:21], off
	v_lshl_add_u64 v[20:21], v[38:39], 0, s[84:85]
	s_mov_b32 m0, s49
	s_nop 0
	global_load_lds_dwordx4 v[20:21], off
	v_lshl_add_u64 v[20:21], v[40:41], 0, s[84:85]
	s_mov_b32 m0, s50
	s_nop 0
	global_load_lds_dwordx4 v[20:21], off
	s_waitcnt vmcnt(8)
	s_waitcnt lgkmcnt(0)
	s_setprio 1
	s_barrier
	v_mfma_f32_16x16x32_bf16 v[20:23], v[8:11], v[44:47], v[176:179]
	v_mfma_f32_16x16x32_bf16 v[56:59], v[28:31], v[48:51], v[20:23]
	v_mfma_f32_16x16x32_bf16 v[20:23], v[32:35], v[44:47], v[180:183]
	v_mfma_f32_16x16x32_bf16 v[52:55], v[64:67], v[48:51], v[20:23]
	v_mfma_f32_16x16x32_bf16 v[20:23], v[8:11], v[88:91], v[184:187]
	v_mfma_f32_16x16x32_bf16 v[40:43], v[28:31], v[92:95], v[20:23]
	v_mfma_f32_16x16x32_bf16 v[20:23], v[32:35], v[88:91], v[188:191]
	v_mfma_f32_16x16x32_bf16 v[36:39], v[64:67], v[92:95], v[20:23]
	v_mfma_f32_16x16x32_bf16 v[20:23], v[8:11], v[96:99], v[192:195]
	v_mfma_f32_16x16x32_bf16 v[4:7], v[8:11], v[104:107], v[4:7]
	v_mfma_f32_16x16x32_bf16 v[24:27], v[28:31], v[100:103], v[20:23]
	v_mfma_f32_16x16x32_bf16 v[20:23], v[32:35], v[96:99], v[200:203]
	v_mfma_f32_16x16x32_bf16 v[8:11], v[28:31], v[196:199], v[4:7]
	v_mfma_f32_16x16x32_bf16 v[4:7], v[32:35], v[104:107], v[12:15]
	v_mfma_f32_16x16x32_bf16 v[20:23], v[64:67], v[100:103], v[20:23]
	v_mfma_f32_16x16x32_bf16 v[4:7], v[64:67], v[196:199], v[4:7]
	v_mfma_f32_16x16x32_bf16 v[12:15], v[224:227], v[44:47], v[16:19]
	v_mfma_f32_16x16x32_bf16 v[64:67], v[228:231], v[48:51], v[12:15]
	v_mfma_f32_16x16x32_bf16 v[12:15], v[232:235], v[44:47], v[108:111]
	v_mfma_f32_16x16x32_bf16 v[60:63], v[236:239], v[48:51], v[12:15]
	v_mfma_f32_16x16x32_bf16 v[12:15], v[224:227], v[88:91], v[204:207]
	v_mfma_f32_16x16x32_bf16 v[48:51], v[228:231], v[92:95], v[12:15]
	v_mfma_f32_16x16x32_bf16 v[12:15], v[232:235], v[88:91], v[112:115]
	v_mfma_f32_16x16x32_bf16 v[44:47], v[236:239], v[92:95], v[12:15]
	v_mfma_f32_16x16x32_bf16 v[12:15], v[224:227], v[96:99], v[208:211]
	v_mfma_f32_16x16x32_bf16 v[32:35], v[228:231], v[100:103], v[12:15]
	v_mfma_f32_16x16x32_bf16 v[12:15], v[232:235], v[96:99], v[212:215]
	v_mfma_f32_16x16x32_bf16 v[28:31], v[236:239], v[100:103], v[12:15]
	v_mfma_f32_16x16x32_bf16 v[12:15], v[224:227], v[104:107], v[216:219]
	v_mfma_f32_16x16x32_bf16 v[16:19], v[228:231], v[196:199], v[12:15]
	v_mfma_f32_16x16x32_bf16 v[12:15], v[232:235], v[104:107], v[220:223]
	v_mfma_f32_16x16x32_bf16 v[12:15], v[236:239], v[196:199], v[12:15]
	s_barrier
	s_setprio 0
	s_lshl_b32 s28, s28, 11
	s_and_b32 s28, s28, 0x800
	s_add_i32 s60, s28, 0
	s_add_i32 s60, s60, 0x25a00
	s_lshl_b32 s28, s43, 2
	s_add_i32 s28, s60, s28
	s_add_u32 s26, s26, 0x40180
	s_addc_u32 s27, s27, 0
	v_mbcnt_lo_u32_b32 v88, -1, 0
	v_mbcnt_hi_u32_b32 v88, -1, v88
	s_add_u32 s61, s24, 0x200
	v_lshl_add_u32 v88, v88, 2, s28
	s_addc_u32 s62, s25, 0
	s_mov_b32 s76, 0
	s_waitcnt vmcnt(8)
	ds_write_b32 v88, v84
.LBB0_1648:
	ds_read_b128 v[88:91], v2
	ds_read_b128 v[92:95], v2 offset:1024
	ds_read_b128 v[96:99], v2 offset:2048
	ds_read_b128 v[100:103], v2 offset:3072
	ds_read_b128 v[104:107], v85
	ds_read_b128 v[108:111], v85 offset:1024
	ds_read_b128 v[112:115], v85 offset:2048
	ds_read_b128 v[176:179], v85 offset:3072
	s_add_u32 s24, s26, 0xfffc0080
	s_addc_u32 s25, s27, -1
	s_cmp_eq_u32 s76, 12
	s_cselect_b32 s29, s19, s25
	s_cselect_b32 s28, s18, s24
	s_cselect_b32 s25, s21, s62
	s_cselect_b32 s24, s20, s61
	s_mov_b32 m0, s15
	v_lshl_add_u64 v[212:213], s[26:27], 0, v[170:171]
	ds_read_b128 v[180:183], v175
	ds_read_b128 v[184:187], v175 offset:1024
	ds_read_b128 v[188:191], v175 offset:2048
	ds_read_b128 v[192:195], v175 offset:3072
	ds_read_b128 v[196:199], v175 offset:4096
	ds_read_b128 v[200:203], v175 offset:5120
	ds_read_b128 v[204:207], v175 offset:6144
	ds_read_b128 v[208:211], v175 offset:7168
	global_load_lds_dwordx4 v[212:213], off
	v_lshl_add_u64 v[212:213], s[26:27], 0, v[172:173]
	s_mov_b32 m0, s17
	s_nop 0
	global_load_lds_dwordx4 v[212:213], off
	s_waitcnt vmcnt(8)
	s_waitcnt lgkmcnt(0)
	s_setprio 1
	s_barrier
	v_mfma_f32_16x16x32_bf16 v[152:155], v[88:91], v[180:183], v[152:155]
	v_mfma_f32_16x16x32_bf16 v[148:151], v[96:99], v[180:183], v[148:151]
	v_mfma_f32_16x16x32_bf16 v[136:139], v[88:91], v[188:191], v[136:139]
	v_mfma_f32_16x16x32_bf16 v[132:135], v[96:99], v[188:191], v[132:135]
	v_mfma_f32_16x16x32_bf16 v[120:123], v[88:91], v[196:199], v[120:123]
	v_mfma_f32_16x16x32_bf16 v[116:119], v[96:99], v[196:199], v[116:119]
	v_mfma_f32_16x16x32_bf16 v[72:75], v[88:91], v[204:207], v[72:75]
	v_mfma_f32_16x16x32_bf16 v[68:71], v[96:99], v[204:207], v[68:71]
	v_mfma_f32_16x16x32_bf16 v[152:155], v[92:95], v[184:187], v[152:155]
	v_mfma_f32_16x16x32_bf16 v[148:151], v[100:103], v[184:187], v[148:151]
	v_mfma_f32_16x16x32_bf16 v[136:139], v[92:95], v[192:195], v[136:139]
	v_mfma_f32_16x16x32_bf16 v[132:135], v[100:103], v[192:195], v[132:135]
	v_mfma_f32_16x16x32_bf16 v[120:123], v[92:95], v[200:203], v[120:123]
	v_mfma_f32_16x16x32_bf16 v[116:119], v[100:103], v[200:203], v[116:119]
	v_mfma_f32_16x16x32_bf16 v[72:75], v[92:95], v[208:211], v[72:75]
	v_mfma_f32_16x16x32_bf16 v[68:71], v[100:103], v[208:211], v[68:71]
	v_mfma_f32_16x16x32_bf16 v[160:163], v[104:107], v[180:183], v[160:163]
	v_mfma_f32_16x16x32_bf16 v[156:159], v[112:115], v[180:183], v[156:159]
	v_mfma_f32_16x16x32_bf16 v[144:147], v[104:107], v[188:191], v[144:147]
	v_mfma_f32_16x16x32_bf16 v[140:143], v[112:115], v[188:191], v[140:143]
	v_mfma_f32_16x16x32_bf16 v[128:131], v[104:107], v[196:199], v[128:131]
	v_mfma_f32_16x16x32_bf16 v[124:127], v[112:115], v[196:199], v[124:127]
	v_mfma_f32_16x16x32_bf16 v[80:83], v[104:107], v[204:207], v[80:83]
	v_mfma_f32_16x16x32_bf16 v[76:79], v[112:115], v[204:207], v[76:79]
	v_mfma_f32_16x16x32_bf16 v[160:163], v[108:111], v[184:187], v[160:163]
	v_mfma_f32_16x16x32_bf16 v[156:159], v[176:179], v[184:187], v[156:159]
	v_mfma_f32_16x16x32_bf16 v[144:147], v[108:111], v[192:195], v[144:147]
	v_mfma_f32_16x16x32_bf16 v[140:143], v[176:179], v[192:195], v[140:143]
	v_mfma_f32_16x16x32_bf16 v[128:131], v[108:111], v[200:203], v[128:131]
	v_mfma_f32_16x16x32_bf16 v[124:127], v[176:179], v[200:203], v[124:127]
	v_mfma_f32_16x16x32_bf16 v[80:83], v[108:111], v[208:211], v[80:83]
	v_mfma_f32_16x16x32_bf16 v[76:79], v[176:179], v[208:211], v[76:79]
	s_barrier
	s_setprio 0
	s_mov_b32 m0, s23
	v_lshl_add_u64 v[212:213], s[24:25], 0, v[164:165]
	s_add_u32 s66, s24, 0x40000
	ds_read_b128 v[180:183], v175 offset:16384
	ds_read_b128 v[184:187], v175 offset:17408
	ds_read_b128 v[188:191], v175 offset:18432
	ds_read_b128 v[192:195], v175 offset:19456
	ds_read_b128 v[196:199], v175 offset:20480
	ds_read_b128 v[200:203], v175 offset:21504
	ds_read_b128 v[204:207], v175 offset:22528
	ds_read_b128 v[208:211], v175 offset:23552
	global_load_lds_dwordx4 v[212:213], off
	v_lshl_add_u64 v[214:215], s[24:25], 0, v[168:169]
	s_mov_b32 m0, s53
	s_addc_u32 s67, s25, 0
	global_load_lds_dwordx4 v[214:215], off
	v_lshl_add_u64 v[216:217], s[66:67], 0, v[164:165]
	s_mov_b32 m0, s54
	v_lshl_add_u64 v[218:219], s[28:29], 0, v[166:167]
	global_load_lds_dwordx4 v[216:217], off
	v_lshl_add_u64 v[216:217], s[66:67], 0, v[168:169]
	s_mov_b32 m0, s55
	s_nop 0
	global_load_lds_dwordx4 v[216:217], off
	v_lshl_add_u64 v[216:217], s[28:29], 0, v[0:1]
	s_mov_b32 m0, s44
	s_nop 0
	global_load_lds_dwordx4 v[216:217], off
	s_mov_b32 m0, s45
	s_nop 0
	global_load_lds_dwordx4 v[218:219], off
	s_waitcnt vmcnt(8)
	s_waitcnt lgkmcnt(0)
	s_setprio 1
	s_barrier
	v_mfma_f32_16x16x32_bf16 v[56:59], v[88:91], v[180:183], v[56:59]
	v_mfma_f32_16x16x32_bf16 v[52:55], v[96:99], v[180:183], v[52:55]
	v_mfma_f32_16x16x32_bf16 v[40:43], v[88:91], v[188:191], v[40:43]
	v_mfma_f32_16x16x32_bf16 v[36:39], v[96:99], v[188:191], v[36:39]
	v_mfma_f32_16x16x32_bf16 v[24:27], v[88:91], v[196:199], v[24:27]
	v_mfma_f32_16x16x32_bf16 v[20:23], v[96:99], v[196:199], v[20:23]
	v_mfma_f32_16x16x32_bf16 v[8:11], v[88:91], v[204:207], v[8:11]
	v_mfma_f32_16x16x32_bf16 v[4:7], v[96:99], v[204:207], v[4:7]
	v_mfma_f32_16x16x32_bf16 v[56:59], v[92:95], v[184:187], v[56:59]
	v_mfma_f32_16x16x32_bf16 v[52:55], v[100:103], v[184:187], v[52:55]
	v_mfma_f32_16x16x32_bf16 v[40:43], v[92:95], v[192:195], v[40:43]
	v_mfma_f32_16x16x32_bf16 v[36:39], v[100:103], v[192:195], v[36:39]
	v_mfma_f32_16x16x32_bf16 v[24:27], v[92:95], v[200:203], v[24:27]
	v_mfma_f32_16x16x32_bf16 v[20:23], v[100:103], v[200:203], v[20:23]
	v_mfma_f32_16x16x32_bf16 v[8:11], v[92:95], v[208:211], v[8:11]
	v_mfma_f32_16x16x32_bf16 v[4:7], v[100:103], v[208:211], v[4:7]
	v_mfma_f32_16x16x32_bf16 v[64:67], v[104:107], v[180:183], v[64:67]
	v_mfma_f32_16x16x32_bf16 v[60:63], v[112:115], v[180:183], v[60:63]
	v_mfma_f32_16x16x32_bf16 v[48:51], v[104:107], v[188:191], v[48:51]
	v_mfma_f32_16x16x32_bf16 v[44:47], v[112:115], v[188:191], v[44:47]
	v_mfma_f32_16x16x32_bf16 v[32:35], v[104:107], v[196:199], v[32:35]
	v_mfma_f32_16x16x32_bf16 v[28:31], v[112:115], v[196:199], v[28:31]
	v_mfma_f32_16x16x32_bf16 v[16:19], v[104:107], v[204:207], v[16:19]
	v_mfma_f32_16x16x32_bf16 v[12:15], v[112:115], v[204:207], v[12:15]
	v_mfma_f32_16x16x32_bf16 v[64:67], v[108:111], v[184:187], v[64:67]
	v_mfma_f32_16x16x32_bf16 v[60:63], v[176:179], v[184:187], v[60:63]
	v_mfma_f32_16x16x32_bf16 v[48:51], v[108:111], v[192:195], v[48:51]
	v_mfma_f32_16x16x32_bf16 v[44:47], v[176:179], v[192:195], v[44:47]
	v_mfma_f32_16x16x32_bf16 v[32:35], v[108:111], v[200:203], v[32:35]
	v_mfma_f32_16x16x32_bf16 v[28:31], v[176:179], v[200:203], v[28:31]
	v_mfma_f32_16x16x32_bf16 v[16:19], v[108:111], v[208:211], v[16:19]
	v_mfma_f32_16x16x32_bf16 v[12:15], v[176:179], v[208:211], v[12:15]
	s_barrier
	s_setprio 0
	ds_read_b128 v[88:91], v86
	ds_read_b128 v[92:95], v86 offset:1024
	ds_read_b128 v[96:99], v86 offset:2048
	ds_read_b128 v[100:103], v86 offset:3072
	ds_read_b128 v[104:107], v87
	ds_read_b128 v[108:111], v87 offset:1024
	ds_read_b128 v[112:115], v87 offset:2048
	ds_read_b128 v[176:179], v87 offset:3072
	s_add_u32 s28, s28, 0x40000
	s_addc_u32 s29, s29, 0
	s_mov_b32 m0, s46
	v_lshl_add_u64 v[220:221], s[28:29], 0, v[0:1]
	ds_read_b128 v[180:183], v175 offset:32768
	ds_read_b128 v[184:187], v175 offset:33792
	ds_read_b128 v[188:191], v175 offset:34816
	ds_read_b128 v[192:195], v175 offset:35840
	ds_read_b128 v[196:199], v175 offset:36864
	ds_read_b128 v[200:203], v175 offset:37888
	ds_read_b128 v[204:207], v175 offset:38912
	ds_read_b128 v[208:211], v175 offset:39936
	global_load_lds_dwordx4 v[220:221], off
	v_lshl_add_u64 v[220:221], s[28:29], 0, v[166:167]
	s_mov_b32 m0, s48
	s_nop 0
	global_load_lds_dwordx4 v[220:221], off
	s_waitcnt vmcnt(8)
	s_waitcnt lgkmcnt(0)
	s_setprio 1
	s_barrier
	v_mfma_f32_16x16x32_bf16 v[152:155], v[88:91], v[180:183], v[152:155]
	v_mfma_f32_16x16x32_bf16 v[148:151], v[96:99], v[180:183], v[148:151]
	v_mfma_f32_16x16x32_bf16 v[136:139], v[88:91], v[188:191], v[136:139]
	v_mfma_f32_16x16x32_bf16 v[132:135], v[96:99], v[188:191], v[132:135]
	v_mfma_f32_16x16x32_bf16 v[120:123], v[88:91], v[196:199], v[120:123]
	v_mfma_f32_16x16x32_bf16 v[116:119], v[96:99], v[196:199], v[116:119]
	v_mfma_f32_16x16x32_bf16 v[72:75], v[88:91], v[204:207], v[72:75]
	v_mfma_f32_16x16x32_bf16 v[68:71], v[96:99], v[204:207], v[68:71]
	v_mfma_f32_16x16x32_bf16 v[152:155], v[92:95], v[184:187], v[152:155]
	v_mfma_f32_16x16x32_bf16 v[148:151], v[100:103], v[184:187], v[148:151]
	v_mfma_f32_16x16x32_bf16 v[136:139], v[92:95], v[192:195], v[136:139]
	v_mfma_f32_16x16x32_bf16 v[132:135], v[100:103], v[192:195], v[132:135]
	v_mfma_f32_16x16x32_bf16 v[120:123], v[92:95], v[200:203], v[120:123]
	v_mfma_f32_16x16x32_bf16 v[116:119], v[100:103], v[200:203], v[116:119]
	v_mfma_f32_16x16x32_bf16 v[72:75], v[92:95], v[208:211], v[72:75]
	v_mfma_f32_16x16x32_bf16 v[68:71], v[100:103], v[208:211], v[68:71]
	v_mfma_f32_16x16x32_bf16 v[160:163], v[104:107], v[180:183], v[160:163]
	v_mfma_f32_16x16x32_bf16 v[156:159], v[112:115], v[180:183], v[156:159]
	v_mfma_f32_16x16x32_bf16 v[144:147], v[104:107], v[188:191], v[144:147]
	v_mfma_f32_16x16x32_bf16 v[140:143], v[112:115], v[188:191], v[140:143]
	v_mfma_f32_16x16x32_bf16 v[128:131], v[104:107], v[196:199], v[128:131]
	v_mfma_f32_16x16x32_bf16 v[124:127], v[112:115], v[196:199], v[124:127]
	v_mfma_f32_16x16x32_bf16 v[80:83], v[104:107], v[204:207], v[80:83]
	v_mfma_f32_16x16x32_bf16 v[76:79], v[112:115], v[204:207], v[76:79]
	v_mfma_f32_16x16x32_bf16 v[160:163], v[108:111], v[184:187], v[160:163]
	v_mfma_f32_16x16x32_bf16 v[156:159], v[176:179], v[184:187], v[156:159]
	v_mfma_f32_16x16x32_bf16 v[144:147], v[108:111], v[192:195], v[144:147]
	v_mfma_f32_16x16x32_bf16 v[140:143], v[176:179], v[192:195], v[140:143]
	v_mfma_f32_16x16x32_bf16 v[128:131], v[108:111], v[200:203], v[128:131]
	v_mfma_f32_16x16x32_bf16 v[124:127], v[176:179], v[200:203], v[124:127]
	v_mfma_f32_16x16x32_bf16 v[80:83], v[108:111], v[208:211], v[80:83]
	v_mfma_f32_16x16x32_bf16 v[76:79], v[176:179], v[208:211], v[76:79]
	s_barrier
	s_setprio 0
	s_mov_b32 m0, s56
	v_lshl_add_u64 v[212:213], v[212:213], 0, s[74:75]
	s_add_u32 s24, s24, 0x40080
	ds_read_b128 v[180:183], v175 offset:49152
	ds_read_b128 v[184:187], v175 offset:50176
	ds_read_b128 v[188:191], v175 offset:51200
	ds_read_b128 v[192:195], v175 offset:52224
	ds_read_b128 v[196:199], v175 offset:53248
	ds_read_b128 v[200:203], v175 offset:54272
	ds_read_b128 v[204:207], v175 offset:55296
	ds_read_b128 v[208:211], v175 offset:56320
	global_load_lds_dwordx4 v[212:213], off
	v_lshl_add_u64 v[212:213], v[214:215], 0, s[74:75]
	s_mov_b32 m0, s57
	s_addc_u32 s25, s25, 0
	global_load_lds_dwordx4 v[212:213], off
	v_lshl_add_u64 v[212:213], s[24:25], 0, v[164:165]
	s_mov_b32 m0, s58
	s_nop 0
	global_load_lds_dwordx4 v[212:213], off
	v_lshl_add_u64 v[212:213], s[24:25], 0, v[168:169]
	s_mov_b32 m0, s59
	s_nop 0
	global_load_lds_dwordx4 v[212:213], off
	v_lshl_add_u64 v[212:213], v[216:217], 0, s[74:75]
	s_mov_b32 m0, s49
	s_nop 0
	global_load_lds_dwordx4 v[212:213], off
	v_lshl_add_u64 v[212:213], v[218:219], 0, s[74:75]
	s_mov_b32 m0, s50
	s_nop 0
	global_load_lds_dwordx4 v[212:213], off
	s_waitcnt vmcnt(8)
	s_waitcnt lgkmcnt(0)
	s_setprio 1
	s_barrier
	v_mfma_f32_16x16x32_bf16 v[56:59], v[88:91], v[180:183], v[56:59]
	v_mfma_f32_16x16x32_bf16 v[52:55], v[96:99], v[180:183], v[52:55]
	v_mfma_f32_16x16x32_bf16 v[40:43], v[88:91], v[188:191], v[40:43]
	v_mfma_f32_16x16x32_bf16 v[36:39], v[96:99], v[188:191], v[36:39]
	v_mfma_f32_16x16x32_bf16 v[24:27], v[88:91], v[196:199], v[24:27]
	v_mfma_f32_16x16x32_bf16 v[20:23], v[96:99], v[196:199], v[20:23]
	v_mfma_f32_16x16x32_bf16 v[8:11], v[88:91], v[204:207], v[8:11]
	v_mfma_f32_16x16x32_bf16 v[4:7], v[96:99], v[204:207], v[4:7]
	v_mfma_f32_16x16x32_bf16 v[56:59], v[92:95], v[184:187], v[56:59]
	v_mfma_f32_16x16x32_bf16 v[52:55], v[100:103], v[184:187], v[52:55]
	v_mfma_f32_16x16x32_bf16 v[40:43], v[92:95], v[192:195], v[40:43]
	v_mfma_f32_16x16x32_bf16 v[36:39], v[100:103], v[192:195], v[36:39]
	v_mfma_f32_16x16x32_bf16 v[24:27], v[92:95], v[200:203], v[24:27]
	v_mfma_f32_16x16x32_bf16 v[20:23], v[100:103], v[200:203], v[20:23]
	v_mfma_f32_16x16x32_bf16 v[8:11], v[92:95], v[208:211], v[8:11]
	v_mfma_f32_16x16x32_bf16 v[4:7], v[100:103], v[208:211], v[4:7]
	v_mfma_f32_16x16x32_bf16 v[64:67], v[104:107], v[180:183], v[64:67]
	v_mfma_f32_16x16x32_bf16 v[60:63], v[112:115], v[180:183], v[60:63]
	v_mfma_f32_16x16x32_bf16 v[48:51], v[104:107], v[188:191], v[48:51]
	v_mfma_f32_16x16x32_bf16 v[44:47], v[112:115], v[188:191], v[44:47]
	v_mfma_f32_16x16x32_bf16 v[32:35], v[104:107], v[196:199], v[32:35]
	v_mfma_f32_16x16x32_bf16 v[28:31], v[112:115], v[196:199], v[28:31]
	v_mfma_f32_16x16x32_bf16 v[16:19], v[104:107], v[204:207], v[16:19]
	v_mfma_f32_16x16x32_bf16 v[12:15], v[112:115], v[204:207], v[12:15]
	v_mfma_f32_16x16x32_bf16 v[64:67], v[108:111], v[184:187], v[64:67]
	v_mfma_f32_16x16x32_bf16 v[60:63], v[176:179], v[184:187], v[60:63]
	v_mfma_f32_16x16x32_bf16 v[48:51], v[108:111], v[192:195], v[48:51]
	v_mfma_f32_16x16x32_bf16 v[44:47], v[176:179], v[192:195], v[44:47]
	v_mfma_f32_16x16x32_bf16 v[32:35], v[108:111], v[200:203], v[32:35]
	v_mfma_f32_16x16x32_bf16 v[28:31], v[176:179], v[200:203], v[28:31]
	v_mfma_f32_16x16x32_bf16 v[16:19], v[108:111], v[208:211], v[16:19]
	v_mfma_f32_16x16x32_bf16 v[12:15], v[176:179], v[208:211], v[12:15]
	s_barrier
	s_setprio 0
	s_add_i32 s76, s76, 2
	s_add_u32 s26, s26, 0x100
	s_addc_u32 s27, s27, 0
	s_add_u32 s61, s61, 0x100
	s_addc_u32 s62, s62, 0
	s_cmp_gt_u32 s76, 13
	s_cbranch_scc0 .LBB0_1648
	s_and_b64 vcc, exec, s[12:13]
	s_cbranch_vccz .LBB0_1651
	s_barrier

.LBB0_1762:
	s_add_i32 s3, 0, 0x10000
	s_add_i32 s41, 0, 0x14000
	v_add_u32_e32 v2, s3, v204
	v_add_u32_e32 v112, s41, v204
	ds_read_b128 v[4:7], v2
	ds_read_b128 v[8:11], v2 offset:1024
	ds_read_b128 v[12:15], v2 offset:2048
	ds_read_b128 v[16:19], v2 offset:3072
	ds_read_b128 v[20:23], v112
	ds_read_b128 v[24:27], v112 offset:1024
	ds_read_b128 v[28:31], v112 offset:2048
	ds_read_b128 v[32:35], v112 offset:3072
	s_add_u32 s28, s24, 0xb0080
	s_addc_u32 s29, s25, 0
	s_add_i32 s0, s44, 0xc000
	v_lshl_add_u64 v[68:69], s[28:29], 0, v[0:1]
	s_mov_b32 m0, s0
	s_add_i32 s1, s44, 0xe000
	ds_read_b128 v[36:39], v205
	ds_read_b128 v[40:43], v205 offset:1024
	ds_read_b128 v[44:47], v205 offset:2048
	ds_read_b128 v[48:51], v205 offset:3072
	ds_read_b128 v[52:55], v205 offset:4096
	ds_read_b128 v[56:59], v205 offset:5120
	ds_read_b128 v[60:63], v205 offset:6144
	ds_read_b128 v[64:67], v205 offset:7168
	global_load_lds_dwordx4 v[68:69], off
	v_lshl_add_u64 v[68:69], s[28:29], 0, v[162:163]
	s_mov_b32 m0, s1
	s_nop 0
	global_load_lds_dwordx4 v[68:69], off
	s_waitcnt vmcnt(8)
	s_waitcnt lgkmcnt(0)
	s_setprio 1
	s_barrier
	v_mfma_f32_16x16x32_bf16 v[68:71], v[4:7], v[36:39], 0
	v_mfma_f32_16x16x32_bf16 v[72:75], v[12:15], v[36:39], 0
	v_mfma_f32_16x16x32_bf16 v[76:79], v[4:7], v[44:47], 0
	v_mfma_f32_16x16x32_bf16 v[80:83], v[12:15], v[44:47], 0
	v_mfma_f32_16x16x32_bf16 v[84:87], v[4:7], v[52:55], 0
	v_mfma_f32_16x16x32_bf16 v[88:91], v[12:15], v[52:55], 0
	v_mfma_f32_16x16x32_bf16 v[92:95], v[4:7], v[60:63], 0
	v_mfma_f32_16x16x32_bf16 v[96:99], v[12:15], v[60:63], 0
	v_mfma_f32_16x16x32_bf16 v[68:71], v[8:11], v[40:43], v[68:71]
	v_mfma_f32_16x16x32_bf16 v[72:75], v[16:19], v[40:43], v[72:75]
	v_mfma_f32_16x16x32_bf16 v[76:79], v[8:11], v[48:51], v[76:79]
	v_mfma_f32_16x16x32_bf16 v[80:83], v[16:19], v[48:51], v[80:83]
	v_mfma_f32_16x16x32_bf16 v[84:87], v[8:11], v[56:59], v[84:87]
	v_mfma_f32_16x16x32_bf16 v[88:91], v[16:19], v[56:59], v[88:91]
	v_mfma_f32_16x16x32_bf16 v[92:95], v[8:11], v[64:67], v[92:95]
	v_mfma_f32_16x16x32_bf16 v[96:99], v[16:19], v[64:67], v[96:99]
	v_mfma_f32_16x16x32_bf16 v[100:103], v[20:23], v[36:39], 0
	v_mfma_f32_16x16x32_bf16 v[36:39], v[28:31], v[36:39], 0
	v_mfma_f32_16x16x32_bf16 v[104:107], v[24:27], v[40:43], v[100:103]
	v_mfma_f32_16x16x32_bf16 v[36:39], v[32:35], v[40:43], v[36:39]
	v_mfma_f32_16x16x32_bf16 v[40:43], v[20:23], v[44:47], 0
	v_mfma_f32_16x16x32_bf16 v[44:47], v[28:31], v[44:47], 0
	v_mfma_f32_16x16x32_bf16 v[40:43], v[24:27], v[48:51], v[40:43]
	v_mfma_f32_16x16x32_bf16 v[44:47], v[32:35], v[48:51], v[44:47]
	v_mfma_f32_16x16x32_bf16 v[48:51], v[20:23], v[52:55], 0
	v_mfma_f32_16x16x32_bf16 v[52:55], v[28:31], v[52:55], 0
	v_mfma_f32_16x16x32_bf16 v[48:51], v[24:27], v[56:59], v[48:51]
	v_mfma_f32_16x16x32_bf16 v[108:111], v[32:35], v[56:59], v[52:55]
	v_mfma_f32_16x16x32_bf16 v[52:55], v[20:23], v[60:63], 0
	s_nop 0
	v_mfma_f32_16x16x32_bf16 v[120:123], v[24:27], v[64:67], v[52:55]
	v_mfma_f32_16x16x32_bf16 v[52:55], v[28:31], v[60:63], 0
	s_nop 0
	v_mfma_f32_16x16x32_bf16 v[132:135], v[32:35], v[64:67], v[52:55]
	s_barrier
	s_setprio 0
	s_add_i32 s3, s3, s35
	v_lshl_add_u64 v[202:203], s[26:27], 0, v[160:161]
	s_mov_b64 s[60:61], 0x100
	s_add_i32 s40, s3, 0x2000
	v_lshl_add_u64 v[118:119], v[202:203], 0, s[60:61]
	s_mov_b32 m0, s3
	v_lshl_add_u64 v[246:247], s[26:27], 0, v[164:165]
	s_add_u32 s28, s26, 0xb0100
	ds_read_b128 v[52:55], v205 offset:16384
	ds_read_b128 v[56:59], v205 offset:17408
	ds_read_b128 v[60:63], v205 offset:18432
	ds_read_b128 v[64:67], v205 offset:19456
	ds_read_b128 v[100:103], v205 offset:20480
	ds_read_b128 v[114:117], v205 offset:21504
	ds_read_b128 v[124:127], v205 offset:22528
	ds_read_b128 v[128:131], v205 offset:23552
	global_load_lds_dwordx4 v[118:119], off
	v_lshl_add_u64 v[118:119], v[246:247], 0, s[60:61]
	s_mov_b32 m0, s40
	s_addc_u32 s29, s27, 0
	s_add_i32 s41, s41, s35
	global_load_lds_dwordx4 v[118:119], off
	v_lshl_add_u64 v[118:119], s[28:29], 0, v[160:161]
	s_mov_b32 m0, s41
	s_add_i32 s59, s41, 0x2000
	global_load_lds_dwordx4 v[118:119], off
	v_lshl_add_u64 v[118:119], s[28:29], 0, v[164:165]
	s_mov_b32 m0, s59
	v_lshl_add_u64 v[248:249], s[24:25], 0, v[0:1]
	global_load_lds_dwordx4 v[118:119], off
	v_lshl_add_u64 v[118:119], v[248:249], 0, s[60:61]
	s_mov_b32 m0, s44
	v_lshl_add_u64 v[250:251], s[24:25], 0, v[162:163]
	global_load_lds_dwordx4 v[118:119], off
	v_lshl_add_u64 v[118:119], v[250:251], 0, s[60:61]
	s_mov_b32 m0, s45
	s_nop 0
	global_load_lds_dwordx4 v[118:119], off
	s_waitcnt vmcnt(8)
	s_waitcnt lgkmcnt(0)
	s_setprio 1
	s_barrier
	v_mfma_f32_16x16x32_bf16 v[136:139], v[4:7], v[52:55], 0
	s_nop 0
	v_mfma_f32_16x16x32_bf16 v[144:147], v[8:11], v[56:59], v[136:139]
	v_mfma_f32_16x16x32_bf16 v[136:139], v[12:15], v[52:55], 0
	s_nop 0
	v_mfma_f32_16x16x32_bf16 v[148:151], v[16:19], v[56:59], v[136:139]
	v_mfma_f32_16x16x32_bf16 v[136:139], v[4:7], v[60:63], 0
	s_nop 0
	v_mfma_f32_16x16x32_bf16 v[152:155], v[8:11], v[64:67], v[136:139]
	v_mfma_f32_16x16x32_bf16 v[136:139], v[12:15], v[60:63], 0
	s_nop 0
	v_mfma_f32_16x16x32_bf16 v[156:159], v[16:19], v[64:67], v[136:139]
	v_mfma_f32_16x16x32_bf16 v[136:139], v[4:7], v[100:103], 0
	v_mfma_f32_16x16x32_bf16 v[4:7], v[4:7], v[124:127], 0
	v_mfma_f32_16x16x32_bf16 v[170:173], v[8:11], v[114:117], v[136:139]
	v_mfma_f32_16x16x32_bf16 v[4:7], v[8:11], v[128:131], v[4:7]
	v_mfma_f32_16x16x32_bf16 v[8:11], v[12:15], v[124:127], 0
	s_nop 0
	v_mfma_f32_16x16x32_bf16 v[8:11], v[16:19], v[128:131], v[8:11]
	v_mfma_f32_16x16x32_bf16 v[136:139], v[12:15], v[100:103], 0
	s_nop 0
	v_mfma_f32_16x16x32_bf16 v[174:177], v[16:19], v[114:117], v[136:139]
	v_mfma_f32_16x16x32_bf16 v[12:15], v[20:23], v[52:55], 0
	v_mfma_f32_16x16x32_bf16 v[16:19], v[28:31], v[52:55], 0
	v_mfma_f32_16x16x32_bf16 v[52:55], v[20:23], v[60:63], 0
	s_nop 0
	v_mfma_f32_16x16x32_bf16 v[178:181], v[24:27], v[64:67], v[52:55]
	v_mfma_f32_16x16x32_bf16 v[52:55], v[28:31], v[60:63], 0
	v_mfma_f32_16x16x32_bf16 v[12:15], v[24:27], v[56:59], v[12:15]
	v_mfma_f32_16x16x32_bf16 v[16:19], v[32:35], v[56:59], v[16:19]
	v_mfma_f32_16x16x32_bf16 v[182:185], v[32:35], v[64:67], v[52:55]
	v_mfma_f32_16x16x32_bf16 v[52:55], v[20:23], v[100:103], 0
	v_mfma_f32_16x16x32_bf16 v[20:23], v[20:23], v[124:127], 0
	v_mfma_f32_16x16x32_bf16 v[186:189], v[24:27], v[114:117], v[52:55]
	v_mfma_f32_16x16x32_bf16 v[52:55], v[28:31], v[100:103], 0
	v_mfma_f32_16x16x32_bf16 v[194:197], v[24:27], v[128:131], v[20:23]
	v_mfma_f32_16x16x32_bf16 v[20:23], v[28:31], v[124:127], 0
	v_mfma_f32_16x16x32_bf16 v[190:193], v[32:35], v[114:117], v[52:55]
	v_mfma_f32_16x16x32_bf16 v[198:201], v[32:35], v[128:131], v[20:23]
	s_barrier
	s_setprio 0
	s_add_i32 s60, 0, 0x18000
	s_add_i32 s62, 0, 0x1c000
	v_add_u32_e32 v113, s60, v204
	v_add_u32_e32 v114, s62, v204
	ds_read_b128 v[20:23], v113
	ds_read_b128 v[24:27], v113 offset:1024
	ds_read_b128 v[28:31], v113 offset:2048
	ds_read_b128 v[32:35], v113 offset:3072
	ds_read_b128 v[206:209], v114
	ds_read_b128 v[210:213], v114 offset:1024
	ds_read_b128 v[214:217], v114 offset:2048
	ds_read_b128 v[218:221], v114 offset:3072
	s_add_u32 s28, s24, 0xb0100
	s_addc_u32 s29, s25, 0
	s_mov_b32 m0, s46
	v_lshl_add_u64 v[60:61], s[28:29], 0, v[0:1]
	ds_read_b128 v[52:55], v205 offset:32768
	ds_read_b128 v[56:59], v205 offset:33792
	ds_read_b128 v[222:225], v205 offset:34816
	ds_read_b128 v[226:229], v205 offset:35840
	ds_read_b128 v[230:233], v205 offset:36864
	ds_read_b128 v[234:237], v205 offset:37888
	ds_read_b128 v[238:241], v205 offset:38912
	ds_read_b128 v[242:245], v205 offset:39936
	global_load_lds_dwordx4 v[60:61], off
	v_lshl_add_u64 v[60:61], s[28:29], 0, v[162:163]
	s_mov_b32 m0, s48
	s_nop 0
	global_load_lds_dwordx4 v[60:61], off
	s_waitcnt vmcnt(8)
	s_waitcnt lgkmcnt(0)
	s_setprio 1
	s_barrier
	v_mfma_f32_16x16x32_bf16 v[60:63], v[20:23], v[52:55], v[68:71]
	v_mfma_f32_16x16x32_bf16 v[140:143], v[24:27], v[56:59], v[60:63]
	v_mfma_f32_16x16x32_bf16 v[60:63], v[28:31], v[52:55], v[72:75]
	v_mfma_f32_16x16x32_bf16 v[136:139], v[32:35], v[56:59], v[60:63]
	v_mfma_f32_16x16x32_bf16 v[60:63], v[20:23], v[222:225], v[76:79]
	v_mfma_f32_16x16x32_bf16 v[128:131], v[24:27], v[226:229], v[60:63]
	v_mfma_f32_16x16x32_bf16 v[60:63], v[28:31], v[222:225], v[80:83]
	v_mfma_f32_16x16x32_bf16 v[124:127], v[32:35], v[226:229], v[60:63]
	v_mfma_f32_16x16x32_bf16 v[60:63], v[20:23], v[230:233], v[84:87]
	v_mfma_f32_16x16x32_bf16 v[116:119], v[24:27], v[234:237], v[60:63]
	v_mfma_f32_16x16x32_bf16 v[60:63], v[28:31], v[230:233], v[88:91]
	v_mfma_f32_16x16x32_bf16 v[100:103], v[32:35], v[234:237], v[60:63]
	v_mfma_f32_16x16x32_bf16 v[60:63], v[20:23], v[238:241], v[92:95]
	v_mfma_f32_16x16x32_bf16 v[88:91], v[24:27], v[242:245], v[60:63]
	v_mfma_f32_16x16x32_bf16 v[60:63], v[28:31], v[238:241], v[96:99]
	v_mfma_f32_16x16x32_bf16 v[76:79], v[32:35], v[242:245], v[60:63]
	v_mfma_f32_16x16x32_bf16 v[60:63], v[206:209], v[52:55], v[104:107]
	v_mfma_f32_16x16x32_bf16 v[36:39], v[214:217], v[52:55], v[36:39]
	v_mfma_f32_16x16x32_bf16 v[64:67], v[210:213], v[56:59], v[60:63]
	v_mfma_f32_16x16x32_bf16 v[60:63], v[218:221], v[56:59], v[36:39]
	v_mfma_f32_16x16x32_bf16 v[36:39], v[206:209], v[222:225], v[40:43]
	v_mfma_f32_16x16x32_bf16 v[56:59], v[210:213], v[226:229], v[36:39]
	v_mfma_f32_16x16x32_bf16 v[36:39], v[214:217], v[222:225], v[44:47]
	v_mfma_f32_16x16x32_bf16 v[52:55], v[218:221], v[226:229], v[36:39]
	v_mfma_f32_16x16x32_bf16 v[36:39], v[206:209], v[230:233], v[48:51]
	v_mfma_f32_16x16x32_bf16 v[48:51], v[210:213], v[234:237], v[36:39]
	v_mfma_f32_16x16x32_bf16 v[36:39], v[214:217], v[230:233], v[108:111]
	v_mfma_f32_16x16x32_bf16 v[44:47], v[218:221], v[234:237], v[36:39]
	v_mfma_f32_16x16x32_bf16 v[36:39], v[206:209], v[238:241], v[120:123]
	v_mfma_f32_16x16x32_bf16 v[40:43], v[210:213], v[242:245], v[36:39]
	v_mfma_f32_16x16x32_bf16 v[36:39], v[214:217], v[238:241], v[132:135]
	v_mfma_f32_16x16x32_bf16 v[36:39], v[218:221], v[242:245], v[36:39]
	s_barrier
	s_setprio 0
	s_add_i32 s60, s60, s35
	s_add_i32 s61, s60, 0x2000
	v_lshl_add_u64 v[68:69], v[202:203], 0, s[84:85]
	s_mov_b32 m0, s60
	s_add_u32 s28, s26, 0xb0180
	ds_read_b128 v[120:123], v205 offset:49152
	ds_read_b128 v[132:135], v205 offset:50176
	ds_read_b128 v[222:225], v205 offset:51200
	ds_read_b128 v[226:229], v205 offset:52224
	ds_read_b128 v[230:233], v205 offset:53248
	ds_read_b128 v[234:237], v205 offset:54272
	ds_read_b128 v[238:241], v205 offset:55296
	ds_read_b128 v[242:245], v205 offset:56320
	global_load_lds_dwordx4 v[68:69], off
	v_lshl_add_u64 v[68:69], v[246:247], 0, s[84:85]
	s_mov_b32 m0, s61
	s_addc_u32 s29, s27, 0
	s_add_i32 s62, s62, s35
	global_load_lds_dwordx4 v[68:69], off
	v_lshl_add_u64 v[68:69], s[28:29], 0, v[160:161]
	s_mov_b32 m0, s62
	s_add_i32 s76, s62, 0x2000
	global_load_lds_dwordx4 v[68:69], off
	v_lshl_add_u64 v[68:69], s[28:29], 0, v[164:165]
	s_mov_b32 m0, s76
	s_nop 0
	global_load_lds_dwordx4 v[68:69], off
	v_lshl_add_u64 v[68:69], v[248:249], 0, s[84:85]
	s_mov_b32 m0, s52
	s_nop 0
	global_load_lds_dwordx4 v[68:69], off
	v_lshl_add_u64 v[68:69], v[250:251], 0, s[84:85]
	s_mov_b32 m0, s53
	s_nop 0
	global_load_lds_dwordx4 v[68:69], off
	s_waitcnt vmcnt(8)
	s_waitcnt lgkmcnt(0)
	s_setprio 1
	s_barrier
	v_mfma_f32_16x16x32_bf16 v[68:71], v[20:23], v[120:123], v[144:147]
	v_mfma_f32_16x16x32_bf16 v[108:111], v[24:27], v[132:135], v[68:71]
	v_mfma_f32_16x16x32_bf16 v[68:71], v[28:31], v[120:123], v[148:151]
	v_mfma_f32_16x16x32_bf16 v[104:107], v[32:35], v[132:135], v[68:71]
	v_mfma_f32_16x16x32_bf16 v[68:71], v[20:23], v[222:225], v[152:155]
	v_mfma_f32_16x16x32_bf16 v[96:99], v[24:27], v[226:229], v[68:71]
	v_mfma_f32_16x16x32_bf16 v[68:71], v[28:31], v[222:225], v[156:159]
	v_mfma_f32_16x16x32_bf16 v[92:95], v[32:35], v[226:229], v[68:71]
	v_mfma_f32_16x16x32_bf16 v[68:71], v[20:23], v[230:233], v[170:173]
	v_mfma_f32_16x16x32_bf16 v[4:7], v[20:23], v[238:241], v[4:7]
	v_mfma_f32_16x16x32_bf16 v[84:87], v[24:27], v[234:237], v[68:71]
	v_mfma_f32_16x16x32_bf16 v[68:71], v[28:31], v[230:233], v[174:177]
	v_mfma_f32_16x16x32_bf16 v[72:75], v[24:27], v[242:245], v[4:7]
	v_mfma_f32_16x16x32_bf16 v[4:7], v[28:31], v[238:241], v[8:11]
	v_mfma_f32_16x16x32_bf16 v[80:83], v[32:35], v[234:237], v[68:71]
	v_mfma_f32_16x16x32_bf16 v[68:71], v[32:35], v[242:245], v[4:7]
	v_mfma_f32_16x16x32_bf16 v[4:7], v[206:209], v[120:123], v[12:15]
	v_mfma_f32_16x16x32_bf16 v[32:35], v[210:213], v[132:135], v[4:7]
	v_mfma_f32_16x16x32_bf16 v[4:7], v[214:217], v[120:123], v[16:19]
	v_mfma_f32_16x16x32_bf16 v[28:31], v[218:221], v[132:135], v[4:7]
	v_mfma_f32_16x16x32_bf16 v[4:7], v[206:209], v[222:225], v[178:181]
	v_mfma_f32_16x16x32_bf16 v[24:27], v[210:213], v[226:229], v[4:7]
	v_mfma_f32_16x16x32_bf16 v[4:7], v[214:217], v[222:225], v[182:185]
	v_mfma_f32_16x16x32_bf16 v[20:23], v[218:221], v[226:229], v[4:7]
	v_mfma_f32_16x16x32_bf16 v[4:7], v[206:209], v[230:233], v[186:189]
	v_mfma_f32_16x16x32_bf16 v[16:19], v[210:213], v[234:237], v[4:7]
	v_mfma_f32_16x16x32_bf16 v[4:7], v[214:217], v[230:233], v[190:193]
	v_mfma_f32_16x16x32_bf16 v[12:15], v[218:221], v[234:237], v[4:7]
	v_mfma_f32_16x16x32_bf16 v[4:7], v[206:209], v[238:241], v[194:197]
	v_mfma_f32_16x16x32_bf16 v[8:11], v[210:213], v[242:245], v[4:7]
	v_mfma_f32_16x16x32_bf16 v[4:7], v[214:217], v[238:241], v[198:201]
	v_mfma_f32_16x16x32_bf16 v[4:7], v[218:221], v[242:245], v[4:7]
	s_barrier
	s_setprio 0
	s_add_u32 s77, s26, 0x200
	s_addc_u32 s79, s27, 0
	s_mov_b32 s80, 0
.LBB0_1763:
	ds_read_b128 v[120:123], v2
	ds_read_b128 v[132:135], v2 offset:1024
	ds_read_b128 v[144:147], v2 offset:2048
	ds_read_b128 v[148:151], v2 offset:3072
	ds_read_b128 v[152:155], v112
	ds_read_b128 v[156:159], v112 offset:1024
	ds_read_b128 v[170:173], v112 offset:2048
	ds_read_b128 v[174:177], v112 offset:3072
	s_add_u32 s26, s24, 0x200
	s_addc_u32 s27, s25, 0
	s_cmp_eq_u32 s80, 40
	s_cselect_b32 s29, s21, s27
	s_cselect_b32 s28, s20, s26
	s_cselect_b32 s27, s23, s79
	s_cselect_b32 s26, s22, s77
	s_mov_b32 m0, s0
	v_lshl_add_u64 v[202:203], s[24:25], 0, v[166:167]
	ds_read_b128 v[178:181], v205
	ds_read_b128 v[182:185], v205 offset:1024
	ds_read_b128 v[186:189], v205 offset:2048
	ds_read_b128 v[190:193], v205 offset:3072
	ds_read_b128 v[194:197], v205 offset:4096
	ds_read_b128 v[198:201], v205 offset:5120
	ds_read_b128 v[206:209], v205 offset:6144
	ds_read_b128 v[210:213], v205 offset:7168
	global_load_lds_dwordx4 v[202:203], off
	v_lshl_add_u64 v[202:203], s[24:25], 0, v[168:169]
	s_mov_b32 m0, s1
	s_nop 0
	global_load_lds_dwordx4 v[202:203], off
	s_waitcnt vmcnt(8)
	s_waitcnt lgkmcnt(0)
	s_setprio 1
	s_barrier
	v_mfma_f32_16x16x32_bf16 v[140:143], v[120:123], v[178:181], v[140:143]
	v_mfma_f32_16x16x32_bf16 v[136:139], v[144:147], v[178:181], v[136:139]
	v_mfma_f32_16x16x32_bf16 v[128:131], v[120:123], v[186:189], v[128:131]
	v_mfma_f32_16x16x32_bf16 v[124:127], v[144:147], v[186:189], v[124:127]
	v_mfma_f32_16x16x32_bf16 v[116:119], v[120:123], v[194:197], v[116:119]
	v_mfma_f32_16x16x32_bf16 v[100:103], v[144:147], v[194:197], v[100:103]
	v_mfma_f32_16x16x32_bf16 v[88:91], v[120:123], v[206:209], v[88:91]
	v_mfma_f32_16x16x32_bf16 v[76:79], v[144:147], v[206:209], v[76:79]
	v_mfma_f32_16x16x32_bf16 v[140:143], v[132:135], v[182:185], v[140:143]
	v_mfma_f32_16x16x32_bf16 v[136:139], v[148:151], v[182:185], v[136:139]
	v_mfma_f32_16x16x32_bf16 v[128:131], v[132:135], v[190:193], v[128:131]
	v_mfma_f32_16x16x32_bf16 v[124:127], v[148:151], v[190:193], v[124:127]
	v_mfma_f32_16x16x32_bf16 v[116:119], v[132:135], v[198:201], v[116:119]
	v_mfma_f32_16x16x32_bf16 v[100:103], v[148:151], v[198:201], v[100:103]
	v_mfma_f32_16x16x32_bf16 v[88:91], v[132:135], v[210:213], v[88:91]
	v_mfma_f32_16x16x32_bf16 v[76:79], v[148:151], v[210:213], v[76:79]
	v_mfma_f32_16x16x32_bf16 v[64:67], v[152:155], v[178:181], v[64:67]
	v_mfma_f32_16x16x32_bf16 v[60:63], v[170:173], v[178:181], v[60:63]
	v_mfma_f32_16x16x32_bf16 v[56:59], v[152:155], v[186:189], v[56:59]
	v_mfma_f32_16x16x32_bf16 v[52:55], v[170:173], v[186:189], v[52:55]
	v_mfma_f32_16x16x32_bf16 v[48:51], v[152:155], v[194:197], v[48:51]
	v_mfma_f32_16x16x32_bf16 v[44:47], v[170:173], v[194:197], v[44:47]
	v_mfma_f32_16x16x32_bf16 v[40:43], v[152:155], v[206:209], v[40:43]
	v_mfma_f32_16x16x32_bf16 v[36:39], v[170:173], v[206:209], v[36:39]
	v_mfma_f32_16x16x32_bf16 v[64:67], v[156:159], v[182:185], v[64:67]
	v_mfma_f32_16x16x32_bf16 v[60:63], v[174:177], v[182:185], v[60:63]
	v_mfma_f32_16x16x32_bf16 v[56:59], v[156:159], v[190:193], v[56:59]
	v_mfma_f32_16x16x32_bf16 v[52:55], v[174:177], v[190:193], v[52:55]
	v_mfma_f32_16x16x32_bf16 v[48:51], v[156:159], v[198:201], v[48:51]
	v_mfma_f32_16x16x32_bf16 v[44:47], v[174:177], v[198:201], v[44:47]
	v_mfma_f32_16x16x32_bf16 v[40:43], v[156:159], v[210:213], v[40:43]
	v_mfma_f32_16x16x32_bf16 v[36:39], v[174:177], v[210:213], v[36:39]
	s_barrier
	s_setprio 0
	s_mov_b32 m0, s3
	v_lshl_add_u64 v[202:203], s[26:27], 0, v[160:161]
	s_add_u32 s66, s26, 0xb0000
	ds_read_b128 v[178:181], v205 offset:16384
	ds_read_b128 v[182:185], v205 offset:17408
	ds_read_b128 v[186:189], v205 offset:18432
	ds_read_b128 v[190:193], v205 offset:19456
	ds_read_b128 v[194:197], v205 offset:20480
	ds_read_b128 v[198:201], v205 offset:21504
	ds_read_b128 v[206:209], v205 offset:22528
	ds_read_b128 v[210:213], v205 offset:23552
	global_load_lds_dwordx4 v[202:203], off
	v_lshl_add_u64 v[214:215], s[26:27], 0, v[164:165]
	s_mov_b32 m0, s40
	s_addc_u32 s67, s27, 0
	global_load_lds_dwordx4 v[214:215], off
	v_lshl_add_u64 v[216:217], s[66:67], 0, v[160:161]
	s_mov_b32 m0, s41
	v_lshl_add_u64 v[218:219], s[28:29], 0, v[162:163]
	global_load_lds_dwordx4 v[216:217], off
	v_lshl_add_u64 v[216:217], s[66:67], 0, v[164:165]
	s_mov_b32 m0, s59
	s_nop 0
	global_load_lds_dwordx4 v[216:217], off
	v_lshl_add_u64 v[216:217], s[28:29], 0, v[0:1]
	s_mov_b32 m0, s44
	s_nop 0
	global_load_lds_dwordx4 v[216:217], off
	s_mov_b32 m0, s45
	s_nop 0
	global_load_lds_dwordx4 v[218:219], off
	s_waitcnt vmcnt(8)
	s_waitcnt lgkmcnt(0)
	s_setprio 1
	s_barrier
	v_mfma_f32_16x16x32_bf16 v[108:111], v[120:123], v[178:181], v[108:111]
	v_mfma_f32_16x16x32_bf16 v[104:107], v[144:147], v[178:181], v[104:107]
	v_mfma_f32_16x16x32_bf16 v[96:99], v[120:123], v[186:189], v[96:99]
	v_mfma_f32_16x16x32_bf16 v[92:95], v[144:147], v[186:189], v[92:95]
	v_mfma_f32_16x16x32_bf16 v[84:87], v[120:123], v[194:197], v[84:87]
	v_mfma_f32_16x16x32_bf16 v[80:83], v[144:147], v[194:197], v[80:83]
	v_mfma_f32_16x16x32_bf16 v[72:75], v[120:123], v[206:209], v[72:75]
	v_mfma_f32_16x16x32_bf16 v[68:71], v[144:147], v[206:209], v[68:71]
	v_mfma_f32_16x16x32_bf16 v[108:111], v[132:135], v[182:185], v[108:111]
	v_mfma_f32_16x16x32_bf16 v[104:107], v[148:151], v[182:185], v[104:107]
	v_mfma_f32_16x16x32_bf16 v[96:99], v[132:135], v[190:193], v[96:99]
	v_mfma_f32_16x16x32_bf16 v[92:95], v[148:151], v[190:193], v[92:95]
	v_mfma_f32_16x16x32_bf16 v[84:87], v[132:135], v[198:201], v[84:87]
	v_mfma_f32_16x16x32_bf16 v[80:83], v[148:151], v[198:201], v[80:83]
	v_mfma_f32_16x16x32_bf16 v[72:75], v[132:135], v[210:213], v[72:75]
	v_mfma_f32_16x16x32_bf16 v[68:71], v[148:151], v[210:213], v[68:71]
	v_mfma_f32_16x16x32_bf16 v[32:35], v[152:155], v[178:181], v[32:35]
	v_mfma_f32_16x16x32_bf16 v[28:31], v[170:173], v[178:181], v[28:31]
	v_mfma_f32_16x16x32_bf16 v[24:27], v[152:155], v[186:189], v[24:27]
	v_mfma_f32_16x16x32_bf16 v[20:23], v[170:173], v[186:189], v[20:23]
	v_mfma_f32_16x16x32_bf16 v[16:19], v[152:155], v[194:197], v[16:19]
	v_mfma_f32_16x16x32_bf16 v[12:15], v[170:173], v[194:197], v[12:15]
	v_mfma_f32_16x16x32_bf16 v[8:11], v[152:155], v[206:209], v[8:11]
	v_mfma_f32_16x16x32_bf16 v[4:7], v[170:173], v[206:209], v[4:7]
	v_mfma_f32_16x16x32_bf16 v[32:35], v[156:159], v[182:185], v[32:35]
	v_mfma_f32_16x16x32_bf16 v[28:31], v[174:177], v[182:185], v[28:31]
	v_mfma_f32_16x16x32_bf16 v[24:27], v[156:159], v[190:193], v[24:27]
	v_mfma_f32_16x16x32_bf16 v[20:23], v[174:177], v[190:193], v[20:23]
	v_mfma_f32_16x16x32_bf16 v[16:19], v[156:159], v[198:201], v[16:19]
	v_mfma_f32_16x16x32_bf16 v[12:15], v[174:177], v[198:201], v[12:15]
	v_mfma_f32_16x16x32_bf16 v[8:11], v[156:159], v[210:213], v[8:11]
	v_mfma_f32_16x16x32_bf16 v[4:7], v[174:177], v[210:213], v[4:7]
	s_barrier
	s_setprio 0
	ds_read_b128 v[120:123], v113
	ds_read_b128 v[132:135], v113 offset:1024
	ds_read_b128 v[144:147], v113 offset:2048
	ds_read_b128 v[148:151], v113 offset:3072
	ds_read_b128 v[152:155], v114
	ds_read_b128 v[156:159], v114 offset:1024
	ds_read_b128 v[170:173], v114 offset:2048
	ds_read_b128 v[174:177], v114 offset:3072
	s_add_u32 s28, s28, 0xb0000
	s_addc_u32 s29, s29, 0
	s_mov_b32 m0, s46
	v_lshl_add_u64 v[220:221], s[28:29], 0, v[0:1]
	ds_read_b128 v[178:181], v205 offset:32768
	ds_read_b128 v[182:185], v205 offset:33792
	ds_read_b128 v[186:189], v205 offset:34816
	ds_read_b128 v[190:193], v205 offset:35840
	ds_read_b128 v[194:197], v205 offset:36864
	ds_read_b128 v[198:201], v205 offset:37888
	ds_read_b128 v[206:209], v205 offset:38912
	ds_read_b128 v[210:213], v205 offset:39936
	global_load_lds_dwordx4 v[220:221], off
	v_lshl_add_u64 v[220:221], s[28:29], 0, v[162:163]
	s_mov_b32 m0, s48
	s_nop 0
	global_load_lds_dwordx4 v[220:221], off
	s_waitcnt vmcnt(8)
	s_waitcnt lgkmcnt(0)
	s_setprio 1
	s_barrier
	v_mfma_f32_16x16x32_bf16 v[140:143], v[120:123], v[178:181], v[140:143]
	v_mfma_f32_16x16x32_bf16 v[136:139], v[144:147], v[178:181], v[136:139]
	v_mfma_f32_16x16x32_bf16 v[128:131], v[120:123], v[186:189], v[128:131]
	v_mfma_f32_16x16x32_bf16 v[124:127], v[144:147], v[186:189], v[124:127]
	v_mfma_f32_16x16x32_bf16 v[116:119], v[120:123], v[194:197], v[116:119]
	v_mfma_f32_16x16x32_bf16 v[100:103], v[144:147], v[194:197], v[100:103]
	v_mfma_f32_16x16x32_bf16 v[88:91], v[120:123], v[206:209], v[88:91]
	v_mfma_f32_16x16x32_bf16 v[76:79], v[144:147], v[206:209], v[76:79]
	v_mfma_f32_16x16x32_bf16 v[140:143], v[132:135], v[182:185], v[140:143]
	v_mfma_f32_16x16x32_bf16 v[136:139], v[148:151], v[182:185], v[136:139]
	v_mfma_f32_16x16x32_bf16 v[128:131], v[132:135], v[190:193], v[128:131]
	v_mfma_f32_16x16x32_bf16 v[124:127], v[148:151], v[190:193], v[124:127]
	v_mfma_f32_16x16x32_bf16 v[116:119], v[132:135], v[198:201], v[116:119]
	v_mfma_f32_16x16x32_bf16 v[100:103], v[148:151], v[198:201], v[100:103]
	v_mfma_f32_16x16x32_bf16 v[88:91], v[132:135], v[210:213], v[88:91]
	v_mfma_f32_16x16x32_bf16 v[76:79], v[148:151], v[210:213], v[76:79]
	v_mfma_f32_16x16x32_bf16 v[64:67], v[152:155], v[178:181], v[64:67]
	v_mfma_f32_16x16x32_bf16 v[60:63], v[170:173], v[178:181], v[60:63]
	v_mfma_f32_16x16x32_bf16 v[56:59], v[152:155], v[186:189], v[56:59]
	v_mfma_f32_16x16x32_bf16 v[52:55], v[170:173], v[186:189], v[52:55]
	v_mfma_f32_16x16x32_bf16 v[48:51], v[152:155], v[194:197], v[48:51]
	v_mfma_f32_16x16x32_bf16 v[44:47], v[170:173], v[194:197], v[44:47]
	v_mfma_f32_16x16x32_bf16 v[40:43], v[152:155], v[206:209], v[40:43]
	v_mfma_f32_16x16x32_bf16 v[36:39], v[170:173], v[206:209], v[36:39]
	v_mfma_f32_16x16x32_bf16 v[64:67], v[156:159], v[182:185], v[64:67]
	v_mfma_f32_16x16x32_bf16 v[60:63], v[174:177], v[182:185], v[60:63]
	v_mfma_f32_16x16x32_bf16 v[56:59], v[156:159], v[190:193], v[56:59]
	v_mfma_f32_16x16x32_bf16 v[52:55], v[174:177], v[190:193], v[52:55]
	v_mfma_f32_16x16x32_bf16 v[48:51], v[156:159], v[198:201], v[48:51]
	v_mfma_f32_16x16x32_bf16 v[44:47], v[174:177], v[198:201], v[44:47]
	v_mfma_f32_16x16x32_bf16 v[40:43], v[156:159], v[210:213], v[40:43]
	v_mfma_f32_16x16x32_bf16 v[36:39], v[174:177], v[210:213], v[36:39]
	s_barrier
	s_setprio 0
	s_mov_b32 m0, s60
	v_lshl_add_u64 v[202:203], v[202:203], 0, s[74:75]
	s_add_u32 s26, s26, 0xb0080
	ds_read_b128 v[178:181], v205 offset:49152
	ds_read_b128 v[182:185], v205 offset:50176
	ds_read_b128 v[186:189], v205 offset:51200
	ds_read_b128 v[190:193], v205 offset:52224
	ds_read_b128 v[194:197], v205 offset:53248
	ds_read_b128 v[198:201], v205 offset:54272
	ds_read_b128 v[206:209], v205 offset:55296
	ds_read_b128 v[210:213], v205 offset:56320
	global_load_lds_dwordx4 v[202:203], off
	v_lshl_add_u64 v[202:203], v[214:215], 0, s[74:75]
	s_mov_b32 m0, s61
	s_addc_u32 s27, s27, 0
	global_load_lds_dwordx4 v[202:203], off
	v_lshl_add_u64 v[202:203], s[26:27], 0, v[160:161]
	s_mov_b32 m0, s62
	s_nop 0
	global_load_lds_dwordx4 v[202:203], off
	v_lshl_add_u64 v[202:203], s[26:27], 0, v[164:165]
	s_mov_b32 m0, s76
	s_nop 0
	global_load_lds_dwordx4 v[202:203], off
	v_lshl_add_u64 v[202:203], v[216:217], 0, s[74:75]
	s_mov_b32 m0, s52
	s_nop 0
	global_load_lds_dwordx4 v[202:203], off
	v_lshl_add_u64 v[202:203], v[218:219], 0, s[74:75]
	s_mov_b32 m0, s53
	s_nop 0
	global_load_lds_dwordx4 v[202:203], off
	s_waitcnt vmcnt(8)
	s_waitcnt lgkmcnt(0)
	s_setprio 1
	s_barrier
	v_mfma_f32_16x16x32_bf16 v[108:111], v[120:123], v[178:181], v[108:111]
	v_mfma_f32_16x16x32_bf16 v[104:107], v[144:147], v[178:181], v[104:107]
	v_mfma_f32_16x16x32_bf16 v[96:99], v[120:123], v[186:189], v[96:99]
	v_mfma_f32_16x16x32_bf16 v[92:95], v[144:147], v[186:189], v[92:95]
	v_mfma_f32_16x16x32_bf16 v[84:87], v[120:123], v[194:197], v[84:87]
	v_mfma_f32_16x16x32_bf16 v[80:83], v[144:147], v[194:197], v[80:83]
	v_mfma_f32_16x16x32_bf16 v[72:75], v[120:123], v[206:209], v[72:75]
	v_mfma_f32_16x16x32_bf16 v[68:71], v[144:147], v[206:209], v[68:71]
	v_mfma_f32_16x16x32_bf16 v[108:111], v[132:135], v[182:185], v[108:111]
	v_mfma_f32_16x16x32_bf16 v[104:107], v[148:151], v[182:185], v[104:107]
	v_mfma_f32_16x16x32_bf16 v[96:99], v[132:135], v[190:193], v[96:99]
	v_mfma_f32_16x16x32_bf16 v[92:95], v[148:151], v[190:193], v[92:95]
	v_mfma_f32_16x16x32_bf16 v[84:87], v[132:135], v[198:201], v[84:87]
	v_mfma_f32_16x16x32_bf16 v[80:83], v[148:151], v[198:201], v[80:83]
	v_mfma_f32_16x16x32_bf16 v[72:75], v[132:135], v[210:213], v[72:75]
	v_mfma_f32_16x16x32_bf16 v[68:71], v[148:151], v[210:213], v[68:71]
	v_mfma_f32_16x16x32_bf16 v[32:35], v[152:155], v[178:181], v[32:35]
	v_mfma_f32_16x16x32_bf16 v[28:31], v[170:173], v[178:181], v[28:31]
	v_mfma_f32_16x16x32_bf16 v[24:27], v[152:155], v[186:189], v[24:27]
	v_mfma_f32_16x16x32_bf16 v[20:23], v[170:173], v[186:189], v[20:23]
	v_mfma_f32_16x16x32_bf16 v[16:19], v[152:155], v[194:197], v[16:19]
	v_mfma_f32_16x16x32_bf16 v[12:15], v[170:173], v[194:197], v[12:15]
	v_mfma_f32_16x16x32_bf16 v[8:11], v[152:155], v[206:209], v[8:11]
	v_mfma_f32_16x16x32_bf16 v[4:7], v[170:173], v[206:209], v[4:7]
	v_mfma_f32_16x16x32_bf16 v[32:35], v[156:159], v[182:185], v[32:35]
	v_mfma_f32_16x16x32_bf16 v[28:31], v[174:177], v[182:185], v[28:31]
	v_mfma_f32_16x16x32_bf16 v[24:27], v[156:159], v[190:193], v[24:27]
	v_mfma_f32_16x16x32_bf16 v[20:23], v[174:177], v[190:193], v[20:23]
	v_mfma_f32_16x16x32_bf16 v[16:19], v[156:159], v[198:201], v[16:19]
	v_mfma_f32_16x16x32_bf16 v[12:15], v[174:177], v[198:201], v[12:15]
	v_mfma_f32_16x16x32_bf16 v[8:11], v[156:159], v[210:213], v[8:11]
	v_mfma_f32_16x16x32_bf16 v[4:7], v[174:177], v[210:213], v[4:7]
	s_barrier
	s_setprio 0
	s_add_i32 s80, s80, 2
	s_add_u32 s24, s24, 0x100
	s_addc_u32 s25, s25, 0
	s_add_u32 s77, s77, 0x100
	s_addc_u32 s79, s79, 0
	s_cmp_gt_u32 s80, 41
	s_cbranch_scc0 .LBB0_1763
	s_and_b64 vcc, exec, s[18:19]
	s_cbranch_vccz .LBB0_1766
	s_barrier

.LBB0_1817:
	s_and_b32 s15, s2, 0x1e0
	s_bitset1_b32 s15, 15
	v_or_b32_e32 v0, s15, v86
	v_mul_u32_u24_e32 v0, 0xb00, v0
	s_ashr_i32 s16, s0, 4
	v_lshlrev_b32_e32 v2, 1, v0
	s_lshl_b32 s14, s16, 6
	v_lshl_add_u64 v[52:53], v[78:79], 0, v[2:3]
	s_mov_b32 s17, 0x16000
	v_or_b32_e32 v1, s14, v86
	v_add_co_u32_e32 v0, vcc, s17, v52
	v_mad_i64_i32 v[4:5], s[18:19], v1, s60, v[76:77]
	s_nop 0
	v_addc_co_u32_e32 v1, vcc, 0, v53, vcc
	v_add_co_u32_e32 v54, vcc, s17, v4
	s_mov_b32 s17, 0x2c000
	s_nop 0
	v_addc_co_u32_e32 v55, vcc, 0, v5, vcc
	v_add_co_u32_e32 v82, vcc, s17, v4
	s_mov_b32 s17, 0x42000
	s_nop 0
	v_addc_co_u32_e32 v83, vcc, 0, v5, vcc
	v_add_co_u32_e32 v84, vcc, s17, v4
	s_waitcnt lgkmcnt(0)
	s_nop 1
	v_addc_co_u32_e32 v85, vcc, 0, v5, vcc
	v_mov_b64_e32 v[132:133], v[0:1]
	v_mov_b64_e32 v[134:135], v[52:53]
	v_mov_b64_e32 v[136:137], v[54:55]
	v_add_u32_e32 v0, s15, v87
	v_ashrrev_i32_e32 v1, 31, v0
	v_lshlrev_b64 v[24:25], 8, v[0:1]
	v_lshl_add_u64 v[24:25], v[80:81], 0, v[24:25]
	global_load_dwordx4 v[24:27], v[24:25], off
	v_or_b32_e32 v68, s14, v88
	v_lshlrev_b64 v[28:29], 10, v[0:1]
	v_ashrrev_i32_e32 v69, 31, v68
	v_lshl_add_u64 v[28:29], v[28:29], 0, v[68:69]
	v_lshlrev_b64 v[70:71], 1, v[28:29]
	v_lshl_add_u64 v[28:29], s[4:5], 0, v[70:71]
	global_load_dwordx2 v[72:73], v[28:29], off
	v_lshlrev_b64 v[60:61], 2, v[68:69]
	v_lshl_add_u64 v[56:57], s[10:11], 0, v[60:61]
	global_load_dwordx4 v[56:59], v[56:57], off
	v_lshl_add_u64 v[52:53], s[12:13], 0, v[60:61]
	global_load_dwordx4 v[52:55], v[52:53], off
	global_load_dwordx4 v[140:143], v[4:5], off
	global_load_dwordx4 v[144:147], v[136:137], off
	global_load_dwordx4 v[148:151], v[82:83], off
	global_load_dwordx4 v[152:155], v[84:85], off
	global_load_dwordx4 v[156:159], v[134:135], off
	global_load_dwordx4 v[160:163], v[132:133], off
	global_load_dwordx4 v[164:167], v[4:5], off offset:64
	global_load_dwordx4 v[168:171], v[136:137], off offset:64
	global_load_dwordx4 v[172:175], v[82:83], off offset:64
	global_load_dwordx4 v[176:179], v[84:85], off offset:64
	global_load_dwordx4 v[180:183], v[134:135], off offset:64
	global_load_dwordx4 v[184:187], v[132:133], off offset:64
	global_load_dwordx4 v[188:191], v[4:5], off offset:128
	global_load_dwordx4 v[192:195], v[136:137], off offset:128
	global_load_dwordx4 v[196:199], v[82:83], off offset:128
	global_load_dwordx4 v[200:203], v[84:85], off offset:128
	global_load_dwordx4 v[204:207], v[134:135], off offset:128
	global_load_dwordx4 v[208:211], v[132:133], off offset:128
	global_load_dwordx4 v[212:215], v[4:5], off offset:192
	global_load_dwordx4 v[216:219], v[136:137], off offset:192
	global_load_dwordx4 v[220:223], v[82:83], off offset:192
	global_load_dwordx4 v[224:227], v[84:85], off offset:192
	global_load_dwordx4 v[228:231], v[134:135], off offset:192
	global_load_dwordx4 v[232:235], v[132:133], off offset:192
	global_load_dwordx4 v[236:239], v[4:5], off offset:256
	global_load_dwordx4 v[240:243], v[136:137], off offset:256
	global_load_dwordx4 v[6:9], v[82:83], off offset:256
	global_load_dwordx4 v[10:13], v[84:85], off offset:256
	global_load_dwordx4 v[14:17], v[134:135], off offset:256
	global_load_dwordx4 v[18:21], v[132:133], off offset:256
	s_waitcnt vmcnt(24)
	v_mfma_f32_16x16x32_bf16 v[100:103], v[140:143], v[156:159], 0
	v_mfma_f32_16x16x32_bf16 v[104:107], v[144:147], v[156:159], 0
	v_mfma_f32_16x16x32_bf16 v[108:111], v[148:151], v[156:159], 0
	v_mfma_f32_16x16x32_bf16 v[112:115], v[152:155], v[156:159], 0
	v_mfma_f32_16x16x32_bf16 v[116:119], v[140:143], v[160:163], 0
	v_mfma_f32_16x16x32_bf16 v[120:123], v[144:147], v[160:163], 0
	v_mfma_f32_16x16x32_bf16 v[124:127], v[148:151], v[160:163], 0
	v_mfma_f32_16x16x32_bf16 v[128:131], v[152:155], v[160:163], 0
	global_load_dwordx4 v[140:143], v[4:5], off offset:320
	global_load_dwordx4 v[144:147], v[136:137], off offset:320
	global_load_dwordx4 v[148:151], v[82:83], off offset:320
	global_load_dwordx4 v[152:155], v[84:85], off offset:320
	global_load_dwordx4 v[156:159], v[134:135], off offset:320
	global_load_dwordx4 v[160:163], v[132:133], off offset:320
	s_waitcnt vmcnt(24)
	v_mfma_f32_16x16x32_bf16 v[100:103], v[164:167], v[180:183], v[100:103]
	v_mfma_f32_16x16x32_bf16 v[104:107], v[168:171], v[180:183], v[104:107]
	v_mfma_f32_16x16x32_bf16 v[108:111], v[172:175], v[180:183], v[108:111]
	v_mfma_f32_16x16x32_bf16 v[112:115], v[176:179], v[180:183], v[112:115]
	v_mfma_f32_16x16x32_bf16 v[116:119], v[164:167], v[184:187], v[116:119]
	v_mfma_f32_16x16x32_bf16 v[120:123], v[168:171], v[184:187], v[120:123]
	v_mfma_f32_16x16x32_bf16 v[124:127], v[172:175], v[184:187], v[124:127]
	v_mfma_f32_16x16x32_bf16 v[128:131], v[176:179], v[184:187], v[128:131]
	global_load_dwordx4 v[164:167], v[4:5], off offset:384
	global_load_dwordx4 v[168:171], v[136:137], off offset:384
	global_load_dwordx4 v[172:175], v[82:83], off offset:384
	global_load_dwordx4 v[176:179], v[84:85], off offset:384
	global_load_dwordx4 v[180:183], v[134:135], off offset:384
	global_load_dwordx4 v[184:187], v[132:133], off offset:384
	s_waitcnt vmcnt(24)
	v_mfma_f32_16x16x32_bf16 v[100:103], v[188:191], v[204:207], v[100:103]
	v_mfma_f32_16x16x32_bf16 v[104:107], v[192:195], v[204:207], v[104:107]
	v_mfma_f32_16x16x32_bf16 v[108:111], v[196:199], v[204:207], v[108:111]
	v_mfma_f32_16x16x32_bf16 v[112:115], v[200:203], v[204:207], v[112:115]
	v_mfma_f32_16x16x32_bf16 v[116:119], v[188:191], v[208:211], v[116:119]
	v_mfma_f32_16x16x32_bf16 v[120:123], v[192:195], v[208:211], v[120:123]
	v_mfma_f32_16x16x32_bf16 v[124:127], v[196:199], v[208:211], v[124:127]
	v_mfma_f32_16x16x32_bf16 v[128:131], v[200:203], v[208:211], v[128:131]
	global_load_dwordx4 v[188:191], v[4:5], off offset:448
	global_load_dwordx4 v[192:195], v[136:137], off offset:448
	global_load_dwordx4 v[196:199], v[82:83], off offset:448
	global_load_dwordx4 v[200:203], v[84:85], off offset:448
	global_load_dwordx4 v[204:207], v[134:135], off offset:448
	global_load_dwordx4 v[208:211], v[132:133], off offset:448
	s_waitcnt vmcnt(24)
	v_mfma_f32_16x16x32_bf16 v[100:103], v[212:215], v[228:231], v[100:103]
	v_mfma_f32_16x16x32_bf16 v[104:107], v[216:219], v[228:231], v[104:107]
	v_mfma_f32_16x16x32_bf16 v[108:111], v[220:223], v[228:231], v[108:111]
	v_mfma_f32_16x16x32_bf16 v[112:115], v[224:227], v[228:231], v[112:115]
	v_mfma_f32_16x16x32_bf16 v[116:119], v[212:215], v[232:235], v[116:119]
	v_mfma_f32_16x16x32_bf16 v[120:123], v[216:219], v[232:235], v[120:123]
	v_mfma_f32_16x16x32_bf16 v[124:127], v[220:223], v[232:235], v[124:127]
	v_mfma_f32_16x16x32_bf16 v[128:131], v[224:227], v[232:235], v[128:131]
	global_load_dwordx4 v[212:215], v[4:5], off offset:512
	global_load_dwordx4 v[216:219], v[136:137], off offset:512
	global_load_dwordx4 v[220:223], v[82:83], off offset:512
	global_load_dwordx4 v[224:227], v[84:85], off offset:512
	global_load_dwordx4 v[228:231], v[134:135], off offset:512
	global_load_dwordx4 v[232:235], v[132:133], off offset:512
	s_waitcnt vmcnt(24)
	v_mfma_f32_16x16x32_bf16 v[100:103], v[236:239], v[14:17], v[100:103]
	v_mfma_f32_16x16x32_bf16 v[104:107], v[240:243], v[14:17], v[104:107]
	v_mfma_f32_16x16x32_bf16 v[108:111], v[6:9], v[14:17], v[108:111]
	v_mfma_f32_16x16x32_bf16 v[112:115], v[10:13], v[14:17], v[112:115]
	v_mfma_f32_16x16x32_bf16 v[116:119], v[236:239], v[18:21], v[116:119]
	v_mfma_f32_16x16x32_bf16 v[120:123], v[240:243], v[18:21], v[120:123]
	v_mfma_f32_16x16x32_bf16 v[124:127], v[6:9], v[18:21], v[124:127]
	v_mfma_f32_16x16x32_bf16 v[128:131], v[10:13], v[18:21], v[128:131]
	global_load_dwordx4 v[236:239], v[4:5], off offset:576
	global_load_dwordx4 v[240:243], v[136:137], off offset:576
	global_load_dwordx4 v[6:9], v[82:83], off offset:576
	global_load_dwordx4 v[10:13], v[84:85], off offset:576
	global_load_dwordx4 v[14:17], v[134:135], off offset:576
	global_load_dwordx4 v[18:21], v[132:133], off offset:576
	s_waitcnt vmcnt(24)
	v_mfma_f32_16x16x32_bf16 v[100:103], v[140:143], v[156:159], v[100:103]
	v_mfma_f32_16x16x32_bf16 v[104:107], v[144:147], v[156:159], v[104:107]
	v_mfma_f32_16x16x32_bf16 v[108:111], v[148:151], v[156:159], v[108:111]
	v_mfma_f32_16x16x32_bf16 v[112:115], v[152:155], v[156:159], v[112:115]
	v_mfma_f32_16x16x32_bf16 v[116:119], v[140:143], v[160:163], v[116:119]
	v_mfma_f32_16x16x32_bf16 v[120:123], v[144:147], v[160:163], v[120:123]
	v_mfma_f32_16x16x32_bf16 v[124:127], v[148:151], v[160:163], v[124:127]
	v_mfma_f32_16x16x32_bf16 v[128:131], v[152:155], v[160:163], v[128:131]
	global_load_dwordx4 v[140:143], v[4:5], off offset:640
	global_load_dwordx4 v[144:147], v[136:137], off offset:640
	global_load_dwordx4 v[148:151], v[82:83], off offset:640
	global_load_dwordx4 v[152:155], v[84:85], off offset:640
	global_load_dwordx4 v[156:159], v[134:135], off offset:640
	global_load_dwordx4 v[160:163], v[132:133], off offset:640
	s_waitcnt vmcnt(24)
	v_mfma_f32_16x16x32_bf16 v[100:103], v[164:167], v[180:183], v[100:103]
	v_mfma_f32_16x16x32_bf16 v[104:107], v[168:171], v[180:183], v[104:107]
	v_mfma_f32_16x16x32_bf16 v[108:111], v[172:175], v[180:183], v[108:111]
	v_mfma_f32_16x16x32_bf16 v[112:115], v[176:179], v[180:183], v[112:115]
	v_mfma_f32_16x16x32_bf16 v[116:119], v[164:167], v[184:187], v[116:119]
	v_mfma_f32_16x16x32_bf16 v[120:123], v[168:171], v[184:187], v[120:123]
	v_mfma_f32_16x16x32_bf16 v[124:127], v[172:175], v[184:187], v[124:127]
	v_mfma_f32_16x16x32_bf16 v[128:131], v[176:179], v[184:187], v[128:131]
	s_waitcnt vmcnt(18)
	v_mfma_f32_16x16x32_bf16 v[100:103], v[188:191], v[204:207], v[100:103]
	v_mfma_f32_16x16x32_bf16 v[104:107], v[192:195], v[204:207], v[104:107]
	v_mfma_f32_16x16x32_bf16 v[108:111], v[196:199], v[204:207], v[108:111]
	v_mfma_f32_16x16x32_bf16 v[112:115], v[200:203], v[204:207], v[112:115]
	v_mfma_f32_16x16x32_bf16 v[116:119], v[188:191], v[208:211], v[116:119]
	v_mfma_f32_16x16x32_bf16 v[120:123], v[192:195], v[208:211], v[120:123]
	v_mfma_f32_16x16x32_bf16 v[124:127], v[196:199], v[208:211], v[124:127]
	v_mfma_f32_16x16x32_bf16 v[128:131], v[200:203], v[208:211], v[128:131]
	s_waitcnt vmcnt(12)
	v_mfma_f32_16x16x32_bf16 v[100:103], v[212:215], v[228:231], v[100:103]
	v_mfma_f32_16x16x32_bf16 v[104:107], v[216:219], v[228:231], v[104:107]
	v_mfma_f32_16x16x32_bf16 v[108:111], v[220:223], v[228:231], v[108:111]
	v_mfma_f32_16x16x32_bf16 v[112:115], v[224:227], v[228:231], v[112:115]
	v_mfma_f32_16x16x32_bf16 v[116:119], v[212:215], v[232:235], v[116:119]
	v_mfma_f32_16x16x32_bf16 v[120:123], v[216:219], v[232:235], v[120:123]
	v_mfma_f32_16x16x32_bf16 v[124:127], v[220:223], v[232:235], v[124:127]
	v_mfma_f32_16x16x32_bf16 v[128:131], v[224:227], v[232:235], v[128:131]
	s_waitcnt vmcnt(6)
	v_mfma_f32_16x16x32_bf16 v[100:103], v[236:239], v[14:17], v[100:103]
	v_mfma_f32_16x16x32_bf16 v[104:107], v[240:243], v[14:17], v[104:107]
	v_mfma_f32_16x16x32_bf16 v[108:111], v[6:9], v[14:17], v[108:111]
	v_mfma_f32_16x16x32_bf16 v[112:115], v[10:13], v[14:17], v[112:115]
	v_mfma_f32_16x16x32_bf16 v[116:119], v[236:239], v[18:21], v[116:119]
	v_mfma_f32_16x16x32_bf16 v[120:123], v[240:243], v[18:21], v[120:123]
	v_mfma_f32_16x16x32_bf16 v[124:127], v[6:9], v[18:21], v[124:127]
	v_mfma_f32_16x16x32_bf16 v[128:131], v[10:13], v[18:21], v[128:131]
	s_waitcnt vmcnt(0)
	v_mfma_f32_16x16x32_bf16 v[100:103], v[140:143], v[156:159], v[100:103]
	v_mfma_f32_16x16x32_bf16 v[104:107], v[144:147], v[156:159], v[104:107]
	v_mfma_f32_16x16x32_bf16 v[108:111], v[148:151], v[156:159], v[108:111]
	v_mfma_f32_16x16x32_bf16 v[112:115], v[152:155], v[156:159], v[112:115]
	v_mfma_f32_16x16x32_bf16 v[116:119], v[140:143], v[160:163], v[116:119]
	v_mfma_f32_16x16x32_bf16 v[120:123], v[144:147], v[160:163], v[120:123]
	v_mfma_f32_16x16x32_bf16 v[124:127], v[148:151], v[160:163], v[124:127]
	v_mfma_f32_16x16x32_bf16 v[128:131], v[152:155], v[160:163], v[128:131]
	s_nop 7
	s_nop 1
	ds_write_b128 v94, v[100:103]
	ds_write_b128 v95, v[104:107]
	ds_write_b128 v96, v[108:111]
	ds_write_b128 v97, v[112:115]
	ds_write_b128 v94, v[116:119] offset:4096
	ds_write_b128 v95, v[120:123] offset:4096
	ds_write_b128 v96, v[124:127] offset:4096
	ds_write_b128 v97, v[128:131] offset:4096
	s_waitcnt vmcnt(0)
	v_pk_add_f32 v[12:13], v[24:25], v[26:27]
	ds_bpermute_b32 v14, v90, v12
	ds_bpermute_b32 v15, v90, v13
	s_waitcnt lgkmcnt(0)
	v_pk_add_f32 v[12:13], v[12:13], v[14:15]
	ds_bpermute_b32 v14, v91, v12
	ds_bpermute_b32 v15, v91, v13
	s_waitcnt lgkmcnt(0)
	v_pk_add_f32 v[12:13], v[12:13], v[14:15]
	ds_bpermute_b32 v14, v92, v12
	s_waitcnt lgkmcnt(0)
	s_barrier
	ds_read_b128 v[4:7], v89
	ds_read_b128 v[8:11], v89 offset:8192
	ds_bpermute_b32 v15, v92, v13
	s_waitcnt lgkmcnt(2)
	v_pk_add_f32 v[6:7], v[6:7], 0 op_sel_hi:[1,0]
	v_pk_add_f32 v[16:17], v[4:5], 0 op_sel_hi:[1,0]
	s_waitcnt lgkmcnt(1)
	v_pk_add_f32 v[18:19], v[6:7], v[10:11]
	ds_read_b128 v[4:7], v89 offset:16384
	v_pk_add_f32 v[16:17], v[16:17], v[8:9]
	ds_read_b128 v[8:11], v89 offset:24576
	s_waitcnt lgkmcnt(2)
	v_pk_add_f32 v[12:13], v[12:13], v[14:15]
	ds_bpermute_b32 v14, v93, v12
	s_waitcnt lgkmcnt(2)
	v_pk_add_f32 v[6:7], v[18:19], v[6:7]
	v_pk_add_f32 v[4:5], v[16:17], v[4:5]
	s_waitcnt lgkmcnt(1)
	v_pk_add_f32 v[16:17], v[6:7], v[10:11]
	v_pk_add_f32 v[18:19], v[4:5], v[8:9]
	ds_read_b128 v[4:7], v89 offset:32768
	ds_read_b128 v[8:11], v89 offset:40960
	ds_bpermute_b32 v15, v93, v13
	s_waitcnt lgkmcnt(2)
	v_pk_add_f32 v[6:7], v[16:17], v[6:7]
	v_pk_add_f32 v[16:17], v[18:19], v[4:5]
	s_waitcnt lgkmcnt(1)
	v_pk_add_f32 v[18:19], v[6:7], v[10:11]
	s_waitcnt lgkmcnt(0)
	v_pk_add_f32 v[10:11], v[12:13], v[14:15]
	v_pk_add_f32 v[14:15], v[16:17], v[8:9]
	v_pk_mul_f32 v[12:13], v[10:11], s[78:79] op_sel_hi:[1,0]
	ds_read_b128 v[4:7], v89 offset:49152
	v_fma_f32 v2, -v12, v12, v13
	v_max_f32_e32 v2, 0, v2
	v_add_f32_e32 v2, 0x3727c5ac, v2
	v_mul_f32_e32 v10, 0x4f800000, v2
	v_cmp_gt_f32_e32 vcc, s89, v2
	s_nop 1
	v_cndmask_b32_e32 v2, v2, v10, vcc
	v_sqrt_f32_e32 v13, v2
	ds_read_b128 v[8:11], v89 offset:57344
	s_waitcnt lgkmcnt(1)
	v_pk_add_f32 v[4:5], v[14:15], v[4:5]
	v_pk_add_f32 v[6:7], v[18:19], v[6:7]
	v_add_u32_e32 v16, -1, v13
	v_fma_f32 v17, -v16, v13, v2
	v_cmp_ge_f32_e64 s[40:41], 0, v17
	v_add_u32_e32 v17, 1, v13
	s_waitcnt lgkmcnt(0)
	v_pk_add_f32 v[4:5], v[4:5], v[8:9]
	v_cndmask_b32_e64 v16, v13, v16, s[40:41]
	v_fma_f32 v13, -v17, v13, v2
	v_cmp_lt_f32_e64 s[40:41], 0, v13
	v_pk_add_f32 v[6:7], v[6:7], v[10:11]
	s_waitcnt vmcnt(2)
	v_and_b32_e32 v11, 0xffff0000, v73
	v_cndmask_b32_e64 v13, v16, v17, s[40:41]
	v_mul_f32_e32 v16, 0x37800000, v13
	v_cndmask_b32_e32 v13, v13, v16, vcc
	v_cmp_class_f32_e32 vcc, v2, v248
	s_nop 1
	v_cndmask_b32_e32 v2, v13, v2, vcc
	v_div_scale_f32 v13, s[14:15], v2, v2, 1.0
	v_rcp_f32_e32 v16, v13
	s_nop 0
	v_fma_f32 v8, -v13, v16, 1.0
	v_fmac_f32_e32 v16, v8, v16
	v_div_scale_f32 v8, vcc, 1.0, v2, 1.0
	v_mul_f32_e32 v9, v8, v16
	v_fma_f32 v10, -v13, v9, v8
	v_fmac_f32_e32 v9, v10, v16
	v_fma_f32 v8, -v13, v9, v8
	v_div_fmas_f32 v8, v8, v16, v9
	v_div_fixup_f32 v2, v8, v2, 1.0
	v_lshlrev_b32_e32 v8, 16, v72
	v_and_b32_e32 v9, 0xffff0000, v72
	v_mul_f32_e64 v12, v12, -v2
	v_lshlrev_b32_e32 v10, 16, v73
	v_pk_fma_f32 v[8:9], v[2:3], v[8:9], v[12:13] op_sel_hi:[0,1,0]
	v_pk_fma_f32 v[10:11], v[2:3], v[10:11], v[12:13] op_sel_hi:[0,1,0]
	s_waitcnt vmcnt(0)
	v_pk_fma_f32 v[8:9], v[56:57], v[8:9], v[52:53]
	v_pk_fma_f32 v[10:11], v[58:59], v[10:11], v[54:55]
	v_pk_mul_f32 v[8:9], v[8:9], s[94:95] op_sel_hi:[1,0]
	v_pk_mul_f32 v[10:11], v[10:11], s[94:95] op_sel_hi:[1,0]
	v_pk_fma_f32 v[4:5], v[4:5], 0.5, v[8:9] op_sel_hi:[1,0,1]
	v_pk_fma_f32 v[6:7], v[6:7], 0.5, v[10:11] op_sel_hi:[1,0,1]
	v_cvt_pk_f16_f32 v8, v4, v5
	v_cvt_pk_f16_f32 v9, v6, v7
	v_cvt_f32_f16_e32 v4, v8
	v_cvt_f32_f16_sdwa v5, v8 dst_sel:DWORD dst_unused:UNUSED_PAD src0_sel:WORD_1
	v_cvt_f32_f16_e32 v6, v9
	v_cvt_f32_f16_sdwa v7, v9 dst_sel:DWORD dst_unused:UNUSED_PAD src0_sel:WORD_1
	v_mov_b32_e32 v14, v4
	v_pk_mul_f32 v[10:11], v[4:5], v[4:5]
	v_pk_mul_f32 v[12:13], v[6:7], v[6:7]
	v_mov_b32_e32 v15, v10
	v_mov_b32_e32 v10, v5
	v_pk_add_f32 v[4:5], v[14:15], v[10:11]
	v_mov_b32_e32 v10, v6
	v_mov_b32_e32 v11, v12
	v_mov_b32_e32 v12, v7
	v_pk_add_f32 v[6:7], v[10:11], v[12:13]
	v_lshl_add_u64 v[10:11], s[6:7], 0, v[70:71]
	v_pk_add_f32 v[4:5], v[4:5], v[6:7]
	ds_bpermute_b32 v6, v90, v4
	ds_bpermute_b32 v7, v90, v5
	global_store_dwordx2 v[10:11], v[8:9], off
	s_waitcnt lgkmcnt(0)
	v_pk_add_f32 v[4:5], v[4:5], v[6:7]
	ds_bpermute_b32 v6, v91, v4
	ds_bpermute_b32 v7, v91, v5
	s_waitcnt lgkmcnt(0)
	v_pk_add_f32 v[4:5], v[4:5], v[6:7]
	ds_bpermute_b32 v6, v92, v4
	ds_bpermute_b32 v7, v92, v5
	s_waitcnt lgkmcnt(0)
	v_pk_add_f32 v[4:5], v[4:5], v[6:7]
	ds_bpermute_b32 v6, v93, v4
	ds_bpermute_b32 v7, v93, v5
	s_and_saveexec_b64 s[14:15], s[38:39]
	s_cbranch_execz .LBB0_1816
	v_lshlrev_b64 v[0:1], 6, v[0:1]
	s_lshl_b32 s16, s16, 2
	v_lshl_add_u64 v[0:1], v[0:1], 2, s[8:9]
	s_ashr_i32 s17, s16, 31
	v_lshl_add_u64 v[8:9], s[16:17], 2, v[0:1]
	s_waitcnt lgkmcnt(0)
	v_pk_add_f32 v[0:1], v[4:5], v[6:7]
	v_mov_b32_e32 v2, v3
	global_store_dwordx4 v[8:9], v[0:3], off
	s_branch .LBB0_1816

.LBB0_1882:
	s_ashr_i32 s19, s18, 31
	s_lshl_b64 s[20:21], s[18:19], 17
	s_add_u32 s20, s1, s20
	s_addc_u32 s21, s3, s21
	s_ashr_i32 s17, s16, 31
	s_lshl_b64 s[22:23], s[16:17], 17
	s_add_u32 s22, s34, s22
	s_addc_u32 s23, s35, s23
	s_add_i32 s53, 0, 0x10000
	s_and_b64 s[28:29], s[38:39], exec
	s_cselect_b32 s31, s21, s25
	s_cselect_b32 s30, s20, s24
	s_add_i32 s52, 0, 0x14000
	v_add_u32_e32 v2, s53, v138
	v_add_u32_e32 v214, s52, v138
	ds_read_b128 v[4:7], v2
	ds_read_b128 v[8:11], v2 offset:1024
	ds_read_b128 v[12:15], v2 offset:2048
	ds_read_b128 v[16:19], v2 offset:3072
	ds_read_b128 v[20:23], v214
	ds_read_b128 v[24:27], v214 offset:1024
	ds_read_b128 v[28:31], v214 offset:2048
	ds_read_b128 v[32:35], v214 offset:3072
	v_mov_b32_e32 v253, 1
	v_mov_b64_e32 v[248:249], 0xaff
	s_and_b64 s[28:29], s[38:39], exec
	s_cselect_b32 s29, s23, s27
	s_cselect_b32 s28, s22, s26
	s_add_u32 s50, s24, 0x10080
	s_addc_u32 s51, s25, 0
	s_add_i32 s19, s40, 0xc000
	v_lshl_add_u64 v[68:69], s[50:51], 0, v[0:1]
	s_mov_b32 m0, s19
	s_add_i32 s17, s40, 0xe000
	ds_read_b128 v[36:39], v139
	ds_read_b128 v[40:43], v139 offset:1024
	ds_read_b128 v[44:47], v139 offset:2048
	ds_read_b128 v[48:51], v139 offset:3072
	ds_read_b128 v[52:55], v139 offset:4096
	ds_read_b128 v[56:59], v139 offset:5120
	ds_read_b128 v[60:63], v139 offset:6144
	ds_read_b128 v[64:67], v139 offset:7168
	global_load_lds_dwordx4 v[68:69], off
	v_lshl_add_u64 v[68:69], s[50:51], 0, v[134:135]
	s_mov_b32 m0, s17
	s_nop 0
	global_load_lds_dwordx4 v[68:69], off
	s_waitcnt vmcnt(8)
	s_waitcnt lgkmcnt(0)
	s_setprio 1
	s_barrier
	v_mfma_f32_16x16x32_bf16 v[68:71], v[4:7], v[36:39], 0
	v_mfma_f32_16x16x32_bf16 v[72:75], v[12:15], v[36:39], 0
	v_mfma_f32_16x16x32_bf16 v[76:79], v[4:7], v[44:47], 0
	v_mfma_f32_16x16x32_bf16 v[80:83], v[12:15], v[44:47], 0
	v_mfma_f32_16x16x32_bf16 v[84:87], v[4:7], v[52:55], 0
	v_mfma_f32_16x16x32_bf16 v[88:91], v[12:15], v[52:55], 0
	v_mfma_f32_16x16x32_bf16 v[92:95], v[4:7], v[60:63], 0
	v_mfma_f32_16x16x32_bf16 v[96:99], v[12:15], v[60:63], 0
	v_mfma_f32_16x16x32_bf16 v[68:71], v[8:11], v[40:43], v[68:71]
	v_mfma_f32_16x16x32_bf16 v[72:75], v[16:19], v[40:43], v[72:75]
	v_mfma_f32_16x16x32_bf16 v[76:79], v[8:11], v[48:51], v[76:79]
	v_mfma_f32_16x16x32_bf16 v[80:83], v[16:19], v[48:51], v[80:83]
	v_mfma_f32_16x16x32_bf16 v[84:87], v[8:11], v[56:59], v[84:87]
	v_mfma_f32_16x16x32_bf16 v[88:91], v[16:19], v[56:59], v[88:91]
	v_mfma_f32_16x16x32_bf16 v[92:95], v[8:11], v[64:67], v[92:95]
	v_mfma_f32_16x16x32_bf16 v[96:99], v[16:19], v[64:67], v[96:99]
	v_mfma_f32_16x16x32_bf16 v[100:103], v[20:23], v[36:39], 0
	v_mfma_f32_16x16x32_bf16 v[36:39], v[28:31], v[36:39], 0
	v_mfma_f32_16x16x32_bf16 v[100:103], v[24:27], v[40:43], v[100:103]
	v_mfma_f32_16x16x32_bf16 v[36:39], v[32:35], v[40:43], v[36:39]
	v_mfma_f32_16x16x32_bf16 v[40:43], v[20:23], v[44:47], 0
	v_mfma_f32_16x16x32_bf16 v[44:47], v[28:31], v[44:47], 0
	v_mfma_f32_16x16x32_bf16 v[40:43], v[24:27], v[48:51], v[40:43]
	v_mfma_f32_16x16x32_bf16 v[44:47], v[32:35], v[48:51], v[44:47]
	v_mfma_f32_16x16x32_bf16 v[48:51], v[20:23], v[52:55], 0
	v_mfma_f32_16x16x32_bf16 v[52:55], v[28:31], v[52:55], 0
	v_mfma_f32_16x16x32_bf16 v[48:51], v[24:27], v[56:59], v[48:51]
	v_mfma_f32_16x16x32_bf16 v[52:55], v[32:35], v[56:59], v[52:55]
	v_mfma_f32_16x16x32_bf16 v[56:59], v[20:23], v[60:63], 0
	v_mfma_f32_16x16x32_bf16 v[60:63], v[28:31], v[60:63], 0
	v_mfma_f32_16x16x32_bf16 v[56:59], v[24:27], v[64:67], v[56:59]
	v_mfma_f32_16x16x32_bf16 v[60:63], v[32:35], v[64:67], v[60:63]
	s_barrier
	s_setprio 0
	s_add_i32 s53, s53, s37
	v_lshl_add_u64 v[204:205], s[26:27], 0, v[132:133]
	s_mov_b64 s[56:57], 0x100
	s_add_i32 s50, s53, 0x2000
	v_lshl_add_u64 v[140:141], v[204:205], 0, s[56:57]
	s_mov_b32 m0, s53
	v_lshl_add_u64 v[206:207], s[26:27], 0, v[136:137]
	s_add_u32 s54, s26, 0x10100
	ds_read_b128 v[64:67], v139 offset:16384
	ds_read_b128 v[104:107], v139 offset:17408
	ds_read_b128 v[108:111], v139 offset:18432
	ds_read_b128 v[112:115], v139 offset:19456
	ds_read_b128 v[116:119], v139 offset:20480
	ds_read_b128 v[120:123], v139 offset:21504
	ds_read_b128 v[124:127], v139 offset:22528
	ds_read_b128 v[128:131], v139 offset:23552
	global_load_lds_dwordx4 v[140:141], off
	v_lshl_add_u64 v[140:141], v[206:207], 0, s[56:57]
	s_mov_b32 m0, s50
	s_addc_u32 s55, s27, 0
	s_add_i32 s51, s52, s37
	global_load_lds_dwordx4 v[140:141], off
	v_lshl_add_u64 v[140:141], s[54:55], 0, v[132:133]
	s_mov_b32 m0, s51
	s_add_i32 s52, s51, 0x2000
	global_load_lds_dwordx4 v[140:141], off
	v_lshl_add_u64 v[140:141], s[54:55], 0, v[136:137]
	s_mov_b32 m0, s52
	v_lshl_add_u64 v[208:209], s[24:25], 0, v[0:1]
	global_load_lds_dwordx4 v[140:141], off
	v_lshl_add_u64 v[140:141], v[208:209], 0, s[56:57]
	s_mov_b32 m0, s40
	v_lshl_add_u64 v[210:211], s[24:25], 0, v[134:135]
	global_load_lds_dwordx4 v[140:141], off
	v_lshl_add_u64 v[140:141], v[210:211], 0, s[56:57]
	s_mov_b32 m0, s41
	s_nop 0
	global_load_lds_dwordx4 v[140:141], off
	s_waitcnt vmcnt(8)
	s_waitcnt lgkmcnt(0)
	s_setprio 1
	s_barrier
	v_mfma_f32_16x16x32_bf16 v[140:143], v[4:7], v[64:67], 0
	v_mfma_f32_16x16x32_bf16 v[148:151], v[4:7], v[108:111], 0
	v_mfma_f32_16x16x32_bf16 v[156:159], v[4:7], v[116:119], 0
	v_mfma_f32_16x16x32_bf16 v[4:7], v[4:7], v[124:127], 0
	v_mfma_f32_16x16x32_bf16 v[140:143], v[8:11], v[104:107], v[140:143]
	v_mfma_f32_16x16x32_bf16 v[148:151], v[8:11], v[112:115], v[148:151]
	v_mfma_f32_16x16x32_bf16 v[156:159], v[8:11], v[120:123], v[156:159]
	v_mfma_f32_16x16x32_bf16 v[4:7], v[8:11], v[128:131], v[4:7]
	v_mfma_f32_16x16x32_bf16 v[8:11], v[12:15], v[124:127], 0
	s_nop 0
	v_mfma_f32_16x16x32_bf16 v[8:11], v[16:19], v[128:131], v[8:11]
	v_mfma_f32_16x16x32_bf16 v[144:147], v[12:15], v[64:67], 0
	v_mfma_f32_16x16x32_bf16 v[152:155], v[12:15], v[108:111], 0
	v_mfma_f32_16x16x32_bf16 v[160:163], v[12:15], v[116:119], 0
	v_mfma_f32_16x16x32_bf16 v[144:147], v[16:19], v[104:107], v[144:147]
	v_mfma_f32_16x16x32_bf16 v[152:155], v[16:19], v[112:115], v[152:155]
	v_mfma_f32_16x16x32_bf16 v[160:163], v[16:19], v[120:123], v[160:163]
	v_mfma_f32_16x16x32_bf16 v[12:15], v[20:23], v[64:67], 0
	v_mfma_f32_16x16x32_bf16 v[16:19], v[28:31], v[64:67], 0
	v_mfma_f32_16x16x32_bf16 v[12:15], v[24:27], v[104:107], v[12:15]
	v_mfma_f32_16x16x32_bf16 v[16:19], v[32:35], v[104:107], v[16:19]
	v_mfma_f32_16x16x32_bf16 v[64:67], v[20:23], v[108:111], 0
	v_mfma_f32_16x16x32_bf16 v[104:107], v[28:31], v[108:111], 0
	v_mfma_f32_16x16x32_bf16 v[108:111], v[20:23], v[116:119], 0
	v_mfma_f32_16x16x32_bf16 v[20:23], v[20:23], v[124:127], 0
	v_mfma_f32_16x16x32_bf16 v[64:67], v[24:27], v[112:115], v[64:67]
	v_mfma_f32_16x16x32_bf16 v[104:107], v[32:35], v[112:115], v[104:107]
	v_mfma_f32_16x16x32_bf16 v[108:111], v[24:27], v[120:123], v[108:111]
	v_mfma_f32_16x16x32_bf16 v[112:115], v[28:31], v[116:119], 0
	v_mfma_f32_16x16x32_bf16 v[20:23], v[24:27], v[128:131], v[20:23]
	v_mfma_f32_16x16x32_bf16 v[24:27], v[28:31], v[124:127], 0
	v_mfma_f32_16x16x32_bf16 v[112:115], v[32:35], v[120:123], v[112:115]
	v_mfma_f32_16x16x32_bf16 v[24:27], v[32:35], v[128:131], v[24:27]
	s_barrier
	s_setprio 0
	s_add_i32 s56, 0, 0x18000
	s_add_i32 s58, 0, 0x1c000
	v_add_u32_e32 v215, s56, v138
	v_add_u32_e32 v216, s58, v138
	ds_read_b128 v[28:31], v215
	ds_read_b128 v[32:35], v215 offset:1024
	ds_read_b128 v[116:119], v215 offset:2048
	ds_read_b128 v[120:123], v215 offset:3072
	ds_read_b128 v[124:127], v216
	ds_read_b128 v[128:131], v216 offset:1024
	ds_read_b128 v[164:167], v216 offset:2048
	ds_read_b128 v[168:171], v216 offset:3072
	s_add_u32 s54, s24, 0x10100
	s_addc_u32 s55, s25, 0
	s_mov_b32 m0, s42
	v_lshl_add_u64 v[212:213], s[54:55], 0, v[0:1]
	ds_read_b128 v[172:175], v139 offset:32768
	ds_read_b128 v[176:179], v139 offset:33792
	ds_read_b128 v[180:183], v139 offset:34816
	ds_read_b128 v[184:187], v139 offset:35840
	ds_read_b128 v[188:191], v139 offset:36864
	ds_read_b128 v[192:195], v139 offset:37888
	ds_read_b128 v[196:199], v139 offset:38912
	ds_read_b128 v[200:203], v139 offset:39936
	global_load_lds_dwordx4 v[212:213], off
	v_lshl_add_u64 v[212:213], s[54:55], 0, v[134:135]
	s_mov_b32 m0, s43
	s_nop 0
	global_load_lds_dwordx4 v[212:213], off
	s_waitcnt vmcnt(8)
	s_waitcnt lgkmcnt(0)
	s_setprio 1
	s_barrier
	v_mfma_f32_16x16x32_bf16 v[68:71], v[28:31], v[172:175], v[68:71]
	v_mfma_f32_16x16x32_bf16 v[72:75], v[116:119], v[172:175], v[72:75]
	v_mfma_f32_16x16x32_bf16 v[76:79], v[28:31], v[180:183], v[76:79]
	v_mfma_f32_16x16x32_bf16 v[80:83], v[116:119], v[180:183], v[80:83]
	v_mfma_f32_16x16x32_bf16 v[84:87], v[28:31], v[188:191], v[84:87]
	v_mfma_f32_16x16x32_bf16 v[88:91], v[116:119], v[188:191], v[88:91]
	v_mfma_f32_16x16x32_bf16 v[92:95], v[28:31], v[196:199], v[92:95]
	v_mfma_f32_16x16x32_bf16 v[96:99], v[116:119], v[196:199], v[96:99]
	v_mfma_f32_16x16x32_bf16 v[68:71], v[32:35], v[176:179], v[68:71]
	v_mfma_f32_16x16x32_bf16 v[72:75], v[120:123], v[176:179], v[72:75]
	v_mfma_f32_16x16x32_bf16 v[76:79], v[32:35], v[184:187], v[76:79]
	v_mfma_f32_16x16x32_bf16 v[80:83], v[120:123], v[184:187], v[80:83]
	v_mfma_f32_16x16x32_bf16 v[84:87], v[32:35], v[192:195], v[84:87]
	v_mfma_f32_16x16x32_bf16 v[88:91], v[120:123], v[192:195], v[88:91]
	v_mfma_f32_16x16x32_bf16 v[92:95], v[32:35], v[200:203], v[92:95]
	v_mfma_f32_16x16x32_bf16 v[96:99], v[120:123], v[200:203], v[96:99]
	v_mfma_f32_16x16x32_bf16 v[100:103], v[124:127], v[172:175], v[100:103]
	v_mfma_f32_16x16x32_bf16 v[36:39], v[164:167], v[172:175], v[36:39]
	v_mfma_f32_16x16x32_bf16 v[40:43], v[124:127], v[180:183], v[40:43]
	v_mfma_f32_16x16x32_bf16 v[44:47], v[164:167], v[180:183], v[44:47]
	v_mfma_f32_16x16x32_bf16 v[48:51], v[124:127], v[188:191], v[48:51]
	v_mfma_f32_16x16x32_bf16 v[52:55], v[164:167], v[188:191], v[52:55]
	v_mfma_f32_16x16x32_bf16 v[56:59], v[124:127], v[196:199], v[56:59]
	v_mfma_f32_16x16x32_bf16 v[60:63], v[164:167], v[196:199], v[60:63]
	v_mfma_f32_16x16x32_bf16 v[100:103], v[128:131], v[176:179], v[100:103]
	v_mfma_f32_16x16x32_bf16 v[36:39], v[168:171], v[176:179], v[36:39]
	v_mfma_f32_16x16x32_bf16 v[40:43], v[128:131], v[184:187], v[40:43]
	v_mfma_f32_16x16x32_bf16 v[44:47], v[168:171], v[184:187], v[44:47]
	v_mfma_f32_16x16x32_bf16 v[48:51], v[128:131], v[192:195], v[48:51]
	v_mfma_f32_16x16x32_bf16 v[52:55], v[168:171], v[192:195], v[52:55]
	v_mfma_f32_16x16x32_bf16 v[56:59], v[128:131], v[200:203], v[56:59]
	v_mfma_f32_16x16x32_bf16 v[60:63], v[168:171], v[200:203], v[60:63]
	s_barrier
	s_setprio 0
	s_add_i32 s55, s56, s37
	s_add_i32 s54, s55, 0x2000
	v_lshl_add_u64 v[204:205], v[204:205], 0, s[84:85]
	s_mov_b32 m0, s55
	s_add_u32 s56, s26, 0x10180
	ds_read_b128 v[172:175], v139 offset:49152
	ds_read_b128 v[176:179], v139 offset:50176
	ds_read_b128 v[180:183], v139 offset:51200
	ds_read_b128 v[184:187], v139 offset:52224
	ds_read_b128 v[188:191], v139 offset:53248
	ds_read_b128 v[192:195], v139 offset:54272
	ds_read_b128 v[196:199], v139 offset:55296
	ds_read_b128 v[200:203], v139 offset:56320
	global_load_lds_dwordx4 v[204:205], off
	v_lshl_add_u64 v[204:205], v[206:207], 0, s[84:85]
	s_mov_b32 m0, s54
	s_addc_u32 s57, s27, 0
	s_add_i32 s26, s58, s37
	global_load_lds_dwordx4 v[204:205], off
	v_lshl_add_u64 v[204:205], s[56:57], 0, v[132:133]
	s_mov_b32 m0, s26
	s_add_i32 s27, s26, 0x2000
	global_load_lds_dwordx4 v[204:205], off
	v_lshl_add_u64 v[204:205], s[56:57], 0, v[136:137]
	s_mov_b32 m0, s27
	s_nop 0
	global_load_lds_dwordx4 v[204:205], off
	v_lshl_add_u64 v[204:205], v[208:209], 0, s[84:85]
	s_mov_b32 m0, s46
	s_nop 0
	global_load_lds_dwordx4 v[204:205], off
	v_lshl_add_u64 v[204:205], v[210:211], 0, s[84:85]
	s_mov_b32 m0, s48
	s_nop 0
	global_load_lds_dwordx4 v[204:205], off
	s_waitcnt vmcnt(8)
	s_waitcnt lgkmcnt(0)
	s_setprio 1
	s_barrier
	v_mfma_f32_16x16x32_bf16 v[4:7], v[28:31], v[196:199], v[4:7]
	v_mfma_f32_16x16x32_bf16 v[8:11], v[116:119], v[196:199], v[8:11]
	v_mfma_f32_16x16x32_bf16 v[140:143], v[28:31], v[172:175], v[140:143]
	v_mfma_f32_16x16x32_bf16 v[144:147], v[116:119], v[172:175], v[144:147]
	v_mfma_f32_16x16x32_bf16 v[148:151], v[28:31], v[180:183], v[148:151]
	v_mfma_f32_16x16x32_bf16 v[152:155], v[116:119], v[180:183], v[152:155]
	v_mfma_f32_16x16x32_bf16 v[156:159], v[28:31], v[188:191], v[156:159]
	v_mfma_f32_16x16x32_bf16 v[160:163], v[116:119], v[188:191], v[160:163]
	v_mfma_f32_16x16x32_bf16 v[4:7], v[32:35], v[200:203], v[4:7]
	v_mfma_f32_16x16x32_bf16 v[8:11], v[120:123], v[200:203], v[8:11]
	v_mfma_f32_16x16x32_bf16 v[140:143], v[32:35], v[176:179], v[140:143]
	v_mfma_f32_16x16x32_bf16 v[144:147], v[120:123], v[176:179], v[144:147]
	v_mfma_f32_16x16x32_bf16 v[148:151], v[32:35], v[184:187], v[148:151]
	v_mfma_f32_16x16x32_bf16 v[152:155], v[120:123], v[184:187], v[152:155]
	v_mfma_f32_16x16x32_bf16 v[156:159], v[32:35], v[192:195], v[156:159]
	v_mfma_f32_16x16x32_bf16 v[160:163], v[120:123], v[192:195], v[160:163]
	v_mfma_f32_16x16x32_bf16 v[12:15], v[124:127], v[172:175], v[12:15]
	v_mfma_f32_16x16x32_bf16 v[16:19], v[164:167], v[172:175], v[16:19]
	v_mfma_f32_16x16x32_bf16 v[28:31], v[124:127], v[180:183], v[64:67]
	v_mfma_f32_16x16x32_bf16 v[32:35], v[164:167], v[180:183], v[104:107]
	v_mfma_f32_16x16x32_bf16 v[64:67], v[124:127], v[188:191], v[108:111]
	v_mfma_f32_16x16x32_bf16 v[104:107], v[164:167], v[188:191], v[112:115]
	v_mfma_f32_16x16x32_bf16 v[20:23], v[124:127], v[196:199], v[20:23]
	v_mfma_f32_16x16x32_bf16 v[24:27], v[164:167], v[196:199], v[24:27]
	v_mfma_f32_16x16x32_bf16 v[12:15], v[128:131], v[176:179], v[12:15]
	v_mfma_f32_16x16x32_bf16 v[16:19], v[168:171], v[176:179], v[16:19]
	v_mfma_f32_16x16x32_bf16 v[28:31], v[128:131], v[184:187], v[28:31]
	v_mfma_f32_16x16x32_bf16 v[32:35], v[168:171], v[184:187], v[32:35]
	v_mfma_f32_16x16x32_bf16 v[64:67], v[128:131], v[192:195], v[64:67]
	v_mfma_f32_16x16x32_bf16 v[104:107], v[168:171], v[192:195], v[104:107]
	v_mfma_f32_16x16x32_bf16 v[20:23], v[128:131], v[200:203], v[20:23]
	v_mfma_f32_16x16x32_bf16 v[24:27], v[168:171], v[200:203], v[24:27]
	s_barrier
	s_setprio 0
	ds_read_b128 v[108:111], v2
	ds_read_b128 v[112:115], v2 offset:1024
	ds_read_b128 v[116:119], v2 offset:2048
	ds_read_b128 v[120:123], v2 offset:3072
	ds_read_b128 v[124:127], v214
	ds_read_b128 v[128:131], v214 offset:1024
	ds_read_b128 v[164:167], v214 offset:2048
	ds_read_b128 v[168:171], v214 offset:3072
	s_add_u32 s24, s24, 0x10180
	s_addc_u32 s25, s25, 0
	s_mov_b32 m0, s19
	v_lshl_add_u64 v[204:205], s[24:25], 0, v[0:1]
	ds_read_b128 v[172:175], v139
	ds_read_b128 v[176:179], v139 offset:1024
	ds_read_b128 v[180:183], v139 offset:2048
	ds_read_b128 v[184:187], v139 offset:3072
	ds_read_b128 v[188:191], v139 offset:4096
	ds_read_b128 v[192:195], v139 offset:5120
	ds_read_b128 v[196:199], v139 offset:6144
	ds_read_b128 v[200:203], v139 offset:7168
	global_load_lds_dwordx4 v[204:205], off
	v_lshl_add_u64 v[204:205], s[24:25], 0, v[134:135]
	s_mov_b32 m0, s17
	s_nop 0
	global_load_lds_dwordx4 v[204:205], off
	s_waitcnt vmcnt(8)
	s_waitcnt lgkmcnt(0)
	s_setprio 1
	s_barrier
	v_mfma_f32_16x16x32_bf16 v[68:71], v[108:111], v[172:175], v[68:71]
	v_mfma_f32_16x16x32_bf16 v[72:75], v[116:119], v[172:175], v[72:75]
	v_mfma_f32_16x16x32_bf16 v[76:79], v[108:111], v[180:183], v[76:79]
	v_mfma_f32_16x16x32_bf16 v[80:83], v[116:119], v[180:183], v[80:83]
	v_mfma_f32_16x16x32_bf16 v[84:87], v[108:111], v[188:191], v[84:87]
	v_mfma_f32_16x16x32_bf16 v[88:91], v[116:119], v[188:191], v[88:91]
	v_mfma_f32_16x16x32_bf16 v[92:95], v[108:111], v[196:199], v[92:95]
	v_mfma_f32_16x16x32_bf16 v[96:99], v[116:119], v[196:199], v[96:99]
	v_mfma_f32_16x16x32_bf16 v[68:71], v[112:115], v[176:179], v[68:71]
	v_mfma_f32_16x16x32_bf16 v[72:75], v[120:123], v[176:179], v[72:75]
	v_mfma_f32_16x16x32_bf16 v[76:79], v[112:115], v[184:187], v[76:79]
	v_mfma_f32_16x16x32_bf16 v[80:83], v[120:123], v[184:187], v[80:83]
	v_mfma_f32_16x16x32_bf16 v[84:87], v[112:115], v[192:195], v[84:87]
	v_mfma_f32_16x16x32_bf16 v[88:91], v[120:123], v[192:195], v[88:91]
	v_mfma_f32_16x16x32_bf16 v[92:95], v[112:115], v[200:203], v[92:95]
	v_mfma_f32_16x16x32_bf16 v[96:99], v[120:123], v[200:203], v[96:99]
	v_mfma_f32_16x16x32_bf16 v[36:39], v[164:167], v[172:175], v[36:39]
	v_mfma_f32_16x16x32_bf16 v[100:103], v[124:127], v[172:175], v[100:103]
	v_mfma_f32_16x16x32_bf16 v[172:175], v[168:171], v[176:179], v[36:39]
	v_mfma_f32_16x16x32_bf16 v[36:39], v[124:127], v[180:183], v[40:43]
	v_mfma_f32_16x16x32_bf16 v[204:207], v[128:131], v[176:179], v[100:103]
	v_mfma_f32_16x16x32_bf16 v[176:179], v[128:131], v[184:187], v[36:39]
	v_mfma_f32_16x16x32_bf16 v[36:39], v[164:167], v[180:183], v[44:47]
	v_mfma_f32_16x16x32_bf16 v[44:47], v[168:171], v[184:187], v[36:39]
	v_mfma_f32_16x16x32_bf16 v[36:39], v[124:127], v[188:191], v[48:51]
	v_mfma_f32_16x16x32_bf16 v[48:51], v[128:131], v[192:195], v[36:39]
	v_mfma_f32_16x16x32_bf16 v[36:39], v[164:167], v[188:191], v[52:55]
	v_mfma_f32_16x16x32_bf16 v[52:55], v[168:171], v[192:195], v[36:39]
	v_mfma_f32_16x16x32_bf16 v[36:39], v[124:127], v[196:199], v[56:59]
	v_mfma_f32_16x16x32_bf16 v[56:59], v[128:131], v[200:203], v[36:39]
	v_mfma_f32_16x16x32_bf16 v[36:39], v[164:167], v[196:199], v[60:63]
	v_mfma_f32_16x16x32_bf16 v[60:63], v[168:171], v[200:203], v[36:39]
	s_barrier
	s_setprio 0
	s_mov_b32 m0, s53
	v_lshl_add_u64 v[240:241], s[28:29], 0, v[132:133]
	s_add_u32 s24, s28, 0x10000
	s_nop 1
	ds_read_b128 v[36:39], v139 offset:16384
	ds_read_b128 v[40:43], v139 offset:17408
	ds_read_b128 v[100:103], v139 offset:18432
	ds_read_b128 v[180:183], v139 offset:19456
	ds_read_b128 v[184:187], v139 offset:20480
	ds_read_b128 v[188:191], v139 offset:21504
	ds_read_b128 v[192:195], v139 offset:22528
	ds_read_b128 v[196:199], v139 offset:23552
	global_load_lds_dwordx4 v[240:241], off
	v_lshl_add_u64 v[242:243], s[28:29], 0, v[136:137]
	s_mov_b32 m0, s50
	s_addc_u32 s25, s29, 0
	global_load_lds_dwordx4 v[242:243], off
	v_lshl_add_u64 v[200:201], s[24:25], 0, v[132:133]
	s_mov_b32 m0, s51
	v_lshl_add_u64 v[244:245], s[30:31], 0, v[0:1]
	global_load_lds_dwordx4 v[200:201], off
	v_lshl_add_u64 v[200:201], s[24:25], 0, v[136:137]
	s_mov_b32 m0, s52
	v_lshl_add_u64 v[246:247], s[30:31], 0, v[134:135]
	global_load_lds_dwordx4 v[200:201], off
	s_mov_b32 m0, s40
	s_nop 0
	global_load_lds_dwordx4 v[244:245], off
	s_mov_b32 m0, s41
	s_nop 0
	global_load_lds_dwordx4 v[246:247], off
	s_waitcnt vmcnt(8)
	s_waitcnt lgkmcnt(0)
	s_setprio 1
	s_barrier
	v_mfma_f32_16x16x32_bf16 v[4:7], v[108:111], v[192:195], v[4:7]
	v_mfma_f32_16x16x32_bf16 v[8:11], v[116:119], v[192:195], v[8:11]
	v_mfma_f32_16x16x32_bf16 v[140:143], v[108:111], v[36:39], v[140:143]
	v_mfma_f32_16x16x32_bf16 v[144:147], v[116:119], v[36:39], v[144:147]
	v_mfma_f32_16x16x32_bf16 v[148:151], v[108:111], v[100:103], v[148:151]
	v_mfma_f32_16x16x32_bf16 v[152:155], v[116:119], v[100:103], v[152:155]
	v_mfma_f32_16x16x32_bf16 v[156:159], v[108:111], v[184:187], v[156:159]
	v_mfma_f32_16x16x32_bf16 v[160:163], v[116:119], v[184:187], v[160:163]
	v_mfma_f32_16x16x32_bf16 v[4:7], v[112:115], v[196:199], v[4:7]
	v_mfma_f32_16x16x32_bf16 v[8:11], v[120:123], v[196:199], v[8:11]
	v_mfma_f32_16x16x32_bf16 v[140:143], v[112:115], v[40:43], v[140:143]
	v_mfma_f32_16x16x32_bf16 v[144:147], v[120:123], v[40:43], v[144:147]
	v_mfma_f32_16x16x32_bf16 v[148:151], v[112:115], v[180:183], v[148:151]
	v_mfma_f32_16x16x32_bf16 v[152:155], v[120:123], v[180:183], v[152:155]
	v_mfma_f32_16x16x32_bf16 v[156:159], v[112:115], v[188:191], v[156:159]
	v_mfma_f32_16x16x32_bf16 v[160:163], v[120:123], v[188:191], v[160:163]
	v_mfma_f32_16x16x32_bf16 v[12:15], v[124:127], v[36:39], v[12:15]
	v_mfma_f32_16x16x32_bf16 v[16:19], v[164:167], v[36:39], v[16:19]
	v_mfma_f32_16x16x32_bf16 v[28:31], v[124:127], v[100:103], v[28:31]
	v_mfma_f32_16x16x32_bf16 v[32:35], v[164:167], v[100:103], v[32:35]
	v_mfma_f32_16x16x32_bf16 v[36:39], v[124:127], v[184:187], v[64:67]
	v_mfma_f32_16x16x32_bf16 v[28:31], v[128:131], v[180:183], v[28:31]
	v_mfma_f32_16x16x32_bf16 v[32:35], v[168:171], v[180:183], v[32:35]
	v_mfma_f32_16x16x32_bf16 v[180:183], v[128:131], v[188:191], v[36:39]
	v_mfma_f32_16x16x32_bf16 v[36:39], v[164:167], v[184:187], v[104:107]
	v_mfma_f32_16x16x32_bf16 v[20:23], v[124:127], v[192:195], v[20:23]
	v_mfma_f32_16x16x32_bf16 v[12:15], v[128:131], v[40:43], v[12:15]
	v_mfma_f32_16x16x32_bf16 v[16:19], v[168:171], v[40:43], v[16:19]
	v_mfma_f32_16x16x32_bf16 v[184:187], v[168:171], v[188:191], v[36:39]
	v_mfma_f32_16x16x32_bf16 v[188:191], v[128:131], v[196:199], v[20:23]
	v_mfma_f32_16x16x32_bf16 v[20:23], v[164:167], v[192:195], v[24:27]
	v_mfma_f32_16x16x32_bf16 v[164:167], v[168:171], v[196:199], v[20:23]
	s_barrier
	s_setprio 0
	ds_read_b128 v[64:67], v215
	ds_read_b128 v[168:171], v215 offset:1024
	ds_read_b128 v[192:195], v215 offset:2048
	ds_read_b128 v[196:199], v215 offset:3072
	ds_read_b128 v[200:203], v216
	ds_read_b128 v[208:211], v216 offset:1024
	ds_read_b128 v[212:215], v216 offset:2048
	ds_read_b128 v[216:219], v216 offset:3072
	s_add_u32 s24, s30, 0x10000
	s_addc_u32 s25, s31, 0
	s_mov_b32 m0, s42
	v_lshl_add_u64 v[36:37], s[24:25], 0, v[0:1]
	ds_read_b128 v[20:23], v139 offset:32768
	ds_read_b128 v[24:27], v139 offset:33792
	ds_read_b128 v[112:115], v139 offset:34816
	ds_read_b128 v[220:223], v139 offset:35840
	ds_read_b128 v[224:227], v139 offset:36864
	ds_read_b128 v[228:231], v139 offset:37888
	ds_read_b128 v[232:235], v139 offset:38912
	ds_read_b128 v[236:239], v139 offset:39936
	global_load_lds_dwordx4 v[36:37], off
	v_lshl_add_u64 v[36:37], s[24:25], 0, v[134:135]
	s_mov_b32 m0, s43
	s_nop 0
	global_load_lds_dwordx4 v[36:37], off
	s_waitcnt vmcnt(8)
	s_waitcnt lgkmcnt(0)
	s_setprio 1
	s_barrier
	v_mfma_f32_16x16x32_bf16 v[36:39], v[64:67], v[20:23], v[68:71]
	v_mfma_f32_16x16x32_bf16 v[116:119], v[168:171], v[24:27], v[36:39]
	v_mfma_f32_16x16x32_bf16 v[36:39], v[192:195], v[20:23], v[72:75]
	v_mfma_f32_16x16x32_bf16 v[120:123], v[196:199], v[24:27], v[36:39]
	v_mfma_f32_16x16x32_bf16 v[36:39], v[64:67], v[112:115], v[76:79]
	v_mfma_f32_16x16x32_bf16 v[100:103], v[168:171], v[220:223], v[36:39]
	v_mfma_f32_16x16x32_bf16 v[36:39], v[192:195], v[112:115], v[80:83]
	v_mfma_f32_16x16x32_bf16 v[104:107], v[196:199], v[220:223], v[36:39]
	v_mfma_f32_16x16x32_bf16 v[36:39], v[64:67], v[224:227], v[84:87]
	v_mfma_f32_16x16x32_bf16 v[68:71], v[168:171], v[228:231], v[36:39]
	v_mfma_f32_16x16x32_bf16 v[36:39], v[192:195], v[224:227], v[88:91]
	v_mfma_f32_16x16x32_bf16 v[72:75], v[196:199], v[228:231], v[36:39]
	v_mfma_f32_16x16x32_bf16 v[36:39], v[64:67], v[232:235], v[92:95]
	v_mfma_f32_16x16x32_bf16 v[40:43], v[192:195], v[232:235], v[96:99]
	v_mfma_f32_16x16x32_bf16 v[36:39], v[168:171], v[236:239], v[36:39]
	v_mfma_f32_16x16x32_bf16 v[40:43], v[196:199], v[236:239], v[40:43]
	v_mfma_f32_16x16x32_bf16 v[76:79], v[200:203], v[20:23], v[204:207]
	v_mfma_f32_16x16x32_bf16 v[20:23], v[212:215], v[20:23], v[172:175]
	v_mfma_f32_16x16x32_bf16 v[128:131], v[216:219], v[24:27], v[20:23]
	v_mfma_f32_16x16x32_bf16 v[20:23], v[200:203], v[112:115], v[176:179]
	v_mfma_f32_16x16x32_bf16 v[108:111], v[208:211], v[220:223], v[20:23]
	v_mfma_f32_16x16x32_bf16 v[20:23], v[212:215], v[112:115], v[44:47]
	v_mfma_f32_16x16x32_bf16 v[112:115], v[216:219], v[220:223], v[20:23]
	v_mfma_f32_16x16x32_bf16 v[20:23], v[200:203], v[224:227], v[48:51]
	v_mfma_f32_16x16x32_bf16 v[124:127], v[208:211], v[24:27], v[76:79]
	v_mfma_f32_16x16x32_bf16 v[76:79], v[208:211], v[228:231], v[20:23]
	v_mfma_f32_16x16x32_bf16 v[20:23], v[212:215], v[224:227], v[52:55]
	v_mfma_f32_16x16x32_bf16 v[80:83], v[216:219], v[228:231], v[20:23]
	v_mfma_f32_16x16x32_bf16 v[20:23], v[200:203], v[232:235], v[56:59]
	v_mfma_f32_16x16x32_bf16 v[44:47], v[208:211], v[236:239], v[20:23]
	v_mfma_f32_16x16x32_bf16 v[20:23], v[212:215], v[232:235], v[60:63]
	v_mfma_f32_16x16x32_bf16 v[48:51], v[216:219], v[236:239], v[20:23]
	s_barrier
	s_setprio 0
	s_mov_b32 m0, s55
	s_nop 3
	v_lshl_add_u64 v[20:21], v[240:241], 0, s[74:75]
	s_add_u32 s24, s28, 0x10080
	ds_read_b128 v[60:63], v139 offset:49152
	ds_read_b128 v[96:99], v139 offset:50176
	ds_read_b128 v[172:175], v139 offset:51200
	ds_read_b128 v[176:179], v139 offset:52224
	ds_read_b128 v[204:207], v139 offset:53248
	ds_read_b128 v[220:223], v139 offset:54272
	ds_read_b128 v[224:227], v139 offset:55296
	ds_read_b128 v[228:231], v139 offset:56320
	global_load_lds_dwordx4 v[20:21], off
	v_lshl_add_u64 v[20:21], v[242:243], 0, s[74:75]
	s_mov_b32 m0, s54
	s_addc_u32 s25, s29, 0
	global_load_lds_dwordx4 v[20:21], off
	v_lshl_add_u64 v[20:21], s[24:25], 0, v[132:133]
	s_mov_b32 m0, s26
	s_nop 0
	global_load_lds_dwordx4 v[20:21], off
	v_lshl_add_u64 v[20:21], s[24:25], 0, v[136:137]
	s_mov_b32 m0, s27
	s_nop 0
	global_load_lds_dwordx4 v[20:21], off
	v_lshl_add_u64 v[20:21], v[244:245], 0, s[74:75]
	s_mov_b32 m0, s46
	s_nop 0
	global_load_lds_dwordx4 v[20:21], off
	v_lshl_add_u64 v[20:21], v[246:247], 0, s[74:75]
	s_mov_b32 m0, s48
	s_nop 0
	global_load_lds_dwordx4 v[20:21], off
	s_waitcnt vmcnt(8)
	s_waitcnt lgkmcnt(0)
	s_setprio 1
	s_barrier
	v_mfma_f32_16x16x32_bf16 v[20:23], v[64:67], v[60:63], v[140:143]
	v_mfma_f32_16x16x32_bf16 v[84:87], v[168:171], v[96:99], v[20:23]
	v_mfma_f32_16x16x32_bf16 v[20:23], v[192:195], v[60:63], v[144:147]
	v_mfma_f32_16x16x32_bf16 v[88:91], v[196:199], v[96:99], v[20:23]
	v_mfma_f32_16x16x32_bf16 v[20:23], v[64:67], v[172:175], v[148:151]
	v_mfma_f32_16x16x32_bf16 v[52:55], v[168:171], v[176:179], v[20:23]
	v_mfma_f32_16x16x32_bf16 v[20:23], v[192:195], v[172:175], v[152:155]
	v_mfma_f32_16x16x32_bf16 v[56:59], v[196:199], v[176:179], v[20:23]
	v_mfma_f32_16x16x32_bf16 v[20:23], v[64:67], v[204:207], v[156:159]
	v_mfma_f32_16x16x32_bf16 v[24:27], v[192:195], v[204:207], v[160:163]
	v_mfma_f32_16x16x32_bf16 v[4:7], v[64:67], v[224:227], v[4:7]
	v_mfma_f32_16x16x32_bf16 v[8:11], v[192:195], v[224:227], v[8:11]
	v_mfma_f32_16x16x32_bf16 v[20:23], v[168:171], v[220:223], v[20:23]
	v_mfma_f32_16x16x32_bf16 v[24:27], v[196:199], v[220:223], v[24:27]
	v_mfma_f32_16x16x32_bf16 v[4:7], v[168:171], v[228:231], v[4:7]
	v_mfma_f32_16x16x32_bf16 v[8:11], v[196:199], v[228:231], v[8:11]
	v_mfma_f32_16x16x32_bf16 v[12:15], v[200:203], v[60:63], v[12:15]
	v_mfma_f32_16x16x32_bf16 v[92:95], v[208:211], v[96:99], v[12:15]
	v_mfma_f32_16x16x32_bf16 v[12:15], v[212:215], v[60:63], v[16:19]
	v_mfma_f32_16x16x32_bf16 v[96:99], v[216:219], v[96:99], v[12:15]
	v_mfma_f32_16x16x32_bf16 v[12:15], v[200:203], v[172:175], v[28:31]
	v_mfma_f32_16x16x32_bf16 v[60:63], v[208:211], v[176:179], v[12:15]
	v_mfma_f32_16x16x32_bf16 v[12:15], v[212:215], v[172:175], v[32:35]
	v_mfma_f32_16x16x32_bf16 v[64:67], v[216:219], v[176:179], v[12:15]
	v_mfma_f32_16x16x32_bf16 v[12:15], v[200:203], v[204:207], v[180:183]
	v_mfma_f32_16x16x32_bf16 v[28:31], v[208:211], v[220:223], v[12:15]
	v_mfma_f32_16x16x32_bf16 v[12:15], v[212:215], v[204:207], v[184:187]
	v_mfma_f32_16x16x32_bf16 v[32:35], v[216:219], v[220:223], v[12:15]
	v_mfma_f32_16x16x32_bf16 v[12:15], v[200:203], v[224:227], v[188:191]
	v_mfma_f32_16x16x32_bf16 v[16:19], v[212:215], v[224:227], v[164:167]
	v_mfma_f32_16x16x32_bf16 v[12:15], v[208:211], v[228:231], v[12:15]
	v_mfma_f32_16x16x32_bf16 v[16:19], v[216:219], v[228:231], v[16:19]
	s_barrier
	s_setprio 0
	s_andn2_b64 vcc, exec, s[10:11]
	s_cbranch_vccnz .LBB0_1884
	s_barrier

.LBB0_1933:
	s_add_u32 s21, s28, 0xfffc0080
	s_addc_u32 s30, s29, -1
	s_add_i32 s49, 0, 0x10000
	s_cmp_eq_u32 s3, 12
	s_cselect_b32 s35, s25, s30
	s_cselect_b32 s34, s24, s21
	v_add_u32_e32 v2, s49, v235
	s_cselect_b32 s31, s27, s1
	s_cselect_b32 s30, s26, s0
	s_add_i32 s21, 0, 0x14000
	ds_read_b128 v[116:119], v2
	ds_read_b128 v[120:123], v2 offset:1024
	ds_read_b128 v[124:127], v2 offset:2048
	ds_read_b128 v[128:131], v2 offset:3072
	v_add_u32_e32 v2, s21, v235
	ds_read_b128 v[148:151], v2
	ds_read_b128 v[152:155], v2 offset:1024
	ds_read_b128 v[156:159], v2 offset:2048
	ds_read_b128 v[160:163], v2 offset:3072
	v_lshl_add_u64 v[206:207], s[28:29], 0, v[186:187]
	s_add_i32 m0, s59, 0xc000
	ds_read_b128 v[164:167], v236
	ds_read_b128 v[168:171], v236 offset:1024
	ds_read_b128 v[172:175], v236 offset:2048
	ds_read_b128 v[176:179], v236 offset:3072
	ds_read_b128 v[188:191], v236 offset:4096
	ds_read_b128 v[192:195], v236 offset:5120
	ds_read_b128 v[196:199], v236 offset:6144
	ds_read_b128 v[202:205], v236 offset:7168
	global_load_lds_dwordx4 v[206:207], off
	v_lshl_add_u64 v[206:207], s[28:29], 0, v[200:201]
	s_add_i32 m0, s59, 0xe000
	s_nop 0
	global_load_lds_dwordx4 v[206:207], off
	s_waitcnt vmcnt(8)
	s_waitcnt lgkmcnt(0)
	s_setprio 1
	s_barrier
	v_mfma_f32_16x16x32_f16 v[144:147], v[116:119], v[164:167], v[144:147]
	v_mfma_f32_16x16x32_f16 v[140:143], v[124:127], v[164:167], v[140:143]
	v_mfma_f32_16x16x32_f16 v[136:139], v[116:119], v[172:175], v[136:139]
	v_mfma_f32_16x16x32_f16 v[132:135], v[124:127], v[172:175], v[132:135]
	v_mfma_f32_16x16x32_f16 v[112:115], v[116:119], v[188:191], v[112:115]
	v_mfma_f32_16x16x32_f16 v[108:111], v[124:127], v[188:191], v[108:111]
	v_mfma_f32_16x16x32_f16 v[104:107], v[116:119], v[196:199], v[104:107]
	v_mfma_f32_16x16x32_f16 v[100:103], v[124:127], v[196:199], v[100:103]
	v_mfma_f32_16x16x32_f16 v[144:147], v[120:123], v[168:171], v[144:147]
	v_mfma_f32_16x16x32_f16 v[140:143], v[128:131], v[168:171], v[140:143]
	v_mfma_f32_16x16x32_f16 v[136:139], v[120:123], v[176:179], v[136:139]
	v_mfma_f32_16x16x32_f16 v[132:135], v[128:131], v[176:179], v[132:135]
	v_mfma_f32_16x16x32_f16 v[112:115], v[120:123], v[192:195], v[112:115]
	v_mfma_f32_16x16x32_f16 v[108:111], v[128:131], v[192:195], v[108:111]
	v_mfma_f32_16x16x32_f16 v[104:107], v[120:123], v[202:205], v[104:107]
	v_mfma_f32_16x16x32_f16 v[100:103], v[128:131], v[202:205], v[100:103]
	v_mfma_f32_16x16x32_f16 v[64:67], v[148:151], v[164:167], v[64:67]
	v_mfma_f32_16x16x32_f16 v[60:63], v[156:159], v[164:167], v[60:63]
	v_mfma_f32_16x16x32_f16 v[56:59], v[148:151], v[172:175], v[56:59]
	v_mfma_f32_16x16x32_f16 v[52:55], v[156:159], v[172:175], v[52:55]
	v_mfma_f32_16x16x32_f16 v[48:51], v[148:151], v[188:191], v[48:51]
	v_mfma_f32_16x16x32_f16 v[44:47], v[156:159], v[188:191], v[44:47]
	v_mfma_f32_16x16x32_f16 v[40:43], v[148:151], v[196:199], v[40:43]
	v_mfma_f32_16x16x32_f16 v[36:39], v[156:159], v[196:199], v[36:39]
	v_mfma_f32_16x16x32_f16 v[64:67], v[152:155], v[168:171], v[64:67]
	v_mfma_f32_16x16x32_f16 v[60:63], v[160:163], v[168:171], v[60:63]
	v_mfma_f32_16x16x32_f16 v[56:59], v[152:155], v[176:179], v[56:59]
	v_mfma_f32_16x16x32_f16 v[52:55], v[160:163], v[176:179], v[52:55]
	v_mfma_f32_16x16x32_f16 v[48:51], v[152:155], v[192:195], v[48:51]
	v_mfma_f32_16x16x32_f16 v[44:47], v[160:163], v[192:195], v[44:47]
	v_mfma_f32_16x16x32_f16 v[40:43], v[152:155], v[202:205], v[40:43]
	v_mfma_f32_16x16x32_f16 v[36:39], v[160:163], v[202:205], v[36:39]
	s_barrier
	s_setprio 0
	s_add_i32 s49, s49, s51
	v_lshl_add_u64 v[206:207], s[30:31], 0, v[180:181]
	s_mov_b32 m0, s49
	ds_read_b128 v[164:167], v236 offset:16384
	ds_read_b128 v[168:171], v236 offset:17408
	ds_read_b128 v[172:175], v236 offset:18432
	ds_read_b128 v[176:179], v236 offset:19456
	ds_read_b128 v[188:191], v236 offset:20480
	ds_read_b128 v[192:195], v236 offset:21504
	ds_read_b128 v[196:199], v236 offset:22528
	ds_read_b128 v[202:205], v236 offset:23552
	global_load_lds_dwordx4 v[206:207], off
	s_add_i32 m0, s49, 0x2000
	s_add_u32 s66, s30, 0x40000
	v_lshl_add_u64 v[208:209], s[30:31], 0, v[184:185]
	s_addc_u32 s67, s31, 0
	s_add_i32 s21, s21, s51
	global_load_lds_dwordx4 v[208:209], off
	v_lshl_add_u64 v[210:211], s[66:67], 0, v[180:181]
	s_mov_b32 m0, s21
	v_lshl_add_u64 v[212:213], s[34:35], 0, v[182:183]
	global_load_lds_dwordx4 v[210:211], off
	v_lshl_add_u64 v[210:211], s[66:67], 0, v[184:185]
	s_add_i32 m0, s21, 0x2000
	s_nop 0
	global_load_lds_dwordx4 v[210:211], off
	v_lshl_add_u64 v[210:211], s[34:35], 0, v[0:1]
	s_mov_b32 m0, s59
	s_nop 0
	global_load_lds_dwordx4 v[210:211], off
	s_mov_b32 m0, s64
	s_nop 0
	global_load_lds_dwordx4 v[212:213], off
	s_waitcnt vmcnt(8)
	s_waitcnt lgkmcnt(0)
	s_setprio 1
	s_barrier
	v_mfma_f32_16x16x32_f16 v[96:99], v[116:119], v[164:167], v[96:99]
	v_mfma_f32_16x16x32_f16 v[92:95], v[124:127], v[164:167], v[92:95]
	v_mfma_f32_16x16x32_f16 v[88:91], v[116:119], v[172:175], v[88:91]
	v_mfma_f32_16x16x32_f16 v[84:87], v[124:127], v[172:175], v[84:87]
	v_mfma_f32_16x16x32_f16 v[80:83], v[116:119], v[188:191], v[80:83]
	v_mfma_f32_16x16x32_f16 v[76:79], v[124:127], v[188:191], v[76:79]
	v_mfma_f32_16x16x32_f16 v[72:75], v[116:119], v[196:199], v[72:75]
	v_mfma_f32_16x16x32_f16 v[68:71], v[124:127], v[196:199], v[68:71]
	v_mfma_f32_16x16x32_f16 v[96:99], v[120:123], v[168:171], v[96:99]
	v_mfma_f32_16x16x32_f16 v[92:95], v[128:131], v[168:171], v[92:95]
	v_mfma_f32_16x16x32_f16 v[88:91], v[120:123], v[176:179], v[88:91]
	v_mfma_f32_16x16x32_f16 v[84:87], v[128:131], v[176:179], v[84:87]
	v_mfma_f32_16x16x32_f16 v[80:83], v[120:123], v[192:195], v[80:83]
	v_mfma_f32_16x16x32_f16 v[76:79], v[128:131], v[192:195], v[76:79]
	v_mfma_f32_16x16x32_f16 v[72:75], v[120:123], v[202:205], v[72:75]
	v_mfma_f32_16x16x32_f16 v[68:71], v[128:131], v[202:205], v[68:71]
	v_mfma_f32_16x16x32_f16 v[32:35], v[148:151], v[164:167], v[32:35]
	v_mfma_f32_16x16x32_f16 v[28:31], v[156:159], v[164:167], v[28:31]
	v_mfma_f32_16x16x32_f16 v[24:27], v[148:151], v[172:175], v[24:27]
	v_mfma_f32_16x16x32_f16 v[20:23], v[156:159], v[172:175], v[20:23]
	v_mfma_f32_16x16x32_f16 v[16:19], v[148:151], v[188:191], v[16:19]
	v_mfma_f32_16x16x32_f16 v[12:15], v[156:159], v[188:191], v[12:15]
	v_mfma_f32_16x16x32_f16 v[8:11], v[148:151], v[196:199], v[8:11]
	v_mfma_f32_16x16x32_f16 v[4:7], v[156:159], v[196:199], v[4:7]
	v_mfma_f32_16x16x32_f16 v[32:35], v[152:155], v[168:171], v[32:35]
	v_mfma_f32_16x16x32_f16 v[28:31], v[160:163], v[168:171], v[28:31]
	v_mfma_f32_16x16x32_f16 v[24:27], v[152:155], v[176:179], v[24:27]
	v_mfma_f32_16x16x32_f16 v[20:23], v[160:163], v[176:179], v[20:23]
	v_mfma_f32_16x16x32_f16 v[16:19], v[152:155], v[192:195], v[16:19]
	v_mfma_f32_16x16x32_f16 v[12:15], v[160:163], v[192:195], v[12:15]
	v_mfma_f32_16x16x32_f16 v[8:11], v[152:155], v[202:205], v[8:11]
	v_mfma_f32_16x16x32_f16 v[4:7], v[160:163], v[202:205], v[4:7]
	s_barrier
	s_setprio 0
	s_add_i32 s21, 0, 0x18000
	v_add_u32_e32 v2, s21, v235
	s_add_i32 s49, 0, 0x1c000
	ds_read_b128 v[116:119], v2
	ds_read_b128 v[120:123], v2 offset:1024
	ds_read_b128 v[124:127], v2 offset:2048
	ds_read_b128 v[128:131], v2 offset:3072
	v_add_u32_e32 v2, s49, v235
	ds_read_b128 v[148:151], v2
	ds_read_b128 v[152:155], v2 offset:1024
	ds_read_b128 v[156:159], v2 offset:2048
	ds_read_b128 v[160:163], v2 offset:3072
	s_add_u32 s34, s34, 0x40000
	s_addc_u32 s35, s35, 0
	s_mov_b32 m0, s76
	v_lshl_add_u64 v[214:215], s[34:35], 0, v[0:1]
	ds_read_b128 v[164:167], v236 offset:32768
	ds_read_b128 v[168:171], v236 offset:33792
	ds_read_b128 v[172:175], v236 offset:34816
	ds_read_b128 v[176:179], v236 offset:35840
	ds_read_b128 v[188:191], v236 offset:36864
	ds_read_b128 v[192:195], v236 offset:37888
	ds_read_b128 v[196:199], v236 offset:38912
	ds_read_b128 v[202:205], v236 offset:39936
	global_load_lds_dwordx4 v[214:215], off
	v_lshl_add_u64 v[214:215], s[34:35], 0, v[182:183]
	s_mov_b32 m0, s77
	s_nop 0
	global_load_lds_dwordx4 v[214:215], off
	s_waitcnt vmcnt(8)
	s_waitcnt lgkmcnt(0)
	s_setprio 1
	s_barrier
	v_mfma_f32_16x16x32_f16 v[144:147], v[116:119], v[164:167], v[144:147]
	v_mfma_f32_16x16x32_f16 v[140:143], v[124:127], v[164:167], v[140:143]
	v_mfma_f32_16x16x32_f16 v[136:139], v[116:119], v[172:175], v[136:139]
	v_mfma_f32_16x16x32_f16 v[132:135], v[124:127], v[172:175], v[132:135]
	v_mfma_f32_16x16x32_f16 v[112:115], v[116:119], v[188:191], v[112:115]
	v_mfma_f32_16x16x32_f16 v[108:111], v[124:127], v[188:191], v[108:111]
	v_mfma_f32_16x16x32_f16 v[104:107], v[116:119], v[196:199], v[104:107]
	v_mfma_f32_16x16x32_f16 v[100:103], v[124:127], v[196:199], v[100:103]
	v_mfma_f32_16x16x32_f16 v[144:147], v[120:123], v[168:171], v[144:147]
	v_mfma_f32_16x16x32_f16 v[140:143], v[128:131], v[168:171], v[140:143]
	v_mfma_f32_16x16x32_f16 v[136:139], v[120:123], v[176:179], v[136:139]
	v_mfma_f32_16x16x32_f16 v[132:135], v[128:131], v[176:179], v[132:135]
	v_mfma_f32_16x16x32_f16 v[112:115], v[120:123], v[192:195], v[112:115]
	v_mfma_f32_16x16x32_f16 v[108:111], v[128:131], v[192:195], v[108:111]
	v_mfma_f32_16x16x32_f16 v[104:107], v[120:123], v[202:205], v[104:107]
	v_mfma_f32_16x16x32_f16 v[100:103], v[128:131], v[202:205], v[100:103]
	v_mfma_f32_16x16x32_f16 v[64:67], v[148:151], v[164:167], v[64:67]
	v_mfma_f32_16x16x32_f16 v[60:63], v[156:159], v[164:167], v[60:63]
	v_mfma_f32_16x16x32_f16 v[56:59], v[148:151], v[172:175], v[56:59]
	v_mfma_f32_16x16x32_f16 v[52:55], v[156:159], v[172:175], v[52:55]
	v_mfma_f32_16x16x32_f16 v[48:51], v[148:151], v[188:191], v[48:51]
	v_mfma_f32_16x16x32_f16 v[44:47], v[156:159], v[188:191], v[44:47]
	v_mfma_f32_16x16x32_f16 v[40:43], v[148:151], v[196:199], v[40:43]
	v_mfma_f32_16x16x32_f16 v[36:39], v[156:159], v[196:199], v[36:39]
	v_mfma_f32_16x16x32_f16 v[64:67], v[152:155], v[168:171], v[64:67]
	v_mfma_f32_16x16x32_f16 v[60:63], v[160:163], v[168:171], v[60:63]
	v_mfma_f32_16x16x32_f16 v[56:59], v[152:155], v[176:179], v[56:59]
	v_mfma_f32_16x16x32_f16 v[52:55], v[160:163], v[176:179], v[52:55]
	v_mfma_f32_16x16x32_f16 v[48:51], v[152:155], v[192:195], v[48:51]
	v_mfma_f32_16x16x32_f16 v[44:47], v[160:163], v[192:195], v[44:47]
	v_mfma_f32_16x16x32_f16 v[40:43], v[152:155], v[202:205], v[40:43]
	v_mfma_f32_16x16x32_f16 v[36:39], v[160:163], v[202:205], v[36:39]
	s_barrier
	s_setprio 0
	s_add_i32 s21, s21, s51
	v_lshl_add_u64 v[206:207], v[206:207], 0, s[74:75]
	s_mov_b32 m0, s21
	ds_read_b128 v[164:167], v236 offset:49152
	ds_read_b128 v[168:171], v236 offset:50176
	ds_read_b128 v[172:175], v236 offset:51200
	ds_read_b128 v[176:179], v236 offset:52224
	ds_read_b128 v[188:191], v236 offset:53248
	ds_read_b128 v[192:195], v236 offset:54272
	ds_read_b128 v[196:199], v236 offset:55296
	ds_read_b128 v[202:205], v236 offset:56320
	global_load_lds_dwordx4 v[206:207], off
	s_add_i32 m0, s21, 0x2000
	s_add_u32 s30, s30, 0x40080
	v_lshl_add_u64 v[206:207], v[208:209], 0, s[74:75]
	s_addc_u32 s31, s31, 0
	s_add_i32 s21, s49, s51
	global_load_lds_dwordx4 v[206:207], off
	v_lshl_add_u64 v[206:207], s[30:31], 0, v[180:181]
	s_mov_b32 m0, s21
	s_nop 0
	global_load_lds_dwordx4 v[206:207], off
	v_lshl_add_u64 v[206:207], s[30:31], 0, v[184:185]
	s_add_i32 m0, s21, 0x2000
	s_nop 0
	global_load_lds_dwordx4 v[206:207], off
	v_lshl_add_u64 v[206:207], v[210:211], 0, s[74:75]
	s_mov_b32 m0, s88
	s_nop 0
	global_load_lds_dwordx4 v[206:207], off
	v_lshl_add_u64 v[206:207], v[212:213], 0, s[74:75]
	s_mov_b32 m0, s90
	s_nop 0
	global_load_lds_dwordx4 v[206:207], off
	s_waitcnt vmcnt(8)
	s_waitcnt lgkmcnt(0)
	s_setprio 1
	s_barrier
	v_mfma_f32_16x16x32_f16 v[96:99], v[116:119], v[164:167], v[96:99]
	v_mfma_f32_16x16x32_f16 v[92:95], v[124:127], v[164:167], v[92:95]
	v_mfma_f32_16x16x32_f16 v[88:91], v[116:119], v[172:175], v[88:91]
	v_mfma_f32_16x16x32_f16 v[84:87], v[124:127], v[172:175], v[84:87]
	v_mfma_f32_16x16x32_f16 v[80:83], v[116:119], v[188:191], v[80:83]
	v_mfma_f32_16x16x32_f16 v[76:79], v[124:127], v[188:191], v[76:79]
	v_mfma_f32_16x16x32_f16 v[72:75], v[116:119], v[196:199], v[72:75]
	v_mfma_f32_16x16x32_f16 v[68:71], v[124:127], v[196:199], v[68:71]
	v_mfma_f32_16x16x32_f16 v[96:99], v[120:123], v[168:171], v[96:99]
	v_mfma_f32_16x16x32_f16 v[92:95], v[128:131], v[168:171], v[92:95]
	v_mfma_f32_16x16x32_f16 v[88:91], v[120:123], v[176:179], v[88:91]
	v_mfma_f32_16x16x32_f16 v[84:87], v[128:131], v[176:179], v[84:87]
	v_mfma_f32_16x16x32_f16 v[80:83], v[120:123], v[192:195], v[80:83]
	v_mfma_f32_16x16x32_f16 v[76:79], v[128:131], v[192:195], v[76:79]
	v_mfma_f32_16x16x32_f16 v[72:75], v[120:123], v[202:205], v[72:75]
	v_mfma_f32_16x16x32_f16 v[68:71], v[128:131], v[202:205], v[68:71]
	v_mfma_f32_16x16x32_f16 v[32:35], v[148:151], v[164:167], v[32:35]
	v_mfma_f32_16x16x32_f16 v[28:31], v[156:159], v[164:167], v[28:31]
	v_mfma_f32_16x16x32_f16 v[24:27], v[148:151], v[172:175], v[24:27]
	v_mfma_f32_16x16x32_f16 v[20:23], v[156:159], v[172:175], v[20:23]
	v_mfma_f32_16x16x32_f16 v[16:19], v[148:151], v[188:191], v[16:19]
	v_mfma_f32_16x16x32_f16 v[12:15], v[156:159], v[188:191], v[12:15]
	v_mfma_f32_16x16x32_f16 v[8:11], v[148:151], v[196:199], v[8:11]
	v_mfma_f32_16x16x32_f16 v[4:7], v[156:159], v[196:199], v[4:7]
	v_mfma_f32_16x16x32_f16 v[32:35], v[152:155], v[168:171], v[32:35]
	v_mfma_f32_16x16x32_f16 v[28:31], v[160:163], v[168:171], v[28:31]
	v_mfma_f32_16x16x32_f16 v[24:27], v[152:155], v[176:179], v[24:27]
	v_mfma_f32_16x16x32_f16 v[20:23], v[160:163], v[176:179], v[20:23]
	v_mfma_f32_16x16x32_f16 v[16:19], v[152:155], v[192:195], v[16:19]
	v_mfma_f32_16x16x32_f16 v[12:15], v[160:163], v[192:195], v[12:15]
	v_mfma_f32_16x16x32_f16 v[8:11], v[152:155], v[202:205], v[8:11]
	v_mfma_f32_16x16x32_f16 v[4:7], v[160:163], v[202:205], v[4:7]
	s_barrier
	s_setprio 0
	s_add_i32 s3, s3, 2
	s_add_u32 s28, s28, 0x100
	s_addc_u32 s29, s29, 0
	s_add_u32 s0, s0, 0x100
	s_addc_u32 s1, s1, 0
	s_cmp_gt_u32 s3, 13
	s_cbranch_scc0 .LBB0_1933
	s_and_b64 vcc, exec, s[18:19]
	s_cbranch_vccz .LBB0_1936
	s_barrier
